# phase4 native sparse attention rewritten by hand (exact rank selection, double-buffered K/V blocks, unmasked fast path for fully visible blocks, hardware bf16 pack); phase7 memory attention rewritten
# speedup vs baseline: 1.1735x; 1.0305x over previous
; DEVI int launder(int x) { asm volatile("" : "+v"(x)); return x; }
; DEVI float bf2f(u16 h) { return __uint_as_float(((unsigned)h) << 16); }
; DEVI float sigmoidf_(float x) { return __builtin_amdgcn_rcpf(1.f + __expf(-x)); }
; DEVI void phase_nsa(const Params& p, unsigned char* smem) {
;     ...
;   for (int tile = blockIdx.x; tile < 2048; tile += gridDim.x) {
;     const int tid = launder(threadIdx.x), lane = tid & 63, w = tid >> 6, col = lane & 15, quad = lane >> 4;
;     const int tj = tile >> 5, ti = tj & 15, tk = tj >> 4;
;     const int qtile = (tk == 0) ? 63 - ti : (tk == 1) ? 32 + ti : (tk == 2) ? 31 - ti : ti;
;     const int bg = tile & 31, b = bg >> 1, g = bg & 1, q0 = qtile * 32;
;     const bool need_sel = (q0 + 31) >= 16 * 64;
;     const int h = g * 4 + w;
;     __syncthreads();
;     if (tid < 32) selm[tid] = 0u;
;     {
;       const u16* kcp = p.kc + (size_t)bg * 128 * 64;
;       const u16* vcp = p.vcT + (size_t)bg * 64 * 128;
; #pragma unroll
;       for (int i = 0; i < 4; ++i) {
;         const int c = tid + 256 * i;
;         const int row = c >> 3, ch = (c & 7) << 3;
;         *(uint4*)(sK + row * 72 + ch) = *(const uint4*)(kcp + row * 64 + ch);
;         const int row2 = c >> 4, ch2 = (c & 15) << 3;
;         *(uint4*)(sVt + row2 * 136 + ch2) = *(const uint4*)(vcp + row2 * 128 + ch2);
;       }
;     }
;     bf16x8 qf[2][2];
;     float gate[2][3];
;     int tq[2];
; #pragma unroll
;     for (int qt = 0; qt < 2; ++qt) {
;       const int t = q0 + 16 * qt + col;
;       tq[qt] = t;
;       const size_t tok = (size_t)b * T + t;
;       const u16* qp = p.proj + tok * LDP + C_Q + h * 64 + 8 * quad;
;       qf[qt][0] = *(const bf16x8*)qp;
;       qf[qt][1] = *(const bf16x8*)(qp + 32);
; #pragma unroll
;       for (int br = 0; br < 3; ++br) gate[qt][br] = sigmoidf_(bf2f(p.proj[tok * LDP + C_GATE + h * 3 + br]));
;     }
;     __syncthreads();
.LBB0_748:
	s_cmp_gt_i32 s88, 4
	s_cselect_b64 s[0:1], -1, 0
	s_cmp_lt_i32 s89, 4
	s_cselect_b64 s[2:3], -1, 0
	s_or_b64 s[0:1], s[0:1], s[2:3]
	s_and_b64 vcc, exec, s[0:1]
	s_cbranch_vccnz .LBB0_888
	v_writelane_b32 v247, s70, 42
	s_cmpk_gt_i32 s90, 0x7ff
	s_nop 0
	v_writelane_b32 v247, s71, 43
	v_writelane_b32 v247, s68, 44
	s_nop 1
	v_writelane_b32 v247, s69, 45
	v_writelane_b32 v247, s66, 46
	v_writelane_b32 v247, s90, 47
	s_cbranch_scc1 .LBB0_834
	s_load_dwordx2 s[0:1], s[68:69], 0xe8
	s_load_dwordx2 s[2:3], s[68:69], 0xf0
	s_load_dwordx2 s[4:5], s[68:69], 0x100
	s_load_dwordx2 s[6:7], s[68:69], 0x108
	s_load_dwordx2 s[8:9], s[68:69], 0x180
	s_load_dwordx2 s[10:11], s[68:69], 0x190
	s_load_dwordx2 s[12:13], s[68:69], 0x198
	s_load_dword s15, s[68:69], 0x200
	s_mov_b32 s14, s90
	v_and_b32_e32 v197, 15, v210
	v_bfe_u32 v198, v210, 4, 2
	v_and_b32_e32 v199, 63, v210
	v_xor_b32_e32 v195, 16, v199
	v_lshlrev_b32_e32 v195, 2, v195
	v_add_u32_e32 v196, 48, v199
	v_and_b32_e32 v196, 63, v196
	v_lshlrev_b32_e32 v196, 2, v196
	v_mul_u32_u24_e32 v190, 0x90, v197
	v_lshl_add_u32 v190, v198, 4, v190
	v_mul_u32_u24_e32 v191, 0x90, v197
	v_lshl_add_u32 v191, v198, 3, v191
	v_mul_u32_u24_e32 v192, 0x110, v197
	v_lshl_add_u32 v192, v198, 3, v192
	v_lshrrev_b32_e32 v211, 3, v210
	v_and_b32_e32 v212, 7, v210
	v_lshlrev_b32_e32 v212, 4, v212
	v_mul_u32_u24_e32 v193, 0x90, v211
	v_add_u32_e32 v193, v212, v193
	v_mul_u32_u24_e32 v201, 0x1240, v211
	v_add_u32_e32 v201, v212, v201
	v_add_u32_e32 v202, 0x24800, v201
	v_mul_u32_u24_e32 v203, 0x1080, v211
	v_add_u32_e32 v203, v212, v203
	v_add_u32_e32 v204, 0x21000, v203
	v_lshrrev_b32_e32 v211, 4, v210
	v_and_b32_e32 v212, 15, v210
	v_lshlrev_b32_e32 v212, 4, v212
	v_mul_u32_u24_e32 v194, 0x110, v211
	v_add_u32_e32 v194, v212, v194
	v_lshrrev_b32_e32 v209, 6, v210
	v_mul_u32_u24_e32 v205, 0x1240, v197
	v_lshl_add_u32 v205, v209, 7, v205
	v_lshl_add_u32 v205, v198, 4, v205
	v_add_u32_e32 v206, 0x12400, v205
	v_mov_b32_e32 v200, 0x3e38aa3b
	s_waitcnt lgkmcnt(0)
	s_cmp_ge_u32 s14, 0x800
	s_cbranch_scc1 .Lp4_done
.Lp4_tile:
	s_lshr_b32 s22, s14, 5
	s_and_b32 s23, s22, 15
	s_lshr_b32 s22, s22, 4
	s_sub_u32 s24, 63, s23
	s_cmp_eq_u32 s22, 1
	s_cselect_b32 s19, 32, 0
	s_add_u32 s19, s19, s23
	s_cmp_eq_u32 s22, 0
	s_cselect_b32 s19, s24, s19
	s_sub_u32 s24, 31, s23
	s_cmp_eq_u32 s22, 2
	s_cselect_b32 s19, s24, s19
	s_lshl_b32 s19, s19, 5
	s_and_b32 s18, s14, 31
	s_lshr_b32 s16, s18, 1
	s_and_b32 s17, s18, 1
	s_add_u32 s20, s19, 31
	s_cmp_ge_u32 s20, 0x400
	s_cselect_b32 s21, 1, 0
	s_lshr_b32 s20, s20, 6
	s_lshl_b32 s44, s16, 11
	s_add_u32 s44, s44, s19
	s_mul_i32 s44, s44, 0x1240
	s_sub_u32 s45, s19, 0x1ff
	s_lshr_b32 s45, s45, 6
	s_cmp_ge_u32 s19, 0x1ff
	s_cselect_b32 s45, s45, 0
	v_add_u32_e32 v186, s19, v197
	v_add_u32_e32 v187, 16, v186
	s_barrier
	v_mov_b32_e32 v214, 0
	v_lshlrev_b32_e32 v215, 2, v210
	v_cmp_gt_u32_e64 s[32:33], 32, v210
	s_and_saveexec_b64 s[34:35], s[32:33]
	ds_write_b32 v215, v214 offset:56960
	s_mov_b64 exec, s[34:35]
	s_lshl_b32 s22, s17, 9
	s_add_u32 s22, s22, s44
	v_add_u32_e32 v216, s22, v205
	v_add_u32_e32 v217, s22, v206
	global_load_dwordx4 v[0:3], v216, s[0:1] offset:2048
	global_load_dwordx4 v[4:7], v216, s[0:1] offset:2112
	global_load_dwordx4 v[8:11], v217, s[0:1] offset:2048
	global_load_dwordx4 v[12:15], v217, s[0:1] offset:2112
	v_mul_u32_u24_e32 v218, 0x1240, v197
	v_mul_u32_u24_e32 v220, 6, v209
	v_add_u32_e32 v218, v220, v218
	s_mul_i32 s22, s17, 24
	s_add_u32 s22, s22, s44
	s_add_u32 s22, s22, 0x1200
	v_add_u32_e32 v218, s22, v218
	v_add_u32_e32 v219, 0x12400, v218
	global_load_ushort v176, v218, s[0:1]
	global_load_ushort v177, v218, s[0:1] offset:2
	global_load_ushort v178, v218, s[0:1] offset:4
	global_load_ushort v179, v219, s[0:1]
	global_load_ushort v180, v219, s[0:1] offset:2
	global_load_ushort v181, v219, s[0:1] offset:4
	s_lshl_b32 s22, s16, 11
	s_add_u32 s22, s22, s19
	s_lshl_b32 s22, s22, 6
	v_lshlrev_b32_e32 v221, 6, v197
	v_add_u32_e32 v221, s22, v221
	v_add_u32_e32 v222, 0x400, v221
	v_lshlrev_b32_e32 v223, 4, v210
	s_lshl_b32 s22, s18, 14
	v_add_u32_e32 v223, s22, v223
	v_mov_b32_e32 v224, v223
	global_load_dwordx4 v[160:163], v224, s[10:11]
	v_add_u32_e32 v225, 0x1000, v223
	global_load_dwordx4 v[164:167], v225, s[10:11]
	v_add_u32_e32 v226, 0x2000, v223
	global_load_dwordx4 v[168:171], v226, s[10:11]
	v_add_u32_e32 v227, 0x3000, v223
	global_load_dwordx4 v[172:175], v227, s[10:11]
	s_waitcnt vmcnt(0)
	ds_write_b128 v193, v[160:163]
	ds_write_b128 v193, v[164:167] offset:4608
	ds_write_b128 v193, v[168:171] offset:9216
	ds_write_b128 v193, v[172:175] offset:13824
	global_load_dwordx4 v[160:163], v224, s[12:13]
	global_load_dwordx4 v[164:167], v225, s[12:13]
	global_load_dwordx4 v[168:171], v226, s[12:13]
	global_load_dwordx4 v[172:175], v227, s[12:13]
	s_waitcnt vmcnt(0)
	ds_write_b128 v194, v[160:163] offset:18432
	ds_write_b128 v194, v[164:167] offset:22784
	ds_write_b128 v194, v[168:171] offset:27136
	ds_write_b128 v194, v[172:175] offset:31488
	global_load_dwordx4 v[144:147], v221, s[8:9]
	global_load_dwordx4 v[148:151], v221, s[8:9] offset:16
	global_load_dwordx4 v[152:155], v221, s[8:9] offset:32
	global_load_dwordx4 v[156:159], v221, s[8:9] offset:48
	global_load_dwordx4 v[160:163], v222, s[8:9]
	global_load_dwordx4 v[164:167], v222, s[8:9] offset:16
	global_load_dwordx4 v[168:171], v222, s[8:9] offset:32
	global_load_dwordx4 v[172:175], v222, s[8:9] offset:48
	s_waitcnt vmcnt(8) lgkmcnt(0)
	v_lshlrev_b32_e32 v176, 16, v176
	v_mul_f32_e32 v228, 0xbfb8aa3b, v176
	v_exp_f32_e32 v228, v228
	s_nop 0
	v_add_f32_e32 v228, 0x3f800000, v228
	v_rcp_f32_e32 v176, v228
	s_nop 0
	v_lshlrev_b32_e32 v177, 16, v177
	v_mul_f32_e32 v228, 0xbfb8aa3b, v177
	v_exp_f32_e32 v228, v228
	s_nop 0
	v_add_f32_e32 v228, 0x3f800000, v228
	v_rcp_f32_e32 v177, v228
	s_nop 0
	v_lshlrev_b32_e32 v178, 16, v178
	v_mul_f32_e32 v228, 0xbfb8aa3b, v178
	v_exp_f32_e32 v228, v228
	s_nop 0
	v_add_f32_e32 v228, 0x3f800000, v228
	v_rcp_f32_e32 v178, v228
	s_nop 0
	v_lshlrev_b32_e32 v179, 16, v179
	v_mul_f32_e32 v228, 0xbfb8aa3b, v179
	v_exp_f32_e32 v228, v228
	s_nop 0
	v_add_f32_e32 v228, 0x3f800000, v228
	v_rcp_f32_e32 v179, v228
	s_nop 0
	v_lshlrev_b32_e32 v180, 16, v180
	v_mul_f32_e32 v228, 0xbfb8aa3b, v180
	v_exp_f32_e32 v228, v228
	s_nop 0
	v_add_f32_e32 v228, 0x3f800000, v228
	v_rcp_f32_e32 v180, v228
	s_nop 0
	v_lshlrev_b32_e32 v181, 16, v181
	v_mul_f32_e32 v228, 0xbfb8aa3b, v181
	v_exp_f32_e32 v228, v228
	s_nop 0
	v_add_f32_e32 v228, 0x3f800000, v228
	v_rcp_f32_e32 v181, v228
	s_nop 0
	s_barrier
; DEVI f32x4 mfma16(bf16x8 a, bf16x8 b, f32x4 c) { return __builtin_amdgcn_mfma_f32_16x16x32_bf16(a, b, c, 0, 0, 0); }
; DEVI void phase_nsa(const Params& p, unsigned char* smem) {
;     ...
;       for (int qt = 0; qt < 2; ++qt) {
;         f32x4 s[8];
; #pragma unroll
;         for (int kt = 0; kt < 8; ++kt) {
;           s[kt] = f32x4{0.f, 0.f, 0.f, 0.f};
; #pragma unroll
;           for (int ks = 0; ks < 2; ++ks) {
;             const bf16x8 kf = *(const bf16x8*)(sK + (16 * kt + col) * 72 + 32 * ks + 8 * quad);
;             s[kt] = mfma16(kf, qf[qt][ks], s[kt]);
;           }
;         }
;         const int t = tq[qt];
;         float mx = -1e30f;
; #pragma unroll
;         for (int kt = 0; kt < 8; ++kt)
; #pragma unroll
;           for (int r = 0; r < 4; ++r) {
;             const int c = 16 * kt + 4 * quad + r;
;             const bool v = (16 * c + 31) <= t;
;             const float sv = v ? s[kt][r] : -1e30f;
;             s[kt][r] = sv;
;             mx = fmaxf(mx, sv);
;           }
;         mx = fmaxf(mx, __shfl_xor(mx, 16));
;         mx = fmaxf(mx, __shfl_xor(mx, 32));
	v_mov_b32_e32 v230, 0xf149f2ca
	s_mov_b32 s38, 0xffff0000
	s_mov_b32 s39, 0xffffffff
	ds_read_b128 v[112:115], v190
	ds_read_b128 v[116:119], v190 offset:64
	s_waitcnt lgkmcnt(0)
	v_mfma_f32_16x16x32_bf16 v[80:83], v[112:115], v[0:3], 0
	v_mfma_f32_16x16x32_bf16 v[80:83], v[116:119], v[4:7], v[80:83]
	ds_read_b128 v[120:123], v190 offset:2304
	ds_read_b128 v[124:127], v190 offset:2368
	s_waitcnt lgkmcnt(0)
	v_mfma_f32_16x16x32_bf16 v[84:87], v[120:123], v[0:3], 0
	v_mfma_f32_16x16x32_bf16 v[84:87], v[124:127], v[4:7], v[84:87]
	ds_read_b128 v[128:131], v190 offset:4608
	ds_read_b128 v[132:135], v190 offset:4672
	s_waitcnt lgkmcnt(0)
	v_mfma_f32_16x16x32_bf16 v[88:91], v[128:131], v[0:3], 0
	v_mfma_f32_16x16x32_bf16 v[88:91], v[132:135], v[4:7], v[88:91]
	ds_read_b128 v[136:139], v190 offset:6912
	ds_read_b128 v[140:143], v190 offset:6976
	s_waitcnt lgkmcnt(0)
	v_mfma_f32_16x16x32_bf16 v[92:95], v[136:139], v[0:3], 0
	v_mfma_f32_16x16x32_bf16 v[92:95], v[140:143], v[4:7], v[92:95]
	ds_read_b128 v[112:115], v190 offset:9216
	ds_read_b128 v[116:119], v190 offset:9280
	s_waitcnt lgkmcnt(0)
	v_mfma_f32_16x16x32_bf16 v[96:99], v[112:115], v[0:3], 0
	v_mfma_f32_16x16x32_bf16 v[96:99], v[116:119], v[4:7], v[96:99]
	ds_read_b128 v[120:123], v190 offset:11520
	ds_read_b128 v[124:127], v190 offset:11584
	s_waitcnt lgkmcnt(0)
	v_mfma_f32_16x16x32_bf16 v[100:103], v[120:123], v[0:3], 0
	v_mfma_f32_16x16x32_bf16 v[100:103], v[124:127], v[4:7], v[100:103]
	ds_read_b128 v[128:131], v190 offset:13824
	ds_read_b128 v[132:135], v190 offset:13888
	s_waitcnt lgkmcnt(0)
	v_mfma_f32_16x16x32_bf16 v[104:107], v[128:131], v[0:3], 0
	v_mfma_f32_16x16x32_bf16 v[104:107], v[132:135], v[4:7], v[104:107]
	ds_read_b128 v[136:139], v190 offset:16128
	ds_read_b128 v[140:143], v190 offset:16192
	s_waitcnt lgkmcnt(0)
	v_mfma_f32_16x16x32_bf16 v[108:111], v[136:139], v[0:3], 0
	v_mfma_f32_16x16x32_bf16 v[108:111], v[140:143], v[4:7], v[108:111]
	s_nop 7
	v_subrev_u32_e32 v231, 31, v186
	v_ashrrev_i32_e32 v231, 4, v231
	v_lshlrev_b32_e32 v232, 2, v198
	v_sub_u32_e32 v231, v231, v232
	v_subrev_u32_e32 v246, 0, v231
	v_cmp_le_i32_e64 s[32:33], 0, v246
	v_cmp_le_i32_e64 s[34:35], 1, v246
	v_cmp_le_i32_e64 s[36:37], 2, v246
	v_cmp_le_i32_e64 s[46:47], 3, v246
	v_cndmask_b32_e64 v80, v230, v80, s[32:33]
	v_cndmask_b32_e64 v81, v230, v81, s[34:35]
	v_cndmask_b32_e64 v82, v230, v82, s[36:37]
	v_cndmask_b32_e64 v83, v230, v83, s[46:47]
	v_subrev_u32_e32 v246, 16, v231
	v_cmp_le_i32_e64 s[32:33], 0, v246
	v_cmp_le_i32_e64 s[34:35], 1, v246
	v_cmp_le_i32_e64 s[36:37], 2, v246
	v_cmp_le_i32_e64 s[46:47], 3, v246
	v_cndmask_b32_e64 v84, v230, v84, s[32:33]
	v_cndmask_b32_e64 v85, v230, v85, s[34:35]
	v_cndmask_b32_e64 v86, v230, v86, s[36:37]
	v_cndmask_b32_e64 v87, v230, v87, s[46:47]
	v_subrev_u32_e32 v246, 32, v231
	v_cmp_le_i32_e64 s[32:33], 0, v246
	v_cmp_le_i32_e64 s[34:35], 1, v246
	v_cmp_le_i32_e64 s[36:37], 2, v246
	v_cmp_le_i32_e64 s[46:47], 3, v246
	v_cndmask_b32_e64 v88, v230, v88, s[32:33]
	v_cndmask_b32_e64 v89, v230, v89, s[34:35]
	v_cndmask_b32_e64 v90, v230, v90, s[36:37]
	v_cndmask_b32_e64 v91, v230, v91, s[46:47]
	v_subrev_u32_e32 v246, 48, v231
	v_cmp_le_i32_e64 s[32:33], 0, v246
	v_cmp_le_i32_e64 s[34:35], 1, v246
	v_cmp_le_i32_e64 s[36:37], 2, v246
	v_cmp_le_i32_e64 s[46:47], 3, v246
	v_cndmask_b32_e64 v92, v230, v92, s[32:33]
	v_cndmask_b32_e64 v93, v230, v93, s[34:35]
	v_cndmask_b32_e64 v94, v230, v94, s[36:37]
	v_cndmask_b32_e64 v95, v230, v95, s[46:47]
	v_subrev_u32_e32 v246, 64, v231
	v_cmp_le_i32_e64 s[32:33], 0, v246
	v_cmp_le_i32_e64 s[34:35], 1, v246
	v_cmp_le_i32_e64 s[36:37], 2, v246
	v_cmp_le_i32_e64 s[46:47], 3, v246
	v_cndmask_b32_e64 v96, v230, v96, s[32:33]
	v_cndmask_b32_e64 v97, v230, v97, s[34:35]
	v_cndmask_b32_e64 v98, v230, v98, s[36:37]
	v_cndmask_b32_e64 v99, v230, v99, s[46:47]
	v_subrev_u32_e32 v246, 0x50, v231
	v_cmp_le_i32_e64 s[32:33], 0, v246
	v_cmp_le_i32_e64 s[34:35], 1, v246
	v_cmp_le_i32_e64 s[36:37], 2, v246
	v_cmp_le_i32_e64 s[46:47], 3, v246
	v_cndmask_b32_e64 v100, v230, v100, s[32:33]
	v_cndmask_b32_e64 v101, v230, v101, s[34:35]
	v_cndmask_b32_e64 v102, v230, v102, s[36:37]
	v_cndmask_b32_e64 v103, v230, v103, s[46:47]
	v_subrev_u32_e32 v246, 0x60, v231
	v_cmp_le_i32_e64 s[32:33], 0, v246
	v_cmp_le_i32_e64 s[34:35], 1, v246
	v_cmp_le_i32_e64 s[36:37], 2, v246
	v_cmp_le_i32_e64 s[46:47], 3, v246
	v_cndmask_b32_e64 v104, v230, v104, s[32:33]
	v_cndmask_b32_e64 v105, v230, v105, s[34:35]
	v_cndmask_b32_e64 v106, v230, v106, s[36:37]
	v_cndmask_b32_e64 v107, v230, v107, s[46:47]
	v_subrev_u32_e32 v246, 0x70, v231
	v_cmp_le_i32_e64 s[32:33], 0, v246
	v_cmp_le_i32_e64 s[34:35], 1, v246
	v_cmp_le_i32_e64 s[36:37], 2, v246
	v_cmp_le_i32_e64 s[46:47], 3, v246
	v_cndmask_b32_e64 v108, v230, v108, s[32:33]
	v_cndmask_b32_e64 v109, v230, v109, s[34:35]
	v_cndmask_b32_e64 v110, v230, v110, s[36:37]
	v_cndmask_b32_e64 v111, v230, v111, s[46:47]
	v_max_f32_e32 v233, v80, v81
	v_max_f32_e32 v233, v82, v233
	v_max_f32_e32 v233, v83, v233
	v_max_f32_e32 v233, v84, v233
	v_max_f32_e32 v233, v85, v233
	v_max_f32_e32 v233, v86, v233
	v_max_f32_e32 v233, v87, v233
	v_max_f32_e32 v233, v88, v233
	v_max_f32_e32 v233, v89, v233
	v_max_f32_e32 v233, v90, v233
	v_max_f32_e32 v233, v91, v233
	v_max_f32_e32 v233, v92, v233
	v_max_f32_e32 v233, v93, v233
	v_max_f32_e32 v233, v94, v233
	v_max_f32_e32 v233, v95, v233
	v_max_f32_e32 v233, v96, v233
	v_max_f32_e32 v233, v97, v233
	v_max_f32_e32 v233, v98, v233
	v_max_f32_e32 v233, v99, v233
	v_max_f32_e32 v233, v100, v233
	v_max_f32_e32 v233, v101, v233
	v_max_f32_e32 v233, v102, v233
	v_max_f32_e32 v233, v103, v233
	v_max_f32_e32 v233, v104, v233
	v_max_f32_e32 v233, v105, v233
	v_max_f32_e32 v233, v106, v233
	v_max_f32_e32 v233, v107, v233
	v_max_f32_e32 v233, v108, v233
	v_max_f32_e32 v233, v109, v233
	v_max_f32_e32 v233, v110, v233
	v_max_f32_e32 v233, v111, v233
	ds_bpermute_b32 v234, v195, v233
	s_waitcnt lgkmcnt(0)
; DEVI float fexp2(float x) { return __builtin_amdgcn_exp2f(x); }
; DEVI void phase_nsa(const Params& p, unsigned char* smem) {
;     ...
;         float ps = 0.f;
;         const float mcc = fmaxf(mx, -1e20f) * c2;
; #pragma unroll
;         for (int kt = 0; kt < 8; ++kt)
; #pragma unroll
;           for (int r = 0; r < 4; ++r) {
;             const float pv = fexp2(__builtin_fmaf(s[kt][r], c2, -mcc));
;             ps += pv;
;             s[kt][r] = pv;
;           }
;         ps += __shfl_xor(ps, 16);
;         ps += __shfl_xor(ps, 32);
;         const float inv = ps > 0.f ? 1.f / ps : 0.f;
; #pragma unroll
;         for (int kt = 0; kt < 8; ++kt)
; #pragma unroll
;           for (int r = 0; r < 4; ++r) s[kt][r] *= inv;
;         float prev3 = 0.f;
; #pragma unroll
;         for (int kt = 0; kt < 8; ++kt) {
;           const float sum4 = s[kt][0] + s[kt][1] + s[kt][2] + s[kt][3];
;           const float xs = __shfl(s[kt][3], srcl);
;           const float extra = quad ? xs : prev3;
;           prev3 = xs;
;           if (need_sel) impH[(w * 32 + 16 * qt + col) * 33 + 4 * kt + quad] = sum4 + extra;
;         }
	v_max_f32_e32 v233, v234, v233
	v_mov_b32_e32 v234, v233
	v_mov_b32_e32 v235, v233
	s_nop 1
	v_permlane32_swap_b32_e32 v234, v235
	v_max_f32_e32 v233, v234, v235
	v_max_f32_e32 v236, 0xe0ad78ec, v233
	v_mul_f32_e32 v236, 0xbe38aa3b, v236
	v_fma_f32 v80, v80, v200, v236
	v_exp_f32_e32 v80, v80
	v_fma_f32 v81, v81, v200, v236
	v_exp_f32_e32 v81, v81
	v_fma_f32 v82, v82, v200, v236
	v_exp_f32_e32 v82, v82
	v_fma_f32 v83, v83, v200, v236
	v_exp_f32_e32 v83, v83
	v_fma_f32 v84, v84, v200, v236
	v_exp_f32_e32 v84, v84
	v_fma_f32 v85, v85, v200, v236
	v_exp_f32_e32 v85, v85
	v_fma_f32 v86, v86, v200, v236
	v_exp_f32_e32 v86, v86
	v_fma_f32 v87, v87, v200, v236
	v_exp_f32_e32 v87, v87
	v_fma_f32 v88, v88, v200, v236
	v_exp_f32_e32 v88, v88
	v_fma_f32 v89, v89, v200, v236
	v_exp_f32_e32 v89, v89
	v_fma_f32 v90, v90, v200, v236
	v_exp_f32_e32 v90, v90
	v_fma_f32 v91, v91, v200, v236
	v_exp_f32_e32 v91, v91
	v_fma_f32 v92, v92, v200, v236
	v_exp_f32_e32 v92, v92
	v_fma_f32 v93, v93, v200, v236
	v_exp_f32_e32 v93, v93
	v_fma_f32 v94, v94, v200, v236
	v_exp_f32_e32 v94, v94
	v_fma_f32 v95, v95, v200, v236
	v_exp_f32_e32 v95, v95
	v_fma_f32 v96, v96, v200, v236
	v_exp_f32_e32 v96, v96
	v_fma_f32 v97, v97, v200, v236
	v_exp_f32_e32 v97, v97
	v_fma_f32 v98, v98, v200, v236
	v_exp_f32_e32 v98, v98
	v_fma_f32 v99, v99, v200, v236
	v_exp_f32_e32 v99, v99
	v_fma_f32 v100, v100, v200, v236
	v_exp_f32_e32 v100, v100
	v_fma_f32 v101, v101, v200, v236
	v_exp_f32_e32 v101, v101
	v_fma_f32 v102, v102, v200, v236
	v_exp_f32_e32 v102, v102
	v_fma_f32 v103, v103, v200, v236
	v_exp_f32_e32 v103, v103
	v_fma_f32 v104, v104, v200, v236
	v_exp_f32_e32 v104, v104
	v_fma_f32 v105, v105, v200, v236
	v_exp_f32_e32 v105, v105
	v_fma_f32 v106, v106, v200, v236
	v_exp_f32_e32 v106, v106
	v_fma_f32 v107, v107, v200, v236
	v_exp_f32_e32 v107, v107
	v_fma_f32 v108, v108, v200, v236
	v_exp_f32_e32 v108, v108
	v_fma_f32 v109, v109, v200, v236
	v_exp_f32_e32 v109, v109
	v_fma_f32 v110, v110, v200, v236
	v_exp_f32_e32 v110, v110
	v_fma_f32 v111, v111, v200, v236
	v_exp_f32_e32 v111, v111
	s_nop 0
	v_add_f32_e32 v237, v80, v81
	v_add_f32_e32 v237, v82, v237
	v_add_f32_e32 v237, v83, v237
	v_add_f32_e32 v237, v84, v237
	v_add_f32_e32 v237, v85, v237
	v_add_f32_e32 v237, v86, v237
	v_add_f32_e32 v237, v87, v237
	v_add_f32_e32 v237, v88, v237
	v_add_f32_e32 v237, v89, v237
	v_add_f32_e32 v237, v90, v237
	v_add_f32_e32 v237, v91, v237
	v_add_f32_e32 v237, v92, v237
	v_add_f32_e32 v237, v93, v237
	v_add_f32_e32 v237, v94, v237
	v_add_f32_e32 v237, v95, v237
	v_add_f32_e32 v237, v96, v237
	v_add_f32_e32 v237, v97, v237
	v_add_f32_e32 v237, v98, v237
	v_add_f32_e32 v237, v99, v237
	v_add_f32_e32 v237, v100, v237
	v_add_f32_e32 v237, v101, v237
	v_add_f32_e32 v237, v102, v237
	v_add_f32_e32 v237, v103, v237
	v_add_f32_e32 v237, v104, v237
	v_add_f32_e32 v237, v105, v237
	v_add_f32_e32 v237, v106, v237
	v_add_f32_e32 v237, v107, v237
	v_add_f32_e32 v237, v108, v237
	v_add_f32_e32 v237, v109, v237
	v_add_f32_e32 v237, v110, v237
	v_add_f32_e32 v237, v111, v237
	ds_bpermute_b32 v234, v195, v237
	s_waitcnt lgkmcnt(0)
	v_add_f32_e32 v237, v234, v237
	v_mov_b32_e32 v234, v237
	v_mov_b32_e32 v235, v237
	s_nop 1
	v_permlane32_swap_b32_e32 v234, v235
	v_add_f32_e32 v237, v234, v235
	v_rcp_f32_e32 v238, v237
	s_nop 0
	v_fma_f32 v239, -v237, v238, 1.0
	v_fma_f32 v238, v239, v238, v238
	v_cmp_lt_f32_e64 s[32:33], 0, v237
	v_mov_b32_e32 v240, 0
	s_nop 0
	v_cndmask_b32_e64 v238, v240, v238, s[32:33]
	v_mul_f32_e32 v80, v238, v80
	v_mul_f32_e32 v81, v238, v81
	v_mul_f32_e32 v82, v238, v82
	v_mul_f32_e32 v83, v238, v83
	v_mul_f32_e32 v84, v238, v84
	v_mul_f32_e32 v85, v238, v85
	v_mul_f32_e32 v86, v238, v86
	v_mul_f32_e32 v87, v238, v87
	v_mul_f32_e32 v88, v238, v88
	v_mul_f32_e32 v89, v238, v89
	v_mul_f32_e32 v90, v238, v90
	v_mul_f32_e32 v91, v238, v91
	v_mul_f32_e32 v92, v238, v92
	v_mul_f32_e32 v93, v238, v93
	v_mul_f32_e32 v94, v238, v94
	v_mul_f32_e32 v95, v238, v95
	v_mul_f32_e32 v96, v238, v96
	v_mul_f32_e32 v97, v238, v97
	v_mul_f32_e32 v98, v238, v98
	v_mul_f32_e32 v99, v238, v99
	v_mul_f32_e32 v100, v238, v100
	v_mul_f32_e32 v101, v238, v101
	v_mul_f32_e32 v102, v238, v102
	v_mul_f32_e32 v103, v238, v103
	v_mul_f32_e32 v104, v238, v104
	v_mul_f32_e32 v105, v238, v105
	v_mul_f32_e32 v106, v238, v106
	v_mul_f32_e32 v107, v238, v107
	v_mul_f32_e32 v108, v238, v108
	v_mul_f32_e32 v109, v238, v109
	v_mul_f32_e32 v110, v238, v110
	v_mul_f32_e32 v111, v238, v111
	s_cmp_eq_u32 s21, 0
	s_cbranch_scc1 .Lp4_noimp0
	v_lshl_add_u32 v241, v209, 5, v197
	v_mul_u32_u24_e32 v241, 33, v241
	v_add_u32_e32 v241, v198, v241
	v_lshlrev_b32_e32 v241, 2, v241
	v_mov_b32_e32 v242, 0
	ds_bpermute_b32 v243, v196, v83
	v_add_f32_e32 v244, v80, v81
	v_add_f32_e32 v244, v82, v244
	v_add_f32_e32 v244, v83, v244
	s_waitcnt lgkmcnt(0)
	v_cndmask_b32_e64 v245, v242, v243, s[38:39]
	v_mov_b32_e32 v242, v243
	v_add_f32_e32 v244, v245, v244
	ds_write_b32 v241, v244 offset:35840
	ds_bpermute_b32 v243, v196, v87
	v_add_f32_e32 v244, v84, v85
	v_add_f32_e32 v244, v86, v244
	v_add_f32_e32 v244, v87, v244
	s_waitcnt lgkmcnt(0)
	v_cndmask_b32_e64 v245, v242, v243, s[38:39]
	v_mov_b32_e32 v242, v243
	v_add_f32_e32 v244, v245, v244
	ds_write_b32 v241, v244 offset:35856
	ds_bpermute_b32 v243, v196, v91
	v_add_f32_e32 v244, v88, v89
	v_add_f32_e32 v244, v90, v244
	v_add_f32_e32 v244, v91, v244
	s_waitcnt lgkmcnt(0)
	v_cndmask_b32_e64 v245, v242, v243, s[38:39]
	v_mov_b32_e32 v242, v243
	v_add_f32_e32 v244, v245, v244
	ds_write_b32 v241, v244 offset:35872
	ds_bpermute_b32 v243, v196, v95
	v_add_f32_e32 v244, v92, v93
	v_add_f32_e32 v244, v94, v244
	v_add_f32_e32 v244, v95, v244
	s_waitcnt lgkmcnt(0)
	v_cndmask_b32_e64 v245, v242, v243, s[38:39]
	v_mov_b32_e32 v242, v243
	v_add_f32_e32 v244, v245, v244
	ds_write_b32 v241, v244 offset:35888
	ds_bpermute_b32 v243, v196, v99
	v_add_f32_e32 v244, v96, v97
	v_add_f32_e32 v244, v98, v244
	v_add_f32_e32 v244, v99, v244
	s_waitcnt lgkmcnt(0)
	v_cndmask_b32_e64 v245, v242, v243, s[38:39]
	v_mov_b32_e32 v242, v243
	v_add_f32_e32 v244, v245, v244
	ds_write_b32 v241, v244 offset:35904
	ds_bpermute_b32 v243, v196, v103
	v_add_f32_e32 v244, v100, v101
	v_add_f32_e32 v244, v102, v244
	v_add_f32_e32 v244, v103, v244
	s_waitcnt lgkmcnt(0)
	v_cndmask_b32_e64 v245, v242, v243, s[38:39]
	v_mov_b32_e32 v242, v243
	v_add_f32_e32 v244, v245, v244
	ds_write_b32 v241, v244 offset:35920
	ds_bpermute_b32 v243, v196, v107
	v_add_f32_e32 v244, v104, v105
	v_add_f32_e32 v244, v106, v244
	v_add_f32_e32 v244, v107, v244
	s_waitcnt lgkmcnt(0)
	v_cndmask_b32_e64 v245, v242, v243, s[38:39]
	v_mov_b32_e32 v242, v243
	v_add_f32_e32 v244, v245, v244
	ds_write_b32 v241, v244 offset:35936
	ds_bpermute_b32 v243, v196, v111
	v_add_f32_e32 v244, v108, v109
	v_add_f32_e32 v244, v110, v244
	v_add_f32_e32 v244, v111, v244
	s_waitcnt lgkmcnt(0)
	v_cndmask_b32_e64 v245, v242, v243, s[38:39]
	v_mov_b32_e32 v242, v243
	v_add_f32_e32 v244, v245, v244
	ds_write_b32 v241, v244 offset:35952
; DEVI unsigned pack2(float a, float b) { return (unsigned)f2bf(a) | ((unsigned)f2bf(b) << 16); }
; DEVI f32x4 mfma16(bf16x8 a, bf16x8 b, f32x4 c) { return __builtin_amdgcn_mfma_f32_16x16x32_bf16(a, b, c, 0, 0, 0); }
; DEVI void phase_nsa(const Params& p, unsigned char* smem) {
;     ...
;         for (int kt = 0; kt < 8; ++kt) {
;           s[kt] = f32x4{0.f, 0.f, 0.f, 0.f};
; #pragma unroll
;           for (int ks = 0; ks < 2; ++ks) {
;             const bf16x8 kf = *(const bf16x8*)(sK + (16 * kt + col) * 72 + 32 * ks + 8 * quad);
;             s[kt] = mfma16(kf, qf[qt][ks], s[kt]);
;           }
;     ...
;         bf16x8 pb[4];
; #pragma unroll
;         for (int kk = 0; kk < 4; ++kk) {
;           union { bf16x8 v; unsigned u[4]; } cv;
;           cv.u[0] = pack2(s[2 * kk][0], s[2 * kk][1]);
;           cv.u[1] = pack2(s[2 * kk][2], s[2 * kk][3]);
;           cv.u[2] = pack2(s[2 * kk + 1][0], s[2 * kk + 1][1]);
;           cv.u[3] = pack2(s[2 * kk + 1][2], s[2 * kk + 1][3]);
;           pb[kk] = cv.v;
;         }
; #pragma unroll
;         for (int dt = 0; dt < 4; ++dt) {
;           f32x4 oc = f32x4{0.f, 0.f, 0.f, 0.f};
; #pragma unroll
;           for (int kk = 0; kk < 4; ++kk) {
;             union { bf16x8 v; uint2 hh[2]; } cv;
;     ...
;             oc = mfma16(cv.v, pb[kk], oc);
;           }
;           comb[qt][dt] = oc * gate[qt][0];
.Lp4_noimp0:
	v_cvt_pk_bf16_f32 v112, v80, v81
	v_cvt_pk_bf16_f32 v113, v82, v83
	v_cvt_pk_bf16_f32 v114, v84, v85
	v_cvt_pk_bf16_f32 v115, v86, v87
	v_cvt_pk_bf16_f32 v116, v88, v89
	v_cvt_pk_bf16_f32 v117, v90, v91
	v_cvt_pk_bf16_f32 v118, v92, v93
	v_cvt_pk_bf16_f32 v119, v94, v95
	v_cvt_pk_bf16_f32 v120, v96, v97
	v_cvt_pk_bf16_f32 v121, v98, v99
	v_cvt_pk_bf16_f32 v122, v100, v101
	v_cvt_pk_bf16_f32 v123, v102, v103
	v_cvt_pk_bf16_f32 v124, v104, v105
	v_cvt_pk_bf16_f32 v125, v106, v107
	v_cvt_pk_bf16_f32 v126, v108, v109
	v_cvt_pk_bf16_f32 v127, v110, v111
	ds_read_b64 v[128:129], v192 offset:18432
	ds_read_b64 v[130:131], v192 offset:18464
	ds_read_b64 v[132:133], v192 offset:18496
	ds_read_b64 v[134:135], v192 offset:18528
	ds_read_b64 v[136:137], v192 offset:18560
	ds_read_b64 v[138:139], v192 offset:18592
	ds_read_b64 v[140:141], v192 offset:18624
	ds_read_b64 v[142:143], v192 offset:18656
	s_waitcnt lgkmcnt(0)
	v_mfma_f32_16x16x32_bf16 v[16:19], v[128:131], v[112:115], 0
	v_mfma_f32_16x16x32_bf16 v[16:19], v[132:135], v[116:119], v[16:19]
	v_mfma_f32_16x16x32_bf16 v[16:19], v[136:139], v[120:123], v[16:19]
	v_mfma_f32_16x16x32_bf16 v[16:19], v[140:143], v[124:127], v[16:19]
	ds_read_b64 v[128:129], v192 offset:22784
	ds_read_b64 v[130:131], v192 offset:22816
	ds_read_b64 v[132:133], v192 offset:22848
	ds_read_b64 v[134:135], v192 offset:22880
	ds_read_b64 v[136:137], v192 offset:22912
	ds_read_b64 v[138:139], v192 offset:22944
	ds_read_b64 v[140:141], v192 offset:22976
	ds_read_b64 v[142:143], v192 offset:23008
	s_waitcnt lgkmcnt(0)
	v_mfma_f32_16x16x32_bf16 v[20:23], v[128:131], v[112:115], 0
	v_mfma_f32_16x16x32_bf16 v[20:23], v[132:135], v[116:119], v[20:23]
	v_mfma_f32_16x16x32_bf16 v[20:23], v[136:139], v[120:123], v[20:23]
	v_mfma_f32_16x16x32_bf16 v[20:23], v[140:143], v[124:127], v[20:23]
	ds_read_b64 v[128:129], v192 offset:27136
	ds_read_b64 v[130:131], v192 offset:27168
	ds_read_b64 v[132:133], v192 offset:27200
	ds_read_b64 v[134:135], v192 offset:27232
	ds_read_b64 v[136:137], v192 offset:27264
	ds_read_b64 v[138:139], v192 offset:27296
	ds_read_b64 v[140:141], v192 offset:27328
	ds_read_b64 v[142:143], v192 offset:27360
	s_waitcnt lgkmcnt(0)
	v_mfma_f32_16x16x32_bf16 v[24:27], v[128:131], v[112:115], 0
	v_mfma_f32_16x16x32_bf16 v[24:27], v[132:135], v[116:119], v[24:27]
	v_mfma_f32_16x16x32_bf16 v[24:27], v[136:139], v[120:123], v[24:27]
	v_mfma_f32_16x16x32_bf16 v[24:27], v[140:143], v[124:127], v[24:27]
	ds_read_b64 v[128:129], v192 offset:31488
	ds_read_b64 v[130:131], v192 offset:31520
	ds_read_b64 v[132:133], v192 offset:31552
	ds_read_b64 v[134:135], v192 offset:31584
	ds_read_b64 v[136:137], v192 offset:31616
	ds_read_b64 v[138:139], v192 offset:31648
	ds_read_b64 v[140:141], v192 offset:31680
	ds_read_b64 v[142:143], v192 offset:31712
	s_waitcnt lgkmcnt(0)
	v_mfma_f32_16x16x32_bf16 v[28:31], v[128:131], v[112:115], 0
	v_mfma_f32_16x16x32_bf16 v[28:31], v[132:135], v[116:119], v[28:31]
	v_mfma_f32_16x16x32_bf16 v[28:31], v[136:139], v[120:123], v[28:31]
	v_mfma_f32_16x16x32_bf16 v[28:31], v[140:143], v[124:127], v[28:31]
	s_nop 7
	v_mul_f32_e32 v48, v176, v16
	v_mul_f32_e32 v49, v176, v17
	v_mul_f32_e32 v50, v176, v18
	v_mul_f32_e32 v51, v176, v19
	v_mul_f32_e32 v52, v176, v20
	v_mul_f32_e32 v53, v176, v21
	v_mul_f32_e32 v54, v176, v22
	v_mul_f32_e32 v55, v176, v23
	v_mul_f32_e32 v56, v176, v24
	v_mul_f32_e32 v57, v176, v25
	v_mul_f32_e32 v58, v176, v26
	v_mul_f32_e32 v59, v176, v27
	v_mul_f32_e32 v60, v176, v28
	v_mul_f32_e32 v61, v176, v29
	v_mul_f32_e32 v62, v176, v30
	v_mul_f32_e32 v63, v176, v31
	ds_read_b128 v[112:115], v190
	ds_read_b128 v[116:119], v190 offset:64
	s_waitcnt lgkmcnt(0)
	v_mfma_f32_16x16x32_bf16 v[80:83], v[112:115], v[8:11], 0
	v_mfma_f32_16x16x32_bf16 v[80:83], v[116:119], v[12:15], v[80:83]
	ds_read_b128 v[120:123], v190 offset:2304
	ds_read_b128 v[124:127], v190 offset:2368
	s_waitcnt lgkmcnt(0)
	v_mfma_f32_16x16x32_bf16 v[84:87], v[120:123], v[8:11], 0
	v_mfma_f32_16x16x32_bf16 v[84:87], v[124:127], v[12:15], v[84:87]
	ds_read_b128 v[128:131], v190 offset:4608
	ds_read_b128 v[132:135], v190 offset:4672
	s_waitcnt lgkmcnt(0)
	v_mfma_f32_16x16x32_bf16 v[88:91], v[128:131], v[8:11], 0
	v_mfma_f32_16x16x32_bf16 v[88:91], v[132:135], v[12:15], v[88:91]
	ds_read_b128 v[136:139], v190 offset:6912
	ds_read_b128 v[140:143], v190 offset:6976
	s_waitcnt lgkmcnt(0)
	v_mfma_f32_16x16x32_bf16 v[92:95], v[136:139], v[8:11], 0
	v_mfma_f32_16x16x32_bf16 v[92:95], v[140:143], v[12:15], v[92:95]
	ds_read_b128 v[112:115], v190 offset:9216
	ds_read_b128 v[116:119], v190 offset:9280
	s_waitcnt lgkmcnt(0)
	v_mfma_f32_16x16x32_bf16 v[96:99], v[112:115], v[8:11], 0
	v_mfma_f32_16x16x32_bf16 v[96:99], v[116:119], v[12:15], v[96:99]
	ds_read_b128 v[120:123], v190 offset:11520
	ds_read_b128 v[124:127], v190 offset:11584
	s_waitcnt lgkmcnt(0)
	v_mfma_f32_16x16x32_bf16 v[100:103], v[120:123], v[8:11], 0
	v_mfma_f32_16x16x32_bf16 v[100:103], v[124:127], v[12:15], v[100:103]
	ds_read_b128 v[128:131], v190 offset:13824
	ds_read_b128 v[132:135], v190 offset:13888
	s_waitcnt lgkmcnt(0)
	v_mfma_f32_16x16x32_bf16 v[104:107], v[128:131], v[8:11], 0
	v_mfma_f32_16x16x32_bf16 v[104:107], v[132:135], v[12:15], v[104:107]
	ds_read_b128 v[136:139], v190 offset:16128
	ds_read_b128 v[140:143], v190 offset:16192
	s_waitcnt lgkmcnt(0)
; DEVI f32x4 mfma16(bf16x8 a, bf16x8 b, f32x4 c) { return __builtin_amdgcn_mfma_f32_16x16x32_bf16(a, b, c, 0, 0, 0); }
; DEVI float fexp2(float x) { return __builtin_amdgcn_exp2f(x); }
; DEVI void phase_nsa(const Params& p, unsigned char* smem) {
;     ...
;         for (int kt = 0; kt < 8; ++kt) {
;           s[kt] = f32x4{0.f, 0.f, 0.f, 0.f};
; #pragma unroll
;           for (int ks = 0; ks < 2; ++ks) {
;             const bf16x8 kf = *(const bf16x8*)(sK + (16 * kt + col) * 72 + 32 * ks + 8 * quad);
;             s[kt] = mfma16(kf, qf[qt][ks], s[kt]);
;           }
;         }
;         const int t = tq[qt];
;         float mx = -1e30f;
; #pragma unroll
;         for (int kt = 0; kt < 8; ++kt)
; #pragma unroll
;           for (int r = 0; r < 4; ++r) {
;             const int c = 16 * kt + 4 * quad + r;
;             const bool v = (16 * c + 31) <= t;
;             const float sv = v ? s[kt][r] : -1e30f;
;             s[kt][r] = sv;
;             mx = fmaxf(mx, sv);
;           }
;         mx = fmaxf(mx, __shfl_xor(mx, 16));
;         mx = fmaxf(mx, __shfl_xor(mx, 32));
;         float ps = 0.f;
;         const float mcc = fmaxf(mx, -1e20f) * c2;
; #pragma unroll
;         for (int kt = 0; kt < 8; ++kt)
; #pragma unroll
;           for (int r = 0; r < 4; ++r) {
;             const float pv = fexp2(__builtin_fmaf(s[kt][r], c2, -mcc));
;             ps += pv;
;             s[kt][r] = pv;
;           }
	v_mfma_f32_16x16x32_bf16 v[108:111], v[136:139], v[8:11], 0
	v_mfma_f32_16x16x32_bf16 v[108:111], v[140:143], v[12:15], v[108:111]
	s_nop 7
	v_subrev_u32_e32 v231, 31, v187
	v_ashrrev_i32_e32 v231, 4, v231
	v_lshlrev_b32_e32 v232, 2, v198
	v_sub_u32_e32 v231, v231, v232
	v_subrev_u32_e32 v246, 0, v231
	v_cmp_le_i32_e64 s[32:33], 0, v246
	v_cmp_le_i32_e64 s[34:35], 1, v246
	v_cmp_le_i32_e64 s[36:37], 2, v246
	v_cmp_le_i32_e64 s[46:47], 3, v246
	v_cndmask_b32_e64 v80, v230, v80, s[32:33]
	v_cndmask_b32_e64 v81, v230, v81, s[34:35]
	v_cndmask_b32_e64 v82, v230, v82, s[36:37]
	v_cndmask_b32_e64 v83, v230, v83, s[46:47]
	v_subrev_u32_e32 v246, 16, v231
	v_cmp_le_i32_e64 s[32:33], 0, v246
	v_cmp_le_i32_e64 s[34:35], 1, v246
	v_cmp_le_i32_e64 s[36:37], 2, v246
	v_cmp_le_i32_e64 s[46:47], 3, v246
	v_cndmask_b32_e64 v84, v230, v84, s[32:33]
	v_cndmask_b32_e64 v85, v230, v85, s[34:35]
	v_cndmask_b32_e64 v86, v230, v86, s[36:37]
	v_cndmask_b32_e64 v87, v230, v87, s[46:47]
	v_subrev_u32_e32 v246, 32, v231
	v_cmp_le_i32_e64 s[32:33], 0, v246
	v_cmp_le_i32_e64 s[34:35], 1, v246
	v_cmp_le_i32_e64 s[36:37], 2, v246
	v_cmp_le_i32_e64 s[46:47], 3, v246
	v_cndmask_b32_e64 v88, v230, v88, s[32:33]
	v_cndmask_b32_e64 v89, v230, v89, s[34:35]
	v_cndmask_b32_e64 v90, v230, v90, s[36:37]
	v_cndmask_b32_e64 v91, v230, v91, s[46:47]
	v_subrev_u32_e32 v246, 48, v231
	v_cmp_le_i32_e64 s[32:33], 0, v246
	v_cmp_le_i32_e64 s[34:35], 1, v246
	v_cmp_le_i32_e64 s[36:37], 2, v246
	v_cmp_le_i32_e64 s[46:47], 3, v246
	v_cndmask_b32_e64 v92, v230, v92, s[32:33]
	v_cndmask_b32_e64 v93, v230, v93, s[34:35]
	v_cndmask_b32_e64 v94, v230, v94, s[36:37]
	v_cndmask_b32_e64 v95, v230, v95, s[46:47]
	v_subrev_u32_e32 v246, 64, v231
	v_cmp_le_i32_e64 s[32:33], 0, v246
	v_cmp_le_i32_e64 s[34:35], 1, v246
	v_cmp_le_i32_e64 s[36:37], 2, v246
	v_cmp_le_i32_e64 s[46:47], 3, v246
	v_cndmask_b32_e64 v96, v230, v96, s[32:33]
	v_cndmask_b32_e64 v97, v230, v97, s[34:35]
	v_cndmask_b32_e64 v98, v230, v98, s[36:37]
	v_cndmask_b32_e64 v99, v230, v99, s[46:47]
	v_subrev_u32_e32 v246, 0x50, v231
	v_cmp_le_i32_e64 s[32:33], 0, v246
	v_cmp_le_i32_e64 s[34:35], 1, v246
	v_cmp_le_i32_e64 s[36:37], 2, v246
	v_cmp_le_i32_e64 s[46:47], 3, v246
	v_cndmask_b32_e64 v100, v230, v100, s[32:33]
	v_cndmask_b32_e64 v101, v230, v101, s[34:35]
	v_cndmask_b32_e64 v102, v230, v102, s[36:37]
	v_cndmask_b32_e64 v103, v230, v103, s[46:47]
	v_subrev_u32_e32 v246, 0x60, v231
	v_cmp_le_i32_e64 s[32:33], 0, v246
	v_cmp_le_i32_e64 s[34:35], 1, v246
	v_cmp_le_i32_e64 s[36:37], 2, v246
	v_cmp_le_i32_e64 s[46:47], 3, v246
	v_cndmask_b32_e64 v104, v230, v104, s[32:33]
	v_cndmask_b32_e64 v105, v230, v105, s[34:35]
	v_cndmask_b32_e64 v106, v230, v106, s[36:37]
	v_cndmask_b32_e64 v107, v230, v107, s[46:47]
	v_subrev_u32_e32 v246, 0x70, v231
	v_cmp_le_i32_e64 s[32:33], 0, v246
	v_cmp_le_i32_e64 s[34:35], 1, v246
	v_cmp_le_i32_e64 s[36:37], 2, v246
	v_cmp_le_i32_e64 s[46:47], 3, v246
	v_cndmask_b32_e64 v108, v230, v108, s[32:33]
	v_cndmask_b32_e64 v109, v230, v109, s[34:35]
	v_cndmask_b32_e64 v110, v230, v110, s[36:37]
	v_cndmask_b32_e64 v111, v230, v111, s[46:47]
	v_max_f32_e32 v233, v80, v81
	v_max_f32_e32 v233, v82, v233
	v_max_f32_e32 v233, v83, v233
	v_max_f32_e32 v233, v84, v233
	v_max_f32_e32 v233, v85, v233
	v_max_f32_e32 v233, v86, v233
	v_max_f32_e32 v233, v87, v233
	v_max_f32_e32 v233, v88, v233
	v_max_f32_e32 v233, v89, v233
	v_max_f32_e32 v233, v90, v233
	v_max_f32_e32 v233, v91, v233
	v_max_f32_e32 v233, v92, v233
	v_max_f32_e32 v233, v93, v233
	v_max_f32_e32 v233, v94, v233
	v_max_f32_e32 v233, v95, v233
	v_max_f32_e32 v233, v96, v233
	v_max_f32_e32 v233, v97, v233
	v_max_f32_e32 v233, v98, v233
	v_max_f32_e32 v233, v99, v233
	v_max_f32_e32 v233, v100, v233
	v_max_f32_e32 v233, v101, v233
	v_max_f32_e32 v233, v102, v233
	v_max_f32_e32 v233, v103, v233
	v_max_f32_e32 v233, v104, v233
	v_max_f32_e32 v233, v105, v233
	v_max_f32_e32 v233, v106, v233
	v_max_f32_e32 v233, v107, v233
	v_max_f32_e32 v233, v108, v233
	v_max_f32_e32 v233, v109, v233
	v_max_f32_e32 v233, v110, v233
	v_max_f32_e32 v233, v111, v233
	ds_bpermute_b32 v234, v195, v233
	s_waitcnt lgkmcnt(0)
	v_max_f32_e32 v233, v234, v233
	v_mov_b32_e32 v234, v233
	v_mov_b32_e32 v235, v233
	s_nop 1
	v_permlane32_swap_b32_e32 v234, v235
	v_max_f32_e32 v233, v234, v235
	v_max_f32_e32 v236, 0xe0ad78ec, v233
	v_mul_f32_e32 v236, 0xbe38aa3b, v236
	v_fma_f32 v80, v80, v200, v236
	v_exp_f32_e32 v80, v80
	v_fma_f32 v81, v81, v200, v236
	v_exp_f32_e32 v81, v81
	v_fma_f32 v82, v82, v200, v236
	v_exp_f32_e32 v82, v82
	v_fma_f32 v83, v83, v200, v236
	v_exp_f32_e32 v83, v83
	v_fma_f32 v84, v84, v200, v236
	v_exp_f32_e32 v84, v84
	v_fma_f32 v85, v85, v200, v236
	v_exp_f32_e32 v85, v85
	v_fma_f32 v86, v86, v200, v236
	v_exp_f32_e32 v86, v86
	v_fma_f32 v87, v87, v200, v236
	v_exp_f32_e32 v87, v87
	v_fma_f32 v88, v88, v200, v236
	v_exp_f32_e32 v88, v88
	v_fma_f32 v89, v89, v200, v236
	v_exp_f32_e32 v89, v89
	v_fma_f32 v90, v90, v200, v236
	v_exp_f32_e32 v90, v90
	v_fma_f32 v91, v91, v200, v236
	v_exp_f32_e32 v91, v91
	v_fma_f32 v92, v92, v200, v236
	v_exp_f32_e32 v92, v92
	v_fma_f32 v93, v93, v200, v236
	v_exp_f32_e32 v93, v93
	v_fma_f32 v94, v94, v200, v236
	v_exp_f32_e32 v94, v94
	v_fma_f32 v95, v95, v200, v236
	v_exp_f32_e32 v95, v95
	v_fma_f32 v96, v96, v200, v236
	v_exp_f32_e32 v96, v96
	v_fma_f32 v97, v97, v200, v236
	v_exp_f32_e32 v97, v97
	v_fma_f32 v98, v98, v200, v236
	v_exp_f32_e32 v98, v98
	v_fma_f32 v99, v99, v200, v236
	v_exp_f32_e32 v99, v99
	v_fma_f32 v100, v100, v200, v236
	v_exp_f32_e32 v100, v100
	v_fma_f32 v101, v101, v200, v236
	v_exp_f32_e32 v101, v101
; DEVI float fexp2(float x) { return __builtin_amdgcn_exp2f(x); }
; DEVI void phase_nsa(const Params& p, unsigned char* smem) {
;     ...
;         for (int kt = 0; kt < 8; ++kt)
; #pragma unroll
;           for (int r = 0; r < 4; ++r) {
;             const float pv = fexp2(__builtin_fmaf(s[kt][r], c2, -mcc));
;             ps += pv;
;             s[kt][r] = pv;
;           }
;         ps += __shfl_xor(ps, 16);
;         ps += __shfl_xor(ps, 32);
;         const float inv = ps > 0.f ? 1.f / ps : 0.f;
; #pragma unroll
;         for (int kt = 0; kt < 8; ++kt)
; #pragma unroll
;           for (int r = 0; r < 4; ++r) s[kt][r] *= inv;
;         float prev3 = 0.f;
; #pragma unroll
;         for (int kt = 0; kt < 8; ++kt) {
;           const float sum4 = s[kt][0] + s[kt][1] + s[kt][2] + s[kt][3];
;           const float xs = __shfl(s[kt][3], srcl);
;           const float extra = quad ? xs : prev3;
;           prev3 = xs;
;           if (need_sel) impH[(w * 32 + 16 * qt + col) * 33 + 4 * kt + quad] = sum4 + extra;
;         }
	v_fma_f32 v102, v102, v200, v236
	v_exp_f32_e32 v102, v102
	v_fma_f32 v103, v103, v200, v236
	v_exp_f32_e32 v103, v103
	v_fma_f32 v104, v104, v200, v236
	v_exp_f32_e32 v104, v104
	v_fma_f32 v105, v105, v200, v236
	v_exp_f32_e32 v105, v105
	v_fma_f32 v106, v106, v200, v236
	v_exp_f32_e32 v106, v106
	v_fma_f32 v107, v107, v200, v236
	v_exp_f32_e32 v107, v107
	v_fma_f32 v108, v108, v200, v236
	v_exp_f32_e32 v108, v108
	v_fma_f32 v109, v109, v200, v236
	v_exp_f32_e32 v109, v109
	v_fma_f32 v110, v110, v200, v236
	v_exp_f32_e32 v110, v110
	v_fma_f32 v111, v111, v200, v236
	v_exp_f32_e32 v111, v111
	s_nop 0
	v_add_f32_e32 v237, v80, v81
	v_add_f32_e32 v237, v82, v237
	v_add_f32_e32 v237, v83, v237
	v_add_f32_e32 v237, v84, v237
	v_add_f32_e32 v237, v85, v237
	v_add_f32_e32 v237, v86, v237
	v_add_f32_e32 v237, v87, v237
	v_add_f32_e32 v237, v88, v237
	v_add_f32_e32 v237, v89, v237
	v_add_f32_e32 v237, v90, v237
	v_add_f32_e32 v237, v91, v237
	v_add_f32_e32 v237, v92, v237
	v_add_f32_e32 v237, v93, v237
	v_add_f32_e32 v237, v94, v237
	v_add_f32_e32 v237, v95, v237
	v_add_f32_e32 v237, v96, v237
	v_add_f32_e32 v237, v97, v237
	v_add_f32_e32 v237, v98, v237
	v_add_f32_e32 v237, v99, v237
	v_add_f32_e32 v237, v100, v237
	v_add_f32_e32 v237, v101, v237
	v_add_f32_e32 v237, v102, v237
	v_add_f32_e32 v237, v103, v237
	v_add_f32_e32 v237, v104, v237
	v_add_f32_e32 v237, v105, v237
	v_add_f32_e32 v237, v106, v237
	v_add_f32_e32 v237, v107, v237
	v_add_f32_e32 v237, v108, v237
	v_add_f32_e32 v237, v109, v237
	v_add_f32_e32 v237, v110, v237
	v_add_f32_e32 v237, v111, v237
	ds_bpermute_b32 v234, v195, v237
	s_waitcnt lgkmcnt(0)
	v_add_f32_e32 v237, v234, v237
	v_mov_b32_e32 v234, v237
	v_mov_b32_e32 v235, v237
	s_nop 1
	v_permlane32_swap_b32_e32 v234, v235
	v_add_f32_e32 v237, v234, v235
	v_rcp_f32_e32 v238, v237
	s_nop 0
	v_fma_f32 v239, -v237, v238, 1.0
	v_fma_f32 v238, v239, v238, v238
	v_cmp_lt_f32_e64 s[32:33], 0, v237
	v_mov_b32_e32 v240, 0
	s_nop 0
	v_cndmask_b32_e64 v238, v240, v238, s[32:33]
	v_mul_f32_e32 v80, v238, v80
	v_mul_f32_e32 v81, v238, v81
	v_mul_f32_e32 v82, v238, v82
	v_mul_f32_e32 v83, v238, v83
	v_mul_f32_e32 v84, v238, v84
	v_mul_f32_e32 v85, v238, v85
	v_mul_f32_e32 v86, v238, v86
	v_mul_f32_e32 v87, v238, v87
	v_mul_f32_e32 v88, v238, v88
	v_mul_f32_e32 v89, v238, v89
	v_mul_f32_e32 v90, v238, v90
	v_mul_f32_e32 v91, v238, v91
	v_mul_f32_e32 v92, v238, v92
	v_mul_f32_e32 v93, v238, v93
	v_mul_f32_e32 v94, v238, v94
	v_mul_f32_e32 v95, v238, v95
	v_mul_f32_e32 v96, v238, v96
	v_mul_f32_e32 v97, v238, v97
	v_mul_f32_e32 v98, v238, v98
	v_mul_f32_e32 v99, v238, v99
	v_mul_f32_e32 v100, v238, v100
	v_mul_f32_e32 v101, v238, v101
	v_mul_f32_e32 v102, v238, v102
	v_mul_f32_e32 v103, v238, v103
	v_mul_f32_e32 v104, v238, v104
	v_mul_f32_e32 v105, v238, v105
	v_mul_f32_e32 v106, v238, v106
	v_mul_f32_e32 v107, v238, v107
	v_mul_f32_e32 v108, v238, v108
	v_mul_f32_e32 v109, v238, v109
	v_mul_f32_e32 v110, v238, v110
	v_mul_f32_e32 v111, v238, v111
	s_cmp_eq_u32 s21, 0
	s_cbranch_scc1 .Lp4_noimp1
	v_lshl_add_u32 v241, v209, 5, v197
	v_add_u32_e32 v241, 16, v241
	v_mul_u32_u24_e32 v241, 33, v241
	v_add_u32_e32 v241, v198, v241
	v_lshlrev_b32_e32 v241, 2, v241
	v_mov_b32_e32 v242, 0
	ds_bpermute_b32 v243, v196, v83
	v_add_f32_e32 v244, v80, v81
	v_add_f32_e32 v244, v82, v244
	v_add_f32_e32 v244, v83, v244
	s_waitcnt lgkmcnt(0)
	v_cndmask_b32_e64 v245, v242, v243, s[38:39]
	v_mov_b32_e32 v242, v243
	v_add_f32_e32 v244, v245, v244
	ds_write_b32 v241, v244 offset:35840
	ds_bpermute_b32 v243, v196, v87
	v_add_f32_e32 v244, v84, v85
	v_add_f32_e32 v244, v86, v244
	v_add_f32_e32 v244, v87, v244
	s_waitcnt lgkmcnt(0)
	v_cndmask_b32_e64 v245, v242, v243, s[38:39]
	v_mov_b32_e32 v242, v243
	v_add_f32_e32 v244, v245, v244
	ds_write_b32 v241, v244 offset:35856
	ds_bpermute_b32 v243, v196, v91
	v_add_f32_e32 v244, v88, v89
	v_add_f32_e32 v244, v90, v244
	v_add_f32_e32 v244, v91, v244
	s_waitcnt lgkmcnt(0)
	v_cndmask_b32_e64 v245, v242, v243, s[38:39]
	v_mov_b32_e32 v242, v243
	v_add_f32_e32 v244, v245, v244
	ds_write_b32 v241, v244 offset:35872
	ds_bpermute_b32 v243, v196, v95
	v_add_f32_e32 v244, v92, v93
	v_add_f32_e32 v244, v94, v244
	v_add_f32_e32 v244, v95, v244
	s_waitcnt lgkmcnt(0)
	v_cndmask_b32_e64 v245, v242, v243, s[38:39]
	v_mov_b32_e32 v242, v243
	v_add_f32_e32 v244, v245, v244
	ds_write_b32 v241, v244 offset:35888
	ds_bpermute_b32 v243, v196, v99
	v_add_f32_e32 v244, v96, v97
	v_add_f32_e32 v244, v98, v244
	v_add_f32_e32 v244, v99, v244
	s_waitcnt lgkmcnt(0)
	v_cndmask_b32_e64 v245, v242, v243, s[38:39]
	v_mov_b32_e32 v242, v243
	v_add_f32_e32 v244, v245, v244
	ds_write_b32 v241, v244 offset:35904
	ds_bpermute_b32 v243, v196, v103
	v_add_f32_e32 v244, v100, v101
	v_add_f32_e32 v244, v102, v244
	v_add_f32_e32 v244, v103, v244
	s_waitcnt lgkmcnt(0)
	v_cndmask_b32_e64 v245, v242, v243, s[38:39]
	v_mov_b32_e32 v242, v243
	v_add_f32_e32 v244, v245, v244
	ds_write_b32 v241, v244 offset:35920
	ds_bpermute_b32 v243, v196, v107
	v_add_f32_e32 v244, v104, v105
	v_add_f32_e32 v244, v106, v244
	v_add_f32_e32 v244, v107, v244
	s_waitcnt lgkmcnt(0)
	v_cndmask_b32_e64 v245, v242, v243, s[38:39]
	v_mov_b32_e32 v242, v243
	v_add_f32_e32 v244, v245, v244
	ds_write_b32 v241, v244 offset:35936
	ds_bpermute_b32 v243, v196, v111
	v_add_f32_e32 v244, v108, v109
	v_add_f32_e32 v244, v110, v244
	v_add_f32_e32 v244, v111, v244
	s_waitcnt lgkmcnt(0)
	v_cndmask_b32_e64 v245, v242, v243, s[38:39]
	v_mov_b32_e32 v242, v243
	v_add_f32_e32 v244, v245, v244
	ds_write_b32 v241, v244 offset:35952
; DEVI unsigned pack2(float a, float b) { return (unsigned)f2bf(a) | ((unsigned)f2bf(b) << 16); }
; DEVI f32x4 mfma16(bf16x8 a, bf16x8 b, f32x4 c) { return __builtin_amdgcn_mfma_f32_16x16x32_bf16(a, b, c, 0, 0, 0); }
; DEVI void phase_nsa(const Params& p, unsigned char* smem) {
;     ...
;         bf16x8 pb[4];
; #pragma unroll
;         for (int kk = 0; kk < 4; ++kk) {
;           union { bf16x8 v; unsigned u[4]; } cv;
;           cv.u[0] = pack2(s[2 * kk][0], s[2 * kk][1]);
;           cv.u[1] = pack2(s[2 * kk][2], s[2 * kk][3]);
;           cv.u[2] = pack2(s[2 * kk + 1][0], s[2 * kk + 1][1]);
;           cv.u[3] = pack2(s[2 * kk + 1][2], s[2 * kk + 1][3]);
;           pb[kk] = cv.v;
;         }
; #pragma unroll
;         for (int dt = 0; dt < 4; ++dt) {
;           f32x4 oc = f32x4{0.f, 0.f, 0.f, 0.f};
; #pragma unroll
;           for (int kk = 0; kk < 4; ++kk) {
;             union { bf16x8 v; uint2 hh[2]; } cv;
;     ...
;             oc = mfma16(cv.v, pb[kk], oc);
;           }
;           comb[qt][dt] = oc * gate[qt][0];
;         }
;       }
;     }
; #pragma unroll
;     for (int qt = 0; qt < 2; ++qt) {
;       const size_t tok = (size_t)b * T + tq[qt];
;       union { bf16x8 v; unsigned u[4]; } own, par, res;
;       own.v = qf[qt][0];
; #pragma unroll
;       for (int j = 0; j < 4; ++j) par.u[j] = (unsigned)__shfl_xor((int)own.u[j], 16);
;       const float4 c0 = *(const float4*)(p.rope + tok * 16), c1 = *(const float4*)(p.rope + tok * 16 + 4);
;       const float4 s0 = *(const float4*)(p.rope + tok * 16 + 8), s1 = *(const float4*)(p.rope + tok * 16 + 12);
;       const float cs[8] = {c0.x, c0.y, c0.z, c0.w, c1.x, c1.y, c1.z, c1.w};
;       const float sn[8] = {s0.x, s0.y, s0.z, s0.w, s1.x, s1.y, s1.z, s1.w};
; #pragma unroll
;       for (int j = 0; j < 4; ++j) {
;         const float o0 = __uint_as_float(own.u[j] << 16), o1 = __uint_as_float(own.u[j] & 0xffff0000u);
;         const float p0 = __uint_as_float(par.u[j] << 16), p1 = __uint_as_float(par.u[j] & 0xffff0000u);
;         const float sg = (quad == 0) ? -1.f : 1.f;
;         const float r0 = o0 * cs[2 * j] + sg * p0 * sn[2 * j];
;         const float r1 = o1 * cs[2 * j + 1] + sg * p1 * sn[2 * j + 1];
;         res.u[j] = (quad < 2) ? pack2(r0, r1) : own.u[j];
;       }
;       qf[qt][0] = res.v;
;     }
.Lp4_noimp1:
	v_cvt_pk_bf16_f32 v112, v80, v81
	v_cvt_pk_bf16_f32 v113, v82, v83
	v_cvt_pk_bf16_f32 v114, v84, v85
	v_cvt_pk_bf16_f32 v115, v86, v87
	v_cvt_pk_bf16_f32 v116, v88, v89
	v_cvt_pk_bf16_f32 v117, v90, v91
	v_cvt_pk_bf16_f32 v118, v92, v93
	v_cvt_pk_bf16_f32 v119, v94, v95
	v_cvt_pk_bf16_f32 v120, v96, v97
	v_cvt_pk_bf16_f32 v121, v98, v99
	v_cvt_pk_bf16_f32 v122, v100, v101
	v_cvt_pk_bf16_f32 v123, v102, v103
	v_cvt_pk_bf16_f32 v124, v104, v105
	v_cvt_pk_bf16_f32 v125, v106, v107
	v_cvt_pk_bf16_f32 v126, v108, v109
	v_cvt_pk_bf16_f32 v127, v110, v111
	ds_read_b64 v[128:129], v192 offset:18432
	ds_read_b64 v[130:131], v192 offset:18464
	ds_read_b64 v[132:133], v192 offset:18496
	ds_read_b64 v[134:135], v192 offset:18528
	ds_read_b64 v[136:137], v192 offset:18560
	ds_read_b64 v[138:139], v192 offset:18592
	ds_read_b64 v[140:141], v192 offset:18624
	ds_read_b64 v[142:143], v192 offset:18656
	s_waitcnt lgkmcnt(0)
	v_mfma_f32_16x16x32_bf16 v[16:19], v[128:131], v[112:115], 0
	v_mfma_f32_16x16x32_bf16 v[16:19], v[132:135], v[116:119], v[16:19]
	v_mfma_f32_16x16x32_bf16 v[16:19], v[136:139], v[120:123], v[16:19]
	v_mfma_f32_16x16x32_bf16 v[16:19], v[140:143], v[124:127], v[16:19]
	ds_read_b64 v[128:129], v192 offset:22784
	ds_read_b64 v[130:131], v192 offset:22816
	ds_read_b64 v[132:133], v192 offset:22848
	ds_read_b64 v[134:135], v192 offset:22880
	ds_read_b64 v[136:137], v192 offset:22912
	ds_read_b64 v[138:139], v192 offset:22944
	ds_read_b64 v[140:141], v192 offset:22976
	ds_read_b64 v[142:143], v192 offset:23008
	s_waitcnt lgkmcnt(0)
	v_mfma_f32_16x16x32_bf16 v[20:23], v[128:131], v[112:115], 0
	v_mfma_f32_16x16x32_bf16 v[20:23], v[132:135], v[116:119], v[20:23]
	v_mfma_f32_16x16x32_bf16 v[20:23], v[136:139], v[120:123], v[20:23]
	v_mfma_f32_16x16x32_bf16 v[20:23], v[140:143], v[124:127], v[20:23]
	ds_read_b64 v[128:129], v192 offset:27136
	ds_read_b64 v[130:131], v192 offset:27168
	ds_read_b64 v[132:133], v192 offset:27200
	ds_read_b64 v[134:135], v192 offset:27232
	ds_read_b64 v[136:137], v192 offset:27264
	ds_read_b64 v[138:139], v192 offset:27296
	ds_read_b64 v[140:141], v192 offset:27328
	ds_read_b64 v[142:143], v192 offset:27360
	s_waitcnt lgkmcnt(0)
	v_mfma_f32_16x16x32_bf16 v[24:27], v[128:131], v[112:115], 0
	v_mfma_f32_16x16x32_bf16 v[24:27], v[132:135], v[116:119], v[24:27]
	v_mfma_f32_16x16x32_bf16 v[24:27], v[136:139], v[120:123], v[24:27]
	v_mfma_f32_16x16x32_bf16 v[24:27], v[140:143], v[124:127], v[24:27]
	ds_read_b64 v[128:129], v192 offset:31488
	ds_read_b64 v[130:131], v192 offset:31520
	ds_read_b64 v[132:133], v192 offset:31552
	ds_read_b64 v[134:135], v192 offset:31584
	ds_read_b64 v[136:137], v192 offset:31616
	ds_read_b64 v[138:139], v192 offset:31648
	ds_read_b64 v[140:141], v192 offset:31680
	ds_read_b64 v[142:143], v192 offset:31712
	s_waitcnt lgkmcnt(0)
	v_mfma_f32_16x16x32_bf16 v[28:31], v[128:131], v[112:115], 0
	v_mfma_f32_16x16x32_bf16 v[28:31], v[132:135], v[116:119], v[28:31]
	v_mfma_f32_16x16x32_bf16 v[28:31], v[136:139], v[120:123], v[28:31]
	v_mfma_f32_16x16x32_bf16 v[28:31], v[140:143], v[124:127], v[28:31]
	s_nop 7
	v_mul_f32_e32 v64, v179, v16
	v_mul_f32_e32 v65, v179, v17
	v_mul_f32_e32 v66, v179, v18
	v_mul_f32_e32 v67, v179, v19
	v_mul_f32_e32 v68, v179, v20
	v_mul_f32_e32 v69, v179, v21
	v_mul_f32_e32 v70, v179, v22
	v_mul_f32_e32 v71, v179, v23
	v_mul_f32_e32 v72, v179, v24
	v_mul_f32_e32 v73, v179, v25
	v_mul_f32_e32 v74, v179, v26
	v_mul_f32_e32 v75, v179, v27
	v_mul_f32_e32 v76, v179, v28
	v_mul_f32_e32 v77, v179, v29
	v_mul_f32_e32 v78, v179, v30
	v_mul_f32_e32 v79, v179, v31
	s_mov_b32 s36, 0xffffffff
	s_mov_b32 s37, 0
	s_mov_b32 s34, 0xffff
	s_mov_b32 s35, 0
	v_mov_b32_e32 v232, 0x3f800000
	v_mov_b32_e32 v233, 0xbf800000
	v_cndmask_b32_e64 v231, v232, v233, s[34:35]
	s_waitcnt vmcnt(0)
	ds_bpermute_b32 v234, v195, v0
	ds_bpermute_b32 v235, v195, v1
	ds_bpermute_b32 v236, v195, v2
	ds_bpermute_b32 v237, v195, v3
	s_waitcnt lgkmcnt(0)
	v_lshlrev_b32_e32 v238, 16, v0
	v_and_b32_e32 v239, 0xffff0000, v0
	v_lshlrev_b32_e32 v240, 16, v234
	v_and_b32_e32 v241, 0xffff0000, v234
	v_mul_f32_e32 v240, v231, v240
	v_mul_f32_e32 v240, v152, v240
	v_fma_f32 v242, v238, v144, v240
	v_mul_f32_e32 v241, v231, v241
	v_mul_f32_e32 v241, v153, v241
	v_fma_f32 v243, v239, v145, v241
	v_cvt_pk_bf16_f32 v244, v242, v243
	v_cndmask_b32_e64 v0, v0, v244, s[36:37]
	v_lshlrev_b32_e32 v238, 16, v1
	v_and_b32_e32 v239, 0xffff0000, v1
	v_lshlrev_b32_e32 v240, 16, v235
	v_and_b32_e32 v241, 0xffff0000, v235
	v_mul_f32_e32 v240, v231, v240
	v_mul_f32_e32 v240, v154, v240
	v_fma_f32 v242, v238, v146, v240
	v_mul_f32_e32 v241, v231, v241
	v_mul_f32_e32 v241, v155, v241
	v_fma_f32 v243, v239, v147, v241
	v_cvt_pk_bf16_f32 v244, v242, v243
	v_cndmask_b32_e64 v1, v1, v244, s[36:37]
	v_lshlrev_b32_e32 v238, 16, v2
	v_and_b32_e32 v239, 0xffff0000, v2
	v_lshlrev_b32_e32 v240, 16, v236
	v_and_b32_e32 v241, 0xffff0000, v236
	v_mul_f32_e32 v240, v231, v240
	v_mul_f32_e32 v240, v156, v240
	v_fma_f32 v242, v238, v148, v240
	v_mul_f32_e32 v241, v231, v241
	v_mul_f32_e32 v241, v157, v241
	v_fma_f32 v243, v239, v149, v241
	v_cvt_pk_bf16_f32 v244, v242, v243
	v_cndmask_b32_e64 v2, v2, v244, s[36:37]
	v_lshlrev_b32_e32 v238, 16, v3
	v_and_b32_e32 v239, 0xffff0000, v3
	v_lshlrev_b32_e32 v240, 16, v237
	v_and_b32_e32 v241, 0xffff0000, v237
	v_mul_f32_e32 v240, v231, v240
	v_mul_f32_e32 v240, v158, v240
	v_fma_f32 v242, v238, v150, v240
	v_mul_f32_e32 v241, v231, v241
	v_mul_f32_e32 v241, v159, v241
	v_fma_f32 v243, v239, v151, v241
	v_cvt_pk_bf16_f32 v244, v242, v243
	v_cndmask_b32_e64 v3, v3, v244, s[36:37]
	ds_bpermute_b32 v234, v195, v8
	ds_bpermute_b32 v235, v195, v9
	ds_bpermute_b32 v236, v195, v10
	ds_bpermute_b32 v237, v195, v11
	s_waitcnt lgkmcnt(0)
; DEVI unsigned pack2(float a, float b) { return (unsigned)f2bf(a) | ((unsigned)f2bf(b) << 16); }
; DEVI void phase_nsa(const Params& p, unsigned char* smem) {
;     ...
;       for (int j = 0; j < 4; ++j) {
;         const float o0 = __uint_as_float(own.u[j] << 16), o1 = __uint_as_float(own.u[j] & 0xffff0000u);
;         const float p0 = __uint_as_float(par.u[j] << 16), p1 = __uint_as_float(par.u[j] & 0xffff0000u);
;         const float sg = (quad == 0) ? -1.f : 1.f;
;         const float r0 = o0 * cs[2 * j] + sg * p0 * sn[2 * j];
;         const float r1 = o1 * cs[2 * j + 1] + sg * p1 * sn[2 * j + 1];
;         res.u[j] = (quad < 2) ? pack2(r0, r1) : own.u[j];
;       }
;       qf[qt][0] = res.v;
;     }
;     __syncthreads();
;     if (!need_sel) {
;       if (tid < 32) selm[tid] = (2u << ((q0 + tid) >> 6)) - 1u;
;     } else {
; #pragma unroll
;     for (int i = 0; i < 4; ++i) {
;       const int cell = tid + 256 * i;
;       const int qi = cell >> 5, s_ = cell & 31;
;       const int cur = (q0 + qi) >> 6;
;       float v = impH[(0 * 32 + qi) * 33 + s_] + impH[(1 * 32 + qi) * 33 + s_] + impH[(2 * 32 + qi) * 33 + s_] +
;                 impH[(3 * 32 + qi) * 33 + s_];
;       const int dist = cur - s_;
;       const bool forced = (s_ == 0) || (dist >= 0 && dist < 2);
;       v = forced ? 1e9f : (s_ <= cur ? v : -1.f);
;       impT[qi * 33 + s_] = v;
;     }
;     __syncthreads();
	v_lshlrev_b32_e32 v238, 16, v8
	v_and_b32_e32 v239, 0xffff0000, v8
	v_lshlrev_b32_e32 v240, 16, v234
	v_and_b32_e32 v241, 0xffff0000, v234
	v_mul_f32_e32 v240, v231, v240
	v_mul_f32_e32 v240, v168, v240
	v_fma_f32 v242, v238, v160, v240
	v_mul_f32_e32 v241, v231, v241
	v_mul_f32_e32 v241, v169, v241
	v_fma_f32 v243, v239, v161, v241
	v_cvt_pk_bf16_f32 v244, v242, v243
	v_cndmask_b32_e64 v8, v8, v244, s[36:37]
	v_lshlrev_b32_e32 v238, 16, v9
	v_and_b32_e32 v239, 0xffff0000, v9
	v_lshlrev_b32_e32 v240, 16, v235
	v_and_b32_e32 v241, 0xffff0000, v235
	v_mul_f32_e32 v240, v231, v240
	v_mul_f32_e32 v240, v170, v240
	v_fma_f32 v242, v238, v162, v240
	v_mul_f32_e32 v241, v231, v241
	v_mul_f32_e32 v241, v171, v241
	v_fma_f32 v243, v239, v163, v241
	v_cvt_pk_bf16_f32 v244, v242, v243
	v_cndmask_b32_e64 v9, v9, v244, s[36:37]
	v_lshlrev_b32_e32 v238, 16, v10
	v_and_b32_e32 v239, 0xffff0000, v10
	v_lshlrev_b32_e32 v240, 16, v236
	v_and_b32_e32 v241, 0xffff0000, v236
	v_mul_f32_e32 v240, v231, v240
	v_mul_f32_e32 v240, v172, v240
	v_fma_f32 v242, v238, v164, v240
	v_mul_f32_e32 v241, v231, v241
	v_mul_f32_e32 v241, v173, v241
	v_fma_f32 v243, v239, v165, v241
	v_cvt_pk_bf16_f32 v244, v242, v243
	v_cndmask_b32_e64 v10, v10, v244, s[36:37]
	v_lshlrev_b32_e32 v238, 16, v11
	v_and_b32_e32 v239, 0xffff0000, v11
	v_lshlrev_b32_e32 v240, 16, v237
	v_and_b32_e32 v241, 0xffff0000, v237
	v_mul_f32_e32 v240, v231, v240
	v_mul_f32_e32 v240, v174, v240
	v_fma_f32 v242, v238, v166, v240
	v_mul_f32_e32 v241, v231, v241
	v_mul_f32_e32 v241, v175, v241
	v_fma_f32 v243, v239, v167, v241
	v_cvt_pk_bf16_f32 v244, v242, v243
	v_cndmask_b32_e64 v11, v11, v244, s[36:37]
	s_barrier
	s_cmp_eq_u32 s21, 0
	s_cbranch_scc0 .Lp4_sel
	v_cmp_gt_u32_e64 s[32:33], 32, v210
	v_add_u32_e32 v231, s19, v210
	v_lshrrev_b32_e32 v231, 6, v231
	v_mov_b32_e32 v233, 2
	v_lshlrev_b32_e32 v231, v231, v233
	v_add_u32_e32 v231, -1, v231
	v_lshlrev_b32_e32 v232, 2, v210
	s_and_saveexec_b64 s[34:35], s[32:33]
	ds_write_b32 v232, v231 offset:56960
	s_mov_b64 exec, s[34:35]
	s_branch .Lp4_selend
.Lp4_sel:
	v_and_b32_e32 v231, 31, v210
	v_lshrrev_b32_e32 v232, 5, v210
	v_mul_u32_u24_e32 v236, 33, v232
	v_add_u32_e32 v236, v231, v236
	v_lshlrev_b32_e32 v236, 2, v236
	ds_read_b32 v238, v236 offset:35840
	ds_read_b32 v239, v236 offset:40064
	ds_read_b32 v240, v236 offset:44288
	ds_read_b32 v241, v236 offset:48512
	v_add_u32_e32 v233, s19, v232
	v_lshrrev_b32_e32 v233, 6, v233
	s_waitcnt lgkmcnt(0)
	v_add_f32_e32 v234, v238, v239
	v_add_f32_e32 v234, v240, v234
	v_add_f32_e32 v234, v241, v234
	v_sub_u32_e32 v237, v233, v231
	v_cmp_le_u32_e64 s[32:33], v231, v233
	v_mov_b32_e32 v242, 0xbf800000
	s_nop 0
	v_cndmask_b32_e64 v234, v242, v234, s[32:33]
	v_cmp_gt_u32_e64 s[32:33], 2, v237
	v_cmp_eq_u32_e64 s[34:35], 0, v231
	s_or_b64 s[32:33], s[32:33], s[34:35]
	v_mov_b32_e32 v242, 0x4e6e6b28
	v_cndmask_b32_e64 v234, v234, v242, s[32:33]
	ds_write_b32 v236, v234 offset:52736
	v_lshrrev_b32_e32 v232, 5, v210
	v_add_u32_e32 v232, 8, v232
	v_mul_u32_u24_e32 v236, 33, v232
	v_add_u32_e32 v236, v231, v236
	v_lshlrev_b32_e32 v236, 2, v236
	ds_read_b32 v238, v236 offset:35840
	ds_read_b32 v239, v236 offset:40064
	ds_read_b32 v240, v236 offset:44288
	ds_read_b32 v241, v236 offset:48512
	v_add_u32_e32 v233, s19, v232
	v_lshrrev_b32_e32 v233, 6, v233
	s_waitcnt lgkmcnt(0)
	v_add_f32_e32 v234, v238, v239
	v_add_f32_e32 v234, v240, v234
	v_add_f32_e32 v234, v241, v234
	v_sub_u32_e32 v237, v233, v231
	v_cmp_le_u32_e64 s[32:33], v231, v233
	v_mov_b32_e32 v242, 0xbf800000
	s_nop 0
	v_cndmask_b32_e64 v234, v242, v234, s[32:33]
	v_cmp_gt_u32_e64 s[32:33], 2, v237
	v_cmp_eq_u32_e64 s[34:35], 0, v231
	s_or_b64 s[32:33], s[32:33], s[34:35]
	v_mov_b32_e32 v242, 0x4e6e6b28
	v_cndmask_b32_e64 v234, v234, v242, s[32:33]
	ds_write_b32 v236, v234 offset:52736
	v_lshrrev_b32_e32 v232, 5, v210
	v_add_u32_e32 v232, 16, v232
	v_mul_u32_u24_e32 v236, 33, v232
	v_add_u32_e32 v236, v231, v236
	v_lshlrev_b32_e32 v236, 2, v236
	ds_read_b32 v238, v236 offset:35840
	ds_read_b32 v239, v236 offset:40064
	ds_read_b32 v240, v236 offset:44288
	ds_read_b32 v241, v236 offset:48512
	v_add_u32_e32 v233, s19, v232
	v_lshrrev_b32_e32 v233, 6, v233
	s_waitcnt lgkmcnt(0)
	v_add_f32_e32 v234, v238, v239
	v_add_f32_e32 v234, v240, v234
	v_add_f32_e32 v234, v241, v234
	v_sub_u32_e32 v237, v233, v231
	v_cmp_le_u32_e64 s[32:33], v231, v233
	v_mov_b32_e32 v242, 0xbf800000
	s_nop 0
	v_cndmask_b32_e64 v234, v242, v234, s[32:33]
	v_cmp_gt_u32_e64 s[32:33], 2, v237
	v_cmp_eq_u32_e64 s[34:35], 0, v231
	s_or_b64 s[32:33], s[32:33], s[34:35]
	v_mov_b32_e32 v242, 0x4e6e6b28
	v_cndmask_b32_e64 v234, v234, v242, s[32:33]
	ds_write_b32 v236, v234 offset:52736
	v_lshrrev_b32_e32 v232, 5, v210
	v_add_u32_e32 v232, 24, v232
	v_mul_u32_u24_e32 v236, 33, v232
	v_add_u32_e32 v236, v231, v236
	v_lshlrev_b32_e32 v236, 2, v236
	ds_read_b32 v238, v236 offset:35840
	ds_read_b32 v239, v236 offset:40064
	ds_read_b32 v240, v236 offset:44288
	ds_read_b32 v241, v236 offset:48512
	v_add_u32_e32 v233, s19, v232
	v_lshrrev_b32_e32 v233, 6, v233
	s_waitcnt lgkmcnt(0)
	v_add_f32_e32 v234, v238, v239
	v_add_f32_e32 v234, v240, v234
	v_add_f32_e32 v234, v241, v234
	v_sub_u32_e32 v237, v233, v231
	v_cmp_le_u32_e64 s[32:33], v231, v233
	v_mov_b32_e32 v242, 0xbf800000
	s_nop 0
	v_cndmask_b32_e64 v234, v242, v234, s[32:33]
	v_cmp_gt_u32_e64 s[32:33], 2, v237
	v_cmp_eq_u32_e64 s[34:35], 0, v231
	s_or_b64 s[32:33], s[32:33], s[34:35]
	v_mov_b32_e32 v242, 0x4e6e6b28
	v_cndmask_b32_e64 v234, v234, v242, s[32:33]
	ds_write_b32 v236, v234 offset:52736
	s_waitcnt lgkmcnt(0)
	s_barrier
; DEVI void phase_nsa(const Params& p, unsigned char* smem) {
;     ...
;     {
;       const int qi = tid >> 3, sub = tid & 7;
;       unsigned bits = 0u;
; #pragma unroll
;       for (int k = 0; k < 4; ++k) {
;         const int s_ = sub * 4 + k;
;         const float v = impT[qi * 33 + s_];
;         int rank = 0;
;         for (int s2 = 0; s2 < 32; ++s2) {
;           const float v2 = impT[qi * 33 + s2];
;           rank += ((v2 > v) || (v2 == v && s2 < s_)) ? 1 : 0;
;         }
;         if (rank < 16) bits |= 1u << s_;
;       }
;       atomicOr(&selm[qi], bits);
	v_lshrrev_b32_e32 v232, 3, v210
	v_mul_u32_u24_e32 v236, 0x84, v232
	ds_read_b32 v80, v236 offset:52736
	ds_read_b32 v81, v236 offset:52740
	ds_read_b32 v82, v236 offset:52744
	ds_read_b32 v83, v236 offset:52748
	ds_read_b32 v84, v236 offset:52752
	ds_read_b32 v85, v236 offset:52756
	ds_read_b32 v86, v236 offset:52760
	ds_read_b32 v87, v236 offset:52764
	ds_read_b32 v88, v236 offset:52768
	ds_read_b32 v89, v236 offset:52772
	ds_read_b32 v90, v236 offset:52776
	ds_read_b32 v91, v236 offset:52780
	ds_read_b32 v92, v236 offset:52784
	ds_read_b32 v93, v236 offset:52788
	ds_read_b32 v94, v236 offset:52792
	ds_read_b32 v95, v236 offset:52796
	ds_read_b32 v96, v236 offset:52800
	ds_read_b32 v97, v236 offset:52804
	ds_read_b32 v98, v236 offset:52808
	ds_read_b32 v99, v236 offset:52812
	ds_read_b32 v100, v236 offset:52816
	ds_read_b32 v101, v236 offset:52820
	ds_read_b32 v102, v236 offset:52824
	ds_read_b32 v103, v236 offset:52828
	ds_read_b32 v104, v236 offset:52832
	ds_read_b32 v105, v236 offset:52836
	ds_read_b32 v106, v236 offset:52840
	ds_read_b32 v107, v236 offset:52844
	ds_read_b32 v108, v236 offset:52848
	ds_read_b32 v109, v236 offset:52852
	ds_read_b32 v110, v236 offset:52856
	ds_read_b32 v111, v236 offset:52860
	v_and_b32_e32 v235, 7, v210
	v_lshlrev_b32_e32 v235, 2, v235
	v_lshl_add_u32 v236, v235, 2, v236
	ds_read_b32 v238, v236 offset:52736
	ds_read_b32 v239, v236 offset:52740
	ds_read_b32 v240, v236 offset:52744
	ds_read_b32 v241, v236 offset:52748
	s_waitcnt lgkmcnt(0)
	v_mov_b32_e32 v242, 0
	v_mov_b32_e32 v244, 0
	v_add_u32_e32 v245, 0, v235
	v_cmp_gt_f32_e64 s[32:33], v80, v238
	v_cmp_eq_f32_e64 s[34:35], v80, v238
	v_cmp_lt_u32_e64 s[36:37], 0, v245
	s_and_b64 s[34:35], s[34:35], s[36:37]
	s_or_b64 s[32:33], s[32:33], s[34:35]
	v_addc_co_u32_e64 v244, s[34:35], 0, v244, s[32:33]
	v_cmp_gt_f32_e64 s[32:33], v81, v238
	v_cmp_eq_f32_e64 s[34:35], v81, v238
	v_cmp_lt_u32_e64 s[36:37], 1, v245
	s_and_b64 s[34:35], s[34:35], s[36:37]
	s_or_b64 s[32:33], s[32:33], s[34:35]
	v_addc_co_u32_e64 v244, s[34:35], 0, v244, s[32:33]
	v_cmp_gt_f32_e64 s[32:33], v82, v238
	v_cmp_eq_f32_e64 s[34:35], v82, v238
	v_cmp_lt_u32_e64 s[36:37], 2, v245
	s_and_b64 s[34:35], s[34:35], s[36:37]
	s_or_b64 s[32:33], s[32:33], s[34:35]
	v_addc_co_u32_e64 v244, s[34:35], 0, v244, s[32:33]
	v_cmp_gt_f32_e64 s[32:33], v83, v238
	v_cmp_eq_f32_e64 s[34:35], v83, v238
	v_cmp_lt_u32_e64 s[36:37], 3, v245
	s_and_b64 s[34:35], s[34:35], s[36:37]
	s_or_b64 s[32:33], s[32:33], s[34:35]
	v_addc_co_u32_e64 v244, s[34:35], 0, v244, s[32:33]
	v_cmp_gt_f32_e64 s[32:33], v84, v238
	v_cmp_eq_f32_e64 s[34:35], v84, v238
	v_cmp_lt_u32_e64 s[36:37], 4, v245
	s_and_b64 s[34:35], s[34:35], s[36:37]
	s_or_b64 s[32:33], s[32:33], s[34:35]
	v_addc_co_u32_e64 v244, s[34:35], 0, v244, s[32:33]
	v_cmp_gt_f32_e64 s[32:33], v85, v238
	v_cmp_eq_f32_e64 s[34:35], v85, v238
	v_cmp_lt_u32_e64 s[36:37], 5, v245
	s_and_b64 s[34:35], s[34:35], s[36:37]
	s_or_b64 s[32:33], s[32:33], s[34:35]
	v_addc_co_u32_e64 v244, s[34:35], 0, v244, s[32:33]
	v_cmp_gt_f32_e64 s[32:33], v86, v238
	v_cmp_eq_f32_e64 s[34:35], v86, v238
	v_cmp_lt_u32_e64 s[36:37], 6, v245
	s_and_b64 s[34:35], s[34:35], s[36:37]
	s_or_b64 s[32:33], s[32:33], s[34:35]
	v_addc_co_u32_e64 v244, s[34:35], 0, v244, s[32:33]
	v_cmp_gt_f32_e64 s[32:33], v87, v238
	v_cmp_eq_f32_e64 s[34:35], v87, v238
	v_cmp_lt_u32_e64 s[36:37], 7, v245
	s_and_b64 s[34:35], s[34:35], s[36:37]
	s_or_b64 s[32:33], s[32:33], s[34:35]
	v_addc_co_u32_e64 v244, s[34:35], 0, v244, s[32:33]
	v_cmp_gt_f32_e64 s[32:33], v88, v238
	v_cmp_eq_f32_e64 s[34:35], v88, v238
	v_cmp_lt_u32_e64 s[36:37], 8, v245
	s_and_b64 s[34:35], s[34:35], s[36:37]
	s_or_b64 s[32:33], s[32:33], s[34:35]
	v_addc_co_u32_e64 v244, s[34:35], 0, v244, s[32:33]
	v_cmp_gt_f32_e64 s[32:33], v89, v238
	v_cmp_eq_f32_e64 s[34:35], v89, v238
	v_cmp_lt_u32_e64 s[36:37], 9, v245
	s_and_b64 s[34:35], s[34:35], s[36:37]
	s_or_b64 s[32:33], s[32:33], s[34:35]
	v_addc_co_u32_e64 v244, s[34:35], 0, v244, s[32:33]
	v_cmp_gt_f32_e64 s[32:33], v90, v238
	v_cmp_eq_f32_e64 s[34:35], v90, v238
	v_cmp_lt_u32_e64 s[36:37], 10, v245
	s_and_b64 s[34:35], s[34:35], s[36:37]
	s_or_b64 s[32:33], s[32:33], s[34:35]
	v_addc_co_u32_e64 v244, s[34:35], 0, v244, s[32:33]
	v_cmp_gt_f32_e64 s[32:33], v91, v238
	v_cmp_eq_f32_e64 s[34:35], v91, v238
	v_cmp_lt_u32_e64 s[36:37], 11, v245
	s_and_b64 s[34:35], s[34:35], s[36:37]
	s_or_b64 s[32:33], s[32:33], s[34:35]
	v_addc_co_u32_e64 v244, s[34:35], 0, v244, s[32:33]
	v_cmp_gt_f32_e64 s[32:33], v92, v238
	v_cmp_eq_f32_e64 s[34:35], v92, v238
	v_cmp_lt_u32_e64 s[36:37], 12, v245
	s_and_b64 s[34:35], s[34:35], s[36:37]
	s_or_b64 s[32:33], s[32:33], s[34:35]
	v_addc_co_u32_e64 v244, s[34:35], 0, v244, s[32:33]
	v_cmp_gt_f32_e64 s[32:33], v93, v238
	v_cmp_eq_f32_e64 s[34:35], v93, v238
	v_cmp_lt_u32_e64 s[36:37], 13, v245
	s_and_b64 s[34:35], s[34:35], s[36:37]
	s_or_b64 s[32:33], s[32:33], s[34:35]
	v_addc_co_u32_e64 v244, s[34:35], 0, v244, s[32:33]
	v_cmp_gt_f32_e64 s[32:33], v94, v238
	v_cmp_eq_f32_e64 s[34:35], v94, v238
	v_cmp_lt_u32_e64 s[36:37], 14, v245
	s_and_b64 s[34:35], s[34:35], s[36:37]
	s_or_b64 s[32:33], s[32:33], s[34:35]
	v_addc_co_u32_e64 v244, s[34:35], 0, v244, s[32:33]
	v_cmp_gt_f32_e64 s[32:33], v95, v238
	v_cmp_eq_f32_e64 s[34:35], v95, v238
	v_cmp_lt_u32_e64 s[36:37], 15, v245
	s_and_b64 s[34:35], s[34:35], s[36:37]
	s_or_b64 s[32:33], s[32:33], s[34:35]
	v_addc_co_u32_e64 v244, s[34:35], 0, v244, s[32:33]
	v_cmp_gt_f32_e64 s[32:33], v96, v238
	v_cmp_eq_f32_e64 s[34:35], v96, v238
	v_cmp_lt_u32_e64 s[36:37], 16, v245
	s_and_b64 s[34:35], s[34:35], s[36:37]
; DEVI void phase_nsa(const Params& p, unsigned char* smem) {
;     ...
; #pragma unroll
;       for (int k = 0; k < 4; ++k) {
;         const int s_ = sub * 4 + k;
;         const float v = impT[qi * 33 + s_];
;         int rank = 0;
;         for (int s2 = 0; s2 < 32; ++s2) {
;           const float v2 = impT[qi * 33 + s2];
;           rank += ((v2 > v) || (v2 == v && s2 < s_)) ? 1 : 0;
;         }
;         if (rank < 16) bits |= 1u << s_;
;       }
	s_or_b64 s[32:33], s[32:33], s[34:35]
	v_addc_co_u32_e64 v244, s[34:35], 0, v244, s[32:33]
	v_cmp_gt_f32_e64 s[32:33], v97, v238
	v_cmp_eq_f32_e64 s[34:35], v97, v238
	v_cmp_lt_u32_e64 s[36:37], 17, v245
	s_and_b64 s[34:35], s[34:35], s[36:37]
	s_or_b64 s[32:33], s[32:33], s[34:35]
	v_addc_co_u32_e64 v244, s[34:35], 0, v244, s[32:33]
	v_cmp_gt_f32_e64 s[32:33], v98, v238
	v_cmp_eq_f32_e64 s[34:35], v98, v238
	v_cmp_lt_u32_e64 s[36:37], 18, v245
	s_and_b64 s[34:35], s[34:35], s[36:37]
	s_or_b64 s[32:33], s[32:33], s[34:35]
	v_addc_co_u32_e64 v244, s[34:35], 0, v244, s[32:33]
	v_cmp_gt_f32_e64 s[32:33], v99, v238
	v_cmp_eq_f32_e64 s[34:35], v99, v238
	v_cmp_lt_u32_e64 s[36:37], 19, v245
	s_and_b64 s[34:35], s[34:35], s[36:37]
	s_or_b64 s[32:33], s[32:33], s[34:35]
	v_addc_co_u32_e64 v244, s[34:35], 0, v244, s[32:33]
	v_cmp_gt_f32_e64 s[32:33], v100, v238
	v_cmp_eq_f32_e64 s[34:35], v100, v238
	v_cmp_lt_u32_e64 s[36:37], 20, v245
	s_and_b64 s[34:35], s[34:35], s[36:37]
	s_or_b64 s[32:33], s[32:33], s[34:35]
	v_addc_co_u32_e64 v244, s[34:35], 0, v244, s[32:33]
	v_cmp_gt_f32_e64 s[32:33], v101, v238
	v_cmp_eq_f32_e64 s[34:35], v101, v238
	v_cmp_lt_u32_e64 s[36:37], 21, v245
	s_and_b64 s[34:35], s[34:35], s[36:37]
	s_or_b64 s[32:33], s[32:33], s[34:35]
	v_addc_co_u32_e64 v244, s[34:35], 0, v244, s[32:33]
	v_cmp_gt_f32_e64 s[32:33], v102, v238
	v_cmp_eq_f32_e64 s[34:35], v102, v238
	v_cmp_lt_u32_e64 s[36:37], 22, v245
	s_and_b64 s[34:35], s[34:35], s[36:37]
	s_or_b64 s[32:33], s[32:33], s[34:35]
	v_addc_co_u32_e64 v244, s[34:35], 0, v244, s[32:33]
	v_cmp_gt_f32_e64 s[32:33], v103, v238
	v_cmp_eq_f32_e64 s[34:35], v103, v238
	v_cmp_lt_u32_e64 s[36:37], 23, v245
	s_and_b64 s[34:35], s[34:35], s[36:37]
	s_or_b64 s[32:33], s[32:33], s[34:35]
	v_addc_co_u32_e64 v244, s[34:35], 0, v244, s[32:33]
	v_cmp_gt_f32_e64 s[32:33], v104, v238
	v_cmp_eq_f32_e64 s[34:35], v104, v238
	v_cmp_lt_u32_e64 s[36:37], 24, v245
	s_and_b64 s[34:35], s[34:35], s[36:37]
	s_or_b64 s[32:33], s[32:33], s[34:35]
	v_addc_co_u32_e64 v244, s[34:35], 0, v244, s[32:33]
	v_cmp_gt_f32_e64 s[32:33], v105, v238
	v_cmp_eq_f32_e64 s[34:35], v105, v238
	v_cmp_lt_u32_e64 s[36:37], 25, v245
	s_and_b64 s[34:35], s[34:35], s[36:37]
	s_or_b64 s[32:33], s[32:33], s[34:35]
	v_addc_co_u32_e64 v244, s[34:35], 0, v244, s[32:33]
	v_cmp_gt_f32_e64 s[32:33], v106, v238
	v_cmp_eq_f32_e64 s[34:35], v106, v238
	v_cmp_lt_u32_e64 s[36:37], 26, v245
	s_and_b64 s[34:35], s[34:35], s[36:37]
	s_or_b64 s[32:33], s[32:33], s[34:35]
	v_addc_co_u32_e64 v244, s[34:35], 0, v244, s[32:33]
	v_cmp_gt_f32_e64 s[32:33], v107, v238
	v_cmp_eq_f32_e64 s[34:35], v107, v238
	v_cmp_lt_u32_e64 s[36:37], 27, v245
	s_and_b64 s[34:35], s[34:35], s[36:37]
	s_or_b64 s[32:33], s[32:33], s[34:35]
	v_addc_co_u32_e64 v244, s[34:35], 0, v244, s[32:33]
	v_cmp_gt_f32_e64 s[32:33], v108, v238
	v_cmp_eq_f32_e64 s[34:35], v108, v238
	v_cmp_lt_u32_e64 s[36:37], 28, v245
	s_and_b64 s[34:35], s[34:35], s[36:37]
	s_or_b64 s[32:33], s[32:33], s[34:35]
	v_addc_co_u32_e64 v244, s[34:35], 0, v244, s[32:33]
	v_cmp_gt_f32_e64 s[32:33], v109, v238
	v_cmp_eq_f32_e64 s[34:35], v109, v238
	v_cmp_lt_u32_e64 s[36:37], 29, v245
	s_and_b64 s[34:35], s[34:35], s[36:37]
	s_or_b64 s[32:33], s[32:33], s[34:35]
	v_addc_co_u32_e64 v244, s[34:35], 0, v244, s[32:33]
	v_cmp_gt_f32_e64 s[32:33], v110, v238
	v_cmp_eq_f32_e64 s[34:35], v110, v238
	v_cmp_lt_u32_e64 s[36:37], 30, v245
	s_and_b64 s[34:35], s[34:35], s[36:37]
	s_or_b64 s[32:33], s[32:33], s[34:35]
	v_addc_co_u32_e64 v244, s[34:35], 0, v244, s[32:33]
	v_cmp_gt_f32_e64 s[32:33], v111, v238
	v_cmp_eq_f32_e64 s[34:35], v111, v238
	v_cmp_lt_u32_e64 s[36:37], 31, v245
	s_and_b64 s[34:35], s[34:35], s[36:37]
	s_or_b64 s[32:33], s[32:33], s[34:35]
	v_addc_co_u32_e64 v244, s[34:35], 0, v244, s[32:33]
	v_mov_b32_e32 v243, 1
	v_lshlrev_b32_e32 v243, v245, v243
	v_cmp_gt_u32_e64 s[32:33], 16, v244
	v_mov_b32_e32 v246, 0
	s_nop 0
	v_cndmask_b32_e64 v243, v246, v243, s[32:33]
	v_or_b32_e32 v242, v243, v242
	v_mov_b32_e32 v244, 0
	v_add_u32_e32 v245, 1, v235
	v_cmp_gt_f32_e64 s[32:33], v80, v239
	v_cmp_eq_f32_e64 s[34:35], v80, v239
	v_cmp_lt_u32_e64 s[36:37], 0, v245
	s_and_b64 s[34:35], s[34:35], s[36:37]
	s_or_b64 s[32:33], s[32:33], s[34:35]
	v_addc_co_u32_e64 v244, s[34:35], 0, v244, s[32:33]
	v_cmp_gt_f32_e64 s[32:33], v81, v239
	v_cmp_eq_f32_e64 s[34:35], v81, v239
	v_cmp_lt_u32_e64 s[36:37], 1, v245
	s_and_b64 s[34:35], s[34:35], s[36:37]
	s_or_b64 s[32:33], s[32:33], s[34:35]
	v_addc_co_u32_e64 v244, s[34:35], 0, v244, s[32:33]
	v_cmp_gt_f32_e64 s[32:33], v82, v239
	v_cmp_eq_f32_e64 s[34:35], v82, v239
	v_cmp_lt_u32_e64 s[36:37], 2, v245
	s_and_b64 s[34:35], s[34:35], s[36:37]
	s_or_b64 s[32:33], s[32:33], s[34:35]
	v_addc_co_u32_e64 v244, s[34:35], 0, v244, s[32:33]
	v_cmp_gt_f32_e64 s[32:33], v83, v239
	v_cmp_eq_f32_e64 s[34:35], v83, v239
	v_cmp_lt_u32_e64 s[36:37], 3, v245
	s_and_b64 s[34:35], s[34:35], s[36:37]
	s_or_b64 s[32:33], s[32:33], s[34:35]
	v_addc_co_u32_e64 v244, s[34:35], 0, v244, s[32:33]
	v_cmp_gt_f32_e64 s[32:33], v84, v239
	v_cmp_eq_f32_e64 s[34:35], v84, v239
	v_cmp_lt_u32_e64 s[36:37], 4, v245
	s_and_b64 s[34:35], s[34:35], s[36:37]
	s_or_b64 s[32:33], s[32:33], s[34:35]
	v_addc_co_u32_e64 v244, s[34:35], 0, v244, s[32:33]
	v_cmp_gt_f32_e64 s[32:33], v85, v239
	v_cmp_eq_f32_e64 s[34:35], v85, v239
	v_cmp_lt_u32_e64 s[36:37], 5, v245
	s_and_b64 s[34:35], s[34:35], s[36:37]
	s_or_b64 s[32:33], s[32:33], s[34:35]
	v_addc_co_u32_e64 v244, s[34:35], 0, v244, s[32:33]
	v_cmp_gt_f32_e64 s[32:33], v86, v239
	v_cmp_eq_f32_e64 s[34:35], v86, v239
	v_cmp_lt_u32_e64 s[36:37], 6, v245
; DEVI void phase_nsa(const Params& p, unsigned char* smem) {
;     ...
; #pragma unroll
;       for (int k = 0; k < 4; ++k) {
;         const int s_ = sub * 4 + k;
;         const float v = impT[qi * 33 + s_];
;         int rank = 0;
;         for (int s2 = 0; s2 < 32; ++s2) {
;           const float v2 = impT[qi * 33 + s2];
;           rank += ((v2 > v) || (v2 == v && s2 < s_)) ? 1 : 0;
;         }
;         if (rank < 16) bits |= 1u << s_;
;       }
	s_and_b64 s[34:35], s[34:35], s[36:37]
	s_or_b64 s[32:33], s[32:33], s[34:35]
	v_addc_co_u32_e64 v244, s[34:35], 0, v244, s[32:33]
	v_cmp_gt_f32_e64 s[32:33], v87, v239
	v_cmp_eq_f32_e64 s[34:35], v87, v239
	v_cmp_lt_u32_e64 s[36:37], 7, v245
	s_and_b64 s[34:35], s[34:35], s[36:37]
	s_or_b64 s[32:33], s[32:33], s[34:35]
	v_addc_co_u32_e64 v244, s[34:35], 0, v244, s[32:33]
	v_cmp_gt_f32_e64 s[32:33], v88, v239
	v_cmp_eq_f32_e64 s[34:35], v88, v239
	v_cmp_lt_u32_e64 s[36:37], 8, v245
	s_and_b64 s[34:35], s[34:35], s[36:37]
	s_or_b64 s[32:33], s[32:33], s[34:35]
	v_addc_co_u32_e64 v244, s[34:35], 0, v244, s[32:33]
	v_cmp_gt_f32_e64 s[32:33], v89, v239
	v_cmp_eq_f32_e64 s[34:35], v89, v239
	v_cmp_lt_u32_e64 s[36:37], 9, v245
	s_and_b64 s[34:35], s[34:35], s[36:37]
	s_or_b64 s[32:33], s[32:33], s[34:35]
	v_addc_co_u32_e64 v244, s[34:35], 0, v244, s[32:33]
	v_cmp_gt_f32_e64 s[32:33], v90, v239
	v_cmp_eq_f32_e64 s[34:35], v90, v239
	v_cmp_lt_u32_e64 s[36:37], 10, v245
	s_and_b64 s[34:35], s[34:35], s[36:37]
	s_or_b64 s[32:33], s[32:33], s[34:35]
	v_addc_co_u32_e64 v244, s[34:35], 0, v244, s[32:33]
	v_cmp_gt_f32_e64 s[32:33], v91, v239
	v_cmp_eq_f32_e64 s[34:35], v91, v239
	v_cmp_lt_u32_e64 s[36:37], 11, v245
	s_and_b64 s[34:35], s[34:35], s[36:37]
	s_or_b64 s[32:33], s[32:33], s[34:35]
	v_addc_co_u32_e64 v244, s[34:35], 0, v244, s[32:33]
	v_cmp_gt_f32_e64 s[32:33], v92, v239
	v_cmp_eq_f32_e64 s[34:35], v92, v239
	v_cmp_lt_u32_e64 s[36:37], 12, v245
	s_and_b64 s[34:35], s[34:35], s[36:37]
	s_or_b64 s[32:33], s[32:33], s[34:35]
	v_addc_co_u32_e64 v244, s[34:35], 0, v244, s[32:33]
	v_cmp_gt_f32_e64 s[32:33], v93, v239
	v_cmp_eq_f32_e64 s[34:35], v93, v239
	v_cmp_lt_u32_e64 s[36:37], 13, v245
	s_and_b64 s[34:35], s[34:35], s[36:37]
	s_or_b64 s[32:33], s[32:33], s[34:35]
	v_addc_co_u32_e64 v244, s[34:35], 0, v244, s[32:33]
	v_cmp_gt_f32_e64 s[32:33], v94, v239
	v_cmp_eq_f32_e64 s[34:35], v94, v239
	v_cmp_lt_u32_e64 s[36:37], 14, v245
	s_and_b64 s[34:35], s[34:35], s[36:37]
	s_or_b64 s[32:33], s[32:33], s[34:35]
	v_addc_co_u32_e64 v244, s[34:35], 0, v244, s[32:33]
	v_cmp_gt_f32_e64 s[32:33], v95, v239
	v_cmp_eq_f32_e64 s[34:35], v95, v239
	v_cmp_lt_u32_e64 s[36:37], 15, v245
	s_and_b64 s[34:35], s[34:35], s[36:37]
	s_or_b64 s[32:33], s[32:33], s[34:35]
	v_addc_co_u32_e64 v244, s[34:35], 0, v244, s[32:33]
	v_cmp_gt_f32_e64 s[32:33], v96, v239
	v_cmp_eq_f32_e64 s[34:35], v96, v239
	v_cmp_lt_u32_e64 s[36:37], 16, v245
	s_and_b64 s[34:35], s[34:35], s[36:37]
	s_or_b64 s[32:33], s[32:33], s[34:35]
	v_addc_co_u32_e64 v244, s[34:35], 0, v244, s[32:33]
	v_cmp_gt_f32_e64 s[32:33], v97, v239
	v_cmp_eq_f32_e64 s[34:35], v97, v239
	v_cmp_lt_u32_e64 s[36:37], 17, v245
	s_and_b64 s[34:35], s[34:35], s[36:37]
	s_or_b64 s[32:33], s[32:33], s[34:35]
	v_addc_co_u32_e64 v244, s[34:35], 0, v244, s[32:33]
	v_cmp_gt_f32_e64 s[32:33], v98, v239
	v_cmp_eq_f32_e64 s[34:35], v98, v239
	v_cmp_lt_u32_e64 s[36:37], 18, v245
	s_and_b64 s[34:35], s[34:35], s[36:37]
	s_or_b64 s[32:33], s[32:33], s[34:35]
	v_addc_co_u32_e64 v244, s[34:35], 0, v244, s[32:33]
	v_cmp_gt_f32_e64 s[32:33], v99, v239
	v_cmp_eq_f32_e64 s[34:35], v99, v239
	v_cmp_lt_u32_e64 s[36:37], 19, v245
	s_and_b64 s[34:35], s[34:35], s[36:37]
	s_or_b64 s[32:33], s[32:33], s[34:35]
	v_addc_co_u32_e64 v244, s[34:35], 0, v244, s[32:33]
	v_cmp_gt_f32_e64 s[32:33], v100, v239
	v_cmp_eq_f32_e64 s[34:35], v100, v239
	v_cmp_lt_u32_e64 s[36:37], 20, v245
	s_and_b64 s[34:35], s[34:35], s[36:37]
	s_or_b64 s[32:33], s[32:33], s[34:35]
	v_addc_co_u32_e64 v244, s[34:35], 0, v244, s[32:33]
	v_cmp_gt_f32_e64 s[32:33], v101, v239
	v_cmp_eq_f32_e64 s[34:35], v101, v239
	v_cmp_lt_u32_e64 s[36:37], 21, v245
	s_and_b64 s[34:35], s[34:35], s[36:37]
	s_or_b64 s[32:33], s[32:33], s[34:35]
	v_addc_co_u32_e64 v244, s[34:35], 0, v244, s[32:33]
	v_cmp_gt_f32_e64 s[32:33], v102, v239
	v_cmp_eq_f32_e64 s[34:35], v102, v239
	v_cmp_lt_u32_e64 s[36:37], 22, v245
	s_and_b64 s[34:35], s[34:35], s[36:37]
	s_or_b64 s[32:33], s[32:33], s[34:35]
	v_addc_co_u32_e64 v244, s[34:35], 0, v244, s[32:33]
	v_cmp_gt_f32_e64 s[32:33], v103, v239
	v_cmp_eq_f32_e64 s[34:35], v103, v239
	v_cmp_lt_u32_e64 s[36:37], 23, v245
	s_and_b64 s[34:35], s[34:35], s[36:37]
	s_or_b64 s[32:33], s[32:33], s[34:35]
	v_addc_co_u32_e64 v244, s[34:35], 0, v244, s[32:33]
	v_cmp_gt_f32_e64 s[32:33], v104, v239
	v_cmp_eq_f32_e64 s[34:35], v104, v239
	v_cmp_lt_u32_e64 s[36:37], 24, v245
	s_and_b64 s[34:35], s[34:35], s[36:37]
	s_or_b64 s[32:33], s[32:33], s[34:35]
	v_addc_co_u32_e64 v244, s[34:35], 0, v244, s[32:33]
	v_cmp_gt_f32_e64 s[32:33], v105, v239
	v_cmp_eq_f32_e64 s[34:35], v105, v239
	v_cmp_lt_u32_e64 s[36:37], 25, v245
	s_and_b64 s[34:35], s[34:35], s[36:37]
	s_or_b64 s[32:33], s[32:33], s[34:35]
	v_addc_co_u32_e64 v244, s[34:35], 0, v244, s[32:33]
	v_cmp_gt_f32_e64 s[32:33], v106, v239
	v_cmp_eq_f32_e64 s[34:35], v106, v239
	v_cmp_lt_u32_e64 s[36:37], 26, v245
	s_and_b64 s[34:35], s[34:35], s[36:37]
	s_or_b64 s[32:33], s[32:33], s[34:35]
	v_addc_co_u32_e64 v244, s[34:35], 0, v244, s[32:33]
	v_cmp_gt_f32_e64 s[32:33], v107, v239
	v_cmp_eq_f32_e64 s[34:35], v107, v239
	v_cmp_lt_u32_e64 s[36:37], 27, v245
	s_and_b64 s[34:35], s[34:35], s[36:37]
	s_or_b64 s[32:33], s[32:33], s[34:35]
	v_addc_co_u32_e64 v244, s[34:35], 0, v244, s[32:33]
	v_cmp_gt_f32_e64 s[32:33], v108, v239
	v_cmp_eq_f32_e64 s[34:35], v108, v239
	v_cmp_lt_u32_e64 s[36:37], 28, v245
	s_and_b64 s[34:35], s[34:35], s[36:37]
	s_or_b64 s[32:33], s[32:33], s[34:35]
	v_addc_co_u32_e64 v244, s[34:35], 0, v244, s[32:33]
	v_cmp_gt_f32_e64 s[32:33], v109, v239
	v_cmp_eq_f32_e64 s[34:35], v109, v239
	v_cmp_lt_u32_e64 s[36:37], 29, v245
; DEVI void phase_nsa(const Params& p, unsigned char* smem) {
;     ...
; #pragma unroll
;       for (int k = 0; k < 4; ++k) {
;         const int s_ = sub * 4 + k;
;         const float v = impT[qi * 33 + s_];
;         int rank = 0;
;         for (int s2 = 0; s2 < 32; ++s2) {
;           const float v2 = impT[qi * 33 + s2];
;           rank += ((v2 > v) || (v2 == v && s2 < s_)) ? 1 : 0;
;         }
;         if (rank < 16) bits |= 1u << s_;
;       }
	s_and_b64 s[34:35], s[34:35], s[36:37]
	s_or_b64 s[32:33], s[32:33], s[34:35]
	v_addc_co_u32_e64 v244, s[34:35], 0, v244, s[32:33]
	v_cmp_gt_f32_e64 s[32:33], v110, v239
	v_cmp_eq_f32_e64 s[34:35], v110, v239
	v_cmp_lt_u32_e64 s[36:37], 30, v245
	s_and_b64 s[34:35], s[34:35], s[36:37]
	s_or_b64 s[32:33], s[32:33], s[34:35]
	v_addc_co_u32_e64 v244, s[34:35], 0, v244, s[32:33]
	v_cmp_gt_f32_e64 s[32:33], v111, v239
	v_cmp_eq_f32_e64 s[34:35], v111, v239
	v_cmp_lt_u32_e64 s[36:37], 31, v245
	s_and_b64 s[34:35], s[34:35], s[36:37]
	s_or_b64 s[32:33], s[32:33], s[34:35]
	v_addc_co_u32_e64 v244, s[34:35], 0, v244, s[32:33]
	v_mov_b32_e32 v243, 1
	v_lshlrev_b32_e32 v243, v245, v243
	v_cmp_gt_u32_e64 s[32:33], 16, v244
	v_mov_b32_e32 v246, 0
	s_nop 0
	v_cndmask_b32_e64 v243, v246, v243, s[32:33]
	v_or_b32_e32 v242, v243, v242
	v_mov_b32_e32 v244, 0
	v_add_u32_e32 v245, 2, v235
	v_cmp_gt_f32_e64 s[32:33], v80, v240
	v_cmp_eq_f32_e64 s[34:35], v80, v240
	v_cmp_lt_u32_e64 s[36:37], 0, v245
	s_and_b64 s[34:35], s[34:35], s[36:37]
	s_or_b64 s[32:33], s[32:33], s[34:35]
	v_addc_co_u32_e64 v244, s[34:35], 0, v244, s[32:33]
	v_cmp_gt_f32_e64 s[32:33], v81, v240
	v_cmp_eq_f32_e64 s[34:35], v81, v240
	v_cmp_lt_u32_e64 s[36:37], 1, v245
	s_and_b64 s[34:35], s[34:35], s[36:37]
	s_or_b64 s[32:33], s[32:33], s[34:35]
	v_addc_co_u32_e64 v244, s[34:35], 0, v244, s[32:33]
	v_cmp_gt_f32_e64 s[32:33], v82, v240
	v_cmp_eq_f32_e64 s[34:35], v82, v240
	v_cmp_lt_u32_e64 s[36:37], 2, v245
	s_and_b64 s[34:35], s[34:35], s[36:37]
	s_or_b64 s[32:33], s[32:33], s[34:35]
	v_addc_co_u32_e64 v244, s[34:35], 0, v244, s[32:33]
	v_cmp_gt_f32_e64 s[32:33], v83, v240
	v_cmp_eq_f32_e64 s[34:35], v83, v240
	v_cmp_lt_u32_e64 s[36:37], 3, v245
	s_and_b64 s[34:35], s[34:35], s[36:37]
	s_or_b64 s[32:33], s[32:33], s[34:35]
	v_addc_co_u32_e64 v244, s[34:35], 0, v244, s[32:33]
	v_cmp_gt_f32_e64 s[32:33], v84, v240
	v_cmp_eq_f32_e64 s[34:35], v84, v240
	v_cmp_lt_u32_e64 s[36:37], 4, v245
	s_and_b64 s[34:35], s[34:35], s[36:37]
	s_or_b64 s[32:33], s[32:33], s[34:35]
	v_addc_co_u32_e64 v244, s[34:35], 0, v244, s[32:33]
	v_cmp_gt_f32_e64 s[32:33], v85, v240
	v_cmp_eq_f32_e64 s[34:35], v85, v240
	v_cmp_lt_u32_e64 s[36:37], 5, v245
	s_and_b64 s[34:35], s[34:35], s[36:37]
	s_or_b64 s[32:33], s[32:33], s[34:35]
	v_addc_co_u32_e64 v244, s[34:35], 0, v244, s[32:33]
	v_cmp_gt_f32_e64 s[32:33], v86, v240
	v_cmp_eq_f32_e64 s[34:35], v86, v240
	v_cmp_lt_u32_e64 s[36:37], 6, v245
	s_and_b64 s[34:35], s[34:35], s[36:37]
	s_or_b64 s[32:33], s[32:33], s[34:35]
	v_addc_co_u32_e64 v244, s[34:35], 0, v244, s[32:33]
	v_cmp_gt_f32_e64 s[32:33], v87, v240
	v_cmp_eq_f32_e64 s[34:35], v87, v240
	v_cmp_lt_u32_e64 s[36:37], 7, v245
	s_and_b64 s[34:35], s[34:35], s[36:37]
	s_or_b64 s[32:33], s[32:33], s[34:35]
	v_addc_co_u32_e64 v244, s[34:35], 0, v244, s[32:33]
	v_cmp_gt_f32_e64 s[32:33], v88, v240
	v_cmp_eq_f32_e64 s[34:35], v88, v240
	v_cmp_lt_u32_e64 s[36:37], 8, v245
	s_and_b64 s[34:35], s[34:35], s[36:37]
	s_or_b64 s[32:33], s[32:33], s[34:35]
	v_addc_co_u32_e64 v244, s[34:35], 0, v244, s[32:33]
	v_cmp_gt_f32_e64 s[32:33], v89, v240
	v_cmp_eq_f32_e64 s[34:35], v89, v240
	v_cmp_lt_u32_e64 s[36:37], 9, v245
	s_and_b64 s[34:35], s[34:35], s[36:37]
	s_or_b64 s[32:33], s[32:33], s[34:35]
	v_addc_co_u32_e64 v244, s[34:35], 0, v244, s[32:33]
	v_cmp_gt_f32_e64 s[32:33], v90, v240
	v_cmp_eq_f32_e64 s[34:35], v90, v240
	v_cmp_lt_u32_e64 s[36:37], 10, v245
	s_and_b64 s[34:35], s[34:35], s[36:37]
	s_or_b64 s[32:33], s[32:33], s[34:35]
	v_addc_co_u32_e64 v244, s[34:35], 0, v244, s[32:33]
	v_cmp_gt_f32_e64 s[32:33], v91, v240
	v_cmp_eq_f32_e64 s[34:35], v91, v240
	v_cmp_lt_u32_e64 s[36:37], 11, v245
	s_and_b64 s[34:35], s[34:35], s[36:37]
	s_or_b64 s[32:33], s[32:33], s[34:35]
	v_addc_co_u32_e64 v244, s[34:35], 0, v244, s[32:33]
	v_cmp_gt_f32_e64 s[32:33], v92, v240
	v_cmp_eq_f32_e64 s[34:35], v92, v240
	v_cmp_lt_u32_e64 s[36:37], 12, v245
	s_and_b64 s[34:35], s[34:35], s[36:37]
	s_or_b64 s[32:33], s[32:33], s[34:35]
	v_addc_co_u32_e64 v244, s[34:35], 0, v244, s[32:33]
	v_cmp_gt_f32_e64 s[32:33], v93, v240
	v_cmp_eq_f32_e64 s[34:35], v93, v240
	v_cmp_lt_u32_e64 s[36:37], 13, v245
	s_and_b64 s[34:35], s[34:35], s[36:37]
	s_or_b64 s[32:33], s[32:33], s[34:35]
	v_addc_co_u32_e64 v244, s[34:35], 0, v244, s[32:33]
	v_cmp_gt_f32_e64 s[32:33], v94, v240
	v_cmp_eq_f32_e64 s[34:35], v94, v240
	v_cmp_lt_u32_e64 s[36:37], 14, v245
	s_and_b64 s[34:35], s[34:35], s[36:37]
	s_or_b64 s[32:33], s[32:33], s[34:35]
	v_addc_co_u32_e64 v244, s[34:35], 0, v244, s[32:33]
	v_cmp_gt_f32_e64 s[32:33], v95, v240
	v_cmp_eq_f32_e64 s[34:35], v95, v240
	v_cmp_lt_u32_e64 s[36:37], 15, v245
	s_and_b64 s[34:35], s[34:35], s[36:37]
	s_or_b64 s[32:33], s[32:33], s[34:35]
	v_addc_co_u32_e64 v244, s[34:35], 0, v244, s[32:33]
	v_cmp_gt_f32_e64 s[32:33], v96, v240
	v_cmp_eq_f32_e64 s[34:35], v96, v240
	v_cmp_lt_u32_e64 s[36:37], 16, v245
	s_and_b64 s[34:35], s[34:35], s[36:37]
	s_or_b64 s[32:33], s[32:33], s[34:35]
	v_addc_co_u32_e64 v244, s[34:35], 0, v244, s[32:33]
	v_cmp_gt_f32_e64 s[32:33], v97, v240
	v_cmp_eq_f32_e64 s[34:35], v97, v240
	v_cmp_lt_u32_e64 s[36:37], 17, v245
	s_and_b64 s[34:35], s[34:35], s[36:37]
	s_or_b64 s[32:33], s[32:33], s[34:35]
	v_addc_co_u32_e64 v244, s[34:35], 0, v244, s[32:33]
	v_cmp_gt_f32_e64 s[32:33], v98, v240
	v_cmp_eq_f32_e64 s[34:35], v98, v240
	v_cmp_lt_u32_e64 s[36:37], 18, v245
	s_and_b64 s[34:35], s[34:35], s[36:37]
	s_or_b64 s[32:33], s[32:33], s[34:35]
	v_addc_co_u32_e64 v244, s[34:35], 0, v244, s[32:33]
	v_cmp_gt_f32_e64 s[32:33], v99, v240
	v_cmp_eq_f32_e64 s[34:35], v99, v240
	v_cmp_lt_u32_e64 s[36:37], 19, v245
; DEVI void phase_nsa(const Params& p, unsigned char* smem) {
;     ...
; #pragma unroll
;       for (int k = 0; k < 4; ++k) {
;         const int s_ = sub * 4 + k;
;         const float v = impT[qi * 33 + s_];
;         int rank = 0;
;         for (int s2 = 0; s2 < 32; ++s2) {
;           const float v2 = impT[qi * 33 + s2];
;           rank += ((v2 > v) || (v2 == v && s2 < s_)) ? 1 : 0;
;         }
;         if (rank < 16) bits |= 1u << s_;
;       }
	s_and_b64 s[34:35], s[34:35], s[36:37]
	s_or_b64 s[32:33], s[32:33], s[34:35]
	v_addc_co_u32_e64 v244, s[34:35], 0, v244, s[32:33]
	v_cmp_gt_f32_e64 s[32:33], v100, v240
	v_cmp_eq_f32_e64 s[34:35], v100, v240
	v_cmp_lt_u32_e64 s[36:37], 20, v245
	s_and_b64 s[34:35], s[34:35], s[36:37]
	s_or_b64 s[32:33], s[32:33], s[34:35]
	v_addc_co_u32_e64 v244, s[34:35], 0, v244, s[32:33]
	v_cmp_gt_f32_e64 s[32:33], v101, v240
	v_cmp_eq_f32_e64 s[34:35], v101, v240
	v_cmp_lt_u32_e64 s[36:37], 21, v245
	s_and_b64 s[34:35], s[34:35], s[36:37]
	s_or_b64 s[32:33], s[32:33], s[34:35]
	v_addc_co_u32_e64 v244, s[34:35], 0, v244, s[32:33]
	v_cmp_gt_f32_e64 s[32:33], v102, v240
	v_cmp_eq_f32_e64 s[34:35], v102, v240
	v_cmp_lt_u32_e64 s[36:37], 22, v245
	s_and_b64 s[34:35], s[34:35], s[36:37]
	s_or_b64 s[32:33], s[32:33], s[34:35]
	v_addc_co_u32_e64 v244, s[34:35], 0, v244, s[32:33]
	v_cmp_gt_f32_e64 s[32:33], v103, v240
	v_cmp_eq_f32_e64 s[34:35], v103, v240
	v_cmp_lt_u32_e64 s[36:37], 23, v245
	s_and_b64 s[34:35], s[34:35], s[36:37]
	s_or_b64 s[32:33], s[32:33], s[34:35]
	v_addc_co_u32_e64 v244, s[34:35], 0, v244, s[32:33]
	v_cmp_gt_f32_e64 s[32:33], v104, v240
	v_cmp_eq_f32_e64 s[34:35], v104, v240
	v_cmp_lt_u32_e64 s[36:37], 24, v245
	s_and_b64 s[34:35], s[34:35], s[36:37]
	s_or_b64 s[32:33], s[32:33], s[34:35]
	v_addc_co_u32_e64 v244, s[34:35], 0, v244, s[32:33]
	v_cmp_gt_f32_e64 s[32:33], v105, v240
	v_cmp_eq_f32_e64 s[34:35], v105, v240
	v_cmp_lt_u32_e64 s[36:37], 25, v245
	s_and_b64 s[34:35], s[34:35], s[36:37]
	s_or_b64 s[32:33], s[32:33], s[34:35]
	v_addc_co_u32_e64 v244, s[34:35], 0, v244, s[32:33]
	v_cmp_gt_f32_e64 s[32:33], v106, v240
	v_cmp_eq_f32_e64 s[34:35], v106, v240
	v_cmp_lt_u32_e64 s[36:37], 26, v245
	s_and_b64 s[34:35], s[34:35], s[36:37]
	s_or_b64 s[32:33], s[32:33], s[34:35]
	v_addc_co_u32_e64 v244, s[34:35], 0, v244, s[32:33]
	v_cmp_gt_f32_e64 s[32:33], v107, v240
	v_cmp_eq_f32_e64 s[34:35], v107, v240
	v_cmp_lt_u32_e64 s[36:37], 27, v245
	s_and_b64 s[34:35], s[34:35], s[36:37]
	s_or_b64 s[32:33], s[32:33], s[34:35]
	v_addc_co_u32_e64 v244, s[34:35], 0, v244, s[32:33]
	v_cmp_gt_f32_e64 s[32:33], v108, v240
	v_cmp_eq_f32_e64 s[34:35], v108, v240
	v_cmp_lt_u32_e64 s[36:37], 28, v245
	s_and_b64 s[34:35], s[34:35], s[36:37]
	s_or_b64 s[32:33], s[32:33], s[34:35]
	v_addc_co_u32_e64 v244, s[34:35], 0, v244, s[32:33]
	v_cmp_gt_f32_e64 s[32:33], v109, v240
	v_cmp_eq_f32_e64 s[34:35], v109, v240
	v_cmp_lt_u32_e64 s[36:37], 29, v245
	s_and_b64 s[34:35], s[34:35], s[36:37]
	s_or_b64 s[32:33], s[32:33], s[34:35]
	v_addc_co_u32_e64 v244, s[34:35], 0, v244, s[32:33]
	v_cmp_gt_f32_e64 s[32:33], v110, v240
	v_cmp_eq_f32_e64 s[34:35], v110, v240
	v_cmp_lt_u32_e64 s[36:37], 30, v245
	s_and_b64 s[34:35], s[34:35], s[36:37]
	s_or_b64 s[32:33], s[32:33], s[34:35]
	v_addc_co_u32_e64 v244, s[34:35], 0, v244, s[32:33]
	v_cmp_gt_f32_e64 s[32:33], v111, v240
	v_cmp_eq_f32_e64 s[34:35], v111, v240
	v_cmp_lt_u32_e64 s[36:37], 31, v245
	s_and_b64 s[34:35], s[34:35], s[36:37]
	s_or_b64 s[32:33], s[32:33], s[34:35]
	v_addc_co_u32_e64 v244, s[34:35], 0, v244, s[32:33]
	v_mov_b32_e32 v243, 1
	v_lshlrev_b32_e32 v243, v245, v243
	v_cmp_gt_u32_e64 s[32:33], 16, v244
	v_mov_b32_e32 v246, 0
	s_nop 0
	v_cndmask_b32_e64 v243, v246, v243, s[32:33]
	v_or_b32_e32 v242, v243, v242
	v_mov_b32_e32 v244, 0
	v_add_u32_e32 v245, 3, v235
	v_cmp_gt_f32_e64 s[32:33], v80, v241
	v_cmp_eq_f32_e64 s[34:35], v80, v241
	v_cmp_lt_u32_e64 s[36:37], 0, v245
	s_and_b64 s[34:35], s[34:35], s[36:37]
	s_or_b64 s[32:33], s[32:33], s[34:35]
	v_addc_co_u32_e64 v244, s[34:35], 0, v244, s[32:33]
	v_cmp_gt_f32_e64 s[32:33], v81, v241
	v_cmp_eq_f32_e64 s[34:35], v81, v241
	v_cmp_lt_u32_e64 s[36:37], 1, v245
	s_and_b64 s[34:35], s[34:35], s[36:37]
	s_or_b64 s[32:33], s[32:33], s[34:35]
	v_addc_co_u32_e64 v244, s[34:35], 0, v244, s[32:33]
	v_cmp_gt_f32_e64 s[32:33], v82, v241
	v_cmp_eq_f32_e64 s[34:35], v82, v241
	v_cmp_lt_u32_e64 s[36:37], 2, v245
	s_and_b64 s[34:35], s[34:35], s[36:37]
	s_or_b64 s[32:33], s[32:33], s[34:35]
	v_addc_co_u32_e64 v244, s[34:35], 0, v244, s[32:33]
	v_cmp_gt_f32_e64 s[32:33], v83, v241
	v_cmp_eq_f32_e64 s[34:35], v83, v241
	v_cmp_lt_u32_e64 s[36:37], 3, v245
	s_and_b64 s[34:35], s[34:35], s[36:37]
	s_or_b64 s[32:33], s[32:33], s[34:35]
	v_addc_co_u32_e64 v244, s[34:35], 0, v244, s[32:33]
	v_cmp_gt_f32_e64 s[32:33], v84, v241
	v_cmp_eq_f32_e64 s[34:35], v84, v241
	v_cmp_lt_u32_e64 s[36:37], 4, v245
	s_and_b64 s[34:35], s[34:35], s[36:37]
	s_or_b64 s[32:33], s[32:33], s[34:35]
	v_addc_co_u32_e64 v244, s[34:35], 0, v244, s[32:33]
	v_cmp_gt_f32_e64 s[32:33], v85, v241
	v_cmp_eq_f32_e64 s[34:35], v85, v241
	v_cmp_lt_u32_e64 s[36:37], 5, v245
	s_and_b64 s[34:35], s[34:35], s[36:37]
	s_or_b64 s[32:33], s[32:33], s[34:35]
	v_addc_co_u32_e64 v244, s[34:35], 0, v244, s[32:33]
	v_cmp_gt_f32_e64 s[32:33], v86, v241
	v_cmp_eq_f32_e64 s[34:35], v86, v241
	v_cmp_lt_u32_e64 s[36:37], 6, v245
	s_and_b64 s[34:35], s[34:35], s[36:37]
	s_or_b64 s[32:33], s[32:33], s[34:35]
	v_addc_co_u32_e64 v244, s[34:35], 0, v244, s[32:33]
	v_cmp_gt_f32_e64 s[32:33], v87, v241
	v_cmp_eq_f32_e64 s[34:35], v87, v241
	v_cmp_lt_u32_e64 s[36:37], 7, v245
	s_and_b64 s[34:35], s[34:35], s[36:37]
	s_or_b64 s[32:33], s[32:33], s[34:35]
	v_addc_co_u32_e64 v244, s[34:35], 0, v244, s[32:33]
	v_cmp_gt_f32_e64 s[32:33], v88, v241
	v_cmp_eq_f32_e64 s[34:35], v88, v241
	v_cmp_lt_u32_e64 s[36:37], 8, v245
	s_and_b64 s[34:35], s[34:35], s[36:37]
	s_or_b64 s[32:33], s[32:33], s[34:35]
	v_addc_co_u32_e64 v244, s[34:35], 0, v244, s[32:33]
	v_cmp_gt_f32_e64 s[32:33], v89, v241
	v_cmp_eq_f32_e64 s[34:35], v89, v241
; DEVI void phase_nsa(const Params& p, unsigned char* smem) {
;     ...
; #pragma unroll
;       for (int k = 0; k < 4; ++k) {
;         const int s_ = sub * 4 + k;
;         const float v = impT[qi * 33 + s_];
;         int rank = 0;
;         for (int s2 = 0; s2 < 32; ++s2) {
;           const float v2 = impT[qi * 33 + s2];
;           rank += ((v2 > v) || (v2 == v && s2 < s_)) ? 1 : 0;
;         }
;         if (rank < 16) bits |= 1u << s_;
;       }
;       atomicOr(&selm[qi], bits);
	v_cmp_lt_u32_e64 s[36:37], 9, v245
	s_and_b64 s[34:35], s[34:35], s[36:37]
	s_or_b64 s[32:33], s[32:33], s[34:35]
	v_addc_co_u32_e64 v244, s[34:35], 0, v244, s[32:33]
	v_cmp_gt_f32_e64 s[32:33], v90, v241
	v_cmp_eq_f32_e64 s[34:35], v90, v241
	v_cmp_lt_u32_e64 s[36:37], 10, v245
	s_and_b64 s[34:35], s[34:35], s[36:37]
	s_or_b64 s[32:33], s[32:33], s[34:35]
	v_addc_co_u32_e64 v244, s[34:35], 0, v244, s[32:33]
	v_cmp_gt_f32_e64 s[32:33], v91, v241
	v_cmp_eq_f32_e64 s[34:35], v91, v241
	v_cmp_lt_u32_e64 s[36:37], 11, v245
	s_and_b64 s[34:35], s[34:35], s[36:37]
	s_or_b64 s[32:33], s[32:33], s[34:35]
	v_addc_co_u32_e64 v244, s[34:35], 0, v244, s[32:33]
	v_cmp_gt_f32_e64 s[32:33], v92, v241
	v_cmp_eq_f32_e64 s[34:35], v92, v241
	v_cmp_lt_u32_e64 s[36:37], 12, v245
	s_and_b64 s[34:35], s[34:35], s[36:37]
	s_or_b64 s[32:33], s[32:33], s[34:35]
	v_addc_co_u32_e64 v244, s[34:35], 0, v244, s[32:33]
	v_cmp_gt_f32_e64 s[32:33], v93, v241
	v_cmp_eq_f32_e64 s[34:35], v93, v241
	v_cmp_lt_u32_e64 s[36:37], 13, v245
	s_and_b64 s[34:35], s[34:35], s[36:37]
	s_or_b64 s[32:33], s[32:33], s[34:35]
	v_addc_co_u32_e64 v244, s[34:35], 0, v244, s[32:33]
	v_cmp_gt_f32_e64 s[32:33], v94, v241
	v_cmp_eq_f32_e64 s[34:35], v94, v241
	v_cmp_lt_u32_e64 s[36:37], 14, v245
	s_and_b64 s[34:35], s[34:35], s[36:37]
	s_or_b64 s[32:33], s[32:33], s[34:35]
	v_addc_co_u32_e64 v244, s[34:35], 0, v244, s[32:33]
	v_cmp_gt_f32_e64 s[32:33], v95, v241
	v_cmp_eq_f32_e64 s[34:35], v95, v241
	v_cmp_lt_u32_e64 s[36:37], 15, v245
	s_and_b64 s[34:35], s[34:35], s[36:37]
	s_or_b64 s[32:33], s[32:33], s[34:35]
	v_addc_co_u32_e64 v244, s[34:35], 0, v244, s[32:33]
	v_cmp_gt_f32_e64 s[32:33], v96, v241
	v_cmp_eq_f32_e64 s[34:35], v96, v241
	v_cmp_lt_u32_e64 s[36:37], 16, v245
	s_and_b64 s[34:35], s[34:35], s[36:37]
	s_or_b64 s[32:33], s[32:33], s[34:35]
	v_addc_co_u32_e64 v244, s[34:35], 0, v244, s[32:33]
	v_cmp_gt_f32_e64 s[32:33], v97, v241
	v_cmp_eq_f32_e64 s[34:35], v97, v241
	v_cmp_lt_u32_e64 s[36:37], 17, v245
	s_and_b64 s[34:35], s[34:35], s[36:37]
	s_or_b64 s[32:33], s[32:33], s[34:35]
	v_addc_co_u32_e64 v244, s[34:35], 0, v244, s[32:33]
	v_cmp_gt_f32_e64 s[32:33], v98, v241
	v_cmp_eq_f32_e64 s[34:35], v98, v241
	v_cmp_lt_u32_e64 s[36:37], 18, v245
	s_and_b64 s[34:35], s[34:35], s[36:37]
	s_or_b64 s[32:33], s[32:33], s[34:35]
	v_addc_co_u32_e64 v244, s[34:35], 0, v244, s[32:33]
	v_cmp_gt_f32_e64 s[32:33], v99, v241
	v_cmp_eq_f32_e64 s[34:35], v99, v241
	v_cmp_lt_u32_e64 s[36:37], 19, v245
	s_and_b64 s[34:35], s[34:35], s[36:37]
	s_or_b64 s[32:33], s[32:33], s[34:35]
	v_addc_co_u32_e64 v244, s[34:35], 0, v244, s[32:33]
	v_cmp_gt_f32_e64 s[32:33], v100, v241
	v_cmp_eq_f32_e64 s[34:35], v100, v241
	v_cmp_lt_u32_e64 s[36:37], 20, v245
	s_and_b64 s[34:35], s[34:35], s[36:37]
	s_or_b64 s[32:33], s[32:33], s[34:35]
	v_addc_co_u32_e64 v244, s[34:35], 0, v244, s[32:33]
	v_cmp_gt_f32_e64 s[32:33], v101, v241
	v_cmp_eq_f32_e64 s[34:35], v101, v241
	v_cmp_lt_u32_e64 s[36:37], 21, v245
	s_and_b64 s[34:35], s[34:35], s[36:37]
	s_or_b64 s[32:33], s[32:33], s[34:35]
	v_addc_co_u32_e64 v244, s[34:35], 0, v244, s[32:33]
	v_cmp_gt_f32_e64 s[32:33], v102, v241
	v_cmp_eq_f32_e64 s[34:35], v102, v241
	v_cmp_lt_u32_e64 s[36:37], 22, v245
	s_and_b64 s[34:35], s[34:35], s[36:37]
	s_or_b64 s[32:33], s[32:33], s[34:35]
	v_addc_co_u32_e64 v244, s[34:35], 0, v244, s[32:33]
	v_cmp_gt_f32_e64 s[32:33], v103, v241
	v_cmp_eq_f32_e64 s[34:35], v103, v241
	v_cmp_lt_u32_e64 s[36:37], 23, v245
	s_and_b64 s[34:35], s[34:35], s[36:37]
	s_or_b64 s[32:33], s[32:33], s[34:35]
	v_addc_co_u32_e64 v244, s[34:35], 0, v244, s[32:33]
	v_cmp_gt_f32_e64 s[32:33], v104, v241
	v_cmp_eq_f32_e64 s[34:35], v104, v241
	v_cmp_lt_u32_e64 s[36:37], 24, v245
	s_and_b64 s[34:35], s[34:35], s[36:37]
	s_or_b64 s[32:33], s[32:33], s[34:35]
	v_addc_co_u32_e64 v244, s[34:35], 0, v244, s[32:33]
	v_cmp_gt_f32_e64 s[32:33], v105, v241
	v_cmp_eq_f32_e64 s[34:35], v105, v241
	v_cmp_lt_u32_e64 s[36:37], 25, v245
	s_and_b64 s[34:35], s[34:35], s[36:37]
	s_or_b64 s[32:33], s[32:33], s[34:35]
	v_addc_co_u32_e64 v244, s[34:35], 0, v244, s[32:33]
	v_cmp_gt_f32_e64 s[32:33], v106, v241
	v_cmp_eq_f32_e64 s[34:35], v106, v241
	v_cmp_lt_u32_e64 s[36:37], 26, v245
	s_and_b64 s[34:35], s[34:35], s[36:37]
	s_or_b64 s[32:33], s[32:33], s[34:35]
	v_addc_co_u32_e64 v244, s[34:35], 0, v244, s[32:33]
	v_cmp_gt_f32_e64 s[32:33], v107, v241
	v_cmp_eq_f32_e64 s[34:35], v107, v241
	v_cmp_lt_u32_e64 s[36:37], 27, v245
	s_and_b64 s[34:35], s[34:35], s[36:37]
	s_or_b64 s[32:33], s[32:33], s[34:35]
	v_addc_co_u32_e64 v244, s[34:35], 0, v244, s[32:33]
	v_cmp_gt_f32_e64 s[32:33], v108, v241
	v_cmp_eq_f32_e64 s[34:35], v108, v241
	v_cmp_lt_u32_e64 s[36:37], 28, v245
	s_and_b64 s[34:35], s[34:35], s[36:37]
	s_or_b64 s[32:33], s[32:33], s[34:35]
	v_addc_co_u32_e64 v244, s[34:35], 0, v244, s[32:33]
	v_cmp_gt_f32_e64 s[32:33], v109, v241
	v_cmp_eq_f32_e64 s[34:35], v109, v241
	v_cmp_lt_u32_e64 s[36:37], 29, v245
	s_and_b64 s[34:35], s[34:35], s[36:37]
	s_or_b64 s[32:33], s[32:33], s[34:35]
	v_addc_co_u32_e64 v244, s[34:35], 0, v244, s[32:33]
	v_cmp_gt_f32_e64 s[32:33], v110, v241
	v_cmp_eq_f32_e64 s[34:35], v110, v241
	v_cmp_lt_u32_e64 s[36:37], 30, v245
	s_and_b64 s[34:35], s[34:35], s[36:37]
	s_or_b64 s[32:33], s[32:33], s[34:35]
	v_addc_co_u32_e64 v244, s[34:35], 0, v244, s[32:33]
	v_cmp_gt_f32_e64 s[32:33], v111, v241
	v_cmp_eq_f32_e64 s[34:35], v111, v241
	v_cmp_lt_u32_e64 s[36:37], 31, v245
	s_and_b64 s[34:35], s[34:35], s[36:37]
	s_or_b64 s[32:33], s[32:33], s[34:35]
	v_addc_co_u32_e64 v244, s[34:35], 0, v244, s[32:33]
	v_mov_b32_e32 v243, 1
	v_lshlrev_b32_e32 v243, v245, v243
	v_cmp_gt_u32_e64 s[32:33], 16, v244
	v_mov_b32_e32 v246, 0
	s_nop 0
	v_cndmask_b32_e64 v243, v246, v243, s[32:33]
	v_or_b32_e32 v242, v243, v242
	v_lshlrev_b32_e32 v232, 2, v232
	s_mov_b32 s32, 0xffffffff
	s_mov_b32 s33, 0xffffffff
	ds_or_b32 v232, v242 offset:56960
; DEVI void phase_nsa(const Params& p, unsigned char* smem) {
;     ...
;     __syncthreads();
;     unsigned sm[2] = {selm[col], selm[16 + col]};
;     unsigned uni = 0u;
; #pragma unroll
;     for (int i = 0; i < 32; ++i) uni |= selm[i];
;     const int kbmax = (q0 + 31) >> 6;
;     {
;       float m[2] = {-1e30f, -1e30f}, l[2] = {0.f, 0.f};
;       f32x4 o[2][4];
; #pragma unroll
;       for (int qt = 0; qt < 2; ++qt)
; #pragma unroll
;         for (int dt = 0; dt < 4; ++dt) o[qt][dt] = f32x4{0.f, 0.f, 0.f, 0.f};
;       unsigned rem = (kbmax >= 31) ? uni : (uni & ((1u << (kbmax + 1)) - 1u));
;       int kb = rem ? (__ffs((int)rem) - 1) : -1;
;       uint4 rk0, rk1, rv0, rv1;
;       const int lr0 = tid >> 3, lch = (tid & 7) << 3;
;     ...
;       if (kb >= 0) { LOADKV_(kb, C_KS, p.vts) }
; #pragma unroll 1
;       while (kb >= 0) {
;         rem &= rem - 1u;
;         const int nkb = rem ? (__ffs((int)rem) - 1) : -1;
;         __syncthreads();
;         STOREKV_()
;         if (nkb >= 0) { LOADKV_(nkb, C_KS, p.vts) }
.Lp4_selend:
	s_waitcnt lgkmcnt(0)
	s_barrier
	v_lshlrev_b32_e32 v231, 2, v197
	ds_read_b32 v188, v231 offset:56960
	ds_read_b32 v189, v231 offset:57024
	v_lshlrev_b32_e32 v232, 2, v199
	v_and_b32_e32 v232, 0x7c, v232
	ds_read_b32 v232, v232 offset:56960
	s_waitcnt lgkmcnt(0)
	s_nop 0
	v_readlane_b32 s28, v232, 0
	s_mov_b32 s29, s28
	v_readlane_b32 s22, v232, 1
	s_or_b32 s28, s28, s22
	s_and_b32 s29, s29, s22
	v_readlane_b32 s22, v232, 2
	s_or_b32 s28, s28, s22
	s_and_b32 s29, s29, s22
	v_readlane_b32 s22, v232, 3
	s_or_b32 s28, s28, s22
	s_and_b32 s29, s29, s22
	v_readlane_b32 s22, v232, 4
	s_or_b32 s28, s28, s22
	s_and_b32 s29, s29, s22
	v_readlane_b32 s22, v232, 5
	s_or_b32 s28, s28, s22
	s_and_b32 s29, s29, s22
	v_readlane_b32 s22, v232, 6
	s_or_b32 s28, s28, s22
	s_and_b32 s29, s29, s22
	v_readlane_b32 s22, v232, 7
	s_or_b32 s28, s28, s22
	s_and_b32 s29, s29, s22
	v_readlane_b32 s22, v232, 8
	s_or_b32 s28, s28, s22
	s_and_b32 s29, s29, s22
	v_readlane_b32 s22, v232, 9
	s_or_b32 s28, s28, s22
	s_and_b32 s29, s29, s22
	v_readlane_b32 s22, v232, 10
	s_or_b32 s28, s28, s22
	s_and_b32 s29, s29, s22
	v_readlane_b32 s22, v232, 11
	s_or_b32 s28, s28, s22
	s_and_b32 s29, s29, s22
	v_readlane_b32 s22, v232, 12
	s_or_b32 s28, s28, s22
	s_and_b32 s29, s29, s22
	v_readlane_b32 s22, v232, 13
	s_or_b32 s28, s28, s22
	s_and_b32 s29, s29, s22
	v_readlane_b32 s22, v232, 14
	s_or_b32 s28, s28, s22
	s_and_b32 s29, s29, s22
	v_readlane_b32 s22, v232, 15
	s_or_b32 s28, s28, s22
	s_and_b32 s29, s29, s22
	v_readlane_b32 s22, v232, 16
	s_or_b32 s28, s28, s22
	s_and_b32 s29, s29, s22
	v_readlane_b32 s22, v232, 17
	s_or_b32 s28, s28, s22
	s_and_b32 s29, s29, s22
	v_readlane_b32 s22, v232, 18
	s_or_b32 s28, s28, s22
	s_and_b32 s29, s29, s22
	v_readlane_b32 s22, v232, 19
	s_or_b32 s28, s28, s22
	s_and_b32 s29, s29, s22
	v_readlane_b32 s22, v232, 20
	s_or_b32 s28, s28, s22
	s_and_b32 s29, s29, s22
	v_readlane_b32 s22, v232, 21
	s_or_b32 s28, s28, s22
	s_and_b32 s29, s29, s22
	v_readlane_b32 s22, v232, 22
	s_or_b32 s28, s28, s22
	s_and_b32 s29, s29, s22
	v_readlane_b32 s22, v232, 23
	s_or_b32 s28, s28, s22
	s_and_b32 s29, s29, s22
	v_readlane_b32 s22, v232, 24
	s_or_b32 s28, s28, s22
	s_and_b32 s29, s29, s22
	v_readlane_b32 s22, v232, 25
	s_or_b32 s28, s28, s22
	s_and_b32 s29, s29, s22
	v_readlane_b32 s22, v232, 26
	s_or_b32 s28, s28, s22
	s_and_b32 s29, s29, s22
	v_readlane_b32 s22, v232, 27
	s_or_b32 s28, s28, s22
	s_and_b32 s29, s29, s22
	v_readlane_b32 s22, v232, 28
	s_or_b32 s28, s28, s22
	s_and_b32 s29, s29, s22
	v_readlane_b32 s22, v232, 29
	s_or_b32 s28, s28, s22
	s_and_b32 s29, s29, s22
	v_readlane_b32 s22, v232, 30
	s_or_b32 s28, s28, s22
	s_and_b32 s29, s29, s22
	v_readlane_b32 s22, v232, 31
	s_or_b32 s28, s28, s22
	s_and_b32 s29, s29, s22
	s_mov_b32 s42, s4
	s_mov_b32 s43, s5
	s_lshl_b32 s31, s17, 7
	s_add_u32 s31, s31, 3584
	s_mov_b32 s41, 0x7fffffff
	v_mov_b32_e32 v16, 0
	v_mov_b32_e32 v17, 0
	v_mov_b32_e32 v18, 0
	v_mov_b32_e32 v19, 0
	v_mov_b32_e32 v20, 0
	v_mov_b32_e32 v21, 0
	v_mov_b32_e32 v22, 0
	v_mov_b32_e32 v23, 0
	v_mov_b32_e32 v24, 0
	v_mov_b32_e32 v25, 0
	v_mov_b32_e32 v26, 0
	v_mov_b32_e32 v27, 0
	v_mov_b32_e32 v28, 0
	v_mov_b32_e32 v29, 0
	v_mov_b32_e32 v30, 0
	v_mov_b32_e32 v31, 0
	v_mov_b32_e32 v32, 0
	v_mov_b32_e32 v33, 0
	v_mov_b32_e32 v34, 0
	v_mov_b32_e32 v35, 0
	v_mov_b32_e32 v36, 0
	v_mov_b32_e32 v37, 0
	v_mov_b32_e32 v38, 0
	v_mov_b32_e32 v39, 0
	v_mov_b32_e32 v40, 0
	v_mov_b32_e32 v41, 0
	v_mov_b32_e32 v42, 0
	v_mov_b32_e32 v43, 0
	v_mov_b32_e32 v44, 0
	v_mov_b32_e32 v45, 0
	v_mov_b32_e32 v46, 0
	v_mov_b32_e32 v47, 0
	v_mov_b32_e32 v182, 0xf149f2ca
	v_mov_b32_e32 v184, 0
	v_mov_b32_e32 v183, 0xf149f2ca
	v_mov_b32_e32 v185, 0
	s_add_u32 s22, s20, 1
	s_lshl_b32 s22, 1, s22
	s_sub_u32 s22, s22, 1
	s_cmp_ge_u32 s20, 31
	s_cselect_b32 s22, -1, s22
	s_and_b32 s25, s28, s22
	s_cmp_eq_u32 s25, 0
	s_cbranch_scc1 .Lp4_sel_end
	s_ff1_i32_b32 s26, s25
	s_add_u32 s22, s25, -1
	s_and_b32 s25, s25, s22
	s_lshl_b32 s22, s16, 11
	s_lshl_b32 s23, s26, 6
	s_add_u32 s22, s22, s23
	s_mul_i32 s22, s22, 0x1240
	s_add_u32 s22, s22, s31
	v_add_u32_e32 v211, s22, v201
	v_add_u32_e32 v212, s22, v202
	global_load_dwordx4 v[160:163], v211, s[0:1]
	global_load_dwordx4 v[164:167], v212, s[0:1]
	s_mul_i32 s22, s18, 0x42000
	s_lshl_b32 s23, s26, 7
	s_add_u32 s22, s22, s23
	v_add_u32_e32 v213, s22, v203
	v_add_u32_e32 v214, s22, v204
	global_load_dwordx4 v[168:171], v213, s[42:43]
	global_load_dwordx4 v[172:175], v214, s[42:43]
	s_mov_b32 s40, 0
.Lp4_sel_loop:
.Lp4_sel_buf0:
	s_waitcnt vmcnt(0)
	ds_write_b128 v193, v[160:163]
	ds_write_b128 v193, v[164:167] offset:4608
	ds_write_b128 v193, v[168:171] offset:18432
	ds_write_b128 v193, v[172:175] offset:23040
	s_ff1_i32_b32 s27, s25
	s_add_u32 s22, s25, -1
	s_and_b32 s25, s25, s22
	s_cmp_lt_i32 s27, 0
	s_cbranch_scc1 .Lp4_sel_nold0
	s_lshl_b32 s22, s16, 11
	s_lshl_b32 s23, s27, 6
	s_add_u32 s22, s22, s23
	s_mul_i32 s22, s22, 0x1240
	s_add_u32 s22, s22, s31
	v_add_u32_e32 v211, s22, v201
	v_add_u32_e32 v212, s22, v202
	global_load_dwordx4 v[160:163], v211, s[0:1]
	global_load_dwordx4 v[164:167], v212, s[0:1]
	s_mul_i32 s22, s18, 0x42000
	s_lshl_b32 s23, s27, 7
	s_add_u32 s22, s22, s23
	v_add_u32_e32 v213, s22, v203
	v_add_u32_e32 v214, s22, v204
	global_load_dwordx4 v[168:171], v213, s[42:43]
	global_load_dwordx4 v[172:175], v214, s[42:43]
; template <int DH, int NQ, int LDK, class MaskF>
; DEVI void attn_qk(const u16* sK, const bf16x8 (&qf)[NQ][DH / 32], f32x4 (&o)[NQ][DH / 16], float (&m)[NQ], float (&l)[NQ],
;                   float c2, int lane, MaskF valid, bf16x8 (&pb)[NQ][2]) {
;     ...
;   __builtin_amdgcn_s_setprio(1);
; #pragma unroll
;   for (int kt = 0; kt < 4; ++kt) {
; #pragma unroll
;     for (int qt = 0; qt < NQ; ++qt) s[qt][kt] = f32x4{0.f, 0.f, 0.f, 0.f};
; #pragma unroll
;     for (int ks = 0; ks < DH / 32; ++ks) {
;       const bf16x8 kf = *(const bf16x8*)(sK + (16 * kt + col) * LDK + 32 * ks + 8 * quad);
; #pragma unroll
;       for (int qt = 0; qt < NQ; ++qt) s[qt][kt] = mfma16(kf, qf[qt][ks], s[qt][kt]);
;     }
;   }
;   __builtin_amdgcn_s_setprio(0);
; #pragma unroll
;   for (int qt = 0; qt < NQ; ++qt) {
;     float mx = -1e30f;
; #pragma unroll
;     for (int kt = 0; kt < 4; ++kt)
; #pragma unroll
;       for (int r = 0; r < 4; ++r) {
;         const bool v = valid(qt, 16 * kt + 4 * quad + r);
;         const float sv = v ? s[qt][kt][r] : -1e30f;
;         s[qt][kt][r] = sv;
;         mx = fmaxf(mx, sv);
;       }
;     mx = fmaxf(mx, __shfl_xor(mx, 16));
;     mx = fmaxf(mx, __shfl_xor(mx, 32));
;     const float mn = fmaxf(m[qt], mx);
;     const float alpha = fexp2((m[qt] - mn) * c2);
;     m[qt] = mn;
;     const float mc = fmaxf(mn, -1e20f) * c2;
;     float ps = 0.f;
; #pragma unroll
;     for (int kt = 0; kt < 4; ++kt)
; #pragma unroll
;       for (int r = 0; r < 4; ++r) {
;         const float pv = fexp2(__builtin_fmaf(s[qt][kt][r], c2, -mc));
;         ps += pv;
;         s[qt][kt][r] = pv;
;       }
;     l[qt] = l[qt] * alpha + ps;
; #pragma unroll
;     for (int dt = 0; dt < DH / 16; ++dt) o[qt][dt] *= alpha;
; #pragma unroll
;     for (int kk = 0; kk < 2; ++kk) {
;       union { bf16x8 v; unsigned u[4]; } cv;
;       cv.u[0] = pack2(s[qt][2 * kk][0], s[qt][2 * kk][1]);
;       cv.u[1] = pack2(s[qt][2 * kk][2], s[qt][2 * kk][3]);
;       cv.u[2] = pack2(s[qt][2 * kk + 1][0], s[qt][2 * kk + 1][1]);
; DEVI void phase_nsa(const Params& p, unsigned char* smem) {
;     ...
;         const int lim0 = ((sm[0] >> kb) & 1u) ? tq[0] : -1, lim1 = ((sm[1] >> kb) & 1u) ? tq[1] : -1;
;         attn_tile<64, 2, 72, 72>(sK, sVt, qf, o, m, l, c2, lane, [&](int qt, int kl) {
;           return (kb * 64 + kl) <= (qt ? lim1 : lim0);
;         });
.Lp4_sel_nold0:
	s_waitcnt lgkmcnt(0)
	s_barrier
	s_lshl_b32 s30, s26, 6
	v_lshrrev_b32_e32 v215, s26, v188
	v_and_b32_e32 v215, 1, v215
	v_cmp_eq_u32_e64 s[32:33], 1, v215
	v_mov_b32_e32 v216, -1
	s_nop 0
	v_cndmask_b32_e64 v207, v216, v186, s[32:33]
	v_lshlrev_b32_e32 v217, 2, v198
	v_sub_u32_e32 v207, v207, v217
	v_lshrrev_b32_e32 v215, s26, v189
	v_and_b32_e32 v215, 1, v215
	v_cmp_eq_u32_e64 s[32:33], 1, v215
	v_mov_b32_e32 v216, -1
	s_nop 0
	v_cndmask_b32_e64 v208, v216, v187, s[32:33]
	v_lshlrev_b32_e32 v217, 2, v198
	v_sub_u32_e32 v208, v208, v217
	s_lshr_b32 s22, s29, s26
	s_and_b32 s22, s22, 1
	s_add_u32 s23, s30, 63
	s_cmp_le_u32 s23, s19
	s_cselect_b32 s24, s22, 0
	s_cmp_eq_u32 s24, 0
	s_cbranch_scc1 .Lp4_sel_masked0
	ds_read_b128 v[112:115], v190
	ds_read_b128 v[116:119], v190 offset:64
	s_waitcnt lgkmcnt(0)
	v_mfma_f32_16x16x32_bf16 v[80:83], v[112:115], v[0:3], 0
	v_mfma_f32_16x16x32_bf16 v[96:99], v[112:115], v[8:11], 0
	v_mfma_f32_16x16x32_bf16 v[80:83], v[116:119], v[4:7], v[80:83]
	v_mfma_f32_16x16x32_bf16 v[96:99], v[116:119], v[12:15], v[96:99]
	ds_read_b128 v[120:123], v190 offset:2304
	ds_read_b128 v[124:127], v190 offset:2368
	s_waitcnt lgkmcnt(0)
	v_mfma_f32_16x16x32_bf16 v[84:87], v[120:123], v[0:3], 0
	v_mfma_f32_16x16x32_bf16 v[100:103], v[120:123], v[8:11], 0
	v_mfma_f32_16x16x32_bf16 v[84:87], v[124:127], v[4:7], v[84:87]
	v_mfma_f32_16x16x32_bf16 v[100:103], v[124:127], v[12:15], v[100:103]
	ds_read_b128 v[128:131], v190 offset:4608
	ds_read_b128 v[132:135], v190 offset:4672
	s_waitcnt lgkmcnt(0)
	v_mfma_f32_16x16x32_bf16 v[88:91], v[128:131], v[0:3], 0
	v_mfma_f32_16x16x32_bf16 v[104:107], v[128:131], v[8:11], 0
	v_mfma_f32_16x16x32_bf16 v[88:91], v[132:135], v[4:7], v[88:91]
	v_mfma_f32_16x16x32_bf16 v[104:107], v[132:135], v[12:15], v[104:107]
	ds_read_b128 v[136:139], v190 offset:6912
	ds_read_b128 v[140:143], v190 offset:6976
	s_waitcnt lgkmcnt(0)
	v_mfma_f32_16x16x32_bf16 v[92:95], v[136:139], v[0:3], 0
	v_mfma_f32_16x16x32_bf16 v[108:111], v[136:139], v[8:11], 0
	v_mfma_f32_16x16x32_bf16 v[92:95], v[140:143], v[4:7], v[92:95]
	v_mfma_f32_16x16x32_bf16 v[108:111], v[140:143], v[12:15], v[108:111]
	s_nop 7
	v_max3_f32 v215, v80, v81, v82
	v_max3_f32 v215, v215, v83, v84
	v_max3_f32 v215, v215, v85, v86
	v_max3_f32 v215, v215, v87, v88
	v_max3_f32 v215, v215, v89, v90
	v_max3_f32 v215, v215, v91, v92
	v_max3_f32 v215, v215, v93, v94
	v_max_f32_e32 v215, v95, v215
	ds_bpermute_b32 v216, v195, v215
	s_waitcnt lgkmcnt(0)
	v_max_f32_e32 v215, v216, v215
	v_mov_b32_e32 v216, v215
	v_mov_b32_e32 v217, v215
	s_nop 1
	v_permlane32_swap_b32_e32 v216, v217
	v_max_f32_e32 v215, v216, v217
	v_max_f32_e32 v218, v182, v215
	v_sub_f32_e32 v219, v182, v218
	v_mul_f32_e32 v219, v200, v219
	v_exp_f32_e32 v219, v219
	v_mov_b32_e32 v182, v218
	v_max_f32_e32 v220, 0xe0ad78ec, v218
	v_mul_f32_e32 v220, 0xbe38aa3b, v220
	v_fma_f32 v80, v80, v200, v220
	v_exp_f32_e32 v80, v80
	v_fma_f32 v81, v81, v200, v220
	v_exp_f32_e32 v81, v81
	v_fma_f32 v82, v82, v200, v220
	v_exp_f32_e32 v82, v82
	v_fma_f32 v83, v83, v200, v220
	v_exp_f32_e32 v83, v83
	v_fma_f32 v84, v84, v200, v220
	v_exp_f32_e32 v84, v84
	v_fma_f32 v85, v85, v200, v220
	v_exp_f32_e32 v85, v85
	v_fma_f32 v86, v86, v200, v220
	v_exp_f32_e32 v86, v86
	v_fma_f32 v87, v87, v200, v220
	v_exp_f32_e32 v87, v87
	v_fma_f32 v88, v88, v200, v220
	v_exp_f32_e32 v88, v88
	v_fma_f32 v89, v89, v200, v220
	v_exp_f32_e32 v89, v89
	v_fma_f32 v90, v90, v200, v220
	v_exp_f32_e32 v90, v90
	v_fma_f32 v91, v91, v200, v220
	v_exp_f32_e32 v91, v91
	v_fma_f32 v92, v92, v200, v220
	v_exp_f32_e32 v92, v92
	v_fma_f32 v93, v93, v200, v220
	v_exp_f32_e32 v93, v93
	v_fma_f32 v94, v94, v200, v220
	v_exp_f32_e32 v94, v94
	v_fma_f32 v95, v95, v200, v220
	v_exp_f32_e32 v95, v95
	s_nop 0
	v_add_f32_e32 v221, v80, v81
	v_add_f32_e32 v221, v82, v221
	v_add_f32_e32 v221, v83, v221
	v_add_f32_e32 v221, v84, v221
	v_add_f32_e32 v221, v85, v221
	v_add_f32_e32 v221, v86, v221
	v_add_f32_e32 v221, v87, v221
	v_add_f32_e32 v221, v88, v221
	v_add_f32_e32 v221, v89, v221
	v_add_f32_e32 v221, v90, v221
	v_add_f32_e32 v221, v91, v221
	v_add_f32_e32 v221, v92, v221
	v_add_f32_e32 v221, v93, v221
	v_add_f32_e32 v221, v94, v221
	v_add_f32_e32 v221, v95, v221
	v_fma_f32 v184, v184, v219, v221
	v_mul_f32_e32 v16, v219, v16
	v_mul_f32_e32 v17, v219, v17
	v_mul_f32_e32 v18, v219, v18
	v_mul_f32_e32 v19, v219, v19
	v_mul_f32_e32 v20, v219, v20
	v_mul_f32_e32 v21, v219, v21
	v_mul_f32_e32 v22, v219, v22
	v_mul_f32_e32 v23, v219, v23
	v_mul_f32_e32 v24, v219, v24
	v_mul_f32_e32 v25, v219, v25
	v_mul_f32_e32 v26, v219, v26
	v_mul_f32_e32 v27, v219, v27
	v_mul_f32_e32 v28, v219, v28
	v_mul_f32_e32 v29, v219, v29
	v_mul_f32_e32 v30, v219, v30
	v_mul_f32_e32 v31, v219, v31
	v_cvt_pk_bf16_f32 v144, v80, v81
	v_cvt_pk_bf16_f32 v145, v82, v83
	v_cvt_pk_bf16_f32 v146, v84, v85
	v_cvt_pk_bf16_f32 v147, v86, v87
	v_cvt_pk_bf16_f32 v148, v88, v89
	v_cvt_pk_bf16_f32 v149, v90, v91
	v_cvt_pk_bf16_f32 v150, v92, v93
	v_cvt_pk_bf16_f32 v151, v94, v95
	v_max3_f32 v215, v96, v97, v98
	v_max3_f32 v215, v215, v99, v100
	v_max3_f32 v215, v215, v101, v102
	v_max3_f32 v215, v215, v103, v104
	v_max3_f32 v215, v215, v105, v106
	v_max3_f32 v215, v215, v107, v108
	v_max3_f32 v215, v215, v109, v110
	v_max_f32_e32 v215, v111, v215
	ds_bpermute_b32 v216, v195, v215
	s_waitcnt lgkmcnt(0)
; DEVI unsigned pack2(float a, float b) { return (unsigned)f2bf(a) | ((unsigned)f2bf(b) << 16); }
; DEVI f32x4 mfma16(bf16x8 a, bf16x8 b, f32x4 c) { return __builtin_amdgcn_mfma_f32_16x16x32_bf16(a, b, c, 0, 0, 0); }
; DEVI float fexp2(float x) { return __builtin_amdgcn_exp2f(x); }
; template <int DH, int NQ, int LDK, class MaskF>
; DEVI void attn_qk(const u16* sK, const bf16x8 (&qf)[NQ][DH / 32], f32x4 (&o)[NQ][DH / 16], float (&m)[NQ], float (&l)[NQ],
;                   float c2, int lane, MaskF valid, bf16x8 (&pb)[NQ][2]) {
;     ...
;     mx = fmaxf(mx, __shfl_xor(mx, 16));
;     mx = fmaxf(mx, __shfl_xor(mx, 32));
;     const float mn = fmaxf(m[qt], mx);
;     const float alpha = fexp2((m[qt] - mn) * c2);
;     m[qt] = mn;
;     const float mc = fmaxf(mn, -1e20f) * c2;
;     float ps = 0.f;
; #pragma unroll
;     for (int kt = 0; kt < 4; ++kt)
; #pragma unroll
;       for (int r = 0; r < 4; ++r) {
;         const float pv = fexp2(__builtin_fmaf(s[qt][kt][r], c2, -mc));
;         ps += pv;
;         s[qt][kt][r] = pv;
;       }
;     l[qt] = l[qt] * alpha + ps;
; #pragma unroll
;     for (int dt = 0; dt < DH / 16; ++dt) o[qt][dt] *= alpha;
; #pragma unroll
;     for (int kk = 0; kk < 2; ++kk) {
;       union { bf16x8 v; unsigned u[4]; } cv;
;       cv.u[0] = pack2(s[qt][2 * kk][0], s[qt][2 * kk][1]);
;       cv.u[1] = pack2(s[qt][2 * kk][2], s[qt][2 * kk][3]);
;       cv.u[2] = pack2(s[qt][2 * kk + 1][0], s[qt][2 * kk + 1][1]);
;       cv.u[3] = pack2(s[qt][2 * kk + 1][2], s[qt][2 * kk + 1][3]);
;       pb[qt][kk] = cv.v;
;     }
;   }
; }
; template <int DH, int NQ, int LDV>
; DEVI void attn_pv(const u16* sVt, const bf16x8 (&pb)[NQ][2], f32x4 (&o)[NQ][DH / 16], int lane) {
;   const int col = lane & 15, quad = lane >> 4;
;   __builtin_amdgcn_s_setprio(1);
; #pragma unroll
;   for (int dt = 0; dt < DH / 16; ++dt) {
; #pragma unroll
;     for (int kk = 0; kk < 2; ++kk) {
;       union { bf16x8 v; uint2 h[2]; } cv;
;       cv.h[0] = *(const uint2*)(sVt + (16 * dt + col) * LDV + 32 * kk + 4 * quad);
;       cv.h[1] = *(const uint2*)(sVt + (16 * dt + col) * LDV + 32 * kk + 16 + 4 * quad);
; #pragma unroll
;       for (int qt = 0; qt < NQ; ++qt) o[qt][dt] = mfma16(cv.v, pb[qt][kk], o[qt][dt]);
;     }
;   }
;   __builtin_amdgcn_s_setprio(0);
	v_max_f32_e32 v215, v216, v215
	v_mov_b32_e32 v216, v215
	v_mov_b32_e32 v217, v215
	s_nop 1
	v_permlane32_swap_b32_e32 v216, v217
	v_max_f32_e32 v215, v216, v217
	v_max_f32_e32 v218, v183, v215
	v_sub_f32_e32 v219, v183, v218
	v_mul_f32_e32 v219, v200, v219
	v_exp_f32_e32 v219, v219
	v_mov_b32_e32 v183, v218
	v_max_f32_e32 v220, 0xe0ad78ec, v218
	v_mul_f32_e32 v220, 0xbe38aa3b, v220
	v_fma_f32 v96, v96, v200, v220
	v_exp_f32_e32 v96, v96
	v_fma_f32 v97, v97, v200, v220
	v_exp_f32_e32 v97, v97
	v_fma_f32 v98, v98, v200, v220
	v_exp_f32_e32 v98, v98
	v_fma_f32 v99, v99, v200, v220
	v_exp_f32_e32 v99, v99
	v_fma_f32 v100, v100, v200, v220
	v_exp_f32_e32 v100, v100
	v_fma_f32 v101, v101, v200, v220
	v_exp_f32_e32 v101, v101
	v_fma_f32 v102, v102, v200, v220
	v_exp_f32_e32 v102, v102
	v_fma_f32 v103, v103, v200, v220
	v_exp_f32_e32 v103, v103
	v_fma_f32 v104, v104, v200, v220
	v_exp_f32_e32 v104, v104
	v_fma_f32 v105, v105, v200, v220
	v_exp_f32_e32 v105, v105
	v_fma_f32 v106, v106, v200, v220
	v_exp_f32_e32 v106, v106
	v_fma_f32 v107, v107, v200, v220
	v_exp_f32_e32 v107, v107
	v_fma_f32 v108, v108, v200, v220
	v_exp_f32_e32 v108, v108
	v_fma_f32 v109, v109, v200, v220
	v_exp_f32_e32 v109, v109
	v_fma_f32 v110, v110, v200, v220
	v_exp_f32_e32 v110, v110
	v_fma_f32 v111, v111, v200, v220
	v_exp_f32_e32 v111, v111
	s_nop 0
	v_add_f32_e32 v221, v96, v97
	v_add_f32_e32 v221, v98, v221
	v_add_f32_e32 v221, v99, v221
	v_add_f32_e32 v221, v100, v221
	v_add_f32_e32 v221, v101, v221
	v_add_f32_e32 v221, v102, v221
	v_add_f32_e32 v221, v103, v221
	v_add_f32_e32 v221, v104, v221
	v_add_f32_e32 v221, v105, v221
	v_add_f32_e32 v221, v106, v221
	v_add_f32_e32 v221, v107, v221
	v_add_f32_e32 v221, v108, v221
	v_add_f32_e32 v221, v109, v221
	v_add_f32_e32 v221, v110, v221
	v_add_f32_e32 v221, v111, v221
	v_fma_f32 v185, v185, v219, v221
	v_mul_f32_e32 v32, v219, v32
	v_mul_f32_e32 v33, v219, v33
	v_mul_f32_e32 v34, v219, v34
	v_mul_f32_e32 v35, v219, v35
	v_mul_f32_e32 v36, v219, v36
	v_mul_f32_e32 v37, v219, v37
	v_mul_f32_e32 v38, v219, v38
	v_mul_f32_e32 v39, v219, v39
	v_mul_f32_e32 v40, v219, v40
	v_mul_f32_e32 v41, v219, v41
	v_mul_f32_e32 v42, v219, v42
	v_mul_f32_e32 v43, v219, v43
	v_mul_f32_e32 v44, v219, v44
	v_mul_f32_e32 v45, v219, v45
	v_mul_f32_e32 v46, v219, v46
	v_mul_f32_e32 v47, v219, v47
	v_cvt_pk_bf16_f32 v152, v96, v97
	v_cvt_pk_bf16_f32 v153, v98, v99
	v_cvt_pk_bf16_f32 v154, v100, v101
	v_cvt_pk_bf16_f32 v155, v102, v103
	v_cvt_pk_bf16_f32 v156, v104, v105
	v_cvt_pk_bf16_f32 v157, v106, v107
	v_cvt_pk_bf16_f32 v158, v108, v109
	v_cvt_pk_bf16_f32 v159, v110, v111
	ds_read_b64 v[112:113], v191 offset:18432
	ds_read_b64 v[114:115], v191 offset:18464
	ds_read_b64 v[116:117], v191 offset:18496
	ds_read_b64 v[118:119], v191 offset:18528
	s_waitcnt lgkmcnt(0)
	v_mfma_f32_16x16x32_bf16 v[16:19], v[112:115], v[144:147], v[16:19]
	v_mfma_f32_16x16x32_bf16 v[32:35], v[112:115], v[152:155], v[32:35]
	v_mfma_f32_16x16x32_bf16 v[16:19], v[116:119], v[148:151], v[16:19]
	v_mfma_f32_16x16x32_bf16 v[32:35], v[116:119], v[156:159], v[32:35]
	ds_read_b64 v[120:121], v191 offset:20736
	ds_read_b64 v[122:123], v191 offset:20768
	ds_read_b64 v[124:125], v191 offset:20800
	ds_read_b64 v[126:127], v191 offset:20832
	s_waitcnt lgkmcnt(0)
	v_mfma_f32_16x16x32_bf16 v[20:23], v[120:123], v[144:147], v[20:23]
	v_mfma_f32_16x16x32_bf16 v[36:39], v[120:123], v[152:155], v[36:39]
	v_mfma_f32_16x16x32_bf16 v[20:23], v[124:127], v[148:151], v[20:23]
	v_mfma_f32_16x16x32_bf16 v[36:39], v[124:127], v[156:159], v[36:39]
	ds_read_b64 v[128:129], v191 offset:23040
	ds_read_b64 v[130:131], v191 offset:23072
	ds_read_b64 v[132:133], v191 offset:23104
	ds_read_b64 v[134:135], v191 offset:23136
	s_waitcnt lgkmcnt(0)
	v_mfma_f32_16x16x32_bf16 v[24:27], v[128:131], v[144:147], v[24:27]
	v_mfma_f32_16x16x32_bf16 v[40:43], v[128:131], v[152:155], v[40:43]
	v_mfma_f32_16x16x32_bf16 v[24:27], v[132:135], v[148:151], v[24:27]
	v_mfma_f32_16x16x32_bf16 v[40:43], v[132:135], v[156:159], v[40:43]
	ds_read_b64 v[136:137], v191 offset:25344
	ds_read_b64 v[138:139], v191 offset:25376
	ds_read_b64 v[140:141], v191 offset:25408
	ds_read_b64 v[142:143], v191 offset:25440
	s_waitcnt lgkmcnt(0)
	v_mfma_f32_16x16x32_bf16 v[28:31], v[136:139], v[144:147], v[28:31]
	v_mfma_f32_16x16x32_bf16 v[44:47], v[136:139], v[152:155], v[44:47]
	v_mfma_f32_16x16x32_bf16 v[28:31], v[140:143], v[148:151], v[28:31]
	v_mfma_f32_16x16x32_bf16 v[44:47], v[140:143], v[156:159], v[44:47]
	s_branch .Lp4_sel_next0
; DEVI float fexp2(float x) { return __builtin_amdgcn_exp2f(x); }
; template <int DH, int NQ, int LDK, class MaskF>
; DEVI void attn_qk(const u16* sK, const bf16x8 (&qf)[NQ][DH / 32], f32x4 (&o)[NQ][DH / 16], float (&m)[NQ], float (&l)[NQ],
;                   float c2, int lane, MaskF valid, bf16x8 (&pb)[NQ][2]) {
;     ...
; #pragma unroll
;   for (int qt = 0; qt < NQ; ++qt) {
;     float mx = -1e30f;
; #pragma unroll
;     for (int kt = 0; kt < 4; ++kt)
; #pragma unroll
;       for (int r = 0; r < 4; ++r) {
;         const bool v = valid(qt, 16 * kt + 4 * quad + r);
;         const float sv = v ? s[qt][kt][r] : -1e30f;
;         s[qt][kt][r] = sv;
;         mx = fmaxf(mx, sv);
;       }
;     mx = fmaxf(mx, __shfl_xor(mx, 16));
;     mx = fmaxf(mx, __shfl_xor(mx, 32));
;     const float mn = fmaxf(m[qt], mx);
;     const float alpha = fexp2((m[qt] - mn) * c2);
;     m[qt] = mn;
;     const float mc = fmaxf(mn, -1e20f) * c2;
;     float ps = 0.f;
; #pragma unroll
;     for (int kt = 0; kt < 4; ++kt)
; #pragma unroll
;       for (int r = 0; r < 4; ++r) {
;         const float pv = fexp2(__builtin_fmaf(s[qt][kt][r], c2, -mc));
;         ps += pv;
;         s[qt][kt][r] = pv;
;       }
;     l[qt] = l[qt] * alpha + ps;
; #pragma unroll
;     for (int dt = 0; dt < DH / 16; ++dt) o[qt][dt] *= alpha;
; DEVI void phase_nsa(const Params& p, unsigned char* smem) {
;     ...
;         const int lim0 = ((sm[0] >> kb) & 1u) ? tq[0] : -1, lim1 = ((sm[1] >> kb) & 1u) ? tq[1] : -1;
;         attn_tile<64, 2, 72, 72>(sK, sVt, qf, o, m, l, c2, lane, [&](int qt, int kl) {
;           return (kb * 64 + kl) <= (qt ? lim1 : lim0);
;         });
.Lp4_sel_masked0:
	ds_read_b128 v[112:115], v190
	ds_read_b128 v[116:119], v190 offset:64
	s_waitcnt lgkmcnt(0)
	v_mfma_f32_16x16x32_bf16 v[80:83], v[112:115], v[0:3], 0
	v_mfma_f32_16x16x32_bf16 v[96:99], v[112:115], v[8:11], 0
	v_mfma_f32_16x16x32_bf16 v[80:83], v[116:119], v[4:7], v[80:83]
	v_mfma_f32_16x16x32_bf16 v[96:99], v[116:119], v[12:15], v[96:99]
	ds_read_b128 v[120:123], v190 offset:2304
	ds_read_b128 v[124:127], v190 offset:2368
	s_waitcnt lgkmcnt(0)
	v_mfma_f32_16x16x32_bf16 v[84:87], v[120:123], v[0:3], 0
	v_mfma_f32_16x16x32_bf16 v[100:103], v[120:123], v[8:11], 0
	v_mfma_f32_16x16x32_bf16 v[84:87], v[124:127], v[4:7], v[84:87]
	v_mfma_f32_16x16x32_bf16 v[100:103], v[124:127], v[12:15], v[100:103]
	ds_read_b128 v[128:131], v190 offset:4608
	ds_read_b128 v[132:135], v190 offset:4672
	s_waitcnt lgkmcnt(0)
	v_mfma_f32_16x16x32_bf16 v[88:91], v[128:131], v[0:3], 0
	v_mfma_f32_16x16x32_bf16 v[104:107], v[128:131], v[8:11], 0
	v_mfma_f32_16x16x32_bf16 v[88:91], v[132:135], v[4:7], v[88:91]
	v_mfma_f32_16x16x32_bf16 v[104:107], v[132:135], v[12:15], v[104:107]
	ds_read_b128 v[136:139], v190 offset:6912
	ds_read_b128 v[140:143], v190 offset:6976
	s_waitcnt lgkmcnt(0)
	v_mfma_f32_16x16x32_bf16 v[92:95], v[136:139], v[0:3], 0
	v_mfma_f32_16x16x32_bf16 v[108:111], v[136:139], v[8:11], 0
	v_mfma_f32_16x16x32_bf16 v[92:95], v[140:143], v[4:7], v[92:95]
	v_mfma_f32_16x16x32_bf16 v[108:111], v[140:143], v[12:15], v[108:111]
	s_nop 7
	v_subrev_u32_e32 v222, s30, v207
	v_subrev_u32_e32 v223, 0, v222
	v_cmp_ge_u32_e64 s[32:33], s41, v223
	v_subrev_u32_e32 v224, 1, v222
	v_cmp_ge_u32_e64 s[34:35], s41, v224
	v_subrev_u32_e32 v225, 2, v222
	v_cmp_ge_u32_e64 s[36:37], s41, v225
	v_subrev_u32_e32 v226, 3, v222
	v_cmp_ge_u32_e64 s[46:47], s41, v226
	v_cndmask_b32_e64 v80, v230, v80, s[32:33]
	v_cndmask_b32_e64 v81, v230, v81, s[34:35]
	v_cndmask_b32_e64 v82, v230, v82, s[36:37]
	v_cndmask_b32_e64 v83, v230, v83, s[46:47]
	v_subrev_u32_e32 v223, 16, v222
	v_cmp_ge_u32_e64 s[32:33], s41, v223
	v_subrev_u32_e32 v224, 17, v222
	v_cmp_ge_u32_e64 s[34:35], s41, v224
	v_subrev_u32_e32 v225, 18, v222
	v_cmp_ge_u32_e64 s[36:37], s41, v225
	v_subrev_u32_e32 v226, 19, v222
	v_cmp_ge_u32_e64 s[46:47], s41, v226
	v_cndmask_b32_e64 v84, v230, v84, s[32:33]
	v_cndmask_b32_e64 v85, v230, v85, s[34:35]
	v_cndmask_b32_e64 v86, v230, v86, s[36:37]
	v_cndmask_b32_e64 v87, v230, v87, s[46:47]
	v_subrev_u32_e32 v223, 32, v222
	v_cmp_ge_u32_e64 s[32:33], s41, v223
	v_subrev_u32_e32 v224, 33, v222
	v_cmp_ge_u32_e64 s[34:35], s41, v224
	v_subrev_u32_e32 v225, 34, v222
	v_cmp_ge_u32_e64 s[36:37], s41, v225
	v_subrev_u32_e32 v226, 35, v222
	v_cmp_ge_u32_e64 s[46:47], s41, v226
	v_cndmask_b32_e64 v88, v230, v88, s[32:33]
	v_cndmask_b32_e64 v89, v230, v89, s[34:35]
	v_cndmask_b32_e64 v90, v230, v90, s[36:37]
	v_cndmask_b32_e64 v91, v230, v91, s[46:47]
	v_subrev_u32_e32 v223, 48, v222
	v_cmp_ge_u32_e64 s[32:33], s41, v223
	v_subrev_u32_e32 v224, 49, v222
	v_cmp_ge_u32_e64 s[34:35], s41, v224
	v_subrev_u32_e32 v225, 50, v222
	v_cmp_ge_u32_e64 s[36:37], s41, v225
	v_subrev_u32_e32 v226, 51, v222
	v_cmp_ge_u32_e64 s[46:47], s41, v226
	v_cndmask_b32_e64 v92, v230, v92, s[32:33]
	v_cndmask_b32_e64 v93, v230, v93, s[34:35]
	v_cndmask_b32_e64 v94, v230, v94, s[36:37]
	v_cndmask_b32_e64 v95, v230, v95, s[46:47]
	v_max3_f32 v215, v80, v81, v82
	v_max3_f32 v215, v215, v83, v84
	v_max3_f32 v215, v215, v85, v86
	v_max3_f32 v215, v215, v87, v88
	v_max3_f32 v215, v215, v89, v90
	v_max3_f32 v215, v215, v91, v92
	v_max3_f32 v215, v215, v93, v94
	v_max_f32_e32 v215, v95, v215
	ds_bpermute_b32 v216, v195, v215
	s_waitcnt lgkmcnt(0)
	v_max_f32_e32 v215, v216, v215
	v_mov_b32_e32 v216, v215
	v_mov_b32_e32 v217, v215
	s_nop 1
	v_permlane32_swap_b32_e32 v216, v217
	v_max_f32_e32 v215, v216, v217
	v_max_f32_e32 v218, v182, v215
	v_sub_f32_e32 v219, v182, v218
	v_mul_f32_e32 v219, v200, v219
	v_exp_f32_e32 v219, v219
	v_mov_b32_e32 v182, v218
	v_max_f32_e32 v220, 0xe0ad78ec, v218
	v_mul_f32_e32 v220, 0xbe38aa3b, v220
	v_fma_f32 v80, v80, v200, v220
	v_exp_f32_e32 v80, v80
	v_fma_f32 v81, v81, v200, v220
	v_exp_f32_e32 v81, v81
	v_fma_f32 v82, v82, v200, v220
	v_exp_f32_e32 v82, v82
	v_fma_f32 v83, v83, v200, v220
	v_exp_f32_e32 v83, v83
	v_fma_f32 v84, v84, v200, v220
	v_exp_f32_e32 v84, v84
	v_fma_f32 v85, v85, v200, v220
	v_exp_f32_e32 v85, v85
	v_fma_f32 v86, v86, v200, v220
	v_exp_f32_e32 v86, v86
	v_fma_f32 v87, v87, v200, v220
	v_exp_f32_e32 v87, v87
	v_fma_f32 v88, v88, v200, v220
	v_exp_f32_e32 v88, v88
	v_fma_f32 v89, v89, v200, v220
	v_exp_f32_e32 v89, v89
	v_fma_f32 v90, v90, v200, v220
	v_exp_f32_e32 v90, v90
	v_fma_f32 v91, v91, v200, v220
	v_exp_f32_e32 v91, v91
	v_fma_f32 v92, v92, v200, v220
	v_exp_f32_e32 v92, v92
	v_fma_f32 v93, v93, v200, v220
	v_exp_f32_e32 v93, v93
	v_fma_f32 v94, v94, v200, v220
	v_exp_f32_e32 v94, v94
	v_fma_f32 v95, v95, v200, v220
	v_exp_f32_e32 v95, v95
	s_nop 0
	v_add_f32_e32 v221, v80, v81
	v_add_f32_e32 v221, v82, v221
	v_add_f32_e32 v221, v83, v221
	v_add_f32_e32 v221, v84, v221
	v_add_f32_e32 v221, v85, v221
	v_add_f32_e32 v221, v86, v221
	v_add_f32_e32 v221, v87, v221
	v_add_f32_e32 v221, v88, v221
	v_add_f32_e32 v221, v89, v221
	v_add_f32_e32 v221, v90, v221
	v_add_f32_e32 v221, v91, v221
	v_add_f32_e32 v221, v92, v221
	v_add_f32_e32 v221, v93, v221
	v_add_f32_e32 v221, v94, v221
	v_add_f32_e32 v221, v95, v221
	v_fma_f32 v184, v184, v219, v221
	v_mul_f32_e32 v16, v219, v16
	v_mul_f32_e32 v17, v219, v17
	v_mul_f32_e32 v18, v219, v18
	v_mul_f32_e32 v19, v219, v19
	v_mul_f32_e32 v20, v219, v20
	v_mul_f32_e32 v21, v219, v21
	v_mul_f32_e32 v22, v219, v22
; DEVI unsigned pack2(float a, float b) { return (unsigned)f2bf(a) | ((unsigned)f2bf(b) << 16); }
; DEVI float fexp2(float x) { return __builtin_amdgcn_exp2f(x); }
; template <int DH, int NQ, int LDK, class MaskF>
; DEVI void attn_qk(const u16* sK, const bf16x8 (&qf)[NQ][DH / 32], f32x4 (&o)[NQ][DH / 16], float (&m)[NQ], float (&l)[NQ],
;                   float c2, int lane, MaskF valid, bf16x8 (&pb)[NQ][2]) {
;     ...
; #pragma unroll
;   for (int qt = 0; qt < NQ; ++qt) {
;     float mx = -1e30f;
; #pragma unroll
;     for (int kt = 0; kt < 4; ++kt)
; #pragma unroll
;       for (int r = 0; r < 4; ++r) {
;         const bool v = valid(qt, 16 * kt + 4 * quad + r);
;         const float sv = v ? s[qt][kt][r] : -1e30f;
;         s[qt][kt][r] = sv;
;         mx = fmaxf(mx, sv);
;       }
;     mx = fmaxf(mx, __shfl_xor(mx, 16));
;     mx = fmaxf(mx, __shfl_xor(mx, 32));
;     const float mn = fmaxf(m[qt], mx);
;     const float alpha = fexp2((m[qt] - mn) * c2);
;     m[qt] = mn;
;     const float mc = fmaxf(mn, -1e20f) * c2;
;     float ps = 0.f;
; #pragma unroll
;     for (int kt = 0; kt < 4; ++kt)
; #pragma unroll
;       for (int r = 0; r < 4; ++r) {
;         const float pv = fexp2(__builtin_fmaf(s[qt][kt][r], c2, -mc));
;         ps += pv;
;         s[qt][kt][r] = pv;
;       }
;     l[qt] = l[qt] * alpha + ps;
; #pragma unroll
;     for (int dt = 0; dt < DH / 16; ++dt) o[qt][dt] *= alpha;
; #pragma unroll
;     for (int kk = 0; kk < 2; ++kk) {
;       union { bf16x8 v; unsigned u[4]; } cv;
;       cv.u[0] = pack2(s[qt][2 * kk][0], s[qt][2 * kk][1]);
;       cv.u[1] = pack2(s[qt][2 * kk][2], s[qt][2 * kk][3]);
;       cv.u[2] = pack2(s[qt][2 * kk + 1][0], s[qt][2 * kk + 1][1]);
;       cv.u[3] = pack2(s[qt][2 * kk + 1][2], s[qt][2 * kk + 1][3]);
;       pb[qt][kk] = cv.v;
;     }
;   }
	v_mul_f32_e32 v23, v219, v23
	v_mul_f32_e32 v24, v219, v24
	v_mul_f32_e32 v25, v219, v25
	v_mul_f32_e32 v26, v219, v26
	v_mul_f32_e32 v27, v219, v27
	v_mul_f32_e32 v28, v219, v28
	v_mul_f32_e32 v29, v219, v29
	v_mul_f32_e32 v30, v219, v30
	v_mul_f32_e32 v31, v219, v31
	v_cvt_pk_bf16_f32 v144, v80, v81
	v_cvt_pk_bf16_f32 v145, v82, v83
	v_cvt_pk_bf16_f32 v146, v84, v85
	v_cvt_pk_bf16_f32 v147, v86, v87
	v_cvt_pk_bf16_f32 v148, v88, v89
	v_cvt_pk_bf16_f32 v149, v90, v91
	v_cvt_pk_bf16_f32 v150, v92, v93
	v_cvt_pk_bf16_f32 v151, v94, v95
	v_subrev_u32_e32 v222, s30, v208
	v_subrev_u32_e32 v223, 0, v222
	v_cmp_ge_u32_e64 s[32:33], s41, v223
	v_subrev_u32_e32 v224, 1, v222
	v_cmp_ge_u32_e64 s[34:35], s41, v224
	v_subrev_u32_e32 v225, 2, v222
	v_cmp_ge_u32_e64 s[36:37], s41, v225
	v_subrev_u32_e32 v226, 3, v222
	v_cmp_ge_u32_e64 s[46:47], s41, v226
	v_cndmask_b32_e64 v96, v230, v96, s[32:33]
	v_cndmask_b32_e64 v97, v230, v97, s[34:35]
	v_cndmask_b32_e64 v98, v230, v98, s[36:37]
	v_cndmask_b32_e64 v99, v230, v99, s[46:47]
	v_subrev_u32_e32 v223, 16, v222
	v_cmp_ge_u32_e64 s[32:33], s41, v223
	v_subrev_u32_e32 v224, 17, v222
	v_cmp_ge_u32_e64 s[34:35], s41, v224
	v_subrev_u32_e32 v225, 18, v222
	v_cmp_ge_u32_e64 s[36:37], s41, v225
	v_subrev_u32_e32 v226, 19, v222
	v_cmp_ge_u32_e64 s[46:47], s41, v226
	v_cndmask_b32_e64 v100, v230, v100, s[32:33]
	v_cndmask_b32_e64 v101, v230, v101, s[34:35]
	v_cndmask_b32_e64 v102, v230, v102, s[36:37]
	v_cndmask_b32_e64 v103, v230, v103, s[46:47]
	v_subrev_u32_e32 v223, 32, v222
	v_cmp_ge_u32_e64 s[32:33], s41, v223
	v_subrev_u32_e32 v224, 33, v222
	v_cmp_ge_u32_e64 s[34:35], s41, v224
	v_subrev_u32_e32 v225, 34, v222
	v_cmp_ge_u32_e64 s[36:37], s41, v225
	v_subrev_u32_e32 v226, 35, v222
	v_cmp_ge_u32_e64 s[46:47], s41, v226
	v_cndmask_b32_e64 v104, v230, v104, s[32:33]
	v_cndmask_b32_e64 v105, v230, v105, s[34:35]
	v_cndmask_b32_e64 v106, v230, v106, s[36:37]
	v_cndmask_b32_e64 v107, v230, v107, s[46:47]
	v_subrev_u32_e32 v223, 48, v222
	v_cmp_ge_u32_e64 s[32:33], s41, v223
	v_subrev_u32_e32 v224, 49, v222
	v_cmp_ge_u32_e64 s[34:35], s41, v224
	v_subrev_u32_e32 v225, 50, v222
	v_cmp_ge_u32_e64 s[36:37], s41, v225
	v_subrev_u32_e32 v226, 51, v222
	v_cmp_ge_u32_e64 s[46:47], s41, v226
	v_cndmask_b32_e64 v108, v230, v108, s[32:33]
	v_cndmask_b32_e64 v109, v230, v109, s[34:35]
	v_cndmask_b32_e64 v110, v230, v110, s[36:37]
	v_cndmask_b32_e64 v111, v230, v111, s[46:47]
	v_max3_f32 v215, v96, v97, v98
	v_max3_f32 v215, v215, v99, v100
	v_max3_f32 v215, v215, v101, v102
	v_max3_f32 v215, v215, v103, v104
	v_max3_f32 v215, v215, v105, v106
	v_max3_f32 v215, v215, v107, v108
	v_max3_f32 v215, v215, v109, v110
	v_max_f32_e32 v215, v111, v215
	ds_bpermute_b32 v216, v195, v215
	s_waitcnt lgkmcnt(0)
	v_max_f32_e32 v215, v216, v215
	v_mov_b32_e32 v216, v215
	v_mov_b32_e32 v217, v215
	s_nop 1
	v_permlane32_swap_b32_e32 v216, v217
	v_max_f32_e32 v215, v216, v217
	v_max_f32_e32 v218, v183, v215
	v_sub_f32_e32 v219, v183, v218
	v_mul_f32_e32 v219, v200, v219
	v_exp_f32_e32 v219, v219
	v_mov_b32_e32 v183, v218
	v_max_f32_e32 v220, 0xe0ad78ec, v218
	v_mul_f32_e32 v220, 0xbe38aa3b, v220
	v_fma_f32 v96, v96, v200, v220
	v_exp_f32_e32 v96, v96
	v_fma_f32 v97, v97, v200, v220
	v_exp_f32_e32 v97, v97
	v_fma_f32 v98, v98, v200, v220
	v_exp_f32_e32 v98, v98
	v_fma_f32 v99, v99, v200, v220
	v_exp_f32_e32 v99, v99
	v_fma_f32 v100, v100, v200, v220
	v_exp_f32_e32 v100, v100
	v_fma_f32 v101, v101, v200, v220
	v_exp_f32_e32 v101, v101
	v_fma_f32 v102, v102, v200, v220
	v_exp_f32_e32 v102, v102
	v_fma_f32 v103, v103, v200, v220
	v_exp_f32_e32 v103, v103
	v_fma_f32 v104, v104, v200, v220
	v_exp_f32_e32 v104, v104
	v_fma_f32 v105, v105, v200, v220
	v_exp_f32_e32 v105, v105
	v_fma_f32 v106, v106, v200, v220
	v_exp_f32_e32 v106, v106
	v_fma_f32 v107, v107, v200, v220
	v_exp_f32_e32 v107, v107
	v_fma_f32 v108, v108, v200, v220
	v_exp_f32_e32 v108, v108
	v_fma_f32 v109, v109, v200, v220
	v_exp_f32_e32 v109, v109
	v_fma_f32 v110, v110, v200, v220
	v_exp_f32_e32 v110, v110
	v_fma_f32 v111, v111, v200, v220
	v_exp_f32_e32 v111, v111
	s_nop 0
	v_add_f32_e32 v221, v96, v97
	v_add_f32_e32 v221, v98, v221
	v_add_f32_e32 v221, v99, v221
	v_add_f32_e32 v221, v100, v221
	v_add_f32_e32 v221, v101, v221
	v_add_f32_e32 v221, v102, v221
	v_add_f32_e32 v221, v103, v221
	v_add_f32_e32 v221, v104, v221
	v_add_f32_e32 v221, v105, v221
	v_add_f32_e32 v221, v106, v221
	v_add_f32_e32 v221, v107, v221
	v_add_f32_e32 v221, v108, v221
	v_add_f32_e32 v221, v109, v221
	v_add_f32_e32 v221, v110, v221
	v_add_f32_e32 v221, v111, v221
	v_fma_f32 v185, v185, v219, v221
	v_mul_f32_e32 v32, v219, v32
	v_mul_f32_e32 v33, v219, v33
	v_mul_f32_e32 v34, v219, v34
	v_mul_f32_e32 v35, v219, v35
	v_mul_f32_e32 v36, v219, v36
	v_mul_f32_e32 v37, v219, v37
	v_mul_f32_e32 v38, v219, v38
	v_mul_f32_e32 v39, v219, v39
	v_mul_f32_e32 v40, v219, v40
	v_mul_f32_e32 v41, v219, v41
	v_mul_f32_e32 v42, v219, v42
	v_mul_f32_e32 v43, v219, v43
	v_mul_f32_e32 v44, v219, v44
	v_mul_f32_e32 v45, v219, v45
	v_mul_f32_e32 v46, v219, v46
	v_mul_f32_e32 v47, v219, v47
	v_cvt_pk_bf16_f32 v152, v96, v97
	v_cvt_pk_bf16_f32 v153, v98, v99
	v_cvt_pk_bf16_f32 v154, v100, v101
	v_cvt_pk_bf16_f32 v155, v102, v103
	v_cvt_pk_bf16_f32 v156, v104, v105
	v_cvt_pk_bf16_f32 v157, v106, v107
	v_cvt_pk_bf16_f32 v158, v108, v109
	v_cvt_pk_bf16_f32 v159, v110, v111
	ds_read_b64 v[112:113], v191 offset:18432
	ds_read_b64 v[114:115], v191 offset:18464
	ds_read_b64 v[116:117], v191 offset:18496
	ds_read_b64 v[118:119], v191 offset:18528
	s_waitcnt lgkmcnt(0)
; DEVI f32x4 mfma16(bf16x8 a, bf16x8 b, f32x4 c) { return __builtin_amdgcn_mfma_f32_16x16x32_bf16(a, b, c, 0, 0, 0); }
; template <int DH, int NQ, int LDV>
; DEVI void attn_pv(const u16* sVt, const bf16x8 (&pb)[NQ][2], f32x4 (&o)[NQ][DH / 16], int lane) {
;   const int col = lane & 15, quad = lane >> 4;
;   __builtin_amdgcn_s_setprio(1);
; #pragma unroll
;   for (int dt = 0; dt < DH / 16; ++dt) {
; #pragma unroll
;     for (int kk = 0; kk < 2; ++kk) {
;       union { bf16x8 v; uint2 h[2]; } cv;
;       cv.h[0] = *(const uint2*)(sVt + (16 * dt + col) * LDV + 32 * kk + 4 * quad);
;       cv.h[1] = *(const uint2*)(sVt + (16 * dt + col) * LDV + 32 * kk + 16 + 4 * quad);
; #pragma unroll
;       for (int qt = 0; qt < NQ; ++qt) o[qt][dt] = mfma16(cv.v, pb[qt][kk], o[qt][dt]);
;     }
;   }
;   __builtin_amdgcn_s_setprio(0);
; DEVI void phase_nsa(const Params& p, unsigned char* smem) {
;     ...
; #pragma unroll 1
;       while (kb >= 0) {
;         rem &= rem - 1u;
;         const int nkb = rem ? (__ffs((int)rem) - 1) : -1;
;         __syncthreads();
;         STOREKV_()
;         if (nkb >= 0) { LOADKV_(nkb, C_KS, p.vts) }
;         __syncthreads();
;         const int lim0 = ((sm[0] >> kb) & 1u) ? tq[0] : -1, lim1 = ((sm[1] >> kb) & 1u) ? tq[1] : -1;
;         attn_tile<64, 2, 72, 72>(sK, sVt, qf, o, m, l, c2, lane, [&](int qt, int kl) {
;           return (kb * 64 + kl) <= (qt ? lim1 : lim0);
;         });
	v_mfma_f32_16x16x32_bf16 v[16:19], v[112:115], v[144:147], v[16:19]
	v_mfma_f32_16x16x32_bf16 v[32:35], v[112:115], v[152:155], v[32:35]
	v_mfma_f32_16x16x32_bf16 v[16:19], v[116:119], v[148:151], v[16:19]
	v_mfma_f32_16x16x32_bf16 v[32:35], v[116:119], v[156:159], v[32:35]
	ds_read_b64 v[120:121], v191 offset:20736
	ds_read_b64 v[122:123], v191 offset:20768
	ds_read_b64 v[124:125], v191 offset:20800
	ds_read_b64 v[126:127], v191 offset:20832
	s_waitcnt lgkmcnt(0)
	v_mfma_f32_16x16x32_bf16 v[20:23], v[120:123], v[144:147], v[20:23]
	v_mfma_f32_16x16x32_bf16 v[36:39], v[120:123], v[152:155], v[36:39]
	v_mfma_f32_16x16x32_bf16 v[20:23], v[124:127], v[148:151], v[20:23]
	v_mfma_f32_16x16x32_bf16 v[36:39], v[124:127], v[156:159], v[36:39]
	ds_read_b64 v[128:129], v191 offset:23040
	ds_read_b64 v[130:131], v191 offset:23072
	ds_read_b64 v[132:133], v191 offset:23104
	ds_read_b64 v[134:135], v191 offset:23136
	s_waitcnt lgkmcnt(0)
	v_mfma_f32_16x16x32_bf16 v[24:27], v[128:131], v[144:147], v[24:27]
	v_mfma_f32_16x16x32_bf16 v[40:43], v[128:131], v[152:155], v[40:43]
	v_mfma_f32_16x16x32_bf16 v[24:27], v[132:135], v[148:151], v[24:27]
	v_mfma_f32_16x16x32_bf16 v[40:43], v[132:135], v[156:159], v[40:43]
	ds_read_b64 v[136:137], v191 offset:25344
	ds_read_b64 v[138:139], v191 offset:25376
	ds_read_b64 v[140:141], v191 offset:25408
	ds_read_b64 v[142:143], v191 offset:25440
	s_waitcnt lgkmcnt(0)
	v_mfma_f32_16x16x32_bf16 v[28:31], v[136:139], v[144:147], v[28:31]
	v_mfma_f32_16x16x32_bf16 v[44:47], v[136:139], v[152:155], v[44:47]
	v_mfma_f32_16x16x32_bf16 v[28:31], v[140:143], v[148:151], v[28:31]
	v_mfma_f32_16x16x32_bf16 v[44:47], v[140:143], v[156:159], v[44:47]
.Lp4_sel_next0:
	s_mov_b32 s26, s27
	s_cmp_lt_i32 s26, 0
	s_cbranch_scc1 .Lp4_sel_end
.Lp4_sel_buf1:
	s_waitcnt vmcnt(0)
	ds_write_b128 v193, v[160:163] offset:9216
	ds_write_b128 v193, v[164:167] offset:13824
	ds_write_b128 v193, v[168:171] offset:27648
	ds_write_b128 v193, v[172:175] offset:32256
	s_ff1_i32_b32 s27, s25
	s_add_u32 s22, s25, -1
	s_and_b32 s25, s25, s22
	s_cmp_lt_i32 s27, 0
	s_cbranch_scc1 .Lp4_sel_nold1
	s_lshl_b32 s22, s16, 11
	s_lshl_b32 s23, s27, 6
	s_add_u32 s22, s22, s23
	s_mul_i32 s22, s22, 0x1240
	s_add_u32 s22, s22, s31
	v_add_u32_e32 v211, s22, v201
	v_add_u32_e32 v212, s22, v202
	global_load_dwordx4 v[160:163], v211, s[0:1]
	global_load_dwordx4 v[164:167], v212, s[0:1]
	s_mul_i32 s22, s18, 0x42000
	s_lshl_b32 s23, s27, 7
	s_add_u32 s22, s22, s23
	v_add_u32_e32 v213, s22, v203
	v_add_u32_e32 v214, s22, v204
	global_load_dwordx4 v[168:171], v213, s[42:43]
	global_load_dwordx4 v[172:175], v214, s[42:43]
.Lp4_sel_nold1:
	s_waitcnt lgkmcnt(0)
	s_barrier
	s_lshl_b32 s30, s26, 6
	v_lshrrev_b32_e32 v215, s26, v188
	v_and_b32_e32 v215, 1, v215
	v_cmp_eq_u32_e64 s[32:33], 1, v215
	v_mov_b32_e32 v216, -1
	s_nop 0
	v_cndmask_b32_e64 v207, v216, v186, s[32:33]
	v_lshlrev_b32_e32 v217, 2, v198
	v_sub_u32_e32 v207, v207, v217
	v_lshrrev_b32_e32 v215, s26, v189
	v_and_b32_e32 v215, 1, v215
	v_cmp_eq_u32_e64 s[32:33], 1, v215
	v_mov_b32_e32 v216, -1
	s_nop 0
	v_cndmask_b32_e64 v208, v216, v187, s[32:33]
	v_lshlrev_b32_e32 v217, 2, v198
	v_sub_u32_e32 v208, v208, v217
	s_lshr_b32 s22, s29, s26
	s_and_b32 s22, s22, 1
	s_add_u32 s23, s30, 63
	s_cmp_le_u32 s23, s19
	s_cselect_b32 s24, s22, 0
	s_cmp_eq_u32 s24, 0
	s_cbranch_scc1 .Lp4_sel_masked1
	ds_read_b128 v[112:115], v190 offset:9216
	ds_read_b128 v[116:119], v190 offset:9280
	s_waitcnt lgkmcnt(0)
	v_mfma_f32_16x16x32_bf16 v[80:83], v[112:115], v[0:3], 0
	v_mfma_f32_16x16x32_bf16 v[96:99], v[112:115], v[8:11], 0
	v_mfma_f32_16x16x32_bf16 v[80:83], v[116:119], v[4:7], v[80:83]
	v_mfma_f32_16x16x32_bf16 v[96:99], v[116:119], v[12:15], v[96:99]
	ds_read_b128 v[120:123], v190 offset:11520
	ds_read_b128 v[124:127], v190 offset:11584
	s_waitcnt lgkmcnt(0)
	v_mfma_f32_16x16x32_bf16 v[84:87], v[120:123], v[0:3], 0
	v_mfma_f32_16x16x32_bf16 v[100:103], v[120:123], v[8:11], 0
	v_mfma_f32_16x16x32_bf16 v[84:87], v[124:127], v[4:7], v[84:87]
	v_mfma_f32_16x16x32_bf16 v[100:103], v[124:127], v[12:15], v[100:103]
	ds_read_b128 v[128:131], v190 offset:13824
	ds_read_b128 v[132:135], v190 offset:13888
	s_waitcnt lgkmcnt(0)
	v_mfma_f32_16x16x32_bf16 v[88:91], v[128:131], v[0:3], 0
	v_mfma_f32_16x16x32_bf16 v[104:107], v[128:131], v[8:11], 0
	v_mfma_f32_16x16x32_bf16 v[88:91], v[132:135], v[4:7], v[88:91]
	v_mfma_f32_16x16x32_bf16 v[104:107], v[132:135], v[12:15], v[104:107]
	ds_read_b128 v[136:139], v190 offset:16128
	ds_read_b128 v[140:143], v190 offset:16192
	s_waitcnt lgkmcnt(0)
	v_mfma_f32_16x16x32_bf16 v[92:95], v[136:139], v[0:3], 0
	v_mfma_f32_16x16x32_bf16 v[108:111], v[136:139], v[8:11], 0
	v_mfma_f32_16x16x32_bf16 v[92:95], v[140:143], v[4:7], v[92:95]
	v_mfma_f32_16x16x32_bf16 v[108:111], v[140:143], v[12:15], v[108:111]
	s_nop 7
	v_max3_f32 v215, v80, v81, v82
	v_max3_f32 v215, v215, v83, v84
	v_max3_f32 v215, v215, v85, v86
	v_max3_f32 v215, v215, v87, v88
	v_max3_f32 v215, v215, v89, v90
	v_max3_f32 v215, v215, v91, v92
	v_max3_f32 v215, v215, v93, v94
	v_max_f32_e32 v215, v95, v215
	ds_bpermute_b32 v216, v195, v215
	s_waitcnt lgkmcnt(0)
; DEVI unsigned pack2(float a, float b) { return (unsigned)f2bf(a) | ((unsigned)f2bf(b) << 16); }
; DEVI float fexp2(float x) { return __builtin_amdgcn_exp2f(x); }
; template <int DH, int NQ, int LDK, class MaskF>
; DEVI void attn_qk(const u16* sK, const bf16x8 (&qf)[NQ][DH / 32], f32x4 (&o)[NQ][DH / 16], float (&m)[NQ], float (&l)[NQ],
;                   float c2, int lane, MaskF valid, bf16x8 (&pb)[NQ][2]) {
;     ...
; #pragma unroll
;   for (int qt = 0; qt < NQ; ++qt) {
;     float mx = -1e30f;
; #pragma unroll
;     for (int kt = 0; kt < 4; ++kt)
; #pragma unroll
;       for (int r = 0; r < 4; ++r) {
;         const bool v = valid(qt, 16 * kt + 4 * quad + r);
;         const float sv = v ? s[qt][kt][r] : -1e30f;
;         s[qt][kt][r] = sv;
;         mx = fmaxf(mx, sv);
;       }
;     mx = fmaxf(mx, __shfl_xor(mx, 16));
;     mx = fmaxf(mx, __shfl_xor(mx, 32));
;     const float mn = fmaxf(m[qt], mx);
;     const float alpha = fexp2((m[qt] - mn) * c2);
;     m[qt] = mn;
;     const float mc = fmaxf(mn, -1e20f) * c2;
;     float ps = 0.f;
; #pragma unroll
;     for (int kt = 0; kt < 4; ++kt)
; #pragma unroll
;       for (int r = 0; r < 4; ++r) {
;         const float pv = fexp2(__builtin_fmaf(s[qt][kt][r], c2, -mc));
;         ps += pv;
;         s[qt][kt][r] = pv;
;       }
;     l[qt] = l[qt] * alpha + ps;
; #pragma unroll
;     for (int dt = 0; dt < DH / 16; ++dt) o[qt][dt] *= alpha;
; #pragma unroll
;     for (int kk = 0; kk < 2; ++kk) {
;       union { bf16x8 v; unsigned u[4]; } cv;
;       cv.u[0] = pack2(s[qt][2 * kk][0], s[qt][2 * kk][1]);
;       cv.u[1] = pack2(s[qt][2 * kk][2], s[qt][2 * kk][3]);
;       cv.u[2] = pack2(s[qt][2 * kk + 1][0], s[qt][2 * kk + 1][1]);
;       cv.u[3] = pack2(s[qt][2 * kk + 1][2], s[qt][2 * kk + 1][3]);
;       pb[qt][kk] = cv.v;
;     }
;   }
	v_max_f32_e32 v215, v216, v215
	v_mov_b32_e32 v216, v215
	v_mov_b32_e32 v217, v215
	s_nop 1
	v_permlane32_swap_b32_e32 v216, v217
	v_max_f32_e32 v215, v216, v217
	v_max_f32_e32 v218, v182, v215
	v_sub_f32_e32 v219, v182, v218
	v_mul_f32_e32 v219, v200, v219
	v_exp_f32_e32 v219, v219
	v_mov_b32_e32 v182, v218
	v_max_f32_e32 v220, 0xe0ad78ec, v218
	v_mul_f32_e32 v220, 0xbe38aa3b, v220
	v_fma_f32 v80, v80, v200, v220
	v_exp_f32_e32 v80, v80
	v_fma_f32 v81, v81, v200, v220
	v_exp_f32_e32 v81, v81
	v_fma_f32 v82, v82, v200, v220
	v_exp_f32_e32 v82, v82
	v_fma_f32 v83, v83, v200, v220
	v_exp_f32_e32 v83, v83
	v_fma_f32 v84, v84, v200, v220
	v_exp_f32_e32 v84, v84
	v_fma_f32 v85, v85, v200, v220
	v_exp_f32_e32 v85, v85
	v_fma_f32 v86, v86, v200, v220
	v_exp_f32_e32 v86, v86
	v_fma_f32 v87, v87, v200, v220
	v_exp_f32_e32 v87, v87
	v_fma_f32 v88, v88, v200, v220
	v_exp_f32_e32 v88, v88
	v_fma_f32 v89, v89, v200, v220
	v_exp_f32_e32 v89, v89
	v_fma_f32 v90, v90, v200, v220
	v_exp_f32_e32 v90, v90
	v_fma_f32 v91, v91, v200, v220
	v_exp_f32_e32 v91, v91
	v_fma_f32 v92, v92, v200, v220
	v_exp_f32_e32 v92, v92
	v_fma_f32 v93, v93, v200, v220
	v_exp_f32_e32 v93, v93
	v_fma_f32 v94, v94, v200, v220
	v_exp_f32_e32 v94, v94
	v_fma_f32 v95, v95, v200, v220
	v_exp_f32_e32 v95, v95
	s_nop 0
	v_add_f32_e32 v221, v80, v81
	v_add_f32_e32 v221, v82, v221
	v_add_f32_e32 v221, v83, v221
	v_add_f32_e32 v221, v84, v221
	v_add_f32_e32 v221, v85, v221
	v_add_f32_e32 v221, v86, v221
	v_add_f32_e32 v221, v87, v221
	v_add_f32_e32 v221, v88, v221
	v_add_f32_e32 v221, v89, v221
	v_add_f32_e32 v221, v90, v221
	v_add_f32_e32 v221, v91, v221
	v_add_f32_e32 v221, v92, v221
	v_add_f32_e32 v221, v93, v221
	v_add_f32_e32 v221, v94, v221
	v_add_f32_e32 v221, v95, v221
	v_fma_f32 v184, v184, v219, v221
	v_mul_f32_e32 v16, v219, v16
	v_mul_f32_e32 v17, v219, v17
	v_mul_f32_e32 v18, v219, v18
	v_mul_f32_e32 v19, v219, v19
	v_mul_f32_e32 v20, v219, v20
	v_mul_f32_e32 v21, v219, v21
	v_mul_f32_e32 v22, v219, v22
	v_mul_f32_e32 v23, v219, v23
	v_mul_f32_e32 v24, v219, v24
	v_mul_f32_e32 v25, v219, v25
	v_mul_f32_e32 v26, v219, v26
	v_mul_f32_e32 v27, v219, v27
	v_mul_f32_e32 v28, v219, v28
	v_mul_f32_e32 v29, v219, v29
	v_mul_f32_e32 v30, v219, v30
	v_mul_f32_e32 v31, v219, v31
	v_cvt_pk_bf16_f32 v144, v80, v81
	v_cvt_pk_bf16_f32 v145, v82, v83
	v_cvt_pk_bf16_f32 v146, v84, v85
	v_cvt_pk_bf16_f32 v147, v86, v87
	v_cvt_pk_bf16_f32 v148, v88, v89
	v_cvt_pk_bf16_f32 v149, v90, v91
	v_cvt_pk_bf16_f32 v150, v92, v93
	v_cvt_pk_bf16_f32 v151, v94, v95
	v_max3_f32 v215, v96, v97, v98
	v_max3_f32 v215, v215, v99, v100
	v_max3_f32 v215, v215, v101, v102
	v_max3_f32 v215, v215, v103, v104
	v_max3_f32 v215, v215, v105, v106
	v_max3_f32 v215, v215, v107, v108
	v_max3_f32 v215, v215, v109, v110
	v_max_f32_e32 v215, v111, v215
	ds_bpermute_b32 v216, v195, v215
	s_waitcnt lgkmcnt(0)
	v_max_f32_e32 v215, v216, v215
	v_mov_b32_e32 v216, v215
	v_mov_b32_e32 v217, v215
	s_nop 1
	v_permlane32_swap_b32_e32 v216, v217
	v_max_f32_e32 v215, v216, v217
	v_max_f32_e32 v218, v183, v215
	v_sub_f32_e32 v219, v183, v218
	v_mul_f32_e32 v219, v200, v219
	v_exp_f32_e32 v219, v219
	v_mov_b32_e32 v183, v218
	v_max_f32_e32 v220, 0xe0ad78ec, v218
	v_mul_f32_e32 v220, 0xbe38aa3b, v220
	v_fma_f32 v96, v96, v200, v220
	v_exp_f32_e32 v96, v96
	v_fma_f32 v97, v97, v200, v220
	v_exp_f32_e32 v97, v97
	v_fma_f32 v98, v98, v200, v220
	v_exp_f32_e32 v98, v98
	v_fma_f32 v99, v99, v200, v220
	v_exp_f32_e32 v99, v99
	v_fma_f32 v100, v100, v200, v220
	v_exp_f32_e32 v100, v100
	v_fma_f32 v101, v101, v200, v220
	v_exp_f32_e32 v101, v101
	v_fma_f32 v102, v102, v200, v220
	v_exp_f32_e32 v102, v102
	v_fma_f32 v103, v103, v200, v220
	v_exp_f32_e32 v103, v103
	v_fma_f32 v104, v104, v200, v220
	v_exp_f32_e32 v104, v104
	v_fma_f32 v105, v105, v200, v220
	v_exp_f32_e32 v105, v105
	v_fma_f32 v106, v106, v200, v220
	v_exp_f32_e32 v106, v106
	v_fma_f32 v107, v107, v200, v220
	v_exp_f32_e32 v107, v107
	v_fma_f32 v108, v108, v200, v220
	v_exp_f32_e32 v108, v108
	v_fma_f32 v109, v109, v200, v220
	v_exp_f32_e32 v109, v109
	v_fma_f32 v110, v110, v200, v220
	v_exp_f32_e32 v110, v110
	v_fma_f32 v111, v111, v200, v220
	v_exp_f32_e32 v111, v111
	s_nop 0
	v_add_f32_e32 v221, v96, v97
	v_add_f32_e32 v221, v98, v221
	v_add_f32_e32 v221, v99, v221
	v_add_f32_e32 v221, v100, v221
	v_add_f32_e32 v221, v101, v221
	v_add_f32_e32 v221, v102, v221
	v_add_f32_e32 v221, v103, v221
	v_add_f32_e32 v221, v104, v221
	v_add_f32_e32 v221, v105, v221
	v_add_f32_e32 v221, v106, v221
	v_add_f32_e32 v221, v107, v221
	v_add_f32_e32 v221, v108, v221
	v_add_f32_e32 v221, v109, v221
	v_add_f32_e32 v221, v110, v221
	v_add_f32_e32 v221, v111, v221
	v_fma_f32 v185, v185, v219, v221
	v_mul_f32_e32 v32, v219, v32
	v_mul_f32_e32 v33, v219, v33
	v_mul_f32_e32 v34, v219, v34
	v_mul_f32_e32 v35, v219, v35
	v_mul_f32_e32 v36, v219, v36
	v_mul_f32_e32 v37, v219, v37
	v_mul_f32_e32 v38, v219, v38
	v_mul_f32_e32 v39, v219, v39
	v_mul_f32_e32 v40, v219, v40
	v_mul_f32_e32 v41, v219, v41
	v_mul_f32_e32 v42, v219, v42
	v_mul_f32_e32 v43, v219, v43
	v_mul_f32_e32 v44, v219, v44
	v_mul_f32_e32 v45, v219, v45
	v_mul_f32_e32 v46, v219, v46
	v_mul_f32_e32 v47, v219, v47
	v_cvt_pk_bf16_f32 v152, v96, v97
	v_cvt_pk_bf16_f32 v153, v98, v99
	v_cvt_pk_bf16_f32 v154, v100, v101
	v_cvt_pk_bf16_f32 v155, v102, v103
	v_cvt_pk_bf16_f32 v156, v104, v105
	v_cvt_pk_bf16_f32 v157, v106, v107
	v_cvt_pk_bf16_f32 v158, v108, v109
	v_cvt_pk_bf16_f32 v159, v110, v111
	ds_read_b64 v[112:113], v191 offset:27648
	ds_read_b64 v[114:115], v191 offset:27680
	ds_read_b64 v[116:117], v191 offset:27712
	ds_read_b64 v[118:119], v191 offset:27744
	s_waitcnt lgkmcnt(0)
; DEVI f32x4 mfma16(bf16x8 a, bf16x8 b, f32x4 c) { return __builtin_amdgcn_mfma_f32_16x16x32_bf16(a, b, c, 0, 0, 0); }
; template <int DH, int NQ, int LDK, class MaskF>
; DEVI void attn_qk(const u16* sK, const bf16x8 (&qf)[NQ][DH / 32], f32x4 (&o)[NQ][DH / 16], float (&m)[NQ], float (&l)[NQ],
;                   float c2, int lane, MaskF valid, bf16x8 (&pb)[NQ][2]) {
;     ...
; #pragma unroll
;   for (int qt = 0; qt < NQ; ++qt) {
;     float mx = -1e30f;
; #pragma unroll
;     for (int kt = 0; kt < 4; ++kt)
; #pragma unroll
;       for (int r = 0; r < 4; ++r) {
;         const bool v = valid(qt, 16 * kt + 4 * quad + r);
;         const float sv = v ? s[qt][kt][r] : -1e30f;
;         s[qt][kt][r] = sv;
;         mx = fmaxf(mx, sv);
;       }
; template <int DH, int NQ, int LDV>
; DEVI void attn_pv(const u16* sVt, const bf16x8 (&pb)[NQ][2], f32x4 (&o)[NQ][DH / 16], int lane) {
;   const int col = lane & 15, quad = lane >> 4;
;   __builtin_amdgcn_s_setprio(1);
; #pragma unroll
;   for (int dt = 0; dt < DH / 16; ++dt) {
; #pragma unroll
;     for (int kk = 0; kk < 2; ++kk) {
;       union { bf16x8 v; uint2 h[2]; } cv;
;       cv.h[0] = *(const uint2*)(sVt + (16 * dt + col) * LDV + 32 * kk + 4 * quad);
;       cv.h[1] = *(const uint2*)(sVt + (16 * dt + col) * LDV + 32 * kk + 16 + 4 * quad);
; #pragma unroll
;       for (int qt = 0; qt < NQ; ++qt) o[qt][dt] = mfma16(cv.v, pb[qt][kk], o[qt][dt]);
;     }
;   }
;   __builtin_amdgcn_s_setprio(0);
	v_mfma_f32_16x16x32_bf16 v[16:19], v[112:115], v[144:147], v[16:19]
	v_mfma_f32_16x16x32_bf16 v[32:35], v[112:115], v[152:155], v[32:35]
	v_mfma_f32_16x16x32_bf16 v[16:19], v[116:119], v[148:151], v[16:19]
	v_mfma_f32_16x16x32_bf16 v[32:35], v[116:119], v[156:159], v[32:35]
	ds_read_b64 v[120:121], v191 offset:29952
	ds_read_b64 v[122:123], v191 offset:29984
	ds_read_b64 v[124:125], v191 offset:30016
	ds_read_b64 v[126:127], v191 offset:30048
	s_waitcnt lgkmcnt(0)
	v_mfma_f32_16x16x32_bf16 v[20:23], v[120:123], v[144:147], v[20:23]
	v_mfma_f32_16x16x32_bf16 v[36:39], v[120:123], v[152:155], v[36:39]
	v_mfma_f32_16x16x32_bf16 v[20:23], v[124:127], v[148:151], v[20:23]
	v_mfma_f32_16x16x32_bf16 v[36:39], v[124:127], v[156:159], v[36:39]
	ds_read_b64 v[128:129], v191 offset:32256
	ds_read_b64 v[130:131], v191 offset:32288
	ds_read_b64 v[132:133], v191 offset:32320
	ds_read_b64 v[134:135], v191 offset:32352
	s_waitcnt lgkmcnt(0)
	v_mfma_f32_16x16x32_bf16 v[24:27], v[128:131], v[144:147], v[24:27]
	v_mfma_f32_16x16x32_bf16 v[40:43], v[128:131], v[152:155], v[40:43]
	v_mfma_f32_16x16x32_bf16 v[24:27], v[132:135], v[148:151], v[24:27]
	v_mfma_f32_16x16x32_bf16 v[40:43], v[132:135], v[156:159], v[40:43]
	ds_read_b64 v[136:137], v191 offset:34560
	ds_read_b64 v[138:139], v191 offset:34592
	ds_read_b64 v[140:141], v191 offset:34624
	ds_read_b64 v[142:143], v191 offset:34656
	s_waitcnt lgkmcnt(0)
	v_mfma_f32_16x16x32_bf16 v[28:31], v[136:139], v[144:147], v[28:31]
	v_mfma_f32_16x16x32_bf16 v[44:47], v[136:139], v[152:155], v[44:47]
	v_mfma_f32_16x16x32_bf16 v[28:31], v[140:143], v[148:151], v[28:31]
	v_mfma_f32_16x16x32_bf16 v[44:47], v[140:143], v[156:159], v[44:47]
	s_branch .Lp4_sel_next1
.Lp4_sel_masked1:
	ds_read_b128 v[112:115], v190 offset:9216
	ds_read_b128 v[116:119], v190 offset:9280
	s_waitcnt lgkmcnt(0)
	v_mfma_f32_16x16x32_bf16 v[80:83], v[112:115], v[0:3], 0
	v_mfma_f32_16x16x32_bf16 v[96:99], v[112:115], v[8:11], 0
	v_mfma_f32_16x16x32_bf16 v[80:83], v[116:119], v[4:7], v[80:83]
	v_mfma_f32_16x16x32_bf16 v[96:99], v[116:119], v[12:15], v[96:99]
	ds_read_b128 v[120:123], v190 offset:11520
	ds_read_b128 v[124:127], v190 offset:11584
	s_waitcnt lgkmcnt(0)
	v_mfma_f32_16x16x32_bf16 v[84:87], v[120:123], v[0:3], 0
	v_mfma_f32_16x16x32_bf16 v[100:103], v[120:123], v[8:11], 0
	v_mfma_f32_16x16x32_bf16 v[84:87], v[124:127], v[4:7], v[84:87]
	v_mfma_f32_16x16x32_bf16 v[100:103], v[124:127], v[12:15], v[100:103]
	ds_read_b128 v[128:131], v190 offset:13824
	ds_read_b128 v[132:135], v190 offset:13888
	s_waitcnt lgkmcnt(0)
	v_mfma_f32_16x16x32_bf16 v[88:91], v[128:131], v[0:3], 0
	v_mfma_f32_16x16x32_bf16 v[104:107], v[128:131], v[8:11], 0
	v_mfma_f32_16x16x32_bf16 v[88:91], v[132:135], v[4:7], v[88:91]
	v_mfma_f32_16x16x32_bf16 v[104:107], v[132:135], v[12:15], v[104:107]
	ds_read_b128 v[136:139], v190 offset:16128
	ds_read_b128 v[140:143], v190 offset:16192
	s_waitcnt lgkmcnt(0)
	v_mfma_f32_16x16x32_bf16 v[92:95], v[136:139], v[0:3], 0
	v_mfma_f32_16x16x32_bf16 v[108:111], v[136:139], v[8:11], 0
	v_mfma_f32_16x16x32_bf16 v[92:95], v[140:143], v[4:7], v[92:95]
	v_mfma_f32_16x16x32_bf16 v[108:111], v[140:143], v[12:15], v[108:111]
	s_nop 7
	v_subrev_u32_e32 v222, s30, v207
	v_subrev_u32_e32 v223, 0, v222
	v_cmp_ge_u32_e64 s[32:33], s41, v223
	v_subrev_u32_e32 v224, 1, v222
	v_cmp_ge_u32_e64 s[34:35], s41, v224
	v_subrev_u32_e32 v225, 2, v222
	v_cmp_ge_u32_e64 s[36:37], s41, v225
	v_subrev_u32_e32 v226, 3, v222
	v_cmp_ge_u32_e64 s[46:47], s41, v226
	v_cndmask_b32_e64 v80, v230, v80, s[32:33]
	v_cndmask_b32_e64 v81, v230, v81, s[34:35]
	v_cndmask_b32_e64 v82, v230, v82, s[36:37]
	v_cndmask_b32_e64 v83, v230, v83, s[46:47]
	v_subrev_u32_e32 v223, 16, v222
	v_cmp_ge_u32_e64 s[32:33], s41, v223
	v_subrev_u32_e32 v224, 17, v222
	v_cmp_ge_u32_e64 s[34:35], s41, v224
	v_subrev_u32_e32 v225, 18, v222
	v_cmp_ge_u32_e64 s[36:37], s41, v225
	v_subrev_u32_e32 v226, 19, v222
	v_cmp_ge_u32_e64 s[46:47], s41, v226
	v_cndmask_b32_e64 v84, v230, v84, s[32:33]
	v_cndmask_b32_e64 v85, v230, v85, s[34:35]
	v_cndmask_b32_e64 v86, v230, v86, s[36:37]
	v_cndmask_b32_e64 v87, v230, v87, s[46:47]
	v_subrev_u32_e32 v223, 32, v222
	v_cmp_ge_u32_e64 s[32:33], s41, v223
	v_subrev_u32_e32 v224, 33, v222
	v_cmp_ge_u32_e64 s[34:35], s41, v224
	v_subrev_u32_e32 v225, 34, v222
	v_cmp_ge_u32_e64 s[36:37], s41, v225
	v_subrev_u32_e32 v226, 35, v222
	v_cmp_ge_u32_e64 s[46:47], s41, v226
	v_cndmask_b32_e64 v88, v230, v88, s[32:33]
	v_cndmask_b32_e64 v89, v230, v89, s[34:35]
	v_cndmask_b32_e64 v90, v230, v90, s[36:37]
	v_cndmask_b32_e64 v91, v230, v91, s[46:47]
	v_subrev_u32_e32 v223, 48, v222
	v_cmp_ge_u32_e64 s[32:33], s41, v223
	v_subrev_u32_e32 v224, 49, v222
	v_cmp_ge_u32_e64 s[34:35], s41, v224
	v_subrev_u32_e32 v225, 50, v222
	v_cmp_ge_u32_e64 s[36:37], s41, v225
	v_subrev_u32_e32 v226, 51, v222
	v_cmp_ge_u32_e64 s[46:47], s41, v226
	v_cndmask_b32_e64 v92, v230, v92, s[32:33]
	v_cndmask_b32_e64 v93, v230, v93, s[34:35]
	v_cndmask_b32_e64 v94, v230, v94, s[36:37]
	v_cndmask_b32_e64 v95, v230, v95, s[46:47]
	v_max3_f32 v215, v80, v81, v82
	v_max3_f32 v215, v215, v83, v84
	v_max3_f32 v215, v215, v85, v86
	v_max3_f32 v215, v215, v87, v88
	v_max3_f32 v215, v215, v89, v90
	v_max3_f32 v215, v215, v91, v92
	v_max3_f32 v215, v215, v93, v94
	v_max_f32_e32 v215, v95, v215
	ds_bpermute_b32 v216, v195, v215
	s_waitcnt lgkmcnt(0)
; DEVI unsigned pack2(float a, float b) { return (unsigned)f2bf(a) | ((unsigned)f2bf(b) << 16); }
; DEVI float fexp2(float x) { return __builtin_amdgcn_exp2f(x); }
; template <int DH, int NQ, int LDK, class MaskF>
; DEVI void attn_qk(const u16* sK, const bf16x8 (&qf)[NQ][DH / 32], f32x4 (&o)[NQ][DH / 16], float (&m)[NQ], float (&l)[NQ],
;                   float c2, int lane, MaskF valid, bf16x8 (&pb)[NQ][2]) {
;     ...
;         const bool v = valid(qt, 16 * kt + 4 * quad + r);
;         const float sv = v ? s[qt][kt][r] : -1e30f;
;         s[qt][kt][r] = sv;
;         mx = fmaxf(mx, sv);
;       }
;     mx = fmaxf(mx, __shfl_xor(mx, 16));
;     mx = fmaxf(mx, __shfl_xor(mx, 32));
;     const float mn = fmaxf(m[qt], mx);
;     const float alpha = fexp2((m[qt] - mn) * c2);
;     m[qt] = mn;
;     const float mc = fmaxf(mn, -1e20f) * c2;
;     float ps = 0.f;
; #pragma unroll
;     for (int kt = 0; kt < 4; ++kt)
; #pragma unroll
;       for (int r = 0; r < 4; ++r) {
;         const float pv = fexp2(__builtin_fmaf(s[qt][kt][r], c2, -mc));
;         ps += pv;
;         s[qt][kt][r] = pv;
;       }
;     l[qt] = l[qt] * alpha + ps;
; #pragma unroll
;     for (int dt = 0; dt < DH / 16; ++dt) o[qt][dt] *= alpha;
; #pragma unroll
;     for (int kk = 0; kk < 2; ++kk) {
;       union { bf16x8 v; unsigned u[4]; } cv;
;       cv.u[0] = pack2(s[qt][2 * kk][0], s[qt][2 * kk][1]);
;       cv.u[1] = pack2(s[qt][2 * kk][2], s[qt][2 * kk][3]);
;       cv.u[2] = pack2(s[qt][2 * kk + 1][0], s[qt][2 * kk + 1][1]);
;       cv.u[3] = pack2(s[qt][2 * kk + 1][2], s[qt][2 * kk + 1][3]);
;       pb[qt][kk] = cv.v;
;     }
;   }
	v_max_f32_e32 v215, v216, v215
	v_mov_b32_e32 v216, v215
	v_mov_b32_e32 v217, v215
	s_nop 1
	v_permlane32_swap_b32_e32 v216, v217
	v_max_f32_e32 v215, v216, v217
	v_max_f32_e32 v218, v182, v215
	v_sub_f32_e32 v219, v182, v218
	v_mul_f32_e32 v219, v200, v219
	v_exp_f32_e32 v219, v219
	v_mov_b32_e32 v182, v218
	v_max_f32_e32 v220, 0xe0ad78ec, v218
	v_mul_f32_e32 v220, 0xbe38aa3b, v220
	v_fma_f32 v80, v80, v200, v220
	v_exp_f32_e32 v80, v80
	v_fma_f32 v81, v81, v200, v220
	v_exp_f32_e32 v81, v81
	v_fma_f32 v82, v82, v200, v220
	v_exp_f32_e32 v82, v82
	v_fma_f32 v83, v83, v200, v220
	v_exp_f32_e32 v83, v83
	v_fma_f32 v84, v84, v200, v220
	v_exp_f32_e32 v84, v84
	v_fma_f32 v85, v85, v200, v220
	v_exp_f32_e32 v85, v85
	v_fma_f32 v86, v86, v200, v220
	v_exp_f32_e32 v86, v86
	v_fma_f32 v87, v87, v200, v220
	v_exp_f32_e32 v87, v87
	v_fma_f32 v88, v88, v200, v220
	v_exp_f32_e32 v88, v88
	v_fma_f32 v89, v89, v200, v220
	v_exp_f32_e32 v89, v89
	v_fma_f32 v90, v90, v200, v220
	v_exp_f32_e32 v90, v90
	v_fma_f32 v91, v91, v200, v220
	v_exp_f32_e32 v91, v91
	v_fma_f32 v92, v92, v200, v220
	v_exp_f32_e32 v92, v92
	v_fma_f32 v93, v93, v200, v220
	v_exp_f32_e32 v93, v93
	v_fma_f32 v94, v94, v200, v220
	v_exp_f32_e32 v94, v94
	v_fma_f32 v95, v95, v200, v220
	v_exp_f32_e32 v95, v95
	s_nop 0
	v_add_f32_e32 v221, v80, v81
	v_add_f32_e32 v221, v82, v221
	v_add_f32_e32 v221, v83, v221
	v_add_f32_e32 v221, v84, v221
	v_add_f32_e32 v221, v85, v221
	v_add_f32_e32 v221, v86, v221
	v_add_f32_e32 v221, v87, v221
	v_add_f32_e32 v221, v88, v221
	v_add_f32_e32 v221, v89, v221
	v_add_f32_e32 v221, v90, v221
	v_add_f32_e32 v221, v91, v221
	v_add_f32_e32 v221, v92, v221
	v_add_f32_e32 v221, v93, v221
	v_add_f32_e32 v221, v94, v221
	v_add_f32_e32 v221, v95, v221
	v_fma_f32 v184, v184, v219, v221
	v_mul_f32_e32 v16, v219, v16
	v_mul_f32_e32 v17, v219, v17
	v_mul_f32_e32 v18, v219, v18
	v_mul_f32_e32 v19, v219, v19
	v_mul_f32_e32 v20, v219, v20
	v_mul_f32_e32 v21, v219, v21
	v_mul_f32_e32 v22, v219, v22
	v_mul_f32_e32 v23, v219, v23
	v_mul_f32_e32 v24, v219, v24
	v_mul_f32_e32 v25, v219, v25
	v_mul_f32_e32 v26, v219, v26
	v_mul_f32_e32 v27, v219, v27
	v_mul_f32_e32 v28, v219, v28
	v_mul_f32_e32 v29, v219, v29
	v_mul_f32_e32 v30, v219, v30
	v_mul_f32_e32 v31, v219, v31
	v_cvt_pk_bf16_f32 v144, v80, v81
	v_cvt_pk_bf16_f32 v145, v82, v83
	v_cvt_pk_bf16_f32 v146, v84, v85
	v_cvt_pk_bf16_f32 v147, v86, v87
	v_cvt_pk_bf16_f32 v148, v88, v89
	v_cvt_pk_bf16_f32 v149, v90, v91
	v_cvt_pk_bf16_f32 v150, v92, v93
	v_cvt_pk_bf16_f32 v151, v94, v95
	v_subrev_u32_e32 v222, s30, v208
	v_subrev_u32_e32 v223, 0, v222
	v_cmp_ge_u32_e64 s[32:33], s41, v223
	v_subrev_u32_e32 v224, 1, v222
	v_cmp_ge_u32_e64 s[34:35], s41, v224
	v_subrev_u32_e32 v225, 2, v222
	v_cmp_ge_u32_e64 s[36:37], s41, v225
	v_subrev_u32_e32 v226, 3, v222
	v_cmp_ge_u32_e64 s[46:47], s41, v226
	v_cndmask_b32_e64 v96, v230, v96, s[32:33]
	v_cndmask_b32_e64 v97, v230, v97, s[34:35]
	v_cndmask_b32_e64 v98, v230, v98, s[36:37]
	v_cndmask_b32_e64 v99, v230, v99, s[46:47]
	v_subrev_u32_e32 v223, 16, v222
	v_cmp_ge_u32_e64 s[32:33], s41, v223
	v_subrev_u32_e32 v224, 17, v222
	v_cmp_ge_u32_e64 s[34:35], s41, v224
	v_subrev_u32_e32 v225, 18, v222
	v_cmp_ge_u32_e64 s[36:37], s41, v225
	v_subrev_u32_e32 v226, 19, v222
	v_cmp_ge_u32_e64 s[46:47], s41, v226
	v_cndmask_b32_e64 v100, v230, v100, s[32:33]
	v_cndmask_b32_e64 v101, v230, v101, s[34:35]
	v_cndmask_b32_e64 v102, v230, v102, s[36:37]
	v_cndmask_b32_e64 v103, v230, v103, s[46:47]
	v_subrev_u32_e32 v223, 32, v222
	v_cmp_ge_u32_e64 s[32:33], s41, v223
	v_subrev_u32_e32 v224, 33, v222
	v_cmp_ge_u32_e64 s[34:35], s41, v224
	v_subrev_u32_e32 v225, 34, v222
	v_cmp_ge_u32_e64 s[36:37], s41, v225
	v_subrev_u32_e32 v226, 35, v222
	v_cmp_ge_u32_e64 s[46:47], s41, v226
	v_cndmask_b32_e64 v104, v230, v104, s[32:33]
	v_cndmask_b32_e64 v105, v230, v105, s[34:35]
	v_cndmask_b32_e64 v106, v230, v106, s[36:37]
	v_cndmask_b32_e64 v107, v230, v107, s[46:47]
	v_subrev_u32_e32 v223, 48, v222
	v_cmp_ge_u32_e64 s[32:33], s41, v223
	v_subrev_u32_e32 v224, 49, v222
	v_cmp_ge_u32_e64 s[34:35], s41, v224
	v_subrev_u32_e32 v225, 50, v222
	v_cmp_ge_u32_e64 s[36:37], s41, v225
	v_subrev_u32_e32 v226, 51, v222
	v_cmp_ge_u32_e64 s[46:47], s41, v226
	v_cndmask_b32_e64 v108, v230, v108, s[32:33]
	v_cndmask_b32_e64 v109, v230, v109, s[34:35]
	v_cndmask_b32_e64 v110, v230, v110, s[36:37]
	v_cndmask_b32_e64 v111, v230, v111, s[46:47]
	v_max3_f32 v215, v96, v97, v98
	v_max3_f32 v215, v215, v99, v100
	v_max3_f32 v215, v215, v101, v102
	v_max3_f32 v215, v215, v103, v104
	v_max3_f32 v215, v215, v105, v106
	v_max3_f32 v215, v215, v107, v108
	v_max3_f32 v215, v215, v109, v110
	v_max_f32_e32 v215, v111, v215
	ds_bpermute_b32 v216, v195, v215
	s_waitcnt lgkmcnt(0)
; DEVI unsigned pack2(float a, float b) { return (unsigned)f2bf(a) | ((unsigned)f2bf(b) << 16); }
; DEVI f32x4 mfma16(bf16x8 a, bf16x8 b, f32x4 c) { return __builtin_amdgcn_mfma_f32_16x16x32_bf16(a, b, c, 0, 0, 0); }
; DEVI float fexp2(float x) { return __builtin_amdgcn_exp2f(x); }
; template <int DH, int NQ, int LDK, class MaskF>
; DEVI void attn_qk(const u16* sK, const bf16x8 (&qf)[NQ][DH / 32], f32x4 (&o)[NQ][DH / 16], float (&m)[NQ], float (&l)[NQ],
;                   float c2, int lane, MaskF valid, bf16x8 (&pb)[NQ][2]) {
;     ...
;     mx = fmaxf(mx, __shfl_xor(mx, 16));
;     mx = fmaxf(mx, __shfl_xor(mx, 32));
;     const float mn = fmaxf(m[qt], mx);
;     const float alpha = fexp2((m[qt] - mn) * c2);
;     m[qt] = mn;
;     const float mc = fmaxf(mn, -1e20f) * c2;
;     float ps = 0.f;
; #pragma unroll
;     for (int kt = 0; kt < 4; ++kt)
; #pragma unroll
;       for (int r = 0; r < 4; ++r) {
;         const float pv = fexp2(__builtin_fmaf(s[qt][kt][r], c2, -mc));
;         ps += pv;
;         s[qt][kt][r] = pv;
;       }
;     l[qt] = l[qt] * alpha + ps;
; #pragma unroll
;     for (int dt = 0; dt < DH / 16; ++dt) o[qt][dt] *= alpha;
; #pragma unroll
;     for (int kk = 0; kk < 2; ++kk) {
;       union { bf16x8 v; unsigned u[4]; } cv;
;       cv.u[0] = pack2(s[qt][2 * kk][0], s[qt][2 * kk][1]);
;       cv.u[1] = pack2(s[qt][2 * kk][2], s[qt][2 * kk][3]);
;       cv.u[2] = pack2(s[qt][2 * kk + 1][0], s[qt][2 * kk + 1][1]);
;       cv.u[3] = pack2(s[qt][2 * kk + 1][2], s[qt][2 * kk + 1][3]);
;       pb[qt][kk] = cv.v;
;     }
;   }
; }
; template <int DH, int NQ, int LDV>
; DEVI void attn_pv(const u16* sVt, const bf16x8 (&pb)[NQ][2], f32x4 (&o)[NQ][DH / 16], int lane) {
;   const int col = lane & 15, quad = lane >> 4;
;   __builtin_amdgcn_s_setprio(1);
; #pragma unroll
;   for (int dt = 0; dt < DH / 16; ++dt) {
; #pragma unroll
;     for (int kk = 0; kk < 2; ++kk) {
;       union { bf16x8 v; uint2 h[2]; } cv;
;       cv.h[0] = *(const uint2*)(sVt + (16 * dt + col) * LDV + 32 * kk + 4 * quad);
;       cv.h[1] = *(const uint2*)(sVt + (16 * dt + col) * LDV + 32 * kk + 16 + 4 * quad);
; #pragma unroll
;       for (int qt = 0; qt < NQ; ++qt) o[qt][dt] = mfma16(cv.v, pb[qt][kk], o[qt][dt]);
;     }
;   }
;   __builtin_amdgcn_s_setprio(0);
; DEVI void phase_nsa(const Params& p, unsigned char* smem) {
;     ...
;         kb = nkb;
	v_max_f32_e32 v215, v216, v215
	v_mov_b32_e32 v216, v215
	v_mov_b32_e32 v217, v215
	s_nop 1
	v_permlane32_swap_b32_e32 v216, v217
	v_max_f32_e32 v215, v216, v217
	v_max_f32_e32 v218, v183, v215
	v_sub_f32_e32 v219, v183, v218
	v_mul_f32_e32 v219, v200, v219
	v_exp_f32_e32 v219, v219
	v_mov_b32_e32 v183, v218
	v_max_f32_e32 v220, 0xe0ad78ec, v218
	v_mul_f32_e32 v220, 0xbe38aa3b, v220
	v_fma_f32 v96, v96, v200, v220
	v_exp_f32_e32 v96, v96
	v_fma_f32 v97, v97, v200, v220
	v_exp_f32_e32 v97, v97
	v_fma_f32 v98, v98, v200, v220
	v_exp_f32_e32 v98, v98
	v_fma_f32 v99, v99, v200, v220
	v_exp_f32_e32 v99, v99
	v_fma_f32 v100, v100, v200, v220
	v_exp_f32_e32 v100, v100
	v_fma_f32 v101, v101, v200, v220
	v_exp_f32_e32 v101, v101
	v_fma_f32 v102, v102, v200, v220
	v_exp_f32_e32 v102, v102
	v_fma_f32 v103, v103, v200, v220
	v_exp_f32_e32 v103, v103
	v_fma_f32 v104, v104, v200, v220
	v_exp_f32_e32 v104, v104
	v_fma_f32 v105, v105, v200, v220
	v_exp_f32_e32 v105, v105
	v_fma_f32 v106, v106, v200, v220
	v_exp_f32_e32 v106, v106
	v_fma_f32 v107, v107, v200, v220
	v_exp_f32_e32 v107, v107
	v_fma_f32 v108, v108, v200, v220
	v_exp_f32_e32 v108, v108
	v_fma_f32 v109, v109, v200, v220
	v_exp_f32_e32 v109, v109
	v_fma_f32 v110, v110, v200, v220
	v_exp_f32_e32 v110, v110
	v_fma_f32 v111, v111, v200, v220
	v_exp_f32_e32 v111, v111
	s_nop 0
	v_add_f32_e32 v221, v96, v97
	v_add_f32_e32 v221, v98, v221
	v_add_f32_e32 v221, v99, v221
	v_add_f32_e32 v221, v100, v221
	v_add_f32_e32 v221, v101, v221
	v_add_f32_e32 v221, v102, v221
	v_add_f32_e32 v221, v103, v221
	v_add_f32_e32 v221, v104, v221
	v_add_f32_e32 v221, v105, v221
	v_add_f32_e32 v221, v106, v221
	v_add_f32_e32 v221, v107, v221
	v_add_f32_e32 v221, v108, v221
	v_add_f32_e32 v221, v109, v221
	v_add_f32_e32 v221, v110, v221
	v_add_f32_e32 v221, v111, v221
	v_fma_f32 v185, v185, v219, v221
	v_mul_f32_e32 v32, v219, v32
	v_mul_f32_e32 v33, v219, v33
	v_mul_f32_e32 v34, v219, v34
	v_mul_f32_e32 v35, v219, v35
	v_mul_f32_e32 v36, v219, v36
	v_mul_f32_e32 v37, v219, v37
	v_mul_f32_e32 v38, v219, v38
	v_mul_f32_e32 v39, v219, v39
	v_mul_f32_e32 v40, v219, v40
	v_mul_f32_e32 v41, v219, v41
	v_mul_f32_e32 v42, v219, v42
	v_mul_f32_e32 v43, v219, v43
	v_mul_f32_e32 v44, v219, v44
	v_mul_f32_e32 v45, v219, v45
	v_mul_f32_e32 v46, v219, v46
	v_mul_f32_e32 v47, v219, v47
	v_cvt_pk_bf16_f32 v152, v96, v97
	v_cvt_pk_bf16_f32 v153, v98, v99
	v_cvt_pk_bf16_f32 v154, v100, v101
	v_cvt_pk_bf16_f32 v155, v102, v103
	v_cvt_pk_bf16_f32 v156, v104, v105
	v_cvt_pk_bf16_f32 v157, v106, v107
	v_cvt_pk_bf16_f32 v158, v108, v109
	v_cvt_pk_bf16_f32 v159, v110, v111
	ds_read_b64 v[112:113], v191 offset:27648
	ds_read_b64 v[114:115], v191 offset:27680
	ds_read_b64 v[116:117], v191 offset:27712
	ds_read_b64 v[118:119], v191 offset:27744
	s_waitcnt lgkmcnt(0)
	v_mfma_f32_16x16x32_bf16 v[16:19], v[112:115], v[144:147], v[16:19]
	v_mfma_f32_16x16x32_bf16 v[32:35], v[112:115], v[152:155], v[32:35]
	v_mfma_f32_16x16x32_bf16 v[16:19], v[116:119], v[148:151], v[16:19]
	v_mfma_f32_16x16x32_bf16 v[32:35], v[116:119], v[156:159], v[32:35]
	ds_read_b64 v[120:121], v191 offset:29952
	ds_read_b64 v[122:123], v191 offset:29984
	ds_read_b64 v[124:125], v191 offset:30016
	ds_read_b64 v[126:127], v191 offset:30048
	s_waitcnt lgkmcnt(0)
	v_mfma_f32_16x16x32_bf16 v[20:23], v[120:123], v[144:147], v[20:23]
	v_mfma_f32_16x16x32_bf16 v[36:39], v[120:123], v[152:155], v[36:39]
	v_mfma_f32_16x16x32_bf16 v[20:23], v[124:127], v[148:151], v[20:23]
	v_mfma_f32_16x16x32_bf16 v[36:39], v[124:127], v[156:159], v[36:39]
	ds_read_b64 v[128:129], v191 offset:32256
	ds_read_b64 v[130:131], v191 offset:32288
	ds_read_b64 v[132:133], v191 offset:32320
	ds_read_b64 v[134:135], v191 offset:32352
	s_waitcnt lgkmcnt(0)
	v_mfma_f32_16x16x32_bf16 v[24:27], v[128:131], v[144:147], v[24:27]
	v_mfma_f32_16x16x32_bf16 v[40:43], v[128:131], v[152:155], v[40:43]
	v_mfma_f32_16x16x32_bf16 v[24:27], v[132:135], v[148:151], v[24:27]
	v_mfma_f32_16x16x32_bf16 v[40:43], v[132:135], v[156:159], v[40:43]
	ds_read_b64 v[136:137], v191 offset:34560
	ds_read_b64 v[138:139], v191 offset:34592
	ds_read_b64 v[140:141], v191 offset:34624
	ds_read_b64 v[142:143], v191 offset:34656
	s_waitcnt lgkmcnt(0)
	v_mfma_f32_16x16x32_bf16 v[28:31], v[136:139], v[144:147], v[28:31]
	v_mfma_f32_16x16x32_bf16 v[44:47], v[136:139], v[152:155], v[44:47]
	v_mfma_f32_16x16x32_bf16 v[28:31], v[140:143], v[148:151], v[28:31]
	v_mfma_f32_16x16x32_bf16 v[44:47], v[140:143], v[156:159], v[44:47]
.Lp4_sel_next1:
	s_mov_b32 s26, s27
	s_cmp_lt_i32 s26, 0
	s_cbranch_scc1 .Lp4_sel_end
	s_branch .Lp4_sel_buf0
; DEVI void phase_nsa(const Params& p, unsigned char* smem) {
;     ...
; #pragma unroll
;       for (int qt = 0; qt < 2; ++qt) {
;         float lt = l[qt];
;         lt += __shfl_xor(lt, 16);
;         lt += __shfl_xor(lt, 32);
;         const float sc = lt > 0.f ? gate[qt][1] / lt : 0.f;
; #pragma unroll
;         for (int dt = 0; dt < 4; ++dt) comb[qt][dt] += o[qt][dt] * sc;
;       }
;     }
;     {
;       float m[2] = {-1e30f, -1e30f}, l[2] = {0.f, 0.f};
;       f32x4 o[2][4];
; #pragma unroll
;       for (int qt = 0; qt < 2; ++qt)
; #pragma unroll
;         for (int dt = 0; dt < 4; ++dt) o[qt][dt] = f32x4{0.f, 0.f, 0.f, 0.f};
;       const int kblo = (q0 >= 511) ? ((q0 - 511) >> 6) : 0;
;       uint4 rk0, rk1, rv0, rv1;
;       const int lr0 = tid >> 3, lch = (tid & 7) << 3;
;       int kb = kblo;
;       LOADKV_(kb, C_KW, p.vtw)
; #pragma unroll 1
;       while (kb >= 0) {
;         const int nkb = (kb < kbmax) ? kb + 1 : -1;
;         __syncthreads();
;         STOREKV_()
;         if (nkb >= 0) { LOADKV_(nkb, C_KW, p.vtw) }
.Lp4_sel_end:
	s_nop 7
	v_mov_b32_e32 v215, v184
	ds_bpermute_b32 v216, v195, v215
	s_waitcnt lgkmcnt(0)
	v_add_f32_e32 v215, v216, v215
	v_mov_b32_e32 v216, v215
	v_mov_b32_e32 v217, v215
	s_nop 1
	v_permlane32_swap_b32_e32 v216, v217
	v_add_f32_e32 v215, v216, v217
	v_rcp_f32_e32 v218, v215
	s_nop 0
	v_fma_f32 v219, -v215, v218, 1.0
	v_fma_f32 v218, v219, v218, v218
	v_mul_f32_e32 v218, v177, v218
	v_cmp_lt_f32_e64 s[32:33], 0, v215
	v_mov_b32_e32 v220, 0
	s_nop 0
	v_cndmask_b32_e64 v218, v220, v218, s[32:33]
	v_fma_f32 v48, v16, v218, v48
	v_fma_f32 v49, v17, v218, v49
	v_fma_f32 v50, v18, v218, v50
	v_fma_f32 v51, v19, v218, v51
	v_fma_f32 v52, v20, v218, v52
	v_fma_f32 v53, v21, v218, v53
	v_fma_f32 v54, v22, v218, v54
	v_fma_f32 v55, v23, v218, v55
	v_fma_f32 v56, v24, v218, v56
	v_fma_f32 v57, v25, v218, v57
	v_fma_f32 v58, v26, v218, v58
	v_fma_f32 v59, v27, v218, v59
	v_fma_f32 v60, v28, v218, v60
	v_fma_f32 v61, v29, v218, v61
	v_fma_f32 v62, v30, v218, v62
	v_fma_f32 v63, v31, v218, v63
	v_mov_b32_e32 v215, v185
	ds_bpermute_b32 v216, v195, v215
	s_waitcnt lgkmcnt(0)
	v_add_f32_e32 v215, v216, v215
	v_mov_b32_e32 v216, v215
	v_mov_b32_e32 v217, v215
	s_nop 1
	v_permlane32_swap_b32_e32 v216, v217
	v_add_f32_e32 v215, v216, v217
	v_rcp_f32_e32 v218, v215
	s_nop 0
	v_fma_f32 v219, -v215, v218, 1.0
	v_fma_f32 v218, v219, v218, v218
	v_mul_f32_e32 v218, v180, v218
	v_cmp_lt_f32_e64 s[32:33], 0, v215
	v_mov_b32_e32 v220, 0
	s_nop 0
	v_cndmask_b32_e64 v218, v220, v218, s[32:33]
	v_fma_f32 v64, v32, v218, v64
	v_fma_f32 v65, v33, v218, v65
	v_fma_f32 v66, v34, v218, v66
	v_fma_f32 v67, v35, v218, v67
	v_fma_f32 v68, v36, v218, v68
	v_fma_f32 v69, v37, v218, v69
	v_fma_f32 v70, v38, v218, v70
	v_fma_f32 v71, v39, v218, v71
	v_fma_f32 v72, v40, v218, v72
	v_fma_f32 v73, v41, v218, v73
	v_fma_f32 v74, v42, v218, v74
	v_fma_f32 v75, v43, v218, v75
	v_fma_f32 v76, v44, v218, v76
	v_fma_f32 v77, v45, v218, v77
	v_fma_f32 v78, v46, v218, v78
	v_fma_f32 v79, v47, v218, v79
	s_barrier
	s_mov_b32 s42, s6
	s_mov_b32 s43, s7
	s_lshl_b32 s31, s17, 7
	s_add_u32 s31, s31, 4096
	s_mov_b32 s41, 0x1ff
	v_mov_b32_e32 v16, 0
	v_mov_b32_e32 v17, 0
	v_mov_b32_e32 v18, 0
	v_mov_b32_e32 v19, 0
	v_mov_b32_e32 v20, 0
	v_mov_b32_e32 v21, 0
	v_mov_b32_e32 v22, 0
	v_mov_b32_e32 v23, 0
	v_mov_b32_e32 v24, 0
	v_mov_b32_e32 v25, 0
	v_mov_b32_e32 v26, 0
	v_mov_b32_e32 v27, 0
	v_mov_b32_e32 v28, 0
	v_mov_b32_e32 v29, 0
	v_mov_b32_e32 v30, 0
	v_mov_b32_e32 v31, 0
	v_mov_b32_e32 v32, 0
	v_mov_b32_e32 v33, 0
	v_mov_b32_e32 v34, 0
	v_mov_b32_e32 v35, 0
	v_mov_b32_e32 v36, 0
	v_mov_b32_e32 v37, 0
	v_mov_b32_e32 v38, 0
	v_mov_b32_e32 v39, 0
	v_mov_b32_e32 v40, 0
	v_mov_b32_e32 v41, 0
	v_mov_b32_e32 v42, 0
	v_mov_b32_e32 v43, 0
	v_mov_b32_e32 v44, 0
	v_mov_b32_e32 v45, 0
	v_mov_b32_e32 v46, 0
	v_mov_b32_e32 v47, 0
	v_mov_b32_e32 v182, 0xf149f2ca
	v_mov_b32_e32 v184, 0
	v_mov_b32_e32 v183, 0xf149f2ca
	v_mov_b32_e32 v185, 0
	s_mov_b32 s26, s45
	s_lshl_b32 s22, s16, 11
	s_lshl_b32 s23, s26, 6
	s_add_u32 s22, s22, s23
	s_mul_i32 s22, s22, 0x1240
	s_add_u32 s22, s22, s31
	v_add_u32_e32 v211, s22, v201
	v_add_u32_e32 v212, s22, v202
	global_load_dwordx4 v[160:163], v211, s[0:1]
	global_load_dwordx4 v[164:167], v212, s[0:1]
	s_mul_i32 s22, s18, 0x42000
	s_lshl_b32 s23, s26, 7
	s_add_u32 s22, s22, s23
	v_add_u32_e32 v213, s22, v203
	v_add_u32_e32 v214, s22, v204
	global_load_dwordx4 v[168:171], v213, s[42:43]
	global_load_dwordx4 v[172:175], v214, s[42:43]
	s_mov_b32 s40, 0
.Lp4_win_loop:
.Lp4_win_buf0:
	s_waitcnt vmcnt(0)
	ds_write_b128 v193, v[160:163]
	ds_write_b128 v193, v[164:167] offset:4608
	ds_write_b128 v193, v[168:171] offset:18432
	ds_write_b128 v193, v[172:175] offset:23040
	s_add_u32 s27, s26, 1
	s_cmp_lt_u32 s26, s20
	s_cselect_b32 s27, s27, -1
	s_cmp_lt_i32 s27, 0
	s_cbranch_scc1 .Lp4_win_nold0
	s_lshl_b32 s22, s16, 11
	s_lshl_b32 s23, s27, 6
	s_add_u32 s22, s22, s23
	s_mul_i32 s22, s22, 0x1240
	s_add_u32 s22, s22, s31
	v_add_u32_e32 v211, s22, v201
	v_add_u32_e32 v212, s22, v202
	global_load_dwordx4 v[160:163], v211, s[0:1]
	global_load_dwordx4 v[164:167], v212, s[0:1]
	s_mul_i32 s22, s18, 0x42000
	s_lshl_b32 s23, s27, 7
	s_add_u32 s22, s22, s23
	v_add_u32_e32 v213, s22, v203
	v_add_u32_e32 v214, s22, v204
	global_load_dwordx4 v[168:171], v213, s[42:43]
	global_load_dwordx4 v[172:175], v214, s[42:43]
; DEVI f32x4 mfma16(bf16x8 a, bf16x8 b, f32x4 c) { return __builtin_amdgcn_mfma_f32_16x16x32_bf16(a, b, c, 0, 0, 0); }
; DEVI float fexp2(float x) { return __builtin_amdgcn_exp2f(x); }
; template <int DH, int NQ, int LDK, class MaskF>
; DEVI void attn_qk(const u16* sK, const bf16x8 (&qf)[NQ][DH / 32], f32x4 (&o)[NQ][DH / 16], float (&m)[NQ], float (&l)[NQ],
;                   float c2, int lane, MaskF valid, bf16x8 (&pb)[NQ][2]) {
;     ...
;   __builtin_amdgcn_s_setprio(1);
; #pragma unroll
;   for (int kt = 0; kt < 4; ++kt) {
; #pragma unroll
;     for (int qt = 0; qt < NQ; ++qt) s[qt][kt] = f32x4{0.f, 0.f, 0.f, 0.f};
; #pragma unroll
;     for (int ks = 0; ks < DH / 32; ++ks) {
;       const bf16x8 kf = *(const bf16x8*)(sK + (16 * kt + col) * LDK + 32 * ks + 8 * quad);
; #pragma unroll
;       for (int qt = 0; qt < NQ; ++qt) s[qt][kt] = mfma16(kf, qf[qt][ks], s[qt][kt]);
;     }
;   }
;   __builtin_amdgcn_s_setprio(0);
; #pragma unroll
;   for (int qt = 0; qt < NQ; ++qt) {
;     float mx = -1e30f;
; #pragma unroll
;     for (int kt = 0; kt < 4; ++kt)
; #pragma unroll
;       for (int r = 0; r < 4; ++r) {
;         const bool v = valid(qt, 16 * kt + 4 * quad + r);
;         const float sv = v ? s[qt][kt][r] : -1e30f;
;         s[qt][kt][r] = sv;
;         mx = fmaxf(mx, sv);
;       }
;     mx = fmaxf(mx, __shfl_xor(mx, 16));
;     mx = fmaxf(mx, __shfl_xor(mx, 32));
;     const float mn = fmaxf(m[qt], mx);
;     const float alpha = fexp2((m[qt] - mn) * c2);
;     m[qt] = mn;
;     const float mc = fmaxf(mn, -1e20f) * c2;
;     float ps = 0.f;
; #pragma unroll
;     for (int kt = 0; kt < 4; ++kt)
; #pragma unroll
;       for (int r = 0; r < 4; ++r) {
;         const float pv = fexp2(__builtin_fmaf(s[qt][kt][r], c2, -mc));
;         ps += pv;
;         s[qt][kt][r] = pv;
;       }
;     l[qt] = l[qt] * alpha + ps;
; #pragma unroll
;     for (int dt = 0; dt < DH / 16; ++dt) o[qt][dt] *= alpha;
; DEVI void phase_nsa(const Params& p, unsigned char* smem) {
;     ...
;       while (kb >= 0) {
;         const int nkb = (kb < kbmax) ? kb + 1 : -1;
;         __syncthreads();
;         STOREKV_()
;         if (nkb >= 0) { LOADKV_(nkb, C_KW, p.vtw) }
;         __syncthreads();
;         attn_tile<64, 2, 72, 72>(sK, sVt, qf, o, m, l, c2, lane, [&](int qt, int kl) {
;           return (unsigned)(tq[qt] - (kb * 64 + kl)) < 512u;
;         });
.Lp4_win_nold0:
	s_waitcnt lgkmcnt(0)
	s_barrier
	s_lshl_b32 s30, s26, 6
	v_lshlrev_b32_e32 v217, 2, v198
	v_sub_u32_e32 v207, v186, v217
	v_lshlrev_b32_e32 v217, 2, v198
	v_sub_u32_e32 v208, v187, v217
	s_add_u32 s23, s30, 63
	s_cmp_le_u32 s23, s19
	s_cselect_b32 s24, 1, 0
	s_add_u32 s23, s30, 0x1e0
	s_cmp_ge_u32 s23, s19
	s_cselect_b32 s24, s24, 0
	s_cmp_eq_u32 s24, 0
	s_cbranch_scc1 .Lp4_win_masked0
	ds_read_b128 v[112:115], v190
	ds_read_b128 v[116:119], v190 offset:64
	s_waitcnt lgkmcnt(0)
	v_mfma_f32_16x16x32_bf16 v[80:83], v[112:115], v[0:3], 0
	v_mfma_f32_16x16x32_bf16 v[96:99], v[112:115], v[8:11], 0
	v_mfma_f32_16x16x32_bf16 v[80:83], v[116:119], v[4:7], v[80:83]
	v_mfma_f32_16x16x32_bf16 v[96:99], v[116:119], v[12:15], v[96:99]
	ds_read_b128 v[120:123], v190 offset:2304
	ds_read_b128 v[124:127], v190 offset:2368
	s_waitcnt lgkmcnt(0)
	v_mfma_f32_16x16x32_bf16 v[84:87], v[120:123], v[0:3], 0
	v_mfma_f32_16x16x32_bf16 v[100:103], v[120:123], v[8:11], 0
	v_mfma_f32_16x16x32_bf16 v[84:87], v[124:127], v[4:7], v[84:87]
	v_mfma_f32_16x16x32_bf16 v[100:103], v[124:127], v[12:15], v[100:103]
	ds_read_b128 v[128:131], v190 offset:4608
	ds_read_b128 v[132:135], v190 offset:4672
	s_waitcnt lgkmcnt(0)
	v_mfma_f32_16x16x32_bf16 v[88:91], v[128:131], v[0:3], 0
	v_mfma_f32_16x16x32_bf16 v[104:107], v[128:131], v[8:11], 0
	v_mfma_f32_16x16x32_bf16 v[88:91], v[132:135], v[4:7], v[88:91]
	v_mfma_f32_16x16x32_bf16 v[104:107], v[132:135], v[12:15], v[104:107]
	ds_read_b128 v[136:139], v190 offset:6912
	ds_read_b128 v[140:143], v190 offset:6976
	s_waitcnt lgkmcnt(0)
	v_mfma_f32_16x16x32_bf16 v[92:95], v[136:139], v[0:3], 0
	v_mfma_f32_16x16x32_bf16 v[108:111], v[136:139], v[8:11], 0
	v_mfma_f32_16x16x32_bf16 v[92:95], v[140:143], v[4:7], v[92:95]
	v_mfma_f32_16x16x32_bf16 v[108:111], v[140:143], v[12:15], v[108:111]
	s_nop 7
	v_max3_f32 v215, v80, v81, v82
	v_max3_f32 v215, v215, v83, v84
	v_max3_f32 v215, v215, v85, v86
	v_max3_f32 v215, v215, v87, v88
	v_max3_f32 v215, v215, v89, v90
	v_max3_f32 v215, v215, v91, v92
	v_max3_f32 v215, v215, v93, v94
	v_max_f32_e32 v215, v95, v215
	ds_bpermute_b32 v216, v195, v215
	s_waitcnt lgkmcnt(0)
	v_max_f32_e32 v215, v216, v215
	v_mov_b32_e32 v216, v215
	v_mov_b32_e32 v217, v215
	s_nop 1
	v_permlane32_swap_b32_e32 v216, v217
	v_max_f32_e32 v215, v216, v217
	v_max_f32_e32 v218, v182, v215
	v_sub_f32_e32 v219, v182, v218
	v_mul_f32_e32 v219, v200, v219
	v_exp_f32_e32 v219, v219
	v_mov_b32_e32 v182, v218
	v_max_f32_e32 v220, 0xe0ad78ec, v218
	v_mul_f32_e32 v220, 0xbe38aa3b, v220
	v_fma_f32 v80, v80, v200, v220
	v_exp_f32_e32 v80, v80
	v_fma_f32 v81, v81, v200, v220
	v_exp_f32_e32 v81, v81
	v_fma_f32 v82, v82, v200, v220
	v_exp_f32_e32 v82, v82
	v_fma_f32 v83, v83, v200, v220
	v_exp_f32_e32 v83, v83
	v_fma_f32 v84, v84, v200, v220
	v_exp_f32_e32 v84, v84
	v_fma_f32 v85, v85, v200, v220
	v_exp_f32_e32 v85, v85
	v_fma_f32 v86, v86, v200, v220
	v_exp_f32_e32 v86, v86
	v_fma_f32 v87, v87, v200, v220
	v_exp_f32_e32 v87, v87
	v_fma_f32 v88, v88, v200, v220
	v_exp_f32_e32 v88, v88
	v_fma_f32 v89, v89, v200, v220
	v_exp_f32_e32 v89, v89
	v_fma_f32 v90, v90, v200, v220
	v_exp_f32_e32 v90, v90
	v_fma_f32 v91, v91, v200, v220
	v_exp_f32_e32 v91, v91
	v_fma_f32 v92, v92, v200, v220
	v_exp_f32_e32 v92, v92
	v_fma_f32 v93, v93, v200, v220
	v_exp_f32_e32 v93, v93
	v_fma_f32 v94, v94, v200, v220
	v_exp_f32_e32 v94, v94
	v_fma_f32 v95, v95, v200, v220
	v_exp_f32_e32 v95, v95
	s_nop 0
	v_add_f32_e32 v221, v80, v81
	v_add_f32_e32 v221, v82, v221
	v_add_f32_e32 v221, v83, v221
	v_add_f32_e32 v221, v84, v221
	v_add_f32_e32 v221, v85, v221
	v_add_f32_e32 v221, v86, v221
	v_add_f32_e32 v221, v87, v221
	v_add_f32_e32 v221, v88, v221
	v_add_f32_e32 v221, v89, v221
	v_add_f32_e32 v221, v90, v221
	v_add_f32_e32 v221, v91, v221
	v_add_f32_e32 v221, v92, v221
	v_add_f32_e32 v221, v93, v221
	v_add_f32_e32 v221, v94, v221
	v_add_f32_e32 v221, v95, v221
	v_fma_f32 v184, v184, v219, v221
	v_mul_f32_e32 v16, v219, v16
	v_mul_f32_e32 v17, v219, v17
	v_mul_f32_e32 v18, v219, v18
	v_mul_f32_e32 v19, v219, v19
	v_mul_f32_e32 v20, v219, v20
	v_mul_f32_e32 v21, v219, v21
	v_mul_f32_e32 v22, v219, v22
	v_mul_f32_e32 v23, v219, v23
	v_mul_f32_e32 v24, v219, v24
	v_mul_f32_e32 v25, v219, v25
	v_mul_f32_e32 v26, v219, v26
	v_mul_f32_e32 v27, v219, v27
	v_mul_f32_e32 v28, v219, v28
	v_mul_f32_e32 v29, v219, v29
	v_mul_f32_e32 v30, v219, v30
	v_mul_f32_e32 v31, v219, v31
	v_cvt_pk_bf16_f32 v144, v80, v81
	v_cvt_pk_bf16_f32 v145, v82, v83
	v_cvt_pk_bf16_f32 v146, v84, v85
	v_cvt_pk_bf16_f32 v147, v86, v87
	v_cvt_pk_bf16_f32 v148, v88, v89
	v_cvt_pk_bf16_f32 v149, v90, v91
	v_cvt_pk_bf16_f32 v150, v92, v93
	v_cvt_pk_bf16_f32 v151, v94, v95
	v_max3_f32 v215, v96, v97, v98
	v_max3_f32 v215, v215, v99, v100
	v_max3_f32 v215, v215, v101, v102
	v_max3_f32 v215, v215, v103, v104
	v_max3_f32 v215, v215, v105, v106
	v_max3_f32 v215, v215, v107, v108
	v_max3_f32 v215, v215, v109, v110
	v_max_f32_e32 v215, v111, v215
	ds_bpermute_b32 v216, v195, v215
	s_waitcnt lgkmcnt(0)
; DEVI unsigned pack2(float a, float b) { return (unsigned)f2bf(a) | ((unsigned)f2bf(b) << 16); }
; DEVI f32x4 mfma16(bf16x8 a, bf16x8 b, f32x4 c) { return __builtin_amdgcn_mfma_f32_16x16x32_bf16(a, b, c, 0, 0, 0); }
; DEVI float fexp2(float x) { return __builtin_amdgcn_exp2f(x); }
; template <int DH, int NQ, int LDK, class MaskF>
; DEVI void attn_qk(const u16* sK, const bf16x8 (&qf)[NQ][DH / 32], f32x4 (&o)[NQ][DH / 16], float (&m)[NQ], float (&l)[NQ],
;                   float c2, int lane, MaskF valid, bf16x8 (&pb)[NQ][2]) {
;     ...
;     mx = fmaxf(mx, __shfl_xor(mx, 16));
;     mx = fmaxf(mx, __shfl_xor(mx, 32));
;     const float mn = fmaxf(m[qt], mx);
;     const float alpha = fexp2((m[qt] - mn) * c2);
;     m[qt] = mn;
;     const float mc = fmaxf(mn, -1e20f) * c2;
;     float ps = 0.f;
; #pragma unroll
;     for (int kt = 0; kt < 4; ++kt)
; #pragma unroll
;       for (int r = 0; r < 4; ++r) {
;         const float pv = fexp2(__builtin_fmaf(s[qt][kt][r], c2, -mc));
;         ps += pv;
;         s[qt][kt][r] = pv;
;       }
;     l[qt] = l[qt] * alpha + ps;
; #pragma unroll
;     for (int dt = 0; dt < DH / 16; ++dt) o[qt][dt] *= alpha;
; #pragma unroll
;     for (int kk = 0; kk < 2; ++kk) {
;       union { bf16x8 v; unsigned u[4]; } cv;
;       cv.u[0] = pack2(s[qt][2 * kk][0], s[qt][2 * kk][1]);
;       cv.u[1] = pack2(s[qt][2 * kk][2], s[qt][2 * kk][3]);
;       cv.u[2] = pack2(s[qt][2 * kk + 1][0], s[qt][2 * kk + 1][1]);
;       cv.u[3] = pack2(s[qt][2 * kk + 1][2], s[qt][2 * kk + 1][3]);
;       pb[qt][kk] = cv.v;
;     }
;   }
; }
; template <int DH, int NQ, int LDV>
; DEVI void attn_pv(const u16* sVt, const bf16x8 (&pb)[NQ][2], f32x4 (&o)[NQ][DH / 16], int lane) {
;   const int col = lane & 15, quad = lane >> 4;
;   __builtin_amdgcn_s_setprio(1);
; #pragma unroll
;   for (int dt = 0; dt < DH / 16; ++dt) {
; #pragma unroll
;     for (int kk = 0; kk < 2; ++kk) {
;       union { bf16x8 v; uint2 h[2]; } cv;
;       cv.h[0] = *(const uint2*)(sVt + (16 * dt + col) * LDV + 32 * kk + 4 * quad);
;       cv.h[1] = *(const uint2*)(sVt + (16 * dt + col) * LDV + 32 * kk + 16 + 4 * quad);
; #pragma unroll
;       for (int qt = 0; qt < NQ; ++qt) o[qt][dt] = mfma16(cv.v, pb[qt][kk], o[qt][dt]);
;     }
;   }
;   __builtin_amdgcn_s_setprio(0);
	v_max_f32_e32 v215, v216, v215
	v_mov_b32_e32 v216, v215
	v_mov_b32_e32 v217, v215
	s_nop 1
	v_permlane32_swap_b32_e32 v216, v217
	v_max_f32_e32 v215, v216, v217
	v_max_f32_e32 v218, v183, v215
	v_sub_f32_e32 v219, v183, v218
	v_mul_f32_e32 v219, v200, v219
	v_exp_f32_e32 v219, v219
	v_mov_b32_e32 v183, v218
	v_max_f32_e32 v220, 0xe0ad78ec, v218
	v_mul_f32_e32 v220, 0xbe38aa3b, v220
	v_fma_f32 v96, v96, v200, v220
	v_exp_f32_e32 v96, v96
	v_fma_f32 v97, v97, v200, v220
	v_exp_f32_e32 v97, v97
	v_fma_f32 v98, v98, v200, v220
	v_exp_f32_e32 v98, v98
	v_fma_f32 v99, v99, v200, v220
	v_exp_f32_e32 v99, v99
	v_fma_f32 v100, v100, v200, v220
	v_exp_f32_e32 v100, v100
	v_fma_f32 v101, v101, v200, v220
	v_exp_f32_e32 v101, v101
	v_fma_f32 v102, v102, v200, v220
	v_exp_f32_e32 v102, v102
	v_fma_f32 v103, v103, v200, v220
	v_exp_f32_e32 v103, v103
	v_fma_f32 v104, v104, v200, v220
	v_exp_f32_e32 v104, v104
	v_fma_f32 v105, v105, v200, v220
	v_exp_f32_e32 v105, v105
	v_fma_f32 v106, v106, v200, v220
	v_exp_f32_e32 v106, v106
	v_fma_f32 v107, v107, v200, v220
	v_exp_f32_e32 v107, v107
	v_fma_f32 v108, v108, v200, v220
	v_exp_f32_e32 v108, v108
	v_fma_f32 v109, v109, v200, v220
	v_exp_f32_e32 v109, v109
	v_fma_f32 v110, v110, v200, v220
	v_exp_f32_e32 v110, v110
	v_fma_f32 v111, v111, v200, v220
	v_exp_f32_e32 v111, v111
	s_nop 0
	v_add_f32_e32 v221, v96, v97
	v_add_f32_e32 v221, v98, v221
	v_add_f32_e32 v221, v99, v221
	v_add_f32_e32 v221, v100, v221
	v_add_f32_e32 v221, v101, v221
	v_add_f32_e32 v221, v102, v221
	v_add_f32_e32 v221, v103, v221
	v_add_f32_e32 v221, v104, v221
	v_add_f32_e32 v221, v105, v221
	v_add_f32_e32 v221, v106, v221
	v_add_f32_e32 v221, v107, v221
	v_add_f32_e32 v221, v108, v221
	v_add_f32_e32 v221, v109, v221
	v_add_f32_e32 v221, v110, v221
	v_add_f32_e32 v221, v111, v221
	v_fma_f32 v185, v185, v219, v221
	v_mul_f32_e32 v32, v219, v32
	v_mul_f32_e32 v33, v219, v33
	v_mul_f32_e32 v34, v219, v34
	v_mul_f32_e32 v35, v219, v35
	v_mul_f32_e32 v36, v219, v36
	v_mul_f32_e32 v37, v219, v37
	v_mul_f32_e32 v38, v219, v38
	v_mul_f32_e32 v39, v219, v39
	v_mul_f32_e32 v40, v219, v40
	v_mul_f32_e32 v41, v219, v41
	v_mul_f32_e32 v42, v219, v42
	v_mul_f32_e32 v43, v219, v43
	v_mul_f32_e32 v44, v219, v44
	v_mul_f32_e32 v45, v219, v45
	v_mul_f32_e32 v46, v219, v46
	v_mul_f32_e32 v47, v219, v47
	v_cvt_pk_bf16_f32 v152, v96, v97
	v_cvt_pk_bf16_f32 v153, v98, v99
	v_cvt_pk_bf16_f32 v154, v100, v101
	v_cvt_pk_bf16_f32 v155, v102, v103
	v_cvt_pk_bf16_f32 v156, v104, v105
	v_cvt_pk_bf16_f32 v157, v106, v107
	v_cvt_pk_bf16_f32 v158, v108, v109
	v_cvt_pk_bf16_f32 v159, v110, v111
	ds_read_b64 v[112:113], v191 offset:18432
	ds_read_b64 v[114:115], v191 offset:18464
	ds_read_b64 v[116:117], v191 offset:18496
	ds_read_b64 v[118:119], v191 offset:18528
	s_waitcnt lgkmcnt(0)
	v_mfma_f32_16x16x32_bf16 v[16:19], v[112:115], v[144:147], v[16:19]
	v_mfma_f32_16x16x32_bf16 v[32:35], v[112:115], v[152:155], v[32:35]
	v_mfma_f32_16x16x32_bf16 v[16:19], v[116:119], v[148:151], v[16:19]
	v_mfma_f32_16x16x32_bf16 v[32:35], v[116:119], v[156:159], v[32:35]
	ds_read_b64 v[120:121], v191 offset:20736
	ds_read_b64 v[122:123], v191 offset:20768
	ds_read_b64 v[124:125], v191 offset:20800
	ds_read_b64 v[126:127], v191 offset:20832
	s_waitcnt lgkmcnt(0)
	v_mfma_f32_16x16x32_bf16 v[20:23], v[120:123], v[144:147], v[20:23]
	v_mfma_f32_16x16x32_bf16 v[36:39], v[120:123], v[152:155], v[36:39]
	v_mfma_f32_16x16x32_bf16 v[20:23], v[124:127], v[148:151], v[20:23]
	v_mfma_f32_16x16x32_bf16 v[36:39], v[124:127], v[156:159], v[36:39]
	ds_read_b64 v[128:129], v191 offset:23040
	ds_read_b64 v[130:131], v191 offset:23072
	ds_read_b64 v[132:133], v191 offset:23104
	ds_read_b64 v[134:135], v191 offset:23136
	s_waitcnt lgkmcnt(0)
	v_mfma_f32_16x16x32_bf16 v[24:27], v[128:131], v[144:147], v[24:27]
	v_mfma_f32_16x16x32_bf16 v[40:43], v[128:131], v[152:155], v[40:43]
	v_mfma_f32_16x16x32_bf16 v[24:27], v[132:135], v[148:151], v[24:27]
	v_mfma_f32_16x16x32_bf16 v[40:43], v[132:135], v[156:159], v[40:43]
	ds_read_b64 v[136:137], v191 offset:25344
	ds_read_b64 v[138:139], v191 offset:25376
	ds_read_b64 v[140:141], v191 offset:25408
	ds_read_b64 v[142:143], v191 offset:25440
	s_waitcnt lgkmcnt(0)
	v_mfma_f32_16x16x32_bf16 v[28:31], v[136:139], v[144:147], v[28:31]
	v_mfma_f32_16x16x32_bf16 v[44:47], v[136:139], v[152:155], v[44:47]
	v_mfma_f32_16x16x32_bf16 v[28:31], v[140:143], v[148:151], v[28:31]
	v_mfma_f32_16x16x32_bf16 v[44:47], v[140:143], v[156:159], v[44:47]
	s_branch .Lp4_win_next0

; template <int DH, int NQ, int LDK, class MaskF>
; DEVI void attn_qk(const u16* sK, const bf16x8 (&qf)[NQ][DH / 32], f32x4 (&o)[NQ][DH / 16], float (&m)[NQ], float (&l)[NQ],
;                   float c2, int lane, MaskF valid, bf16x8 (&pb)[NQ][2]) {
;     ...
;   __builtin_amdgcn_s_setprio(1);
; #pragma unroll
;   for (int kt = 0; kt < 4; ++kt) {
; #pragma unroll
;     for (int qt = 0; qt < NQ; ++qt) s[qt][kt] = f32x4{0.f, 0.f, 0.f, 0.f};
; #pragma unroll
;     for (int ks = 0; ks < DH / 32; ++ks) {
;       const bf16x8 kf = *(const bf16x8*)(sK + (16 * kt + col) * LDK + 32 * ks + 8 * quad);
; #pragma unroll
;       for (int qt = 0; qt < NQ; ++qt) s[qt][kt] = mfma16(kf, qf[qt][ks], s[qt][kt]);
;     }
;   }
;   __builtin_amdgcn_s_setprio(0);
; #pragma unroll
;   for (int qt = 0; qt < NQ; ++qt) {
;     float mx = -1e30f;
; #pragma unroll
;     for (int kt = 0; kt < 4; ++kt)
; #pragma unroll
;       for (int r = 0; r < 4; ++r) {
;         const bool v = valid(qt, 16 * kt + 4 * quad + r);
;         const float sv = v ? s[qt][kt][r] : -1e30f;
;         s[qt][kt][r] = sv;
;         mx = fmaxf(mx, sv);
;       }
;     mx = fmaxf(mx, __shfl_xor(mx, 16));
;     mx = fmaxf(mx, __shfl_xor(mx, 32));
;     const float mn = fmaxf(m[qt], mx);
;     const float alpha = fexp2((m[qt] - mn) * c2);
;     m[qt] = mn;
;     const float mc = fmaxf(mn, -1e20f) * c2;
;     float ps = 0.f;
; #pragma unroll
;     for (int kt = 0; kt < 4; ++kt)
; #pragma unroll
;       for (int r = 0; r < 4; ++r) {
;         const float pv = fexp2(__builtin_fmaf(s[qt][kt][r], c2, -mc));
;         ps += pv;
;         s[qt][kt][r] = pv;
;       }
;     l[qt] = l[qt] * alpha + ps;
; #pragma unroll
;     for (int dt = 0; dt < DH / 16; ++dt) o[qt][dt] *= alpha;
; #pragma unroll
;     for (int kk = 0; kk < 2; ++kk) {
;       union { bf16x8 v; unsigned u[4]; } cv;
;       cv.u[0] = pack2(s[qt][2 * kk][0], s[qt][2 * kk][1]);
;       cv.u[1] = pack2(s[qt][2 * kk][2], s[qt][2 * kk][3]);
;       cv.u[2] = pack2(s[qt][2 * kk + 1][0], s[qt][2 * kk + 1][1]);
;       cv.u[3] = pack2(s[qt][2 * kk + 1][2], s[qt][2 * kk + 1][3]);
;       pb[qt][kk] = cv.v;
;     }
;   }
; DEVI void phase_nsa(const Params& p, unsigned char* smem) {
;     ...
;       while (kb >= 0) {
;         const int nkb = (kb < kbmax) ? kb + 1 : -1;
;         __syncthreads();
;         STOREKV_()
;         if (nkb >= 0) { LOADKV_(nkb, C_KW, p.vtw) }
.Lp4_win_buf1:
	s_waitcnt vmcnt(0)
	ds_write_b128 v193, v[160:163] offset:9216
	ds_write_b128 v193, v[164:167] offset:13824
	ds_write_b128 v193, v[168:171] offset:27648
	ds_write_b128 v193, v[172:175] offset:32256
	s_add_u32 s27, s26, 1
	s_cmp_lt_u32 s26, s20
	s_cselect_b32 s27, s27, -1
	s_cmp_lt_i32 s27, 0
	s_cbranch_scc1 .Lp4_win_nold1
	s_lshl_b32 s22, s16, 11
	s_lshl_b32 s23, s27, 6
	s_add_u32 s22, s22, s23
	s_mul_i32 s22, s22, 0x1240
	s_add_u32 s22, s22, s31
	v_add_u32_e32 v211, s22, v201
	v_add_u32_e32 v212, s22, v202
	global_load_dwordx4 v[160:163], v211, s[0:1]
	global_load_dwordx4 v[164:167], v212, s[0:1]
	s_mul_i32 s22, s18, 0x42000
	s_lshl_b32 s23, s27, 7
	s_add_u32 s22, s22, s23
	v_add_u32_e32 v213, s22, v203
	v_add_u32_e32 v214, s22, v204
	global_load_dwordx4 v[168:171], v213, s[42:43]
	global_load_dwordx4 v[172:175], v214, s[42:43]
.Lp4_win_nold1:
	s_waitcnt lgkmcnt(0)
	s_barrier
	s_lshl_b32 s30, s26, 6
	v_lshlrev_b32_e32 v217, 2, v198
	v_sub_u32_e32 v207, v186, v217
	v_lshlrev_b32_e32 v217, 2, v198
	v_sub_u32_e32 v208, v187, v217
	s_add_u32 s23, s30, 63
	s_cmp_le_u32 s23, s19
	s_cselect_b32 s24, 1, 0
	s_add_u32 s23, s30, 0x1e0
	s_cmp_ge_u32 s23, s19
	s_cselect_b32 s24, s24, 0
	s_cmp_eq_u32 s24, 0
	s_cbranch_scc1 .Lp4_win_masked1
	ds_read_b128 v[112:115], v190 offset:9216
	ds_read_b128 v[116:119], v190 offset:9280
	s_waitcnt lgkmcnt(0)
	v_mfma_f32_16x16x32_bf16 v[80:83], v[112:115], v[0:3], 0
	v_mfma_f32_16x16x32_bf16 v[96:99], v[112:115], v[8:11], 0
	v_mfma_f32_16x16x32_bf16 v[80:83], v[116:119], v[4:7], v[80:83]
	v_mfma_f32_16x16x32_bf16 v[96:99], v[116:119], v[12:15], v[96:99]
	ds_read_b128 v[120:123], v190 offset:11520
	ds_read_b128 v[124:127], v190 offset:11584
	s_waitcnt lgkmcnt(0)
	v_mfma_f32_16x16x32_bf16 v[84:87], v[120:123], v[0:3], 0
	v_mfma_f32_16x16x32_bf16 v[100:103], v[120:123], v[8:11], 0
	v_mfma_f32_16x16x32_bf16 v[84:87], v[124:127], v[4:7], v[84:87]
	v_mfma_f32_16x16x32_bf16 v[100:103], v[124:127], v[12:15], v[100:103]
	ds_read_b128 v[128:131], v190 offset:13824
	ds_read_b128 v[132:135], v190 offset:13888
	s_waitcnt lgkmcnt(0)
	v_mfma_f32_16x16x32_bf16 v[88:91], v[128:131], v[0:3], 0
	v_mfma_f32_16x16x32_bf16 v[104:107], v[128:131], v[8:11], 0
	v_mfma_f32_16x16x32_bf16 v[88:91], v[132:135], v[4:7], v[88:91]
	v_mfma_f32_16x16x32_bf16 v[104:107], v[132:135], v[12:15], v[104:107]
	ds_read_b128 v[136:139], v190 offset:16128
	ds_read_b128 v[140:143], v190 offset:16192
	s_waitcnt lgkmcnt(0)
	v_mfma_f32_16x16x32_bf16 v[92:95], v[136:139], v[0:3], 0
	v_mfma_f32_16x16x32_bf16 v[108:111], v[136:139], v[8:11], 0
	v_mfma_f32_16x16x32_bf16 v[92:95], v[140:143], v[4:7], v[92:95]
	v_mfma_f32_16x16x32_bf16 v[108:111], v[140:143], v[12:15], v[108:111]
	s_nop 7
	v_max3_f32 v215, v80, v81, v82
	v_max3_f32 v215, v215, v83, v84
	v_max3_f32 v215, v215, v85, v86
	v_max3_f32 v215, v215, v87, v88
	v_max3_f32 v215, v215, v89, v90
	v_max3_f32 v215, v215, v91, v92
	v_max3_f32 v215, v215, v93, v94
	v_max_f32_e32 v215, v95, v215
	ds_bpermute_b32 v216, v195, v215
	s_waitcnt lgkmcnt(0)
	v_max_f32_e32 v215, v216, v215
	v_mov_b32_e32 v216, v215
	v_mov_b32_e32 v217, v215
	s_nop 1
	v_permlane32_swap_b32_e32 v216, v217
	v_max_f32_e32 v215, v216, v217
	v_max_f32_e32 v218, v182, v215
	v_sub_f32_e32 v219, v182, v218
	v_mul_f32_e32 v219, v200, v219
	v_exp_f32_e32 v219, v219
	v_mov_b32_e32 v182, v218
	v_max_f32_e32 v220, 0xe0ad78ec, v218
	v_mul_f32_e32 v220, 0xbe38aa3b, v220
	v_fma_f32 v80, v80, v200, v220
	v_exp_f32_e32 v80, v80
	v_fma_f32 v81, v81, v200, v220
	v_exp_f32_e32 v81, v81
	v_fma_f32 v82, v82, v200, v220
	v_exp_f32_e32 v82, v82
	v_fma_f32 v83, v83, v200, v220
	v_exp_f32_e32 v83, v83
	v_fma_f32 v84, v84, v200, v220
	v_exp_f32_e32 v84, v84
	v_fma_f32 v85, v85, v200, v220
	v_exp_f32_e32 v85, v85
	v_fma_f32 v86, v86, v200, v220
	v_exp_f32_e32 v86, v86
	v_fma_f32 v87, v87, v200, v220
	v_exp_f32_e32 v87, v87
	v_fma_f32 v88, v88, v200, v220
	v_exp_f32_e32 v88, v88
	v_fma_f32 v89, v89, v200, v220
	v_exp_f32_e32 v89, v89
	v_fma_f32 v90, v90, v200, v220
	v_exp_f32_e32 v90, v90
	v_fma_f32 v91, v91, v200, v220
	v_exp_f32_e32 v91, v91
	v_fma_f32 v92, v92, v200, v220
	v_exp_f32_e32 v92, v92
	v_fma_f32 v93, v93, v200, v220
	v_exp_f32_e32 v93, v93
	v_fma_f32 v94, v94, v200, v220
	v_exp_f32_e32 v94, v94
	v_fma_f32 v95, v95, v200, v220
	v_exp_f32_e32 v95, v95
	s_nop 0
	v_add_f32_e32 v221, v80, v81
	v_add_f32_e32 v221, v82, v221
	v_add_f32_e32 v221, v83, v221
	v_add_f32_e32 v221, v84, v221
	v_add_f32_e32 v221, v85, v221
	v_add_f32_e32 v221, v86, v221
	v_add_f32_e32 v221, v87, v221
	v_add_f32_e32 v221, v88, v221
	v_add_f32_e32 v221, v89, v221
	v_add_f32_e32 v221, v90, v221
	v_add_f32_e32 v221, v91, v221
	v_add_f32_e32 v221, v92, v221
	v_add_f32_e32 v221, v93, v221
	v_add_f32_e32 v221, v94, v221
	v_add_f32_e32 v221, v95, v221
	v_fma_f32 v184, v184, v219, v221
	v_mul_f32_e32 v16, v219, v16
	v_mul_f32_e32 v17, v219, v17
	v_mul_f32_e32 v18, v219, v18
	v_mul_f32_e32 v19, v219, v19
	v_mul_f32_e32 v20, v219, v20
	v_mul_f32_e32 v21, v219, v21
	v_mul_f32_e32 v22, v219, v22
	v_mul_f32_e32 v23, v219, v23
	v_mul_f32_e32 v24, v219, v24
	v_mul_f32_e32 v25, v219, v25
	v_mul_f32_e32 v26, v219, v26
	v_mul_f32_e32 v27, v219, v27
	v_mul_f32_e32 v28, v219, v28
	v_mul_f32_e32 v29, v219, v29
	v_mul_f32_e32 v30, v219, v30
	v_mul_f32_e32 v31, v219, v31
	v_cvt_pk_bf16_f32 v144, v80, v81
	v_cvt_pk_bf16_f32 v145, v82, v83
	v_cvt_pk_bf16_f32 v146, v84, v85
	v_cvt_pk_bf16_f32 v147, v86, v87
	v_cvt_pk_bf16_f32 v148, v88, v89
	v_cvt_pk_bf16_f32 v149, v90, v91
	v_cvt_pk_bf16_f32 v150, v92, v93
	v_cvt_pk_bf16_f32 v151, v94, v95
	v_max3_f32 v215, v96, v97, v98
	v_max3_f32 v215, v215, v99, v100
	v_max3_f32 v215, v215, v101, v102
	v_max3_f32 v215, v215, v103, v104
	v_max3_f32 v215, v215, v105, v106
	v_max3_f32 v215, v215, v107, v108
	v_max3_f32 v215, v215, v109, v110
	v_max_f32_e32 v215, v111, v215
	ds_bpermute_b32 v216, v195, v215
	s_waitcnt lgkmcnt(0)
; DEVI unsigned pack2(float a, float b) { return (unsigned)f2bf(a) | ((unsigned)f2bf(b) << 16); }
; DEVI f32x4 mfma16(bf16x8 a, bf16x8 b, f32x4 c) { return __builtin_amdgcn_mfma_f32_16x16x32_bf16(a, b, c, 0, 0, 0); }
; DEVI float fexp2(float x) { return __builtin_amdgcn_exp2f(x); }
; template <int DH, int NQ, int LDK, class MaskF>
; DEVI void attn_qk(const u16* sK, const bf16x8 (&qf)[NQ][DH / 32], f32x4 (&o)[NQ][DH / 16], float (&m)[NQ], float (&l)[NQ],
;                   float c2, int lane, MaskF valid, bf16x8 (&pb)[NQ][2]) {
;     ...
;     mx = fmaxf(mx, __shfl_xor(mx, 16));
;     mx = fmaxf(mx, __shfl_xor(mx, 32));
;     const float mn = fmaxf(m[qt], mx);
;     const float alpha = fexp2((m[qt] - mn) * c2);
;     m[qt] = mn;
;     const float mc = fmaxf(mn, -1e20f) * c2;
;     float ps = 0.f;
; #pragma unroll
;     for (int kt = 0; kt < 4; ++kt)
; #pragma unroll
;       for (int r = 0; r < 4; ++r) {
;         const float pv = fexp2(__builtin_fmaf(s[qt][kt][r], c2, -mc));
;         ps += pv;
;         s[qt][kt][r] = pv;
;       }
;     l[qt] = l[qt] * alpha + ps;
; #pragma unroll
;     for (int dt = 0; dt < DH / 16; ++dt) o[qt][dt] *= alpha;
; #pragma unroll
;     for (int kk = 0; kk < 2; ++kk) {
;       union { bf16x8 v; unsigned u[4]; } cv;
;       cv.u[0] = pack2(s[qt][2 * kk][0], s[qt][2 * kk][1]);
;       cv.u[1] = pack2(s[qt][2 * kk][2], s[qt][2 * kk][3]);
;       cv.u[2] = pack2(s[qt][2 * kk + 1][0], s[qt][2 * kk + 1][1]);
;       cv.u[3] = pack2(s[qt][2 * kk + 1][2], s[qt][2 * kk + 1][3]);
;       pb[qt][kk] = cv.v;
;     }
;   }
; }
; template <int DH, int NQ, int LDV>
; DEVI void attn_pv(const u16* sVt, const bf16x8 (&pb)[NQ][2], f32x4 (&o)[NQ][DH / 16], int lane) {
;   const int col = lane & 15, quad = lane >> 4;
;   __builtin_amdgcn_s_setprio(1);
; #pragma unroll
;   for (int dt = 0; dt < DH / 16; ++dt) {
; #pragma unroll
;     for (int kk = 0; kk < 2; ++kk) {
;       union { bf16x8 v; uint2 h[2]; } cv;
;       cv.h[0] = *(const uint2*)(sVt + (16 * dt + col) * LDV + 32 * kk + 4 * quad);
;       cv.h[1] = *(const uint2*)(sVt + (16 * dt + col) * LDV + 32 * kk + 16 + 4 * quad);
; #pragma unroll
;       for (int qt = 0; qt < NQ; ++qt) o[qt][dt] = mfma16(cv.v, pb[qt][kk], o[qt][dt]);
;     }
;   }
;   __builtin_amdgcn_s_setprio(0);
	v_max_f32_e32 v215, v216, v215
	v_mov_b32_e32 v216, v215
	v_mov_b32_e32 v217, v215
	s_nop 1
	v_permlane32_swap_b32_e32 v216, v217
	v_max_f32_e32 v215, v216, v217
	v_max_f32_e32 v218, v183, v215
	v_sub_f32_e32 v219, v183, v218
	v_mul_f32_e32 v219, v200, v219
	v_exp_f32_e32 v219, v219
	v_mov_b32_e32 v183, v218
	v_max_f32_e32 v220, 0xe0ad78ec, v218
	v_mul_f32_e32 v220, 0xbe38aa3b, v220
	v_fma_f32 v96, v96, v200, v220
	v_exp_f32_e32 v96, v96
	v_fma_f32 v97, v97, v200, v220
	v_exp_f32_e32 v97, v97
	v_fma_f32 v98, v98, v200, v220
	v_exp_f32_e32 v98, v98
	v_fma_f32 v99, v99, v200, v220
	v_exp_f32_e32 v99, v99
	v_fma_f32 v100, v100, v200, v220
	v_exp_f32_e32 v100, v100
	v_fma_f32 v101, v101, v200, v220
	v_exp_f32_e32 v101, v101
	v_fma_f32 v102, v102, v200, v220
	v_exp_f32_e32 v102, v102
	v_fma_f32 v103, v103, v200, v220
	v_exp_f32_e32 v103, v103
	v_fma_f32 v104, v104, v200, v220
	v_exp_f32_e32 v104, v104
	v_fma_f32 v105, v105, v200, v220
	v_exp_f32_e32 v105, v105
	v_fma_f32 v106, v106, v200, v220
	v_exp_f32_e32 v106, v106
	v_fma_f32 v107, v107, v200, v220
	v_exp_f32_e32 v107, v107
	v_fma_f32 v108, v108, v200, v220
	v_exp_f32_e32 v108, v108
	v_fma_f32 v109, v109, v200, v220
	v_exp_f32_e32 v109, v109
	v_fma_f32 v110, v110, v200, v220
	v_exp_f32_e32 v110, v110
	v_fma_f32 v111, v111, v200, v220
	v_exp_f32_e32 v111, v111
	s_nop 0
	v_add_f32_e32 v221, v96, v97
	v_add_f32_e32 v221, v98, v221
	v_add_f32_e32 v221, v99, v221
	v_add_f32_e32 v221, v100, v221
	v_add_f32_e32 v221, v101, v221
	v_add_f32_e32 v221, v102, v221
	v_add_f32_e32 v221, v103, v221
	v_add_f32_e32 v221, v104, v221
	v_add_f32_e32 v221, v105, v221
	v_add_f32_e32 v221, v106, v221
	v_add_f32_e32 v221, v107, v221
	v_add_f32_e32 v221, v108, v221
	v_add_f32_e32 v221, v109, v221
	v_add_f32_e32 v221, v110, v221
	v_add_f32_e32 v221, v111, v221
	v_fma_f32 v185, v185, v219, v221
	v_mul_f32_e32 v32, v219, v32
	v_mul_f32_e32 v33, v219, v33
	v_mul_f32_e32 v34, v219, v34
	v_mul_f32_e32 v35, v219, v35
	v_mul_f32_e32 v36, v219, v36
	v_mul_f32_e32 v37, v219, v37
	v_mul_f32_e32 v38, v219, v38
	v_mul_f32_e32 v39, v219, v39
	v_mul_f32_e32 v40, v219, v40
	v_mul_f32_e32 v41, v219, v41
	v_mul_f32_e32 v42, v219, v42
	v_mul_f32_e32 v43, v219, v43
	v_mul_f32_e32 v44, v219, v44
	v_mul_f32_e32 v45, v219, v45
	v_mul_f32_e32 v46, v219, v46
	v_mul_f32_e32 v47, v219, v47
	v_cvt_pk_bf16_f32 v152, v96, v97
	v_cvt_pk_bf16_f32 v153, v98, v99
	v_cvt_pk_bf16_f32 v154, v100, v101
	v_cvt_pk_bf16_f32 v155, v102, v103
	v_cvt_pk_bf16_f32 v156, v104, v105
	v_cvt_pk_bf16_f32 v157, v106, v107
	v_cvt_pk_bf16_f32 v158, v108, v109
	v_cvt_pk_bf16_f32 v159, v110, v111
	ds_read_b64 v[112:113], v191 offset:27648
	ds_read_b64 v[114:115], v191 offset:27680
	ds_read_b64 v[116:117], v191 offset:27712
	ds_read_b64 v[118:119], v191 offset:27744
	s_waitcnt lgkmcnt(0)
	v_mfma_f32_16x16x32_bf16 v[16:19], v[112:115], v[144:147], v[16:19]
	v_mfma_f32_16x16x32_bf16 v[32:35], v[112:115], v[152:155], v[32:35]
	v_mfma_f32_16x16x32_bf16 v[16:19], v[116:119], v[148:151], v[16:19]
	v_mfma_f32_16x16x32_bf16 v[32:35], v[116:119], v[156:159], v[32:35]
	ds_read_b64 v[120:121], v191 offset:29952
	ds_read_b64 v[122:123], v191 offset:29984
	ds_read_b64 v[124:125], v191 offset:30016
	ds_read_b64 v[126:127], v191 offset:30048
	s_waitcnt lgkmcnt(0)
	v_mfma_f32_16x16x32_bf16 v[20:23], v[120:123], v[144:147], v[20:23]
	v_mfma_f32_16x16x32_bf16 v[36:39], v[120:123], v[152:155], v[36:39]
	v_mfma_f32_16x16x32_bf16 v[20:23], v[124:127], v[148:151], v[20:23]
	v_mfma_f32_16x16x32_bf16 v[36:39], v[124:127], v[156:159], v[36:39]
	ds_read_b64 v[128:129], v191 offset:32256
	ds_read_b64 v[130:131], v191 offset:32288
	ds_read_b64 v[132:133], v191 offset:32320
	ds_read_b64 v[134:135], v191 offset:32352
	s_waitcnt lgkmcnt(0)
	v_mfma_f32_16x16x32_bf16 v[24:27], v[128:131], v[144:147], v[24:27]
	v_mfma_f32_16x16x32_bf16 v[40:43], v[128:131], v[152:155], v[40:43]
	v_mfma_f32_16x16x32_bf16 v[24:27], v[132:135], v[148:151], v[24:27]
	v_mfma_f32_16x16x32_bf16 v[40:43], v[132:135], v[156:159], v[40:43]
	ds_read_b64 v[136:137], v191 offset:34560
	ds_read_b64 v[138:139], v191 offset:34592
	ds_read_b64 v[140:141], v191 offset:34624
	ds_read_b64 v[142:143], v191 offset:34656
	s_waitcnt lgkmcnt(0)
	v_mfma_f32_16x16x32_bf16 v[28:31], v[136:139], v[144:147], v[28:31]
	v_mfma_f32_16x16x32_bf16 v[44:47], v[136:139], v[152:155], v[44:47]
	v_mfma_f32_16x16x32_bf16 v[28:31], v[140:143], v[148:151], v[28:31]
	v_mfma_f32_16x16x32_bf16 v[44:47], v[140:143], v[156:159], v[44:47]
	s_branch .Lp4_win_next1

; DEVI unsigned pack2(float a, float b) { return (unsigned)f2bf(a) | ((unsigned)f2bf(b) << 16); }
; DEVI void phase_nsa(const Params& p, unsigned char* smem) {
;     ...
; #pragma unroll
;       for (int qt = 0; qt < 2; ++qt) {
;         float lt = l[qt];
;         lt += __shfl_xor(lt, 16);
;         lt += __shfl_xor(lt, 32);
;         const float sc = lt > 0.f ? gate[qt][2] / lt : 0.f;
; #pragma unroll
;         for (int dt = 0; dt < 4; ++dt) comb[qt][dt] += o[qt][dt] * sc;
;       }
;     }
; #pragma unroll
;     for (int qt = 0; qt < 2; ++qt) {
;       const size_t tok = (size_t)b * T + tq[qt];
; #pragma unroll
;       for (int dt = 0; dt < 4; ++dt) {
;         uint2 pk;
;         pk.x = pack2(comb[qt][dt][0], comb[qt][dt][1]);
;         pk.y = pack2(comb[qt][dt][2], comb[qt][dt][3]);
;         *(uint2*)(p.mix + tok * LDA + 512 + h * 64 + 16 * dt + 4 * quad) = pk;
;       }
;     }
; DEVI void xcd_barrier(const XcdBarrier& b) {
;   asm volatile("s_waitcnt vmcnt(0)" ::: "memory");
;   __syncthreads();
;   if (threadIdx.x == 0) {
;     unsigned* bar = b.bar;
;     __builtin_amdgcn_s_waitcnt(0);
;     unsigned nloc = b.st[0], nx = b.st[1];
;     if (nloc == 0u) { xcd_barrier_complete(bar, b.x, nloc, nx); b.st[0] = nloc; b.st[1] = nx; }
.Lp4_win_end:
	s_nop 7
	v_mov_b32_e32 v215, v184
	ds_bpermute_b32 v216, v195, v215
	s_waitcnt lgkmcnt(0)
	v_add_f32_e32 v215, v216, v215
	v_mov_b32_e32 v216, v215
	v_mov_b32_e32 v217, v215
	s_nop 1
	v_permlane32_swap_b32_e32 v216, v217
	v_add_f32_e32 v215, v216, v217
	v_rcp_f32_e32 v218, v215
	s_nop 0
	v_fma_f32 v219, -v215, v218, 1.0
	v_fma_f32 v218, v219, v218, v218
	v_mul_f32_e32 v218, v178, v218
	v_cmp_lt_f32_e64 s[32:33], 0, v215
	v_mov_b32_e32 v220, 0
	s_nop 0
	v_cndmask_b32_e64 v218, v220, v218, s[32:33]
	v_fma_f32 v48, v16, v218, v48
	v_fma_f32 v49, v17, v218, v49
	v_fma_f32 v50, v18, v218, v50
	v_fma_f32 v51, v19, v218, v51
	v_fma_f32 v52, v20, v218, v52
	v_fma_f32 v53, v21, v218, v53
	v_fma_f32 v54, v22, v218, v54
	v_fma_f32 v55, v23, v218, v55
	v_fma_f32 v56, v24, v218, v56
	v_fma_f32 v57, v25, v218, v57
	v_fma_f32 v58, v26, v218, v58
	v_fma_f32 v59, v27, v218, v59
	v_fma_f32 v60, v28, v218, v60
	v_fma_f32 v61, v29, v218, v61
	v_fma_f32 v62, v30, v218, v62
	v_fma_f32 v63, v31, v218, v63
	v_mov_b32_e32 v215, v185
	ds_bpermute_b32 v216, v195, v215
	s_waitcnt lgkmcnt(0)
	v_add_f32_e32 v215, v216, v215
	v_mov_b32_e32 v216, v215
	v_mov_b32_e32 v217, v215
	s_nop 1
	v_permlane32_swap_b32_e32 v216, v217
	v_add_f32_e32 v215, v216, v217
	v_rcp_f32_e32 v218, v215
	s_nop 0
	v_fma_f32 v219, -v215, v218, 1.0
	v_fma_f32 v218, v219, v218, v218
	v_mul_f32_e32 v218, v181, v218
	v_cmp_lt_f32_e64 s[32:33], 0, v215
	v_mov_b32_e32 v220, 0
	s_nop 0
	v_cndmask_b32_e64 v218, v220, v218, s[32:33]
	v_fma_f32 v64, v32, v218, v64
	v_fma_f32 v65, v33, v218, v65
	v_fma_f32 v66, v34, v218, v66
	v_fma_f32 v67, v35, v218, v67
	v_fma_f32 v68, v36, v218, v68
	v_fma_f32 v69, v37, v218, v69
	v_fma_f32 v70, v38, v218, v70
	v_fma_f32 v71, v39, v218, v71
	v_fma_f32 v72, v40, v218, v72
	v_fma_f32 v73, v41, v218, v73
	v_fma_f32 v74, v42, v218, v74
	v_fma_f32 v75, v43, v218, v75
	v_fma_f32 v76, v44, v218, v76
	v_fma_f32 v77, v45, v218, v77
	v_fma_f32 v78, v46, v218, v78
	v_fma_f32 v79, v47, v218, v79
	v_lshrrev_b32_e32 v217, 6, v210
	v_mul_u32_u24_e32 v215, 0x880, v197
	v_lshl_add_u32 v215, v217, 7, v215
	v_lshl_add_u32 v215, v198, 3, v215
	s_lshl_b32 s22, s16, 11
	s_add_u32 s22, s22, s19
	s_mul_i32 s22, s22, 0x880
	s_lshl_b32 s23, s17, 9
	s_add_u32 s22, s22, s23
	s_add_u32 s22, s22, 0x400
	v_add_u32_e32 v215, s22, v215
	v_add_u32_e32 v216, 0x8800, v215
	v_cvt_pk_bf16_f32 v112, v48, v49
	v_cvt_pk_bf16_f32 v113, v50, v51
	global_store_dwordx2 v215, v[112:113], s[2:3]
	v_cvt_pk_bf16_f32 v114, v52, v53
	v_cvt_pk_bf16_f32 v115, v54, v55
	global_store_dwordx2 v215, v[114:115], s[2:3] offset:32
	v_cvt_pk_bf16_f32 v116, v56, v57
	v_cvt_pk_bf16_f32 v117, v58, v59
	global_store_dwordx2 v215, v[116:117], s[2:3] offset:64
	v_cvt_pk_bf16_f32 v118, v60, v61
	v_cvt_pk_bf16_f32 v119, v62, v63
	global_store_dwordx2 v215, v[118:119], s[2:3] offset:96
	v_cvt_pk_bf16_f32 v116, v64, v65
	v_cvt_pk_bf16_f32 v117, v66, v67
	global_store_dwordx2 v216, v[116:117], s[2:3]
	v_cvt_pk_bf16_f32 v118, v68, v69
	v_cvt_pk_bf16_f32 v119, v70, v71
	global_store_dwordx2 v216, v[118:119], s[2:3] offset:32
	v_cvt_pk_bf16_f32 v112, v72, v73
	v_cvt_pk_bf16_f32 v113, v74, v75
	global_store_dwordx2 v216, v[112:113], s[2:3] offset:64
	v_cvt_pk_bf16_f32 v114, v76, v77
	v_cvt_pk_bf16_f32 v115, v78, v79
	global_store_dwordx2 v216, v[114:115], s[2:3] offset:96
	s_add_u32 s14, s14, s15
	s_cmp_lt_u32 s14, 0x800
	s_cbranch_scc1 .Lp4_tile
.Lp4_done:
	s_waitcnt vmcnt(0)
.LBB0_834:
	v_readlane_b32 s68, v247, 44
	v_readlane_b32 s69, v247, 45
	s_load_dwordx2 s[64:65], s[68:69], 0x1f0
	v_readlane_b32 s70, v247, 42
	s_cmp_lt_i32 s89, 5
	v_readlane_b32 s66, v247, 46
	v_readlane_b32 s90, v247, 47
	v_readlane_b32 s71, v247, 43
	s_cbranch_scc1 .LBB0_888
	s_waitcnt vmcnt(0)
	s_waitcnt lgkmcnt(0)
	s_barrier
	s_mov_b64 s[0:1], exec
	v_readlane_b32 s2, v248, 24
	v_readlane_b32 s3, v248, 25
	s_and_b64 s[2:3], s[0:1], s[2:3]
	s_mov_b64 exec, s[2:3]
	s_cbranch_execz .LBB0_887
	v_mov_b32_e32 v0, 0x12000
	s_waitcnt vmcnt(0) expcnt(0) lgkmcnt(0)
	ds_read_b32 v2, v0
	v_mov_b32_e32 v0, 0x12004
	ds_read_b32 v0, v0
	s_waitcnt lgkmcnt(1)
	v_cmp_ne_u32_e32 vcc, 0, v2
	s_cbranch_vccnz .LBB0_851
	s_load_dwordx2 s[6:7], s[68:69], 0x200
	s_load_dword s5, s[68:69], 0x208
	s_add_u32 s2, s64, 0x1000
	s_addc_u32 s3, s65, 0
	s_add_u32 s4, s64, 0x1100
	s_waitcnt lgkmcnt(0)
	s_mul_i32 s16, s7, s6
	s_mul_i32 s16, s16, s5
	s_addc_u32 s5, s65, 0
	s_add_u32 s6, s64, 0x1200
	s_addc_u32 s7, s65, 0
	s_add_u32 s8, s64, 0x1300
	s_addc_u32 s9, s65, 0
	s_mov_b32 s17, 1
	v_mov_b32_e32 v16, 0
	s_branch .LBB0_839

; DEVI int launder(int x) { asm volatile("" : "+v"(x)); return x; }
; #define LOADK_(kbx) LK1_(0, kbx) LK1_(1, kbx) LK1_(2, kbx) LK1_(3, kbx) LK1_(4, kbx) LK1_(5, kbx) LK1_(6, kbx) LK1_(7, kbx)
; #define STOREK_() SK1_(0) SK1_(1) SK1_(2) SK1_(3) SK1_(4) SK1_(5) SK1_(6) SK1_(7)
; #define LOADV_(kbx) LV1_(0, kbx) LV1_(1, kbx) LV1_(2, kbx) LV1_(3, kbx) LV1_(4, kbx) LV1_(5, kbx) LV1_(6, kbx) LV1_(7, kbx)
; DEVI void phase_memattn(const Params& p, unsigned char* smem) {
;   u16* sK = (u16*)smem;
;   u16* sVt = (u16*)(smem + 33792);
;   const float c2 = 0.0625f * 1.4426950408889634f;
; #pragma unroll 1
;   for (int tile = blockIdx.x; tile < 2048; tile += gridDim.x) {
;     const int tid = launder(threadIdx.x), lane = tid & 63, w = tid >> 6, col = lane & 15, quad = lane >> 4;
;     const int b = tile >> 7, head = (tile >> 5) & 3, q0 = (tile & 31) * 64;
;     const size_t tok = (size_t)b * T + q0 + 16 * w + col;
;     bf16x8 qf[1][8];
; #pragma unroll
;     for (int ks = 0; ks < 8; ++ks) qf[0][ks] = *(const bf16x8*)(p.qm + tok * LDA + head * 256 + 32 * ks + 8 * quad);
;     float m[1] = {-1e30f}, l[1] = {0.f};
;     f32x4 o[1][16];
; #pragma unroll
;     for (int dt = 0; dt < 16; ++dt) o[0][dt] = f32x4{0.f, 0.f, 0.f, 0.f};
;     uint4 rg0, rg1, rg2, rg3, rg4, rg5, rg6, rg7;
;     const int krow = tid >> 5, kch = (tid & 31) << 3;
;     const int vrow = tid >> 3, vch = (tid & 7) << 3;
;     ...
;     __syncthreads();
;     LOADK_(0)
;     STOREK_()
;     LOADV_(0)
;     __syncthreads();
.LBB0_1020:
	s_cmp_gt_i32 s88, 7
	s_cselect_b64 s[0:1], -1, 0
	s_cmp_lt_i32 s89, 7
	s_cselect_b64 s[2:3], -1, 0
	s_or_b64 s[0:1], s[0:1], s[2:3]
	s_and_b64 vcc, exec, s[0:1]
	s_cbranch_vccnz .LBB0_1085
	s_load_dwordx2 s[0:1], s[68:69], 0x1e0
	s_load_dwordx2 s[2:3], s[68:69], 0x118
	s_load_dwordx2 s[4:5], s[68:69], 0x120
	s_load_dwordx2 s[6:7], s[68:69], 0xf0
	s_load_dword s9, s[68:69], 0x200
	s_mov_b32 s8, s90
	v_and_b32_e32 v231, 15, v210
	v_bfe_u32 v232, v210, 4, 2
	v_lshrrev_b32_e32 v233, 6, v210
	v_lshl_add_u32 v234, v233, 4, v231
	v_mul_u32_u24_e32 v234, 0x880, v234
	v_lshl_add_u32 v220, v232, 4, v234
	v_lshl_add_u32 v227, v232, 3, v234
	v_lshrrev_b32_e32 v235, 5, v210
	v_and_b32_e32 v236, 31, v210
	v_lshlrev_b32_e32 v236, 4, v236
	v_mul_u32_u24_e32 v221, 0x880, v235
	v_add_u32_e32 v221, v236, v221
	v_mul_u32_u24_e32 v223, 0x210, v235
	v_add_u32_e32 v223, v236, v223
	v_lshrrev_b32_e32 v235, 3, v210
	v_and_b32_e32 v236, 7, v210
	v_lshlrev_b32_e32 v236, 4, v236
	v_lshl_add_u32 v222, v235, 9, v236
	v_mul_u32_u24_e32 v224, 0x90, v235
	v_add_u32_e32 v224, v236, v224
	v_add_u32_e32 v224, 0x8400, v224
	v_mul_u32_u24_e32 v225, 0x210, v231
	v_lshl_add_u32 v225, v232, 4, v225
	v_mul_u32_u24_e32 v226, 0x90, v231
	v_lshl_add_u32 v226, v232, 3, v226
	v_add_u32_e32 v226, 0x8400, v226
	v_and_b32_e32 v235, 63, v210
	v_xor_b32_e32 v228, 16, v235
	v_lshlrev_b32_e32 v228, 2, v228
	v_mov_b32_e32 v242, 0x3db8aa3b
	s_waitcnt lgkmcnt(0)
	s_cmp_ge_u32 s8, 0x800
	s_cbranch_scc1 .Lp7_done
.Lp7_tile:
	s_lshr_b32 s10, s8, 7
	s_bfe_u32 s11, s8, 0x20005
	s_and_b32 s12, s8, 31
	s_lshl_b32 s12, s12, 6
	s_lshl_b32 s14, s11, 9
	s_lshl_b32 s13, s10, 11
	s_add_u32 s13, s13, s12
	s_mul_i32 s13, s13, 0x880
	s_add_u32 s13, s13, s14
	v_add_u32_e32 v231, s13, v220
	global_load_dwordx4 v[0:3], v231, s[0:1]
	global_load_dwordx4 v[4:7], v231, s[0:1] offset:64
	global_load_dwordx4 v[8:11], v231, s[0:1] offset:128
	global_load_dwordx4 v[12:15], v231, s[0:1] offset:192
	global_load_dwordx4 v[16:19], v231, s[0:1] offset:256
	global_load_dwordx4 v[20:23], v231, s[0:1] offset:320
	global_load_dwordx4 v[24:27], v231, s[0:1] offset:384
	global_load_dwordx4 v[28:31], v231, s[0:1] offset:448
	s_mul_i32 s16, s10, 0x88000
	s_add_u32 s16, s16, s14
	v_add_u32_e32 v231, s16, v221
	global_load_dwordx4 v[144:147], v231, s[2:3]
	s_add_u32 s16, s16, 0x4400
	v_add_u32_e32 v232, s16, v221
	global_load_dwordx4 v[148:151], v232, s[2:3]
	s_add_u32 s16, s16, 0x4400
	v_add_u32_e32 v233, s16, v221
	global_load_dwordx4 v[152:155], v233, s[2:3]
	s_add_u32 s16, s16, 0x4400
	v_add_u32_e32 v234, s16, v221
	global_load_dwordx4 v[156:159], v234, s[2:3]
	s_add_u32 s16, s16, 0x4400
	v_add_u32_e32 v231, s16, v221
	global_load_dwordx4 v[160:163], v231, s[2:3]
	s_add_u32 s16, s16, 0x4400
	v_add_u32_e32 v232, s16, v221
	global_load_dwordx4 v[164:167], v232, s[2:3]
	s_add_u32 s16, s16, 0x4400
	v_add_u32_e32 v233, s16, v221
	global_load_dwordx4 v[168:171], v233, s[2:3]
	s_add_u32 s16, s16, 0x4400
	v_add_u32_e32 v234, s16, v221
	global_load_dwordx4 v[172:175], v234, s[2:3]
	v_mov_b32_e32 v229, 0xf149f2ca
	v_mov_b32_e32 v230, 0
	s_waitcnt vmcnt(0)
	ds_write_b128 v223, v[144:147]
	ds_write_b128 v223, v[148:151] offset:4224
	ds_write_b128 v223, v[152:155] offset:8448
	ds_write_b128 v223, v[156:159] offset:12672
	ds_write_b128 v223, v[160:163] offset:16896
	ds_write_b128 v223, v[164:167] offset:21120
	ds_write_b128 v223, v[168:171] offset:25344
	ds_write_b128 v223, v[172:175] offset:29568
	s_lshl_b32 s16, s10, 2
	s_add_u32 s16, s16, s11
	s_lshl_b32 s16, s16, 17
	v_add_u32_e32 v231, s16, v222
	global_load_dwordx4 v[176:179], v231, s[4:5]
	s_add_u32 s16, s16, 0x4000
	v_add_u32_e32 v232, s16, v222
	global_load_dwordx4 v[180:183], v232, s[4:5]
	s_add_u32 s16, s16, 0x4000
	v_add_u32_e32 v233, s16, v222
	global_load_dwordx4 v[184:187], v233, s[4:5]
	s_add_u32 s16, s16, 0x4000
	v_add_u32_e32 v234, s16, v222
	global_load_dwordx4 v[188:191], v234, s[4:5]
	s_add_u32 s16, s16, 0x4000
	v_add_u32_e32 v231, s16, v222
	global_load_dwordx4 v[192:195], v231, s[4:5]
	s_add_u32 s16, s16, 0x4000
	v_add_u32_e32 v232, s16, v222
	global_load_dwordx4 v[196:199], v232, s[4:5]
	s_add_u32 s16, s16, 0x4000
	v_add_u32_e32 v233, s16, v222
	global_load_dwordx4 v[200:203], v233, s[4:5]
	s_add_u32 s16, s16, 0x4000
	v_add_u32_e32 v234, s16, v222
	global_load_dwordx4 v[204:207], v234, s[4:5]
	s_mul_i32 s16, s10, 0x88000
	s_add_u32 s16, s16, s14
	s_add_u32 s16, s16, 0x22000
	v_add_u32_e32 v231, s16, v221
	global_load_dwordx4 v[144:147], v231, s[2:3]
	s_add_u32 s16, s16, 0x4400
	v_add_u32_e32 v232, s16, v221
	global_load_dwordx4 v[148:151], v232, s[2:3]
	s_add_u32 s16, s16, 0x4400
	v_add_u32_e32 v233, s16, v221
	global_load_dwordx4 v[152:155], v233, s[2:3]
	s_add_u32 s16, s16, 0x4400
	v_add_u32_e32 v234, s16, v221
	global_load_dwordx4 v[156:159], v234, s[2:3]
	s_add_u32 s16, s16, 0x4400
	v_add_u32_e32 v231, s16, v221
	global_load_dwordx4 v[160:163], v231, s[2:3]
	s_add_u32 s16, s16, 0x4400
	v_add_u32_e32 v232, s16, v221
	global_load_dwordx4 v[164:167], v232, s[2:3]
	s_add_u32 s16, s16, 0x4400
	v_add_u32_e32 v233, s16, v221
	global_load_dwordx4 v[168:171], v233, s[2:3]
	s_add_u32 s16, s16, 0x4400
	v_add_u32_e32 v234, s16, v221
	global_load_dwordx4 v[172:175], v234, s[2:3]
	s_waitcnt lgkmcnt(0)
	s_barrier
; template <int DH, int NQ, int LDK, class MaskF>
; DEVI void attn_qk(const u16* sK, const bf16x8 (&qf)[NQ][DH / 32], f32x4 (&o)[NQ][DH / 16], float (&m)[NQ], float (&l)[NQ],
;                   float c2, int lane, MaskF valid, bf16x8 (&pb)[NQ][2]) {
;     ...
;   __builtin_amdgcn_s_setprio(1);
; #pragma unroll
;   for (int kt = 0; kt < 4; ++kt) {
; #pragma unroll
;     for (int qt = 0; qt < NQ; ++qt) s[qt][kt] = f32x4{0.f, 0.f, 0.f, 0.f};
; #pragma unroll
;     for (int ks = 0; ks < DH / 32; ++ks) {
;       const bf16x8 kf = *(const bf16x8*)(sK + (16 * kt + col) * LDK + 32 * ks + 8 * quad);
; #pragma unroll
;       for (int qt = 0; qt < NQ; ++qt) s[qt][kt] = mfma16(kf, qf[qt][ks], s[qt][kt]);
;     }
;   }
;   __builtin_amdgcn_s_setprio(0);
; #pragma unroll
;   for (int qt = 0; qt < NQ; ++qt) {
;     float mx = -1e30f;
; #pragma unroll
;     for (int kt = 0; kt < 4; ++kt)
; #pragma unroll
;       for (int r = 0; r < 4; ++r) {
;         const bool v = valid(qt, 16 * kt + 4 * quad + r);
;         const float sv = v ? s[qt][kt][r] : -1e30f;
;         s[qt][kt][r] = sv;
;         mx = fmaxf(mx, sv);
;       }
;     mx = fmaxf(mx, __shfl_xor(mx, 16));
;     mx = fmaxf(mx, __shfl_xor(mx, 32));
;     const float mn = fmaxf(m[qt], mx);
;     const float alpha = fexp2((m[qt] - mn) * c2);
;     m[qt] = mn;
;     const float mc = fmaxf(mn, -1e20f) * c2;
;     float ps = 0.f;
; #pragma unroll
;     for (int kt = 0; kt < 4; ++kt)
; #pragma unroll
;       for (int r = 0; r < 4; ++r) {
;         const float pv = fexp2(__builtin_fmaf(s[qt][kt][r], c2, -mc));
;         ps += pv;
;         s[qt][kt][r] = pv;
;       }
;     l[qt] = l[qt] * alpha + ps;
; #pragma unroll
;     for (int dt = 0; dt < DH / 16; ++dt) o[qt][dt] *= alpha;
; #pragma unroll
;     for (int kk = 0; kk < 2; ++kk) {
;       union { bf16x8 v; unsigned u[4]; } cv;
;       cv.u[0] = pack2(s[qt][2 * kk][0], s[qt][2 * kk][1]);
;       cv.u[1] = pack2(s[qt][2 * kk][2], s[qt][2 * kk][3]);
;       cv.u[2] = pack2(s[qt][2 * kk + 1][0], s[qt][2 * kk + 1][1]);
;       cv.u[3] = pack2(s[qt][2 * kk + 1][2], s[qt][2 * kk + 1][3]);
;       pb[qt][kk] = cv.v;
;     }
;   }
; DEVI void phase_memattn(const Params& p, unsigned char* smem) {
;     ...
;     for (int kb = 0; kb < 4; ++kb) {
;       bf16x8 pb[1][2];
;       attn_qk<256, 1, 264>(sK, qf, o, m, l, c2, lane, [&](int, int) { return true; }, pb);
;       STOREV_()
	ds_read_b128 v[112:115], v225
	ds_read_b128 v[116:119], v225 offset:64
	ds_read_b128 v[120:123], v225 offset:128
	ds_read_b128 v[124:127], v225 offset:192
	ds_read_b128 v[128:131], v225 offset:256
	ds_read_b128 v[132:135], v225 offset:320
	ds_read_b128 v[136:139], v225 offset:384
	ds_read_b128 v[140:143], v225 offset:448
	s_waitcnt lgkmcnt(4)
	v_mfma_f32_16x16x32_bf16 v[96:99], v[112:115], v[0:3], 0
	v_mfma_f32_16x16x32_bf16 v[96:99], v[116:119], v[4:7], v[96:99]
	v_mfma_f32_16x16x32_bf16 v[96:99], v[120:123], v[8:11], v[96:99]
	v_mfma_f32_16x16x32_bf16 v[96:99], v[124:127], v[12:15], v[96:99]
	ds_read_b128 v[112:115], v225 offset:8448
	ds_read_b128 v[116:119], v225 offset:8512
	ds_read_b128 v[120:123], v225 offset:8576
	ds_read_b128 v[124:127], v225 offset:8640
	s_waitcnt lgkmcnt(4)
	v_mfma_f32_16x16x32_bf16 v[96:99], v[128:131], v[16:19], v[96:99]
	v_mfma_f32_16x16x32_bf16 v[96:99], v[132:135], v[20:23], v[96:99]
	v_mfma_f32_16x16x32_bf16 v[96:99], v[136:139], v[24:27], v[96:99]
	v_mfma_f32_16x16x32_bf16 v[96:99], v[140:143], v[28:31], v[96:99]
	ds_read_b128 v[128:131], v225 offset:8704
	ds_read_b128 v[132:135], v225 offset:8768
	ds_read_b128 v[136:139], v225 offset:8832
	ds_read_b128 v[140:143], v225 offset:8896
	s_waitcnt lgkmcnt(4)
	v_mfma_f32_16x16x32_bf16 v[100:103], v[112:115], v[0:3], 0
	v_mfma_f32_16x16x32_bf16 v[100:103], v[116:119], v[4:7], v[100:103]
	v_mfma_f32_16x16x32_bf16 v[100:103], v[120:123], v[8:11], v[100:103]
	v_mfma_f32_16x16x32_bf16 v[100:103], v[124:127], v[12:15], v[100:103]
	ds_read_b128 v[112:115], v225 offset:16896
	ds_read_b128 v[116:119], v225 offset:16960
	ds_read_b128 v[120:123], v225 offset:17024
	ds_read_b128 v[124:127], v225 offset:17088
	s_waitcnt lgkmcnt(4)
	v_mfma_f32_16x16x32_bf16 v[100:103], v[128:131], v[16:19], v[100:103]
	v_mfma_f32_16x16x32_bf16 v[100:103], v[132:135], v[20:23], v[100:103]
	v_mfma_f32_16x16x32_bf16 v[100:103], v[136:139], v[24:27], v[100:103]
	v_mfma_f32_16x16x32_bf16 v[100:103], v[140:143], v[28:31], v[100:103]
	ds_read_b128 v[128:131], v225 offset:17152
	ds_read_b128 v[132:135], v225 offset:17216
	ds_read_b128 v[136:139], v225 offset:17280
	ds_read_b128 v[140:143], v225 offset:17344
	s_waitcnt lgkmcnt(4)
	v_mfma_f32_16x16x32_bf16 v[104:107], v[112:115], v[0:3], 0
	v_mfma_f32_16x16x32_bf16 v[104:107], v[116:119], v[4:7], v[104:107]
	v_mfma_f32_16x16x32_bf16 v[104:107], v[120:123], v[8:11], v[104:107]
	v_mfma_f32_16x16x32_bf16 v[104:107], v[124:127], v[12:15], v[104:107]
	ds_read_b128 v[112:115], v225 offset:25344
	ds_read_b128 v[116:119], v225 offset:25408
	ds_read_b128 v[120:123], v225 offset:25472
	ds_read_b128 v[124:127], v225 offset:25536
	s_waitcnt lgkmcnt(4)
	v_mfma_f32_16x16x32_bf16 v[104:107], v[128:131], v[16:19], v[104:107]
	v_mfma_f32_16x16x32_bf16 v[104:107], v[132:135], v[20:23], v[104:107]
	v_mfma_f32_16x16x32_bf16 v[104:107], v[136:139], v[24:27], v[104:107]
	v_mfma_f32_16x16x32_bf16 v[104:107], v[140:143], v[28:31], v[104:107]
	ds_read_b128 v[128:131], v225 offset:25600
	ds_read_b128 v[132:135], v225 offset:25664
	ds_read_b128 v[136:139], v225 offset:25728
	ds_read_b128 v[140:143], v225 offset:25792
	s_waitcnt lgkmcnt(4)
	v_mfma_f32_16x16x32_bf16 v[108:111], v[112:115], v[0:3], 0
	v_mfma_f32_16x16x32_bf16 v[108:111], v[116:119], v[4:7], v[108:111]
	v_mfma_f32_16x16x32_bf16 v[108:111], v[120:123], v[8:11], v[108:111]
	v_mfma_f32_16x16x32_bf16 v[108:111], v[124:127], v[12:15], v[108:111]
	s_waitcnt lgkmcnt(0)
	v_mfma_f32_16x16x32_bf16 v[108:111], v[128:131], v[16:19], v[108:111]
	v_mfma_f32_16x16x32_bf16 v[108:111], v[132:135], v[20:23], v[108:111]
	v_mfma_f32_16x16x32_bf16 v[108:111], v[136:139], v[24:27], v[108:111]
	v_mfma_f32_16x16x32_bf16 v[108:111], v[140:143], v[28:31], v[108:111]
	s_nop 7
	v_max3_f32 v235, v96, v97, v98
	v_max3_f32 v235, v235, v99, v100
	v_max3_f32 v235, v235, v101, v102
	v_max3_f32 v235, v235, v103, v104
	v_max3_f32 v235, v235, v105, v106
	v_max3_f32 v235, v235, v107, v108
	v_max3_f32 v235, v235, v109, v110
	v_max_f32_e32 v235, v111, v235
	ds_bpermute_b32 v236, v228, v235
	s_waitcnt lgkmcnt(0)
	v_max_f32_e32 v235, v236, v235
	v_mov_b32_e32 v236, v235
	v_mov_b32_e32 v237, v235
	s_nop 1
	v_permlane32_swap_b32_e32 v236, v237
	v_max_f32_e32 v235, v236, v237
	v_max_f32_e32 v238, v229, v235
	v_sub_f32_e32 v239, v229, v238
	v_mul_f32_e32 v239, 0x3db8aa3b, v239
	v_exp_f32_e32 v239, v239
	v_mov_b32_e32 v229, v238
	v_mul_f32_e32 v240, 0xbdb8aa3b, v238
	v_fma_f32 v96, v96, v242, v240
	v_exp_f32_e32 v96, v96
	v_fma_f32 v97, v97, v242, v240
	v_exp_f32_e32 v97, v97
	v_fma_f32 v98, v98, v242, v240
	v_exp_f32_e32 v98, v98
	v_fma_f32 v99, v99, v242, v240
	v_exp_f32_e32 v99, v99
	v_fma_f32 v100, v100, v242, v240
	v_exp_f32_e32 v100, v100
	v_fma_f32 v101, v101, v242, v240
	v_exp_f32_e32 v101, v101
	v_fma_f32 v102, v102, v242, v240
	v_exp_f32_e32 v102, v102
	v_fma_f32 v103, v103, v242, v240
	v_exp_f32_e32 v103, v103
	v_fma_f32 v104, v104, v242, v240
	v_exp_f32_e32 v104, v104
	v_fma_f32 v105, v105, v242, v240
	v_exp_f32_e32 v105, v105
	v_fma_f32 v106, v106, v242, v240
	v_exp_f32_e32 v106, v106
	v_fma_f32 v107, v107, v242, v240
	v_exp_f32_e32 v107, v107
	v_fma_f32 v108, v108, v242, v240
	v_exp_f32_e32 v108, v108
	v_fma_f32 v109, v109, v242, v240
	v_exp_f32_e32 v109, v109
	v_fma_f32 v110, v110, v242, v240
	v_exp_f32_e32 v110, v110
	v_fma_f32 v111, v111, v242, v240
	v_exp_f32_e32 v111, v111
	s_nop 0
	v_add_f32_e32 v241, v96, v97
	v_add_f32_e32 v241, v98, v241
	v_add_f32_e32 v241, v99, v241
	v_add_f32_e32 v241, v100, v241
	v_add_f32_e32 v241, v101, v241
	v_add_f32_e32 v241, v102, v241
	v_add_f32_e32 v241, v103, v241
	v_add_f32_e32 v241, v104, v241
	v_add_f32_e32 v241, v105, v241
	v_add_f32_e32 v241, v106, v241
	v_add_f32_e32 v241, v107, v241
	v_add_f32_e32 v241, v108, v241
	v_add_f32_e32 v241, v109, v241
	v_add_f32_e32 v241, v110, v241
	v_add_f32_e32 v241, v111, v241
	v_fma_f32 v230, v230, v239, v241
	v_cvt_pk_bf16_f32 v212, v96, v97
	v_cvt_pk_bf16_f32 v213, v98, v99
	v_cvt_pk_bf16_f32 v214, v100, v101
	v_cvt_pk_bf16_f32 v215, v102, v103
	v_cvt_pk_bf16_f32 v216, v104, v105
	v_cvt_pk_bf16_f32 v217, v106, v107
	v_cvt_pk_bf16_f32 v218, v108, v109
	v_cvt_pk_bf16_f32 v219, v110, v111
	s_waitcnt vmcnt(8)
	ds_write_b128 v224, v[176:179]
	ds_write_b128 v224, v[180:183] offset:4608
	ds_write_b128 v224, v[184:187] offset:9216
	ds_write_b128 v224, v[188:191] offset:13824
	ds_write_b128 v224, v[192:195] offset:18432
	ds_write_b128 v224, v[196:199] offset:23040
	ds_write_b128 v224, v[200:203] offset:27648
	ds_write_b128 v224, v[204:207] offset:32256
	s_waitcnt lgkmcnt(0)
	s_barrier
; DEVI f32x4 mfma16(bf16x8 a, bf16x8 b, f32x4 c) { return __builtin_amdgcn_mfma_f32_16x16x32_bf16(a, b, c, 0, 0, 0); }
; #define LOADK_(kbx) LK1_(0, kbx) LK1_(1, kbx) LK1_(2, kbx) LK1_(3, kbx) LK1_(4, kbx) LK1_(5, kbx) LK1_(6, kbx) LK1_(7, kbx)
; template <int DH, int NQ, int LDV>
; DEVI void attn_pv(const u16* sVt, const bf16x8 (&pb)[NQ][2], f32x4 (&o)[NQ][DH / 16], int lane) {
;   const int col = lane & 15, quad = lane >> 4;
;   __builtin_amdgcn_s_setprio(1);
; #pragma unroll
;   for (int dt = 0; dt < DH / 16; ++dt) {
; #pragma unroll
;     for (int kk = 0; kk < 2; ++kk) {
;       union { bf16x8 v; uint2 h[2]; } cv;
;       cv.h[0] = *(const uint2*)(sVt + (16 * dt + col) * LDV + 32 * kk + 4 * quad);
;       cv.h[1] = *(const uint2*)(sVt + (16 * dt + col) * LDV + 32 * kk + 16 + 4 * quad);
; #pragma unroll
;       for (int qt = 0; qt < NQ; ++qt) o[qt][dt] = mfma16(cv.v, pb[qt][kk], o[qt][dt]);
;     }
;   }
;   __builtin_amdgcn_s_setprio(0);
; DEVI void phase_memattn(const Params& p, unsigned char* smem) {
;     ...
;       if (kb < 3) { LOADK_(kb + 1) }
;       __syncthreads();
;       attn_pv<256, 1, 72>(sVt, pb, o, lane);
	s_lshl_b32 s16, s10, 2
	s_add_u32 s16, s16, s11
	s_lshl_b32 s16, s16, 17
	s_add_u32 s16, s16, 128
	v_add_u32_e32 v231, s16, v222
	global_load_dwordx4 v[176:179], v231, s[4:5]
	s_add_u32 s16, s16, 0x4000
	v_add_u32_e32 v232, s16, v222
	global_load_dwordx4 v[180:183], v232, s[4:5]
	s_add_u32 s16, s16, 0x4000
	v_add_u32_e32 v233, s16, v222
	global_load_dwordx4 v[184:187], v233, s[4:5]
	s_add_u32 s16, s16, 0x4000
	v_add_u32_e32 v234, s16, v222
	global_load_dwordx4 v[188:191], v234, s[4:5]
	s_add_u32 s16, s16, 0x4000
	v_add_u32_e32 v231, s16, v222
	global_load_dwordx4 v[192:195], v231, s[4:5]
	s_add_u32 s16, s16, 0x4000
	v_add_u32_e32 v232, s16, v222
	global_load_dwordx4 v[196:199], v232, s[4:5]
	s_add_u32 s16, s16, 0x4000
	v_add_u32_e32 v233, s16, v222
	global_load_dwordx4 v[200:203], v233, s[4:5]
	s_add_u32 s16, s16, 0x4000
	v_add_u32_e32 v234, s16, v222
	global_load_dwordx4 v[204:207], v234, s[4:5]
	ds_read_b64 v[112:113], v226 offset:0
	ds_read_b64 v[114:115], v226 offset:32
	ds_read_b64 v[116:117], v226 offset:64
	ds_read_b64 v[118:119], v226 offset:96
	ds_read_b64 v[120:121], v226 offset:2304
	ds_read_b64 v[122:123], v226 offset:2336
	ds_read_b64 v[124:125], v226 offset:2368
	ds_read_b64 v[126:127], v226 offset:2400
	ds_read_b64 v[128:129], v226 offset:4608
	ds_read_b64 v[130:131], v226 offset:4640
	ds_read_b64 v[132:133], v226 offset:4672
	ds_read_b64 v[134:135], v226 offset:4704
	ds_read_b64 v[136:137], v226 offset:6912
	ds_read_b64 v[138:139], v226 offset:6944
	ds_read_b64 v[140:141], v226 offset:6976
	ds_read_b64 v[142:143], v226 offset:7008
	s_waitcnt lgkmcnt(14)
	v_mfma_f32_16x16x32_bf16 v[32:35], v[112:115], v[212:215], 0
	ds_read_b64 v[112:113], v226 offset:9216
	ds_read_b64 v[114:115], v226 offset:9248
	s_waitcnt lgkmcnt(14)
	v_mfma_f32_16x16x32_bf16 v[32:35], v[116:119], v[216:219], v[32:35]
	ds_read_b64 v[116:117], v226 offset:9280
	ds_read_b64 v[118:119], v226 offset:9312
	s_waitcnt lgkmcnt(14)
	v_mfma_f32_16x16x32_bf16 v[36:39], v[120:123], v[212:215], 0
	ds_read_b64 v[120:121], v226 offset:11520
	ds_read_b64 v[122:123], v226 offset:11552
	s_waitcnt lgkmcnt(14)
	v_mfma_f32_16x16x32_bf16 v[36:39], v[124:127], v[216:219], v[36:39]
	ds_read_b64 v[124:125], v226 offset:11584
	ds_read_b64 v[126:127], v226 offset:11616
	s_waitcnt lgkmcnt(14)
	v_mfma_f32_16x16x32_bf16 v[40:43], v[128:131], v[212:215], 0
	ds_read_b64 v[128:129], v226 offset:13824
	ds_read_b64 v[130:131], v226 offset:13856
	s_waitcnt lgkmcnt(14)
	v_mfma_f32_16x16x32_bf16 v[40:43], v[132:135], v[216:219], v[40:43]
	ds_read_b64 v[132:133], v226 offset:13888
	ds_read_b64 v[134:135], v226 offset:13920
	s_waitcnt lgkmcnt(14)
	v_mfma_f32_16x16x32_bf16 v[44:47], v[136:139], v[212:215], 0
	ds_read_b64 v[136:137], v226 offset:16128
	ds_read_b64 v[138:139], v226 offset:16160
	s_waitcnt lgkmcnt(14)
	v_mfma_f32_16x16x32_bf16 v[44:47], v[140:143], v[216:219], v[44:47]
	ds_read_b64 v[140:141], v226 offset:16192
	ds_read_b64 v[142:143], v226 offset:16224
	s_waitcnt lgkmcnt(14)
	v_mfma_f32_16x16x32_bf16 v[48:51], v[112:115], v[212:215], 0
	ds_read_b64 v[112:113], v226 offset:18432
	ds_read_b64 v[114:115], v226 offset:18464
	s_waitcnt lgkmcnt(14)
	v_mfma_f32_16x16x32_bf16 v[48:51], v[116:119], v[216:219], v[48:51]
	ds_read_b64 v[116:117], v226 offset:18496
	ds_read_b64 v[118:119], v226 offset:18528
	s_waitcnt lgkmcnt(14)
	v_mfma_f32_16x16x32_bf16 v[52:55], v[120:123], v[212:215], 0
	ds_read_b64 v[120:121], v226 offset:20736
	ds_read_b64 v[122:123], v226 offset:20768
	s_waitcnt lgkmcnt(14)
	v_mfma_f32_16x16x32_bf16 v[52:55], v[124:127], v[216:219], v[52:55]
	ds_read_b64 v[124:125], v226 offset:20800
	ds_read_b64 v[126:127], v226 offset:20832
	s_waitcnt lgkmcnt(14)
	v_mfma_f32_16x16x32_bf16 v[56:59], v[128:131], v[212:215], 0
	ds_read_b64 v[128:129], v226 offset:23040
	ds_read_b64 v[130:131], v226 offset:23072
	s_waitcnt lgkmcnt(14)
	v_mfma_f32_16x16x32_bf16 v[56:59], v[132:135], v[216:219], v[56:59]
	ds_read_b64 v[132:133], v226 offset:23104
	ds_read_b64 v[134:135], v226 offset:23136
	s_waitcnt lgkmcnt(14)
	v_mfma_f32_16x16x32_bf16 v[60:63], v[136:139], v[212:215], 0
	ds_read_b64 v[136:137], v226 offset:25344
	ds_read_b64 v[138:139], v226 offset:25376
	s_waitcnt lgkmcnt(14)
	v_mfma_f32_16x16x32_bf16 v[60:63], v[140:143], v[216:219], v[60:63]
	ds_read_b64 v[140:141], v226 offset:25408
	ds_read_b64 v[142:143], v226 offset:25440
	s_waitcnt lgkmcnt(14)
	v_mfma_f32_16x16x32_bf16 v[64:67], v[112:115], v[212:215], 0
	ds_read_b64 v[112:113], v226 offset:27648
	ds_read_b64 v[114:115], v226 offset:27680
	s_waitcnt lgkmcnt(14)
	v_mfma_f32_16x16x32_bf16 v[64:67], v[116:119], v[216:219], v[64:67]
	ds_read_b64 v[116:117], v226 offset:27712
	ds_read_b64 v[118:119], v226 offset:27744
	s_waitcnt lgkmcnt(14)
	v_mfma_f32_16x16x32_bf16 v[68:71], v[120:123], v[212:215], 0
	ds_read_b64 v[120:121], v226 offset:29952
	ds_read_b64 v[122:123], v226 offset:29984
	s_waitcnt lgkmcnt(14)
	v_mfma_f32_16x16x32_bf16 v[68:71], v[124:127], v[216:219], v[68:71]
	ds_read_b64 v[124:125], v226 offset:30016
	ds_read_b64 v[126:127], v226 offset:30048
	s_waitcnt lgkmcnt(14)
	v_mfma_f32_16x16x32_bf16 v[72:75], v[128:131], v[212:215], 0
	ds_read_b64 v[128:129], v226 offset:32256
	ds_read_b64 v[130:131], v226 offset:32288
	s_waitcnt lgkmcnt(14)
	v_mfma_f32_16x16x32_bf16 v[72:75], v[132:135], v[216:219], v[72:75]
	ds_read_b64 v[132:133], v226 offset:32320
	ds_read_b64 v[134:135], v226 offset:32352
	s_waitcnt lgkmcnt(14)
	v_mfma_f32_16x16x32_bf16 v[76:79], v[136:139], v[212:215], 0
	ds_read_b64 v[136:137], v226 offset:34560
	ds_read_b64 v[138:139], v226 offset:34592
	s_waitcnt lgkmcnt(14)
; DEVI f32x4 mfma16(bf16x8 a, bf16x8 b, f32x4 c) { return __builtin_amdgcn_mfma_f32_16x16x32_bf16(a, b, c, 0, 0, 0); }
; #define LOADK_(kbx) LK1_(0, kbx) LK1_(1, kbx) LK1_(2, kbx) LK1_(3, kbx) LK1_(4, kbx) LK1_(5, kbx) LK1_(6, kbx) LK1_(7, kbx)
; #define STOREK_() SK1_(0) SK1_(1) SK1_(2) SK1_(3) SK1_(4) SK1_(5) SK1_(6) SK1_(7)
; #define LOADV_(kbx) LV1_(0, kbx) LV1_(1, kbx) LV1_(2, kbx) LV1_(3, kbx) LV1_(4, kbx) LV1_(5, kbx) LV1_(6, kbx) LV1_(7, kbx)
; template <int DH, int NQ, int LDK, class MaskF>
; DEVI void attn_qk(const u16* sK, const bf16x8 (&qf)[NQ][DH / 32], f32x4 (&o)[NQ][DH / 16], float (&m)[NQ], float (&l)[NQ],
;                   float c2, int lane, MaskF valid, bf16x8 (&pb)[NQ][2]) {
;     ...
;   __builtin_amdgcn_s_setprio(1);
; #pragma unroll
;   for (int kt = 0; kt < 4; ++kt) {
; #pragma unroll
;     for (int qt = 0; qt < NQ; ++qt) s[qt][kt] = f32x4{0.f, 0.f, 0.f, 0.f};
; #pragma unroll
;     for (int ks = 0; ks < DH / 32; ++ks) {
;       const bf16x8 kf = *(const bf16x8*)(sK + (16 * kt + col) * LDK + 32 * ks + 8 * quad);
; #pragma unroll
;       for (int qt = 0; qt < NQ; ++qt) s[qt][kt] = mfma16(kf, qf[qt][ks], s[qt][kt]);
;     }
;   }
;   __builtin_amdgcn_s_setprio(0);
; DEVI void phase_memattn(const Params& p, unsigned char* smem) {
;     ...
;       if (kb < 3) { LOADK_(kb + 1) }
;       __syncthreads();
;       attn_pv<256, 1, 72>(sVt, pb, o, lane);
;       if (kb < 3) {
;         STOREK_()
;         LOADV_(kb + 1)
;       }
	v_mfma_f32_16x16x32_bf16 v[76:79], v[140:143], v[216:219], v[76:79]
	ds_read_b64 v[140:141], v226 offset:34624
	ds_read_b64 v[142:143], v226 offset:34656
	s_waitcnt lgkmcnt(14)
	v_mfma_f32_16x16x32_bf16 v[80:83], v[112:115], v[212:215], 0
	s_waitcnt lgkmcnt(12)
	v_mfma_f32_16x16x32_bf16 v[80:83], v[116:119], v[216:219], v[80:83]
	s_waitcnt lgkmcnt(10)
	v_mfma_f32_16x16x32_bf16 v[84:87], v[120:123], v[212:215], 0
	s_waitcnt lgkmcnt(8)
	v_mfma_f32_16x16x32_bf16 v[84:87], v[124:127], v[216:219], v[84:87]
	s_waitcnt lgkmcnt(6)
	v_mfma_f32_16x16x32_bf16 v[88:91], v[128:131], v[212:215], 0
	s_waitcnt lgkmcnt(4)
	v_mfma_f32_16x16x32_bf16 v[88:91], v[132:135], v[216:219], v[88:91]
	s_waitcnt lgkmcnt(2)
	v_mfma_f32_16x16x32_bf16 v[92:95], v[136:139], v[212:215], 0
	s_waitcnt lgkmcnt(0)
	v_mfma_f32_16x16x32_bf16 v[92:95], v[140:143], v[216:219], v[92:95]
	s_waitcnt vmcnt(8)
	ds_write_b128 v223, v[144:147]
	ds_write_b128 v223, v[148:151] offset:4224
	ds_write_b128 v223, v[152:155] offset:8448
	ds_write_b128 v223, v[156:159] offset:12672
	ds_write_b128 v223, v[160:163] offset:16896
	ds_write_b128 v223, v[164:167] offset:21120
	ds_write_b128 v223, v[168:171] offset:25344
	ds_write_b128 v223, v[172:175] offset:29568
	s_mul_i32 s16, s10, 0x88000
	s_add_u32 s16, s16, s14
	s_add_u32 s16, s16, 0x44000
	v_add_u32_e32 v231, s16, v221
	global_load_dwordx4 v[144:147], v231, s[2:3]
	s_add_u32 s16, s16, 0x4400
	v_add_u32_e32 v232, s16, v221
	global_load_dwordx4 v[148:151], v232, s[2:3]
	s_add_u32 s16, s16, 0x4400
	v_add_u32_e32 v233, s16, v221
	global_load_dwordx4 v[152:155], v233, s[2:3]
	s_add_u32 s16, s16, 0x4400
	v_add_u32_e32 v234, s16, v221
	global_load_dwordx4 v[156:159], v234, s[2:3]
	s_add_u32 s16, s16, 0x4400
	v_add_u32_e32 v231, s16, v221
	global_load_dwordx4 v[160:163], v231, s[2:3]
	s_add_u32 s16, s16, 0x4400
	v_add_u32_e32 v232, s16, v221
	global_load_dwordx4 v[164:167], v232, s[2:3]
	s_add_u32 s16, s16, 0x4400
	v_add_u32_e32 v233, s16, v221
	global_load_dwordx4 v[168:171], v233, s[2:3]
	s_add_u32 s16, s16, 0x4400
	v_add_u32_e32 v234, s16, v221
	global_load_dwordx4 v[172:175], v234, s[2:3]
	s_waitcnt lgkmcnt(0)
	s_barrier
	ds_read_b128 v[112:115], v225
	ds_read_b128 v[116:119], v225 offset:64
	ds_read_b128 v[120:123], v225 offset:128
	ds_read_b128 v[124:127], v225 offset:192
	ds_read_b128 v[128:131], v225 offset:256
	ds_read_b128 v[132:135], v225 offset:320
	ds_read_b128 v[136:139], v225 offset:384
	ds_read_b128 v[140:143], v225 offset:448
	s_waitcnt lgkmcnt(4)
	v_mfma_f32_16x16x32_bf16 v[96:99], v[112:115], v[0:3], 0
	v_mfma_f32_16x16x32_bf16 v[96:99], v[116:119], v[4:7], v[96:99]
	v_mfma_f32_16x16x32_bf16 v[96:99], v[120:123], v[8:11], v[96:99]
	v_mfma_f32_16x16x32_bf16 v[96:99], v[124:127], v[12:15], v[96:99]
	ds_read_b128 v[112:115], v225 offset:8448
	ds_read_b128 v[116:119], v225 offset:8512
	ds_read_b128 v[120:123], v225 offset:8576
	ds_read_b128 v[124:127], v225 offset:8640
	s_waitcnt lgkmcnt(4)
	v_mfma_f32_16x16x32_bf16 v[96:99], v[128:131], v[16:19], v[96:99]
	v_mfma_f32_16x16x32_bf16 v[96:99], v[132:135], v[20:23], v[96:99]
	v_mfma_f32_16x16x32_bf16 v[96:99], v[136:139], v[24:27], v[96:99]
	v_mfma_f32_16x16x32_bf16 v[96:99], v[140:143], v[28:31], v[96:99]
	ds_read_b128 v[128:131], v225 offset:8704
	ds_read_b128 v[132:135], v225 offset:8768
	ds_read_b128 v[136:139], v225 offset:8832
	ds_read_b128 v[140:143], v225 offset:8896
	s_waitcnt lgkmcnt(4)
	v_mfma_f32_16x16x32_bf16 v[100:103], v[112:115], v[0:3], 0
	v_mfma_f32_16x16x32_bf16 v[100:103], v[116:119], v[4:7], v[100:103]
	v_mfma_f32_16x16x32_bf16 v[100:103], v[120:123], v[8:11], v[100:103]
	v_mfma_f32_16x16x32_bf16 v[100:103], v[124:127], v[12:15], v[100:103]
	ds_read_b128 v[112:115], v225 offset:16896
	ds_read_b128 v[116:119], v225 offset:16960
	ds_read_b128 v[120:123], v225 offset:17024
	ds_read_b128 v[124:127], v225 offset:17088
	s_waitcnt lgkmcnt(4)
	v_mfma_f32_16x16x32_bf16 v[100:103], v[128:131], v[16:19], v[100:103]
	v_mfma_f32_16x16x32_bf16 v[100:103], v[132:135], v[20:23], v[100:103]
	v_mfma_f32_16x16x32_bf16 v[100:103], v[136:139], v[24:27], v[100:103]
	v_mfma_f32_16x16x32_bf16 v[100:103], v[140:143], v[28:31], v[100:103]
	ds_read_b128 v[128:131], v225 offset:17152
	ds_read_b128 v[132:135], v225 offset:17216
	ds_read_b128 v[136:139], v225 offset:17280
	ds_read_b128 v[140:143], v225 offset:17344
	s_waitcnt lgkmcnt(4)
	v_mfma_f32_16x16x32_bf16 v[104:107], v[112:115], v[0:3], 0
	v_mfma_f32_16x16x32_bf16 v[104:107], v[116:119], v[4:7], v[104:107]
	v_mfma_f32_16x16x32_bf16 v[104:107], v[120:123], v[8:11], v[104:107]
	v_mfma_f32_16x16x32_bf16 v[104:107], v[124:127], v[12:15], v[104:107]
	ds_read_b128 v[112:115], v225 offset:25344
	ds_read_b128 v[116:119], v225 offset:25408
	ds_read_b128 v[120:123], v225 offset:25472
	ds_read_b128 v[124:127], v225 offset:25536
	s_waitcnt lgkmcnt(4)
	v_mfma_f32_16x16x32_bf16 v[104:107], v[128:131], v[16:19], v[104:107]
	v_mfma_f32_16x16x32_bf16 v[104:107], v[132:135], v[20:23], v[104:107]
	v_mfma_f32_16x16x32_bf16 v[104:107], v[136:139], v[24:27], v[104:107]
	v_mfma_f32_16x16x32_bf16 v[104:107], v[140:143], v[28:31], v[104:107]
	ds_read_b128 v[128:131], v225 offset:25600
	ds_read_b128 v[132:135], v225 offset:25664
	ds_read_b128 v[136:139], v225 offset:25728
	ds_read_b128 v[140:143], v225 offset:25792
	s_waitcnt lgkmcnt(4)
	v_mfma_f32_16x16x32_bf16 v[108:111], v[112:115], v[0:3], 0
	v_mfma_f32_16x16x32_bf16 v[108:111], v[116:119], v[4:7], v[108:111]
	v_mfma_f32_16x16x32_bf16 v[108:111], v[120:123], v[8:11], v[108:111]
	v_mfma_f32_16x16x32_bf16 v[108:111], v[124:127], v[12:15], v[108:111]
	s_waitcnt lgkmcnt(0)
; DEVI unsigned pack2(float a, float b) { return (unsigned)f2bf(a) | ((unsigned)f2bf(b) << 16); }
; DEVI float fexp2(float x) { return __builtin_amdgcn_exp2f(x); }
; template <int DH, int NQ, int LDK, class MaskF>
; DEVI void attn_qk(const u16* sK, const bf16x8 (&qf)[NQ][DH / 32], f32x4 (&o)[NQ][DH / 16], float (&m)[NQ], float (&l)[NQ],
;                   float c2, int lane, MaskF valid, bf16x8 (&pb)[NQ][2]) {
;     ...
; #pragma unroll
;   for (int qt = 0; qt < NQ; ++qt) {
;     float mx = -1e30f;
; #pragma unroll
;     for (int kt = 0; kt < 4; ++kt)
; #pragma unroll
;       for (int r = 0; r < 4; ++r) {
;         const bool v = valid(qt, 16 * kt + 4 * quad + r);
;         const float sv = v ? s[qt][kt][r] : -1e30f;
;         s[qt][kt][r] = sv;
;         mx = fmaxf(mx, sv);
;       }
;     mx = fmaxf(mx, __shfl_xor(mx, 16));
;     mx = fmaxf(mx, __shfl_xor(mx, 32));
;     const float mn = fmaxf(m[qt], mx);
;     const float alpha = fexp2((m[qt] - mn) * c2);
;     m[qt] = mn;
;     const float mc = fmaxf(mn, -1e20f) * c2;
;     float ps = 0.f;
; #pragma unroll
;     for (int kt = 0; kt < 4; ++kt)
; #pragma unroll
;       for (int r = 0; r < 4; ++r) {
;         const float pv = fexp2(__builtin_fmaf(s[qt][kt][r], c2, -mc));
;         ps += pv;
;         s[qt][kt][r] = pv;
;       }
;     l[qt] = l[qt] * alpha + ps;
; #pragma unroll
;     for (int dt = 0; dt < DH / 16; ++dt) o[qt][dt] *= alpha;
; #pragma unroll
;     for (int kk = 0; kk < 2; ++kk) {
;       union { bf16x8 v; unsigned u[4]; } cv;
;       cv.u[0] = pack2(s[qt][2 * kk][0], s[qt][2 * kk][1]);
;       cv.u[1] = pack2(s[qt][2 * kk][2], s[qt][2 * kk][3]);
;       cv.u[2] = pack2(s[qt][2 * kk + 1][0], s[qt][2 * kk + 1][1]);
;       cv.u[3] = pack2(s[qt][2 * kk + 1][2], s[qt][2 * kk + 1][3]);
;       pb[qt][kk] = cv.v;
;     }
;   }
	v_mfma_f32_16x16x32_bf16 v[108:111], v[128:131], v[16:19], v[108:111]
	v_mfma_f32_16x16x32_bf16 v[108:111], v[132:135], v[20:23], v[108:111]
	v_mfma_f32_16x16x32_bf16 v[108:111], v[136:139], v[24:27], v[108:111]
	v_mfma_f32_16x16x32_bf16 v[108:111], v[140:143], v[28:31], v[108:111]
	s_nop 7
	v_max3_f32 v235, v96, v97, v98
	v_max3_f32 v235, v235, v99, v100
	v_max3_f32 v235, v235, v101, v102
	v_max3_f32 v235, v235, v103, v104
	v_max3_f32 v235, v235, v105, v106
	v_max3_f32 v235, v235, v107, v108
	v_max3_f32 v235, v235, v109, v110
	v_max_f32_e32 v235, v111, v235
	ds_bpermute_b32 v236, v228, v235
	s_waitcnt lgkmcnt(0)
	v_max_f32_e32 v235, v236, v235
	v_mov_b32_e32 v236, v235
	v_mov_b32_e32 v237, v235
	s_nop 1
	v_permlane32_swap_b32_e32 v236, v237
	v_max_f32_e32 v235, v236, v237
	v_max_f32_e32 v238, v229, v235
	v_sub_f32_e32 v239, v229, v238
	v_mul_f32_e32 v239, 0x3db8aa3b, v239
	v_exp_f32_e32 v239, v239
	v_mov_b32_e32 v229, v238
	v_mul_f32_e32 v240, 0xbdb8aa3b, v238
	v_fma_f32 v96, v96, v242, v240
	v_exp_f32_e32 v96, v96
	v_fma_f32 v97, v97, v242, v240
	v_exp_f32_e32 v97, v97
	v_fma_f32 v98, v98, v242, v240
	v_exp_f32_e32 v98, v98
	v_fma_f32 v99, v99, v242, v240
	v_exp_f32_e32 v99, v99
	v_fma_f32 v100, v100, v242, v240
	v_exp_f32_e32 v100, v100
	v_fma_f32 v101, v101, v242, v240
	v_exp_f32_e32 v101, v101
	v_fma_f32 v102, v102, v242, v240
	v_exp_f32_e32 v102, v102
	v_fma_f32 v103, v103, v242, v240
	v_exp_f32_e32 v103, v103
	v_fma_f32 v104, v104, v242, v240
	v_exp_f32_e32 v104, v104
	v_fma_f32 v105, v105, v242, v240
	v_exp_f32_e32 v105, v105
	v_fma_f32 v106, v106, v242, v240
	v_exp_f32_e32 v106, v106
	v_fma_f32 v107, v107, v242, v240
	v_exp_f32_e32 v107, v107
	v_fma_f32 v108, v108, v242, v240
	v_exp_f32_e32 v108, v108
	v_fma_f32 v109, v109, v242, v240
	v_exp_f32_e32 v109, v109
	v_fma_f32 v110, v110, v242, v240
	v_exp_f32_e32 v110, v110
	v_fma_f32 v111, v111, v242, v240
	v_exp_f32_e32 v111, v111
	s_nop 0
	v_add_f32_e32 v241, v96, v97
	v_add_f32_e32 v241, v98, v241
	v_add_f32_e32 v241, v99, v241
	v_add_f32_e32 v241, v100, v241
	v_add_f32_e32 v241, v101, v241
	v_add_f32_e32 v241, v102, v241
	v_add_f32_e32 v241, v103, v241
	v_add_f32_e32 v241, v104, v241
	v_add_f32_e32 v241, v105, v241
	v_add_f32_e32 v241, v106, v241
	v_add_f32_e32 v241, v107, v241
	v_add_f32_e32 v241, v108, v241
	v_add_f32_e32 v241, v109, v241
	v_add_f32_e32 v241, v110, v241
	v_add_f32_e32 v241, v111, v241
	v_fma_f32 v230, v230, v239, v241
	v_mul_f32_e32 v32, v239, v32
	v_mul_f32_e32 v33, v239, v33
	v_mul_f32_e32 v34, v239, v34
	v_mul_f32_e32 v35, v239, v35
	v_mul_f32_e32 v36, v239, v36
	v_mul_f32_e32 v37, v239, v37
	v_mul_f32_e32 v38, v239, v38
	v_mul_f32_e32 v39, v239, v39
	v_mul_f32_e32 v40, v239, v40
	v_mul_f32_e32 v41, v239, v41
	v_mul_f32_e32 v42, v239, v42
	v_mul_f32_e32 v43, v239, v43
	v_mul_f32_e32 v44, v239, v44
	v_mul_f32_e32 v45, v239, v45
	v_mul_f32_e32 v46, v239, v46
	v_mul_f32_e32 v47, v239, v47
	v_mul_f32_e32 v48, v239, v48
	v_mul_f32_e32 v49, v239, v49
	v_mul_f32_e32 v50, v239, v50
	v_mul_f32_e32 v51, v239, v51
	v_mul_f32_e32 v52, v239, v52
	v_mul_f32_e32 v53, v239, v53
	v_mul_f32_e32 v54, v239, v54
	v_mul_f32_e32 v55, v239, v55
	v_mul_f32_e32 v56, v239, v56
	v_mul_f32_e32 v57, v239, v57
	v_mul_f32_e32 v58, v239, v58
	v_mul_f32_e32 v59, v239, v59
	v_mul_f32_e32 v60, v239, v60
	v_mul_f32_e32 v61, v239, v61
	v_mul_f32_e32 v62, v239, v62
	v_mul_f32_e32 v63, v239, v63
	v_mul_f32_e32 v64, v239, v64
	v_mul_f32_e32 v65, v239, v65
	v_mul_f32_e32 v66, v239, v66
	v_mul_f32_e32 v67, v239, v67
	v_mul_f32_e32 v68, v239, v68
	v_mul_f32_e32 v69, v239, v69
	v_mul_f32_e32 v70, v239, v70
	v_mul_f32_e32 v71, v239, v71
	v_mul_f32_e32 v72, v239, v72
	v_mul_f32_e32 v73, v239, v73
	v_mul_f32_e32 v74, v239, v74
	v_mul_f32_e32 v75, v239, v75
	v_mul_f32_e32 v76, v239, v76
	v_mul_f32_e32 v77, v239, v77
	v_mul_f32_e32 v78, v239, v78
	v_mul_f32_e32 v79, v239, v79
	v_mul_f32_e32 v80, v239, v80
	v_mul_f32_e32 v81, v239, v81
	v_mul_f32_e32 v82, v239, v82
	v_mul_f32_e32 v83, v239, v83
	v_mul_f32_e32 v84, v239, v84
	v_mul_f32_e32 v85, v239, v85
	v_mul_f32_e32 v86, v239, v86
	v_mul_f32_e32 v87, v239, v87
	v_mul_f32_e32 v88, v239, v88
	v_mul_f32_e32 v89, v239, v89
	v_mul_f32_e32 v90, v239, v90
	v_mul_f32_e32 v91, v239, v91
	v_mul_f32_e32 v92, v239, v92
	v_mul_f32_e32 v93, v239, v93
	v_mul_f32_e32 v94, v239, v94
	v_mul_f32_e32 v95, v239, v95
	v_cvt_pk_bf16_f32 v212, v96, v97
	v_cvt_pk_bf16_f32 v213, v98, v99
	v_cvt_pk_bf16_f32 v214, v100, v101
	v_cvt_pk_bf16_f32 v215, v102, v103
	v_cvt_pk_bf16_f32 v216, v104, v105
	v_cvt_pk_bf16_f32 v217, v106, v107
	v_cvt_pk_bf16_f32 v218, v108, v109
	v_cvt_pk_bf16_f32 v219, v110, v111
	s_waitcnt vmcnt(8)
	ds_write_b128 v224, v[176:179]
	ds_write_b128 v224, v[180:183] offset:4608
	ds_write_b128 v224, v[184:187] offset:9216
	ds_write_b128 v224, v[188:191] offset:13824
	ds_write_b128 v224, v[192:195] offset:18432
	ds_write_b128 v224, v[196:199] offset:23040
	ds_write_b128 v224, v[200:203] offset:27648
	ds_write_b128 v224, v[204:207] offset:32256
	s_waitcnt lgkmcnt(0)
	s_barrier
; DEVI f32x4 mfma16(bf16x8 a, bf16x8 b, f32x4 c) { return __builtin_amdgcn_mfma_f32_16x16x32_bf16(a, b, c, 0, 0, 0); }
; template <int DH, int NQ, int LDV>
; DEVI void attn_pv(const u16* sVt, const bf16x8 (&pb)[NQ][2], f32x4 (&o)[NQ][DH / 16], int lane) {
;   const int col = lane & 15, quad = lane >> 4;
;   __builtin_amdgcn_s_setprio(1);
; #pragma unroll
;   for (int dt = 0; dt < DH / 16; ++dt) {
; #pragma unroll
;     for (int kk = 0; kk < 2; ++kk) {
;       union { bf16x8 v; uint2 h[2]; } cv;
;       cv.h[0] = *(const uint2*)(sVt + (16 * dt + col) * LDV + 32 * kk + 4 * quad);
;       cv.h[1] = *(const uint2*)(sVt + (16 * dt + col) * LDV + 32 * kk + 16 + 4 * quad);
; #pragma unroll
;       for (int qt = 0; qt < NQ; ++qt) o[qt][dt] = mfma16(cv.v, pb[qt][kk], o[qt][dt]);
;     }
;   }
;   __builtin_amdgcn_s_setprio(0);
	s_lshl_b32 s16, s10, 2
	s_add_u32 s16, s16, s11
	s_lshl_b32 s16, s16, 17
	s_add_u32 s16, s16, 256
	v_add_u32_e32 v231, s16, v222
	global_load_dwordx4 v[176:179], v231, s[4:5]
	s_add_u32 s16, s16, 0x4000
	v_add_u32_e32 v232, s16, v222
	global_load_dwordx4 v[180:183], v232, s[4:5]
	s_add_u32 s16, s16, 0x4000
	v_add_u32_e32 v233, s16, v222
	global_load_dwordx4 v[184:187], v233, s[4:5]
	s_add_u32 s16, s16, 0x4000
	v_add_u32_e32 v234, s16, v222
	global_load_dwordx4 v[188:191], v234, s[4:5]
	s_add_u32 s16, s16, 0x4000
	v_add_u32_e32 v231, s16, v222
	global_load_dwordx4 v[192:195], v231, s[4:5]
	s_add_u32 s16, s16, 0x4000
	v_add_u32_e32 v232, s16, v222
	global_load_dwordx4 v[196:199], v232, s[4:5]
	s_add_u32 s16, s16, 0x4000
	v_add_u32_e32 v233, s16, v222
	global_load_dwordx4 v[200:203], v233, s[4:5]
	s_add_u32 s16, s16, 0x4000
	v_add_u32_e32 v234, s16, v222
	global_load_dwordx4 v[204:207], v234, s[4:5]
	ds_read_b64 v[112:113], v226 offset:0
	ds_read_b64 v[114:115], v226 offset:32
	ds_read_b64 v[116:117], v226 offset:64
	ds_read_b64 v[118:119], v226 offset:96
	ds_read_b64 v[120:121], v226 offset:2304
	ds_read_b64 v[122:123], v226 offset:2336
	ds_read_b64 v[124:125], v226 offset:2368
	ds_read_b64 v[126:127], v226 offset:2400
	ds_read_b64 v[128:129], v226 offset:4608
	ds_read_b64 v[130:131], v226 offset:4640
	ds_read_b64 v[132:133], v226 offset:4672
	ds_read_b64 v[134:135], v226 offset:4704
	ds_read_b64 v[136:137], v226 offset:6912
	ds_read_b64 v[138:139], v226 offset:6944
	ds_read_b64 v[140:141], v226 offset:6976
	ds_read_b64 v[142:143], v226 offset:7008
	s_waitcnt lgkmcnt(14)
	v_mfma_f32_16x16x32_bf16 v[32:35], v[112:115], v[212:215], v[32:35]
	ds_read_b64 v[112:113], v226 offset:9216
	ds_read_b64 v[114:115], v226 offset:9248
	s_waitcnt lgkmcnt(14)
	v_mfma_f32_16x16x32_bf16 v[32:35], v[116:119], v[216:219], v[32:35]
	ds_read_b64 v[116:117], v226 offset:9280
	ds_read_b64 v[118:119], v226 offset:9312
	s_waitcnt lgkmcnt(14)
	v_mfma_f32_16x16x32_bf16 v[36:39], v[120:123], v[212:215], v[36:39]
	ds_read_b64 v[120:121], v226 offset:11520
	ds_read_b64 v[122:123], v226 offset:11552
	s_waitcnt lgkmcnt(14)
	v_mfma_f32_16x16x32_bf16 v[36:39], v[124:127], v[216:219], v[36:39]
	ds_read_b64 v[124:125], v226 offset:11584
	ds_read_b64 v[126:127], v226 offset:11616
	s_waitcnt lgkmcnt(14)
	v_mfma_f32_16x16x32_bf16 v[40:43], v[128:131], v[212:215], v[40:43]
	ds_read_b64 v[128:129], v226 offset:13824
	ds_read_b64 v[130:131], v226 offset:13856
	s_waitcnt lgkmcnt(14)
	v_mfma_f32_16x16x32_bf16 v[40:43], v[132:135], v[216:219], v[40:43]
	ds_read_b64 v[132:133], v226 offset:13888
	ds_read_b64 v[134:135], v226 offset:13920
	s_waitcnt lgkmcnt(14)
	v_mfma_f32_16x16x32_bf16 v[44:47], v[136:139], v[212:215], v[44:47]
	ds_read_b64 v[136:137], v226 offset:16128
	ds_read_b64 v[138:139], v226 offset:16160
	s_waitcnt lgkmcnt(14)
	v_mfma_f32_16x16x32_bf16 v[44:47], v[140:143], v[216:219], v[44:47]
	ds_read_b64 v[140:141], v226 offset:16192
	ds_read_b64 v[142:143], v226 offset:16224
	s_waitcnt lgkmcnt(14)
	v_mfma_f32_16x16x32_bf16 v[48:51], v[112:115], v[212:215], v[48:51]
	ds_read_b64 v[112:113], v226 offset:18432
	ds_read_b64 v[114:115], v226 offset:18464
	s_waitcnt lgkmcnt(14)
	v_mfma_f32_16x16x32_bf16 v[48:51], v[116:119], v[216:219], v[48:51]
	ds_read_b64 v[116:117], v226 offset:18496
	ds_read_b64 v[118:119], v226 offset:18528
	s_waitcnt lgkmcnt(14)
	v_mfma_f32_16x16x32_bf16 v[52:55], v[120:123], v[212:215], v[52:55]
	ds_read_b64 v[120:121], v226 offset:20736
	ds_read_b64 v[122:123], v226 offset:20768
	s_waitcnt lgkmcnt(14)
	v_mfma_f32_16x16x32_bf16 v[52:55], v[124:127], v[216:219], v[52:55]
	ds_read_b64 v[124:125], v226 offset:20800
	ds_read_b64 v[126:127], v226 offset:20832
	s_waitcnt lgkmcnt(14)
	v_mfma_f32_16x16x32_bf16 v[56:59], v[128:131], v[212:215], v[56:59]
	ds_read_b64 v[128:129], v226 offset:23040
	ds_read_b64 v[130:131], v226 offset:23072
	s_waitcnt lgkmcnt(14)
	v_mfma_f32_16x16x32_bf16 v[56:59], v[132:135], v[216:219], v[56:59]
	ds_read_b64 v[132:133], v226 offset:23104
	ds_read_b64 v[134:135], v226 offset:23136
	s_waitcnt lgkmcnt(14)
	v_mfma_f32_16x16x32_bf16 v[60:63], v[136:139], v[212:215], v[60:63]
	ds_read_b64 v[136:137], v226 offset:25344
	ds_read_b64 v[138:139], v226 offset:25376
	s_waitcnt lgkmcnt(14)
	v_mfma_f32_16x16x32_bf16 v[60:63], v[140:143], v[216:219], v[60:63]
	ds_read_b64 v[140:141], v226 offset:25408
	ds_read_b64 v[142:143], v226 offset:25440
	s_waitcnt lgkmcnt(14)
	v_mfma_f32_16x16x32_bf16 v[64:67], v[112:115], v[212:215], v[64:67]
	ds_read_b64 v[112:113], v226 offset:27648
	ds_read_b64 v[114:115], v226 offset:27680
	s_waitcnt lgkmcnt(14)
	v_mfma_f32_16x16x32_bf16 v[64:67], v[116:119], v[216:219], v[64:67]
	ds_read_b64 v[116:117], v226 offset:27712
	ds_read_b64 v[118:119], v226 offset:27744
	s_waitcnt lgkmcnt(14)
	v_mfma_f32_16x16x32_bf16 v[68:71], v[120:123], v[212:215], v[68:71]
	ds_read_b64 v[120:121], v226 offset:29952
	ds_read_b64 v[122:123], v226 offset:29984
	s_waitcnt lgkmcnt(14)
	v_mfma_f32_16x16x32_bf16 v[68:71], v[124:127], v[216:219], v[68:71]
	ds_read_b64 v[124:125], v226 offset:30016
	ds_read_b64 v[126:127], v226 offset:30048
	s_waitcnt lgkmcnt(14)
	v_mfma_f32_16x16x32_bf16 v[72:75], v[128:131], v[212:215], v[72:75]
	ds_read_b64 v[128:129], v226 offset:32256
	ds_read_b64 v[130:131], v226 offset:32288
	s_waitcnt lgkmcnt(14)
	v_mfma_f32_16x16x32_bf16 v[72:75], v[132:135], v[216:219], v[72:75]
	ds_read_b64 v[132:133], v226 offset:32320
	ds_read_b64 v[134:135], v226 offset:32352
	s_waitcnt lgkmcnt(14)
	v_mfma_f32_16x16x32_bf16 v[76:79], v[136:139], v[212:215], v[76:79]
	ds_read_b64 v[136:137], v226 offset:34560
	ds_read_b64 v[138:139], v226 offset:34592
	s_waitcnt lgkmcnt(14)
; DEVI f32x4 mfma16(bf16x8 a, bf16x8 b, f32x4 c) { return __builtin_amdgcn_mfma_f32_16x16x32_bf16(a, b, c, 0, 0, 0); }
; #define LOADK_(kbx) LK1_(0, kbx) LK1_(1, kbx) LK1_(2, kbx) LK1_(3, kbx) LK1_(4, kbx) LK1_(5, kbx) LK1_(6, kbx) LK1_(7, kbx)
; #define STOREK_() SK1_(0) SK1_(1) SK1_(2) SK1_(3) SK1_(4) SK1_(5) SK1_(6) SK1_(7)
; #define LOADV_(kbx) LV1_(0, kbx) LV1_(1, kbx) LV1_(2, kbx) LV1_(3, kbx) LV1_(4, kbx) LV1_(5, kbx) LV1_(6, kbx) LV1_(7, kbx)
; template <int DH, int NQ, int LDK, class MaskF>
; DEVI void attn_qk(const u16* sK, const bf16x8 (&qf)[NQ][DH / 32], f32x4 (&o)[NQ][DH / 16], float (&m)[NQ], float (&l)[NQ],
;                   float c2, int lane, MaskF valid, bf16x8 (&pb)[NQ][2]) {
;     ...
;   __builtin_amdgcn_s_setprio(1);
; #pragma unroll
;   for (int kt = 0; kt < 4; ++kt) {
; #pragma unroll
;     for (int qt = 0; qt < NQ; ++qt) s[qt][kt] = f32x4{0.f, 0.f, 0.f, 0.f};
; #pragma unroll
;     for (int ks = 0; ks < DH / 32; ++ks) {
;       const bf16x8 kf = *(const bf16x8*)(sK + (16 * kt + col) * LDK + 32 * ks + 8 * quad);
; #pragma unroll
;       for (int qt = 0; qt < NQ; ++qt) s[qt][kt] = mfma16(kf, qf[qt][ks], s[qt][kt]);
;     }
;   }
;   __builtin_amdgcn_s_setprio(0);
; DEVI void phase_memattn(const Params& p, unsigned char* smem) {
;     ...
;       if (kb < 3) { LOADK_(kb + 1) }
;       __syncthreads();
;       attn_pv<256, 1, 72>(sVt, pb, o, lane);
;       if (kb < 3) {
;         STOREK_()
;         LOADV_(kb + 1)
;       }
	v_mfma_f32_16x16x32_bf16 v[76:79], v[140:143], v[216:219], v[76:79]
	ds_read_b64 v[140:141], v226 offset:34624
	ds_read_b64 v[142:143], v226 offset:34656
	s_waitcnt lgkmcnt(14)
	v_mfma_f32_16x16x32_bf16 v[80:83], v[112:115], v[212:215], v[80:83]
	s_waitcnt lgkmcnt(12)
	v_mfma_f32_16x16x32_bf16 v[80:83], v[116:119], v[216:219], v[80:83]
	s_waitcnt lgkmcnt(10)
	v_mfma_f32_16x16x32_bf16 v[84:87], v[120:123], v[212:215], v[84:87]
	s_waitcnt lgkmcnt(8)
	v_mfma_f32_16x16x32_bf16 v[84:87], v[124:127], v[216:219], v[84:87]
	s_waitcnt lgkmcnt(6)
	v_mfma_f32_16x16x32_bf16 v[88:91], v[128:131], v[212:215], v[88:91]
	s_waitcnt lgkmcnt(4)
	v_mfma_f32_16x16x32_bf16 v[88:91], v[132:135], v[216:219], v[88:91]
	s_waitcnt lgkmcnt(2)
	v_mfma_f32_16x16x32_bf16 v[92:95], v[136:139], v[212:215], v[92:95]
	s_waitcnt lgkmcnt(0)
	v_mfma_f32_16x16x32_bf16 v[92:95], v[140:143], v[216:219], v[92:95]
	s_waitcnt vmcnt(8)
	ds_write_b128 v223, v[144:147]
	ds_write_b128 v223, v[148:151] offset:4224
	ds_write_b128 v223, v[152:155] offset:8448
	ds_write_b128 v223, v[156:159] offset:12672
	ds_write_b128 v223, v[160:163] offset:16896
	ds_write_b128 v223, v[164:167] offset:21120
	ds_write_b128 v223, v[168:171] offset:25344
	ds_write_b128 v223, v[172:175] offset:29568
	s_mul_i32 s16, s10, 0x88000
	s_add_u32 s16, s16, s14
	s_add_u32 s16, s16, 0x66000
	v_add_u32_e32 v231, s16, v221
	global_load_dwordx4 v[144:147], v231, s[2:3]
	s_add_u32 s16, s16, 0x4400
	v_add_u32_e32 v232, s16, v221
	global_load_dwordx4 v[148:151], v232, s[2:3]
	s_add_u32 s16, s16, 0x4400
	v_add_u32_e32 v233, s16, v221
	global_load_dwordx4 v[152:155], v233, s[2:3]
	s_add_u32 s16, s16, 0x4400
	v_add_u32_e32 v234, s16, v221
	global_load_dwordx4 v[156:159], v234, s[2:3]
	s_add_u32 s16, s16, 0x4400
	v_add_u32_e32 v231, s16, v221
	global_load_dwordx4 v[160:163], v231, s[2:3]
	s_add_u32 s16, s16, 0x4400
	v_add_u32_e32 v232, s16, v221
	global_load_dwordx4 v[164:167], v232, s[2:3]
	s_add_u32 s16, s16, 0x4400
	v_add_u32_e32 v233, s16, v221
	global_load_dwordx4 v[168:171], v233, s[2:3]
	s_add_u32 s16, s16, 0x4400
	v_add_u32_e32 v234, s16, v221
	global_load_dwordx4 v[172:175], v234, s[2:3]
	s_waitcnt lgkmcnt(0)
	s_barrier
	ds_read_b128 v[112:115], v225
	ds_read_b128 v[116:119], v225 offset:64
	ds_read_b128 v[120:123], v225 offset:128
	ds_read_b128 v[124:127], v225 offset:192
	ds_read_b128 v[128:131], v225 offset:256
	ds_read_b128 v[132:135], v225 offset:320
	ds_read_b128 v[136:139], v225 offset:384
	ds_read_b128 v[140:143], v225 offset:448
	s_waitcnt lgkmcnt(4)
	v_mfma_f32_16x16x32_bf16 v[96:99], v[112:115], v[0:3], 0
	v_mfma_f32_16x16x32_bf16 v[96:99], v[116:119], v[4:7], v[96:99]
	v_mfma_f32_16x16x32_bf16 v[96:99], v[120:123], v[8:11], v[96:99]
	v_mfma_f32_16x16x32_bf16 v[96:99], v[124:127], v[12:15], v[96:99]
	ds_read_b128 v[112:115], v225 offset:8448
	ds_read_b128 v[116:119], v225 offset:8512
	ds_read_b128 v[120:123], v225 offset:8576
	ds_read_b128 v[124:127], v225 offset:8640
	s_waitcnt lgkmcnt(4)
	v_mfma_f32_16x16x32_bf16 v[96:99], v[128:131], v[16:19], v[96:99]
	v_mfma_f32_16x16x32_bf16 v[96:99], v[132:135], v[20:23], v[96:99]
	v_mfma_f32_16x16x32_bf16 v[96:99], v[136:139], v[24:27], v[96:99]
	v_mfma_f32_16x16x32_bf16 v[96:99], v[140:143], v[28:31], v[96:99]
	ds_read_b128 v[128:131], v225 offset:8704
	ds_read_b128 v[132:135], v225 offset:8768
	ds_read_b128 v[136:139], v225 offset:8832
	ds_read_b128 v[140:143], v225 offset:8896
	s_waitcnt lgkmcnt(4)
	v_mfma_f32_16x16x32_bf16 v[100:103], v[112:115], v[0:3], 0
	v_mfma_f32_16x16x32_bf16 v[100:103], v[116:119], v[4:7], v[100:103]
	v_mfma_f32_16x16x32_bf16 v[100:103], v[120:123], v[8:11], v[100:103]
	v_mfma_f32_16x16x32_bf16 v[100:103], v[124:127], v[12:15], v[100:103]
	ds_read_b128 v[112:115], v225 offset:16896
	ds_read_b128 v[116:119], v225 offset:16960
	ds_read_b128 v[120:123], v225 offset:17024
	ds_read_b128 v[124:127], v225 offset:17088
	s_waitcnt lgkmcnt(4)
	v_mfma_f32_16x16x32_bf16 v[100:103], v[128:131], v[16:19], v[100:103]
	v_mfma_f32_16x16x32_bf16 v[100:103], v[132:135], v[20:23], v[100:103]
	v_mfma_f32_16x16x32_bf16 v[100:103], v[136:139], v[24:27], v[100:103]
	v_mfma_f32_16x16x32_bf16 v[100:103], v[140:143], v[28:31], v[100:103]
	ds_read_b128 v[128:131], v225 offset:17152
	ds_read_b128 v[132:135], v225 offset:17216
	ds_read_b128 v[136:139], v225 offset:17280
	ds_read_b128 v[140:143], v225 offset:17344
	s_waitcnt lgkmcnt(4)
	v_mfma_f32_16x16x32_bf16 v[104:107], v[112:115], v[0:3], 0
	v_mfma_f32_16x16x32_bf16 v[104:107], v[116:119], v[4:7], v[104:107]
	v_mfma_f32_16x16x32_bf16 v[104:107], v[120:123], v[8:11], v[104:107]
	v_mfma_f32_16x16x32_bf16 v[104:107], v[124:127], v[12:15], v[104:107]
	ds_read_b128 v[112:115], v225 offset:25344
	ds_read_b128 v[116:119], v225 offset:25408
	ds_read_b128 v[120:123], v225 offset:25472
	ds_read_b128 v[124:127], v225 offset:25536
	s_waitcnt lgkmcnt(4)
	v_mfma_f32_16x16x32_bf16 v[104:107], v[128:131], v[16:19], v[104:107]
	v_mfma_f32_16x16x32_bf16 v[104:107], v[132:135], v[20:23], v[104:107]
	v_mfma_f32_16x16x32_bf16 v[104:107], v[136:139], v[24:27], v[104:107]
	v_mfma_f32_16x16x32_bf16 v[104:107], v[140:143], v[28:31], v[104:107]
	ds_read_b128 v[128:131], v225 offset:25600
	ds_read_b128 v[132:135], v225 offset:25664
	ds_read_b128 v[136:139], v225 offset:25728
	ds_read_b128 v[140:143], v225 offset:25792
	s_waitcnt lgkmcnt(4)
	v_mfma_f32_16x16x32_bf16 v[108:111], v[112:115], v[0:3], 0
	v_mfma_f32_16x16x32_bf16 v[108:111], v[116:119], v[4:7], v[108:111]
	v_mfma_f32_16x16x32_bf16 v[108:111], v[120:123], v[8:11], v[108:111]
	v_mfma_f32_16x16x32_bf16 v[108:111], v[124:127], v[12:15], v[108:111]
	s_waitcnt lgkmcnt(0)
; DEVI unsigned pack2(float a, float b) { return (unsigned)f2bf(a) | ((unsigned)f2bf(b) << 16); }
; DEVI float fexp2(float x) { return __builtin_amdgcn_exp2f(x); }
; template <int DH, int NQ, int LDK, class MaskF>
; DEVI void attn_qk(const u16* sK, const bf16x8 (&qf)[NQ][DH / 32], f32x4 (&o)[NQ][DH / 16], float (&m)[NQ], float (&l)[NQ],
;                   float c2, int lane, MaskF valid, bf16x8 (&pb)[NQ][2]) {
;     ...
; #pragma unroll
;   for (int qt = 0; qt < NQ; ++qt) {
;     float mx = -1e30f;
; #pragma unroll
;     for (int kt = 0; kt < 4; ++kt)
; #pragma unroll
;       for (int r = 0; r < 4; ++r) {
;         const bool v = valid(qt, 16 * kt + 4 * quad + r);
;         const float sv = v ? s[qt][kt][r] : -1e30f;
;         s[qt][kt][r] = sv;
;         mx = fmaxf(mx, sv);
;       }
;     mx = fmaxf(mx, __shfl_xor(mx, 16));
;     mx = fmaxf(mx, __shfl_xor(mx, 32));
;     const float mn = fmaxf(m[qt], mx);
;     const float alpha = fexp2((m[qt] - mn) * c2);
;     m[qt] = mn;
;     const float mc = fmaxf(mn, -1e20f) * c2;
;     float ps = 0.f;
; #pragma unroll
;     for (int kt = 0; kt < 4; ++kt)
; #pragma unroll
;       for (int r = 0; r < 4; ++r) {
;         const float pv = fexp2(__builtin_fmaf(s[qt][kt][r], c2, -mc));
;         ps += pv;
;         s[qt][kt][r] = pv;
;       }
;     l[qt] = l[qt] * alpha + ps;
; #pragma unroll
;     for (int dt = 0; dt < DH / 16; ++dt) o[qt][dt] *= alpha;
; #pragma unroll
;     for (int kk = 0; kk < 2; ++kk) {
;       union { bf16x8 v; unsigned u[4]; } cv;
;       cv.u[0] = pack2(s[qt][2 * kk][0], s[qt][2 * kk][1]);
;       cv.u[1] = pack2(s[qt][2 * kk][2], s[qt][2 * kk][3]);
;       cv.u[2] = pack2(s[qt][2 * kk + 1][0], s[qt][2 * kk + 1][1]);
;       cv.u[3] = pack2(s[qt][2 * kk + 1][2], s[qt][2 * kk + 1][3]);
;       pb[qt][kk] = cv.v;
;     }
;   }
	v_mfma_f32_16x16x32_bf16 v[108:111], v[128:131], v[16:19], v[108:111]
	v_mfma_f32_16x16x32_bf16 v[108:111], v[132:135], v[20:23], v[108:111]
	v_mfma_f32_16x16x32_bf16 v[108:111], v[136:139], v[24:27], v[108:111]
	v_mfma_f32_16x16x32_bf16 v[108:111], v[140:143], v[28:31], v[108:111]
	s_nop 7
	v_max3_f32 v235, v96, v97, v98
	v_max3_f32 v235, v235, v99, v100
	v_max3_f32 v235, v235, v101, v102
	v_max3_f32 v235, v235, v103, v104
	v_max3_f32 v235, v235, v105, v106
	v_max3_f32 v235, v235, v107, v108
	v_max3_f32 v235, v235, v109, v110
	v_max_f32_e32 v235, v111, v235
	ds_bpermute_b32 v236, v228, v235
	s_waitcnt lgkmcnt(0)
	v_max_f32_e32 v235, v236, v235
	v_mov_b32_e32 v236, v235
	v_mov_b32_e32 v237, v235
	s_nop 1
	v_permlane32_swap_b32_e32 v236, v237
	v_max_f32_e32 v235, v236, v237
	v_max_f32_e32 v238, v229, v235
	v_sub_f32_e32 v239, v229, v238
	v_mul_f32_e32 v239, 0x3db8aa3b, v239
	v_exp_f32_e32 v239, v239
	v_mov_b32_e32 v229, v238
	v_mul_f32_e32 v240, 0xbdb8aa3b, v238
	v_fma_f32 v96, v96, v242, v240
	v_exp_f32_e32 v96, v96
	v_fma_f32 v97, v97, v242, v240
	v_exp_f32_e32 v97, v97
	v_fma_f32 v98, v98, v242, v240
	v_exp_f32_e32 v98, v98
	v_fma_f32 v99, v99, v242, v240
	v_exp_f32_e32 v99, v99
	v_fma_f32 v100, v100, v242, v240
	v_exp_f32_e32 v100, v100
	v_fma_f32 v101, v101, v242, v240
	v_exp_f32_e32 v101, v101
	v_fma_f32 v102, v102, v242, v240
	v_exp_f32_e32 v102, v102
	v_fma_f32 v103, v103, v242, v240
	v_exp_f32_e32 v103, v103
	v_fma_f32 v104, v104, v242, v240
	v_exp_f32_e32 v104, v104
	v_fma_f32 v105, v105, v242, v240
	v_exp_f32_e32 v105, v105
	v_fma_f32 v106, v106, v242, v240
	v_exp_f32_e32 v106, v106
	v_fma_f32 v107, v107, v242, v240
	v_exp_f32_e32 v107, v107
	v_fma_f32 v108, v108, v242, v240
	v_exp_f32_e32 v108, v108
	v_fma_f32 v109, v109, v242, v240
	v_exp_f32_e32 v109, v109
	v_fma_f32 v110, v110, v242, v240
	v_exp_f32_e32 v110, v110
	v_fma_f32 v111, v111, v242, v240
	v_exp_f32_e32 v111, v111
	s_nop 0
	v_add_f32_e32 v241, v96, v97
	v_add_f32_e32 v241, v98, v241
	v_add_f32_e32 v241, v99, v241
	v_add_f32_e32 v241, v100, v241
	v_add_f32_e32 v241, v101, v241
	v_add_f32_e32 v241, v102, v241
	v_add_f32_e32 v241, v103, v241
	v_add_f32_e32 v241, v104, v241
	v_add_f32_e32 v241, v105, v241
	v_add_f32_e32 v241, v106, v241
	v_add_f32_e32 v241, v107, v241
	v_add_f32_e32 v241, v108, v241
	v_add_f32_e32 v241, v109, v241
	v_add_f32_e32 v241, v110, v241
	v_add_f32_e32 v241, v111, v241
	v_fma_f32 v230, v230, v239, v241
	v_mul_f32_e32 v32, v239, v32
	v_mul_f32_e32 v33, v239, v33
	v_mul_f32_e32 v34, v239, v34
	v_mul_f32_e32 v35, v239, v35
	v_mul_f32_e32 v36, v239, v36
	v_mul_f32_e32 v37, v239, v37
	v_mul_f32_e32 v38, v239, v38
	v_mul_f32_e32 v39, v239, v39
	v_mul_f32_e32 v40, v239, v40
	v_mul_f32_e32 v41, v239, v41
	v_mul_f32_e32 v42, v239, v42
	v_mul_f32_e32 v43, v239, v43
	v_mul_f32_e32 v44, v239, v44
	v_mul_f32_e32 v45, v239, v45
	v_mul_f32_e32 v46, v239, v46
	v_mul_f32_e32 v47, v239, v47
	v_mul_f32_e32 v48, v239, v48
	v_mul_f32_e32 v49, v239, v49
	v_mul_f32_e32 v50, v239, v50
	v_mul_f32_e32 v51, v239, v51
	v_mul_f32_e32 v52, v239, v52
	v_mul_f32_e32 v53, v239, v53
	v_mul_f32_e32 v54, v239, v54
	v_mul_f32_e32 v55, v239, v55
	v_mul_f32_e32 v56, v239, v56
	v_mul_f32_e32 v57, v239, v57
	v_mul_f32_e32 v58, v239, v58
	v_mul_f32_e32 v59, v239, v59
	v_mul_f32_e32 v60, v239, v60
	v_mul_f32_e32 v61, v239, v61
	v_mul_f32_e32 v62, v239, v62
	v_mul_f32_e32 v63, v239, v63
	v_mul_f32_e32 v64, v239, v64
	v_mul_f32_e32 v65, v239, v65
	v_mul_f32_e32 v66, v239, v66
	v_mul_f32_e32 v67, v239, v67
	v_mul_f32_e32 v68, v239, v68
	v_mul_f32_e32 v69, v239, v69
	v_mul_f32_e32 v70, v239, v70
	v_mul_f32_e32 v71, v239, v71
	v_mul_f32_e32 v72, v239, v72
	v_mul_f32_e32 v73, v239, v73
	v_mul_f32_e32 v74, v239, v74
	v_mul_f32_e32 v75, v239, v75
	v_mul_f32_e32 v76, v239, v76
	v_mul_f32_e32 v77, v239, v77
	v_mul_f32_e32 v78, v239, v78
	v_mul_f32_e32 v79, v239, v79
	v_mul_f32_e32 v80, v239, v80
	v_mul_f32_e32 v81, v239, v81
	v_mul_f32_e32 v82, v239, v82
	v_mul_f32_e32 v83, v239, v83
	v_mul_f32_e32 v84, v239, v84
	v_mul_f32_e32 v85, v239, v85
	v_mul_f32_e32 v86, v239, v86
	v_mul_f32_e32 v87, v239, v87
	v_mul_f32_e32 v88, v239, v88
	v_mul_f32_e32 v89, v239, v89
	v_mul_f32_e32 v90, v239, v90
	v_mul_f32_e32 v91, v239, v91
	v_mul_f32_e32 v92, v239, v92
	v_mul_f32_e32 v93, v239, v93
	v_mul_f32_e32 v94, v239, v94
	v_mul_f32_e32 v95, v239, v95
	v_cvt_pk_bf16_f32 v212, v96, v97
	v_cvt_pk_bf16_f32 v213, v98, v99
	v_cvt_pk_bf16_f32 v214, v100, v101
	v_cvt_pk_bf16_f32 v215, v102, v103
	v_cvt_pk_bf16_f32 v216, v104, v105
	v_cvt_pk_bf16_f32 v217, v106, v107
	v_cvt_pk_bf16_f32 v218, v108, v109
	v_cvt_pk_bf16_f32 v219, v110, v111
	s_waitcnt vmcnt(8)
	ds_write_b128 v224, v[176:179]
	ds_write_b128 v224, v[180:183] offset:4608
	ds_write_b128 v224, v[184:187] offset:9216
	ds_write_b128 v224, v[188:191] offset:13824
	ds_write_b128 v224, v[192:195] offset:18432
	ds_write_b128 v224, v[196:199] offset:23040
	ds_write_b128 v224, v[200:203] offset:27648
	ds_write_b128 v224, v[204:207] offset:32256
	s_waitcnt lgkmcnt(0)
	s_barrier
; DEVI f32x4 mfma16(bf16x8 a, bf16x8 b, f32x4 c) { return __builtin_amdgcn_mfma_f32_16x16x32_bf16(a, b, c, 0, 0, 0); }
; #define LOADK_(kbx) LK1_(0, kbx) LK1_(1, kbx) LK1_(2, kbx) LK1_(3, kbx) LK1_(4, kbx) LK1_(5, kbx) LK1_(6, kbx) LK1_(7, kbx)
; #define STOREK_() SK1_(0) SK1_(1) SK1_(2) SK1_(3) SK1_(4) SK1_(5) SK1_(6) SK1_(7)
; #define LOADV_(kbx) LV1_(0, kbx) LV1_(1, kbx) LV1_(2, kbx) LV1_(3, kbx) LV1_(4, kbx) LV1_(5, kbx) LV1_(6, kbx) LV1_(7, kbx)
; template <int DH, int NQ, int LDV>
; DEVI void attn_pv(const u16* sVt, const bf16x8 (&pb)[NQ][2], f32x4 (&o)[NQ][DH / 16], int lane) {
;   const int col = lane & 15, quad = lane >> 4;
;   __builtin_amdgcn_s_setprio(1);
; #pragma unroll
;   for (int dt = 0; dt < DH / 16; ++dt) {
; #pragma unroll
;     for (int kk = 0; kk < 2; ++kk) {
;       union { bf16x8 v; uint2 h[2]; } cv;
;       cv.h[0] = *(const uint2*)(sVt + (16 * dt + col) * LDV + 32 * kk + 4 * quad);
;       cv.h[1] = *(const uint2*)(sVt + (16 * dt + col) * LDV + 32 * kk + 16 + 4 * quad);
; #pragma unroll
;       for (int qt = 0; qt < NQ; ++qt) o[qt][dt] = mfma16(cv.v, pb[qt][kk], o[qt][dt]);
;     }
;   }
;   __builtin_amdgcn_s_setprio(0);
; DEVI void phase_memattn(const Params& p, unsigned char* smem) {
;     ...
;       if (kb < 3) { LOADK_(kb + 1) }
;       __syncthreads();
;       attn_pv<256, 1, 72>(sVt, pb, o, lane);
;       if (kb < 3) {
;         STOREK_()
;         LOADV_(kb + 1)
;       }
;       __syncthreads();
	s_lshl_b32 s16, s10, 2
	s_add_u32 s16, s16, s11
	s_lshl_b32 s16, s16, 17
	s_add_u32 s16, s16, 384
	v_add_u32_e32 v231, s16, v222
	global_load_dwordx4 v[176:179], v231, s[4:5]
	s_add_u32 s16, s16, 0x4000
	v_add_u32_e32 v232, s16, v222
	global_load_dwordx4 v[180:183], v232, s[4:5]
	s_add_u32 s16, s16, 0x4000
	v_add_u32_e32 v233, s16, v222
	global_load_dwordx4 v[184:187], v233, s[4:5]
	s_add_u32 s16, s16, 0x4000
	v_add_u32_e32 v234, s16, v222
	global_load_dwordx4 v[188:191], v234, s[4:5]
	s_add_u32 s16, s16, 0x4000
	v_add_u32_e32 v231, s16, v222
	global_load_dwordx4 v[192:195], v231, s[4:5]
	s_add_u32 s16, s16, 0x4000
	v_add_u32_e32 v232, s16, v222
	global_load_dwordx4 v[196:199], v232, s[4:5]
	s_add_u32 s16, s16, 0x4000
	v_add_u32_e32 v233, s16, v222
	global_load_dwordx4 v[200:203], v233, s[4:5]
	s_add_u32 s16, s16, 0x4000
	v_add_u32_e32 v234, s16, v222
	global_load_dwordx4 v[204:207], v234, s[4:5]
	ds_read_b64 v[112:113], v226 offset:0
	ds_read_b64 v[114:115], v226 offset:32
	ds_read_b64 v[116:117], v226 offset:64
	ds_read_b64 v[118:119], v226 offset:96
	ds_read_b64 v[120:121], v226 offset:2304
	ds_read_b64 v[122:123], v226 offset:2336
	ds_read_b64 v[124:125], v226 offset:2368
	ds_read_b64 v[126:127], v226 offset:2400
	ds_read_b64 v[128:129], v226 offset:4608
	ds_read_b64 v[130:131], v226 offset:4640
	ds_read_b64 v[132:133], v226 offset:4672
	ds_read_b64 v[134:135], v226 offset:4704
	ds_read_b64 v[136:137], v226 offset:6912
	ds_read_b64 v[138:139], v226 offset:6944
	ds_read_b64 v[140:141], v226 offset:6976
	ds_read_b64 v[142:143], v226 offset:7008
	s_waitcnt lgkmcnt(14)
	v_mfma_f32_16x16x32_bf16 v[32:35], v[112:115], v[212:215], v[32:35]
	ds_read_b64 v[112:113], v226 offset:9216
	ds_read_b64 v[114:115], v226 offset:9248
	s_waitcnt lgkmcnt(14)
	v_mfma_f32_16x16x32_bf16 v[32:35], v[116:119], v[216:219], v[32:35]
	ds_read_b64 v[116:117], v226 offset:9280
	ds_read_b64 v[118:119], v226 offset:9312
	s_waitcnt lgkmcnt(14)
	v_mfma_f32_16x16x32_bf16 v[36:39], v[120:123], v[212:215], v[36:39]
	ds_read_b64 v[120:121], v226 offset:11520
	ds_read_b64 v[122:123], v226 offset:11552
	s_waitcnt lgkmcnt(14)
	v_mfma_f32_16x16x32_bf16 v[36:39], v[124:127], v[216:219], v[36:39]
	ds_read_b64 v[124:125], v226 offset:11584
	ds_read_b64 v[126:127], v226 offset:11616
	s_waitcnt lgkmcnt(14)
	v_mfma_f32_16x16x32_bf16 v[40:43], v[128:131], v[212:215], v[40:43]
	ds_read_b64 v[128:129], v226 offset:13824
	ds_read_b64 v[130:131], v226 offset:13856
	s_waitcnt lgkmcnt(14)
	v_mfma_f32_16x16x32_bf16 v[40:43], v[132:135], v[216:219], v[40:43]
	ds_read_b64 v[132:133], v226 offset:13888
	ds_read_b64 v[134:135], v226 offset:13920
	s_waitcnt lgkmcnt(14)
	v_mfma_f32_16x16x32_bf16 v[44:47], v[136:139], v[212:215], v[44:47]
	ds_read_b64 v[136:137], v226 offset:16128
	ds_read_b64 v[138:139], v226 offset:16160
	s_waitcnt lgkmcnt(14)
	v_mfma_f32_16x16x32_bf16 v[44:47], v[140:143], v[216:219], v[44:47]
	ds_read_b64 v[140:141], v226 offset:16192
	ds_read_b64 v[142:143], v226 offset:16224
	s_waitcnt lgkmcnt(14)
	v_mfma_f32_16x16x32_bf16 v[48:51], v[112:115], v[212:215], v[48:51]
	ds_read_b64 v[112:113], v226 offset:18432
	ds_read_b64 v[114:115], v226 offset:18464
	s_waitcnt lgkmcnt(14)
	v_mfma_f32_16x16x32_bf16 v[48:51], v[116:119], v[216:219], v[48:51]
	ds_read_b64 v[116:117], v226 offset:18496
	ds_read_b64 v[118:119], v226 offset:18528
	s_waitcnt lgkmcnt(14)
	v_mfma_f32_16x16x32_bf16 v[52:55], v[120:123], v[212:215], v[52:55]
	ds_read_b64 v[120:121], v226 offset:20736
	ds_read_b64 v[122:123], v226 offset:20768
	s_waitcnt lgkmcnt(14)
	v_mfma_f32_16x16x32_bf16 v[52:55], v[124:127], v[216:219], v[52:55]
	ds_read_b64 v[124:125], v226 offset:20800
	ds_read_b64 v[126:127], v226 offset:20832
	s_waitcnt lgkmcnt(14)
	v_mfma_f32_16x16x32_bf16 v[56:59], v[128:131], v[212:215], v[56:59]
	ds_read_b64 v[128:129], v226 offset:23040
	ds_read_b64 v[130:131], v226 offset:23072
	s_waitcnt lgkmcnt(14)
	v_mfma_f32_16x16x32_bf16 v[56:59], v[132:135], v[216:219], v[56:59]
	ds_read_b64 v[132:133], v226 offset:23104
	ds_read_b64 v[134:135], v226 offset:23136
	s_waitcnt lgkmcnt(14)
	v_mfma_f32_16x16x32_bf16 v[60:63], v[136:139], v[212:215], v[60:63]
	ds_read_b64 v[136:137], v226 offset:25344
	ds_read_b64 v[138:139], v226 offset:25376
	s_waitcnt lgkmcnt(14)
	v_mfma_f32_16x16x32_bf16 v[60:63], v[140:143], v[216:219], v[60:63]
	ds_read_b64 v[140:141], v226 offset:25408
	ds_read_b64 v[142:143], v226 offset:25440
	s_waitcnt lgkmcnt(14)
	v_mfma_f32_16x16x32_bf16 v[64:67], v[112:115], v[212:215], v[64:67]
	ds_read_b64 v[112:113], v226 offset:27648
	ds_read_b64 v[114:115], v226 offset:27680
	s_waitcnt lgkmcnt(14)
	v_mfma_f32_16x16x32_bf16 v[64:67], v[116:119], v[216:219], v[64:67]
	ds_read_b64 v[116:117], v226 offset:27712
	ds_read_b64 v[118:119], v226 offset:27744
	s_waitcnt lgkmcnt(14)
	v_mfma_f32_16x16x32_bf16 v[68:71], v[120:123], v[212:215], v[68:71]
	ds_read_b64 v[120:121], v226 offset:29952
	ds_read_b64 v[122:123], v226 offset:29984
	s_waitcnt lgkmcnt(14)
	v_mfma_f32_16x16x32_bf16 v[68:71], v[124:127], v[216:219], v[68:71]
	ds_read_b64 v[124:125], v226 offset:30016
	ds_read_b64 v[126:127], v226 offset:30048
	s_waitcnt lgkmcnt(14)
	v_mfma_f32_16x16x32_bf16 v[72:75], v[128:131], v[212:215], v[72:75]
	ds_read_b64 v[128:129], v226 offset:32256
	ds_read_b64 v[130:131], v226 offset:32288
	s_waitcnt lgkmcnt(14)
	v_mfma_f32_16x16x32_bf16 v[72:75], v[132:135], v[216:219], v[72:75]
	ds_read_b64 v[132:133], v226 offset:32320
	ds_read_b64 v[134:135], v226 offset:32352
	s_waitcnt lgkmcnt(14)
	v_mfma_f32_16x16x32_bf16 v[76:79], v[136:139], v[212:215], v[76:79]
	ds_read_b64 v[136:137], v226 offset:34560
	ds_read_b64 v[138:139], v226 offset:34592
	s_waitcnt lgkmcnt(14)
	v_mfma_f32_16x16x32_bf16 v[76:79], v[140:143], v[216:219], v[76:79]
	ds_read_b64 v[140:141], v226 offset:34624
	ds_read_b64 v[142:143], v226 offset:34656
	s_waitcnt lgkmcnt(14)
	v_mfma_f32_16x16x32_bf16 v[80:83], v[112:115], v[212:215], v[80:83]
	s_waitcnt lgkmcnt(12)
	v_mfma_f32_16x16x32_bf16 v[80:83], v[116:119], v[216:219], v[80:83]
	s_waitcnt lgkmcnt(10)
	v_mfma_f32_16x16x32_bf16 v[84:87], v[120:123], v[212:215], v[84:87]
	s_waitcnt lgkmcnt(8)
	v_mfma_f32_16x16x32_bf16 v[84:87], v[124:127], v[216:219], v[84:87]
	s_waitcnt lgkmcnt(6)
	v_mfma_f32_16x16x32_bf16 v[88:91], v[128:131], v[212:215], v[88:91]
	s_waitcnt lgkmcnt(4)
	v_mfma_f32_16x16x32_bf16 v[88:91], v[132:135], v[216:219], v[88:91]
	s_waitcnt lgkmcnt(2)
	v_mfma_f32_16x16x32_bf16 v[92:95], v[136:139], v[212:215], v[92:95]
	s_waitcnt lgkmcnt(0)
	v_mfma_f32_16x16x32_bf16 v[92:95], v[140:143], v[216:219], v[92:95]
	s_waitcnt vmcnt(8)
	ds_write_b128 v223, v[144:147]
	ds_write_b128 v223, v[148:151] offset:4224
	ds_write_b128 v223, v[152:155] offset:8448
	ds_write_b128 v223, v[156:159] offset:12672
	ds_write_b128 v223, v[160:163] offset:16896
	ds_write_b128 v223, v[164:167] offset:21120
	ds_write_b128 v223, v[168:171] offset:25344
	ds_write_b128 v223, v[172:175] offset:29568
	s_waitcnt lgkmcnt(0)
	s_barrier
; DEVI f32x4 mfma16(bf16x8 a, bf16x8 b, f32x4 c) { return __builtin_amdgcn_mfma_f32_16x16x32_bf16(a, b, c, 0, 0, 0); }
; DEVI float fexp2(float x) { return __builtin_amdgcn_exp2f(x); }
; template <int DH, int NQ, int LDK, class MaskF>
; DEVI void attn_qk(const u16* sK, const bf16x8 (&qf)[NQ][DH / 32], f32x4 (&o)[NQ][DH / 16], float (&m)[NQ], float (&l)[NQ],
;                   float c2, int lane, MaskF valid, bf16x8 (&pb)[NQ][2]) {
;     ...
;   __builtin_amdgcn_s_setprio(1);
; #pragma unroll
;   for (int kt = 0; kt < 4; ++kt) {
; #pragma unroll
;     for (int qt = 0; qt < NQ; ++qt) s[qt][kt] = f32x4{0.f, 0.f, 0.f, 0.f};
; #pragma unroll
;     for (int ks = 0; ks < DH / 32; ++ks) {
;       const bf16x8 kf = *(const bf16x8*)(sK + (16 * kt + col) * LDK + 32 * ks + 8 * quad);
; #pragma unroll
;       for (int qt = 0; qt < NQ; ++qt) s[qt][kt] = mfma16(kf, qf[qt][ks], s[qt][kt]);
;     }
;   }
;   __builtin_amdgcn_s_setprio(0);
; #pragma unroll
;   for (int qt = 0; qt < NQ; ++qt) {
;     float mx = -1e30f;
; #pragma unroll
;     for (int kt = 0; kt < 4; ++kt)
; #pragma unroll
;       for (int r = 0; r < 4; ++r) {
;         const bool v = valid(qt, 16 * kt + 4 * quad + r);
;         const float sv = v ? s[qt][kt][r] : -1e30f;
;         s[qt][kt][r] = sv;
;         mx = fmaxf(mx, sv);
;       }
;     mx = fmaxf(mx, __shfl_xor(mx, 16));
;     mx = fmaxf(mx, __shfl_xor(mx, 32));
;     const float mn = fmaxf(m[qt], mx);
;     const float alpha = fexp2((m[qt] - mn) * c2);
;     m[qt] = mn;
;     const float mc = fmaxf(mn, -1e20f) * c2;
;     float ps = 0.f;
; #pragma unroll
;     for (int kt = 0; kt < 4; ++kt)
; #pragma unroll
;       for (int r = 0; r < 4; ++r) {
;         const float pv = fexp2(__builtin_fmaf(s[qt][kt][r], c2, -mc));
;         ps += pv;
;         s[qt][kt][r] = pv;
;       }
;     l[qt] = l[qt] * alpha + ps;
	ds_read_b128 v[112:115], v225
	ds_read_b128 v[116:119], v225 offset:64
	ds_read_b128 v[120:123], v225 offset:128
	ds_read_b128 v[124:127], v225 offset:192
	ds_read_b128 v[128:131], v225 offset:256
	ds_read_b128 v[132:135], v225 offset:320
	ds_read_b128 v[136:139], v225 offset:384
	ds_read_b128 v[140:143], v225 offset:448
	s_waitcnt lgkmcnt(4)
	v_mfma_f32_16x16x32_bf16 v[96:99], v[112:115], v[0:3], 0
	v_mfma_f32_16x16x32_bf16 v[96:99], v[116:119], v[4:7], v[96:99]
	v_mfma_f32_16x16x32_bf16 v[96:99], v[120:123], v[8:11], v[96:99]
	v_mfma_f32_16x16x32_bf16 v[96:99], v[124:127], v[12:15], v[96:99]
	ds_read_b128 v[112:115], v225 offset:8448
	ds_read_b128 v[116:119], v225 offset:8512
	ds_read_b128 v[120:123], v225 offset:8576
	ds_read_b128 v[124:127], v225 offset:8640
	s_waitcnt lgkmcnt(4)
	v_mfma_f32_16x16x32_bf16 v[96:99], v[128:131], v[16:19], v[96:99]
	v_mfma_f32_16x16x32_bf16 v[96:99], v[132:135], v[20:23], v[96:99]
	v_mfma_f32_16x16x32_bf16 v[96:99], v[136:139], v[24:27], v[96:99]
	v_mfma_f32_16x16x32_bf16 v[96:99], v[140:143], v[28:31], v[96:99]
	ds_read_b128 v[128:131], v225 offset:8704
	ds_read_b128 v[132:135], v225 offset:8768
	ds_read_b128 v[136:139], v225 offset:8832
	ds_read_b128 v[140:143], v225 offset:8896
	s_waitcnt lgkmcnt(4)
	v_mfma_f32_16x16x32_bf16 v[100:103], v[112:115], v[0:3], 0
	v_mfma_f32_16x16x32_bf16 v[100:103], v[116:119], v[4:7], v[100:103]
	v_mfma_f32_16x16x32_bf16 v[100:103], v[120:123], v[8:11], v[100:103]
	v_mfma_f32_16x16x32_bf16 v[100:103], v[124:127], v[12:15], v[100:103]
	ds_read_b128 v[112:115], v225 offset:16896
	ds_read_b128 v[116:119], v225 offset:16960
	ds_read_b128 v[120:123], v225 offset:17024
	ds_read_b128 v[124:127], v225 offset:17088
	s_waitcnt lgkmcnt(4)
	v_mfma_f32_16x16x32_bf16 v[100:103], v[128:131], v[16:19], v[100:103]
	v_mfma_f32_16x16x32_bf16 v[100:103], v[132:135], v[20:23], v[100:103]
	v_mfma_f32_16x16x32_bf16 v[100:103], v[136:139], v[24:27], v[100:103]
	v_mfma_f32_16x16x32_bf16 v[100:103], v[140:143], v[28:31], v[100:103]
	ds_read_b128 v[128:131], v225 offset:17152
	ds_read_b128 v[132:135], v225 offset:17216
	ds_read_b128 v[136:139], v225 offset:17280
	ds_read_b128 v[140:143], v225 offset:17344
	s_waitcnt lgkmcnt(4)
	v_mfma_f32_16x16x32_bf16 v[104:107], v[112:115], v[0:3], 0
	v_mfma_f32_16x16x32_bf16 v[104:107], v[116:119], v[4:7], v[104:107]
	v_mfma_f32_16x16x32_bf16 v[104:107], v[120:123], v[8:11], v[104:107]
	v_mfma_f32_16x16x32_bf16 v[104:107], v[124:127], v[12:15], v[104:107]
	ds_read_b128 v[112:115], v225 offset:25344
	ds_read_b128 v[116:119], v225 offset:25408
	ds_read_b128 v[120:123], v225 offset:25472
	ds_read_b128 v[124:127], v225 offset:25536
	s_waitcnt lgkmcnt(4)
	v_mfma_f32_16x16x32_bf16 v[104:107], v[128:131], v[16:19], v[104:107]
	v_mfma_f32_16x16x32_bf16 v[104:107], v[132:135], v[20:23], v[104:107]
	v_mfma_f32_16x16x32_bf16 v[104:107], v[136:139], v[24:27], v[104:107]
	v_mfma_f32_16x16x32_bf16 v[104:107], v[140:143], v[28:31], v[104:107]
	ds_read_b128 v[128:131], v225 offset:25600
	ds_read_b128 v[132:135], v225 offset:25664
	ds_read_b128 v[136:139], v225 offset:25728
	ds_read_b128 v[140:143], v225 offset:25792
	s_waitcnt lgkmcnt(4)
	v_mfma_f32_16x16x32_bf16 v[108:111], v[112:115], v[0:3], 0
	v_mfma_f32_16x16x32_bf16 v[108:111], v[116:119], v[4:7], v[108:111]
	v_mfma_f32_16x16x32_bf16 v[108:111], v[120:123], v[8:11], v[108:111]
	v_mfma_f32_16x16x32_bf16 v[108:111], v[124:127], v[12:15], v[108:111]
	s_waitcnt lgkmcnt(0)
	v_mfma_f32_16x16x32_bf16 v[108:111], v[128:131], v[16:19], v[108:111]
	v_mfma_f32_16x16x32_bf16 v[108:111], v[132:135], v[20:23], v[108:111]
	v_mfma_f32_16x16x32_bf16 v[108:111], v[136:139], v[24:27], v[108:111]
	v_mfma_f32_16x16x32_bf16 v[108:111], v[140:143], v[28:31], v[108:111]
	s_nop 7
	v_max3_f32 v235, v96, v97, v98
	v_max3_f32 v235, v235, v99, v100
	v_max3_f32 v235, v235, v101, v102
	v_max3_f32 v235, v235, v103, v104
	v_max3_f32 v235, v235, v105, v106
	v_max3_f32 v235, v235, v107, v108
	v_max3_f32 v235, v235, v109, v110
	v_max_f32_e32 v235, v111, v235
	ds_bpermute_b32 v236, v228, v235
	s_waitcnt lgkmcnt(0)
	v_max_f32_e32 v235, v236, v235
	v_mov_b32_e32 v236, v235
	v_mov_b32_e32 v237, v235
	s_nop 1
	v_permlane32_swap_b32_e32 v236, v237
	v_max_f32_e32 v235, v236, v237
	v_max_f32_e32 v238, v229, v235
	v_sub_f32_e32 v239, v229, v238
	v_mul_f32_e32 v239, 0x3db8aa3b, v239
	v_exp_f32_e32 v239, v239
	v_mov_b32_e32 v229, v238
	v_mul_f32_e32 v240, 0xbdb8aa3b, v238
	v_fma_f32 v96, v96, v242, v240
	v_exp_f32_e32 v96, v96
	v_fma_f32 v97, v97, v242, v240
	v_exp_f32_e32 v97, v97
	v_fma_f32 v98, v98, v242, v240
	v_exp_f32_e32 v98, v98
	v_fma_f32 v99, v99, v242, v240
	v_exp_f32_e32 v99, v99
	v_fma_f32 v100, v100, v242, v240
	v_exp_f32_e32 v100, v100
	v_fma_f32 v101, v101, v242, v240
	v_exp_f32_e32 v101, v101
	v_fma_f32 v102, v102, v242, v240
	v_exp_f32_e32 v102, v102
	v_fma_f32 v103, v103, v242, v240
	v_exp_f32_e32 v103, v103
	v_fma_f32 v104, v104, v242, v240
	v_exp_f32_e32 v104, v104
	v_fma_f32 v105, v105, v242, v240
	v_exp_f32_e32 v105, v105
	v_fma_f32 v106, v106, v242, v240
	v_exp_f32_e32 v106, v106
	v_fma_f32 v107, v107, v242, v240
	v_exp_f32_e32 v107, v107
	v_fma_f32 v108, v108, v242, v240
	v_exp_f32_e32 v108, v108
	v_fma_f32 v109, v109, v242, v240
	v_exp_f32_e32 v109, v109
	v_fma_f32 v110, v110, v242, v240
	v_exp_f32_e32 v110, v110
	v_fma_f32 v111, v111, v242, v240
	v_exp_f32_e32 v111, v111
	s_nop 0
	v_add_f32_e32 v241, v96, v97
	v_add_f32_e32 v241, v98, v241
	v_add_f32_e32 v241, v99, v241
	v_add_f32_e32 v241, v100, v241
	v_add_f32_e32 v241, v101, v241
	v_add_f32_e32 v241, v102, v241
	v_add_f32_e32 v241, v103, v241
	v_add_f32_e32 v241, v104, v241
; DEVI unsigned pack2(float a, float b) { return (unsigned)f2bf(a) | ((unsigned)f2bf(b) << 16); }
; DEVI f32x4 mfma16(bf16x8 a, bf16x8 b, f32x4 c) { return __builtin_amdgcn_mfma_f32_16x16x32_bf16(a, b, c, 0, 0, 0); }
; template <int DH, int NQ, int LDK, class MaskF>
; DEVI void attn_qk(const u16* sK, const bf16x8 (&qf)[NQ][DH / 32], f32x4 (&o)[NQ][DH / 16], float (&m)[NQ], float (&l)[NQ],
;                   float c2, int lane, MaskF valid, bf16x8 (&pb)[NQ][2]) {
;     ...
;     l[qt] = l[qt] * alpha + ps;
; #pragma unroll
;     for (int dt = 0; dt < DH / 16; ++dt) o[qt][dt] *= alpha;
; #pragma unroll
;     for (int kk = 0; kk < 2; ++kk) {
;       union { bf16x8 v; unsigned u[4]; } cv;
;       cv.u[0] = pack2(s[qt][2 * kk][0], s[qt][2 * kk][1]);
;       cv.u[1] = pack2(s[qt][2 * kk][2], s[qt][2 * kk][3]);
;       cv.u[2] = pack2(s[qt][2 * kk + 1][0], s[qt][2 * kk + 1][1]);
;       cv.u[3] = pack2(s[qt][2 * kk + 1][2], s[qt][2 * kk + 1][3]);
;       pb[qt][kk] = cv.v;
;     }
;   }
; }
; template <int DH, int NQ, int LDV>
; DEVI void attn_pv(const u16* sVt, const bf16x8 (&pb)[NQ][2], f32x4 (&o)[NQ][DH / 16], int lane) {
;   const int col = lane & 15, quad = lane >> 4;
;   __builtin_amdgcn_s_setprio(1);
; #pragma unroll
;   for (int dt = 0; dt < DH / 16; ++dt) {
; #pragma unroll
;     for (int kk = 0; kk < 2; ++kk) {
;       union { bf16x8 v; uint2 h[2]; } cv;
;       cv.h[0] = *(const uint2*)(sVt + (16 * dt + col) * LDV + 32 * kk + 4 * quad);
;       cv.h[1] = *(const uint2*)(sVt + (16 * dt + col) * LDV + 32 * kk + 16 + 4 * quad);
; #pragma unroll
;       for (int qt = 0; qt < NQ; ++qt) o[qt][dt] = mfma16(cv.v, pb[qt][kk], o[qt][dt]);
;     }
;   }
;   __builtin_amdgcn_s_setprio(0);
	v_add_f32_e32 v241, v105, v241
	v_add_f32_e32 v241, v106, v241
	v_add_f32_e32 v241, v107, v241
	v_add_f32_e32 v241, v108, v241
	v_add_f32_e32 v241, v109, v241
	v_add_f32_e32 v241, v110, v241
	v_add_f32_e32 v241, v111, v241
	v_fma_f32 v230, v230, v239, v241
	v_mul_f32_e32 v32, v239, v32
	v_mul_f32_e32 v33, v239, v33
	v_mul_f32_e32 v34, v239, v34
	v_mul_f32_e32 v35, v239, v35
	v_mul_f32_e32 v36, v239, v36
	v_mul_f32_e32 v37, v239, v37
	v_mul_f32_e32 v38, v239, v38
	v_mul_f32_e32 v39, v239, v39
	v_mul_f32_e32 v40, v239, v40
	v_mul_f32_e32 v41, v239, v41
	v_mul_f32_e32 v42, v239, v42
	v_mul_f32_e32 v43, v239, v43
	v_mul_f32_e32 v44, v239, v44
	v_mul_f32_e32 v45, v239, v45
	v_mul_f32_e32 v46, v239, v46
	v_mul_f32_e32 v47, v239, v47
	v_mul_f32_e32 v48, v239, v48
	v_mul_f32_e32 v49, v239, v49
	v_mul_f32_e32 v50, v239, v50
	v_mul_f32_e32 v51, v239, v51
	v_mul_f32_e32 v52, v239, v52
	v_mul_f32_e32 v53, v239, v53
	v_mul_f32_e32 v54, v239, v54
	v_mul_f32_e32 v55, v239, v55
	v_mul_f32_e32 v56, v239, v56
	v_mul_f32_e32 v57, v239, v57
	v_mul_f32_e32 v58, v239, v58
	v_mul_f32_e32 v59, v239, v59
	v_mul_f32_e32 v60, v239, v60
	v_mul_f32_e32 v61, v239, v61
	v_mul_f32_e32 v62, v239, v62
	v_mul_f32_e32 v63, v239, v63
	v_mul_f32_e32 v64, v239, v64
	v_mul_f32_e32 v65, v239, v65
	v_mul_f32_e32 v66, v239, v66
	v_mul_f32_e32 v67, v239, v67
	v_mul_f32_e32 v68, v239, v68
	v_mul_f32_e32 v69, v239, v69
	v_mul_f32_e32 v70, v239, v70
	v_mul_f32_e32 v71, v239, v71
	v_mul_f32_e32 v72, v239, v72
	v_mul_f32_e32 v73, v239, v73
	v_mul_f32_e32 v74, v239, v74
	v_mul_f32_e32 v75, v239, v75
	v_mul_f32_e32 v76, v239, v76
	v_mul_f32_e32 v77, v239, v77
	v_mul_f32_e32 v78, v239, v78
	v_mul_f32_e32 v79, v239, v79
	v_mul_f32_e32 v80, v239, v80
	v_mul_f32_e32 v81, v239, v81
	v_mul_f32_e32 v82, v239, v82
	v_mul_f32_e32 v83, v239, v83
	v_mul_f32_e32 v84, v239, v84
	v_mul_f32_e32 v85, v239, v85
	v_mul_f32_e32 v86, v239, v86
	v_mul_f32_e32 v87, v239, v87
	v_mul_f32_e32 v88, v239, v88
	v_mul_f32_e32 v89, v239, v89
	v_mul_f32_e32 v90, v239, v90
	v_mul_f32_e32 v91, v239, v91
	v_mul_f32_e32 v92, v239, v92
	v_mul_f32_e32 v93, v239, v93
	v_mul_f32_e32 v94, v239, v94
	v_mul_f32_e32 v95, v239, v95
	v_cvt_pk_bf16_f32 v212, v96, v97
	v_cvt_pk_bf16_f32 v213, v98, v99
	v_cvt_pk_bf16_f32 v214, v100, v101
	v_cvt_pk_bf16_f32 v215, v102, v103
	v_cvt_pk_bf16_f32 v216, v104, v105
	v_cvt_pk_bf16_f32 v217, v106, v107
	v_cvt_pk_bf16_f32 v218, v108, v109
	v_cvt_pk_bf16_f32 v219, v110, v111
	s_waitcnt vmcnt(0)
	ds_write_b128 v224, v[176:179]
	ds_write_b128 v224, v[180:183] offset:4608
	ds_write_b128 v224, v[184:187] offset:9216
	ds_write_b128 v224, v[188:191] offset:13824
	ds_write_b128 v224, v[192:195] offset:18432
	ds_write_b128 v224, v[196:199] offset:23040
	ds_write_b128 v224, v[200:203] offset:27648
	ds_write_b128 v224, v[204:207] offset:32256
	s_waitcnt lgkmcnt(0)
	s_barrier
	ds_read_b64 v[112:113], v226 offset:0
	ds_read_b64 v[114:115], v226 offset:32
	ds_read_b64 v[116:117], v226 offset:64
	ds_read_b64 v[118:119], v226 offset:96
	ds_read_b64 v[120:121], v226 offset:2304
	ds_read_b64 v[122:123], v226 offset:2336
	ds_read_b64 v[124:125], v226 offset:2368
	ds_read_b64 v[126:127], v226 offset:2400
	ds_read_b64 v[128:129], v226 offset:4608
	ds_read_b64 v[130:131], v226 offset:4640
	ds_read_b64 v[132:133], v226 offset:4672
	ds_read_b64 v[134:135], v226 offset:4704
	ds_read_b64 v[136:137], v226 offset:6912
	ds_read_b64 v[138:139], v226 offset:6944
	ds_read_b64 v[140:141], v226 offset:6976
	ds_read_b64 v[142:143], v226 offset:7008
	s_waitcnt lgkmcnt(14)
	v_mfma_f32_16x16x32_bf16 v[32:35], v[112:115], v[212:215], v[32:35]
	ds_read_b64 v[112:113], v226 offset:9216
	ds_read_b64 v[114:115], v226 offset:9248
	s_waitcnt lgkmcnt(14)
	v_mfma_f32_16x16x32_bf16 v[32:35], v[116:119], v[216:219], v[32:35]
	ds_read_b64 v[116:117], v226 offset:9280
	ds_read_b64 v[118:119], v226 offset:9312
	s_waitcnt lgkmcnt(14)
	v_mfma_f32_16x16x32_bf16 v[36:39], v[120:123], v[212:215], v[36:39]
	ds_read_b64 v[120:121], v226 offset:11520
	ds_read_b64 v[122:123], v226 offset:11552
	s_waitcnt lgkmcnt(14)
	v_mfma_f32_16x16x32_bf16 v[36:39], v[124:127], v[216:219], v[36:39]
	ds_read_b64 v[124:125], v226 offset:11584
	ds_read_b64 v[126:127], v226 offset:11616
	s_waitcnt lgkmcnt(14)
	v_mfma_f32_16x16x32_bf16 v[40:43], v[128:131], v[212:215], v[40:43]
	ds_read_b64 v[128:129], v226 offset:13824
	ds_read_b64 v[130:131], v226 offset:13856
	s_waitcnt lgkmcnt(14)
	v_mfma_f32_16x16x32_bf16 v[40:43], v[132:135], v[216:219], v[40:43]
	ds_read_b64 v[132:133], v226 offset:13888
	ds_read_b64 v[134:135], v226 offset:13920
	s_waitcnt lgkmcnt(14)
	v_mfma_f32_16x16x32_bf16 v[44:47], v[136:139], v[212:215], v[44:47]
	ds_read_b64 v[136:137], v226 offset:16128
	ds_read_b64 v[138:139], v226 offset:16160
	s_waitcnt lgkmcnt(14)
	v_mfma_f32_16x16x32_bf16 v[44:47], v[140:143], v[216:219], v[44:47]
	ds_read_b64 v[140:141], v226 offset:16192
	ds_read_b64 v[142:143], v226 offset:16224
	s_waitcnt lgkmcnt(14)
	v_mfma_f32_16x16x32_bf16 v[48:51], v[112:115], v[212:215], v[48:51]
	ds_read_b64 v[112:113], v226 offset:18432
	ds_read_b64 v[114:115], v226 offset:18464
	s_waitcnt lgkmcnt(14)
	v_mfma_f32_16x16x32_bf16 v[48:51], v[116:119], v[216:219], v[48:51]
	ds_read_b64 v[116:117], v226 offset:18496
	ds_read_b64 v[118:119], v226 offset:18528
	s_waitcnt lgkmcnt(14)
	v_mfma_f32_16x16x32_bf16 v[52:55], v[120:123], v[212:215], v[52:55]
	ds_read_b64 v[120:121], v226 offset:20736
	ds_read_b64 v[122:123], v226 offset:20768
	s_waitcnt lgkmcnt(14)
	v_mfma_f32_16x16x32_bf16 v[52:55], v[124:127], v[216:219], v[52:55]
	ds_read_b64 v[124:125], v226 offset:20800
	ds_read_b64 v[126:127], v226 offset:20832
	s_waitcnt lgkmcnt(14)
; DEVI f32x4 mfma16(bf16x8 a, bf16x8 b, f32x4 c) { return __builtin_amdgcn_mfma_f32_16x16x32_bf16(a, b, c, 0, 0, 0); }
; template <int DH, int NQ, int LDV>
; DEVI void attn_pv(const u16* sVt, const bf16x8 (&pb)[NQ][2], f32x4 (&o)[NQ][DH / 16], int lane) {
;   const int col = lane & 15, quad = lane >> 4;
;   __builtin_amdgcn_s_setprio(1);
; #pragma unroll
;   for (int dt = 0; dt < DH / 16; ++dt) {
; #pragma unroll
;     for (int kk = 0; kk < 2; ++kk) {
;       union { bf16x8 v; uint2 h[2]; } cv;
;       cv.h[0] = *(const uint2*)(sVt + (16 * dt + col) * LDV + 32 * kk + 4 * quad);
;       cv.h[1] = *(const uint2*)(sVt + (16 * dt + col) * LDV + 32 * kk + 16 + 4 * quad);
; #pragma unroll
;       for (int qt = 0; qt < NQ; ++qt) o[qt][dt] = mfma16(cv.v, pb[qt][kk], o[qt][dt]);
;     }
;   }
;   __builtin_amdgcn_s_setprio(0);
; DEVI void phase_memattn(const Params& p, unsigned char* smem) {
;     ...
;     float lt = l[0];
;     lt += __shfl_xor(lt, 16);
;     lt += __shfl_xor(lt, 32);
	v_mfma_f32_16x16x32_bf16 v[56:59], v[128:131], v[212:215], v[56:59]
	ds_read_b64 v[128:129], v226 offset:23040
	ds_read_b64 v[130:131], v226 offset:23072
	s_waitcnt lgkmcnt(14)
	v_mfma_f32_16x16x32_bf16 v[56:59], v[132:135], v[216:219], v[56:59]
	ds_read_b64 v[132:133], v226 offset:23104
	ds_read_b64 v[134:135], v226 offset:23136
	s_waitcnt lgkmcnt(14)
	v_mfma_f32_16x16x32_bf16 v[60:63], v[136:139], v[212:215], v[60:63]
	ds_read_b64 v[136:137], v226 offset:25344
	ds_read_b64 v[138:139], v226 offset:25376
	s_waitcnt lgkmcnt(14)
	v_mfma_f32_16x16x32_bf16 v[60:63], v[140:143], v[216:219], v[60:63]
	ds_read_b64 v[140:141], v226 offset:25408
	ds_read_b64 v[142:143], v226 offset:25440
	s_waitcnt lgkmcnt(14)
	v_mfma_f32_16x16x32_bf16 v[64:67], v[112:115], v[212:215], v[64:67]
	ds_read_b64 v[112:113], v226 offset:27648
	ds_read_b64 v[114:115], v226 offset:27680
	s_waitcnt lgkmcnt(14)
	v_mfma_f32_16x16x32_bf16 v[64:67], v[116:119], v[216:219], v[64:67]
	ds_read_b64 v[116:117], v226 offset:27712
	ds_read_b64 v[118:119], v226 offset:27744
	s_waitcnt lgkmcnt(14)
	v_mfma_f32_16x16x32_bf16 v[68:71], v[120:123], v[212:215], v[68:71]
	ds_read_b64 v[120:121], v226 offset:29952
	ds_read_b64 v[122:123], v226 offset:29984
	s_waitcnt lgkmcnt(14)
	v_mfma_f32_16x16x32_bf16 v[68:71], v[124:127], v[216:219], v[68:71]
	ds_read_b64 v[124:125], v226 offset:30016
	ds_read_b64 v[126:127], v226 offset:30048
	s_waitcnt lgkmcnt(14)
	v_mfma_f32_16x16x32_bf16 v[72:75], v[128:131], v[212:215], v[72:75]
	ds_read_b64 v[128:129], v226 offset:32256
	ds_read_b64 v[130:131], v226 offset:32288
	s_waitcnt lgkmcnt(14)
	v_mfma_f32_16x16x32_bf16 v[72:75], v[132:135], v[216:219], v[72:75]
	ds_read_b64 v[132:133], v226 offset:32320
	ds_read_b64 v[134:135], v226 offset:32352
	s_waitcnt lgkmcnt(14)
	v_mfma_f32_16x16x32_bf16 v[76:79], v[136:139], v[212:215], v[76:79]
	ds_read_b64 v[136:137], v226 offset:34560
	ds_read_b64 v[138:139], v226 offset:34592
	s_waitcnt lgkmcnt(14)
	v_mfma_f32_16x16x32_bf16 v[76:79], v[140:143], v[216:219], v[76:79]
	ds_read_b64 v[140:141], v226 offset:34624
	ds_read_b64 v[142:143], v226 offset:34656
	s_waitcnt lgkmcnt(14)
	v_mfma_f32_16x16x32_bf16 v[80:83], v[112:115], v[212:215], v[80:83]
	s_waitcnt lgkmcnt(12)
	v_mfma_f32_16x16x32_bf16 v[80:83], v[116:119], v[216:219], v[80:83]
	s_waitcnt lgkmcnt(10)
	v_mfma_f32_16x16x32_bf16 v[84:87], v[120:123], v[212:215], v[84:87]
	s_waitcnt lgkmcnt(8)
	v_mfma_f32_16x16x32_bf16 v[84:87], v[124:127], v[216:219], v[84:87]
	s_waitcnt lgkmcnt(6)
	v_mfma_f32_16x16x32_bf16 v[88:91], v[128:131], v[212:215], v[88:91]
	s_waitcnt lgkmcnt(4)
	v_mfma_f32_16x16x32_bf16 v[88:91], v[132:135], v[216:219], v[88:91]
	s_waitcnt lgkmcnt(2)
	v_mfma_f32_16x16x32_bf16 v[92:95], v[136:139], v[212:215], v[92:95]
	s_waitcnt lgkmcnt(0)
	v_mfma_f32_16x16x32_bf16 v[92:95], v[140:143], v[216:219], v[92:95]
	s_nop 7
	v_mov_b32_e32 v235, v230
	ds_bpermute_b32 v236, v228, v235
	s_waitcnt lgkmcnt(0)
; DEVI unsigned pack2(float a, float b) { return (unsigned)f2bf(a) | ((unsigned)f2bf(b) << 16); }
; DEVI void phase_memattn(const Params& p, unsigned char* smem) {
;     ...
;     float lt = l[0];
;     lt += __shfl_xor(lt, 16);
;     lt += __shfl_xor(lt, 32);
;     const float inv = 1.f / lt;
; #pragma unroll
;     for (int dt = 0; dt < 16; ++dt) {
;       uint2 pk;
;       pk.x = pack2(o[0][dt][0] * inv, o[0][dt][1] * inv);
;       pk.y = pack2(o[0][dt][2] * inv, o[0][dt][3] * inv);
;       *(uint2*)(p.mix + tok * LDA + head * 256 + 16 * dt + 4 * quad) = pk;
;     }
	v_add_f32_e32 v235, v236, v235
	v_mov_b32_e32 v236, v235
	v_mov_b32_e32 v237, v235
	s_nop 1
	v_permlane32_swap_b32_e32 v236, v237
	v_add_f32_e32 v235, v236, v237
	v_rcp_f32_e32 v238, v235
	s_nop 0
	v_fma_f32 v239, -v235, v238, 1.0
	v_fma_f32 v238, v239, v238, v238
	v_add_u32_e32 v231, s13, v227
	v_mul_f32_e32 v32, v238, v32
	v_mul_f32_e32 v33, v238, v33
	v_mul_f32_e32 v34, v238, v34
	v_mul_f32_e32 v35, v238, v35
	v_cvt_pk_bf16_f32 v212, v32, v33
	v_cvt_pk_bf16_f32 v213, v34, v35
	global_store_dwordx2 v231, v[212:213], s[6:7]
	v_mul_f32_e32 v36, v238, v36
	v_mul_f32_e32 v37, v238, v37
	v_mul_f32_e32 v38, v238, v38
	v_mul_f32_e32 v39, v238, v39
	v_cvt_pk_bf16_f32 v214, v36, v37
	v_cvt_pk_bf16_f32 v215, v38, v39
	global_store_dwordx2 v231, v[214:215], s[6:7] offset:32
	v_mul_f32_e32 v40, v238, v40
	v_mul_f32_e32 v41, v238, v41
	v_mul_f32_e32 v42, v238, v42
	v_mul_f32_e32 v43, v238, v43
	v_cvt_pk_bf16_f32 v212, v40, v41
	v_cvt_pk_bf16_f32 v213, v42, v43
	global_store_dwordx2 v231, v[212:213], s[6:7] offset:64
	v_mul_f32_e32 v44, v238, v44
	v_mul_f32_e32 v45, v238, v45
	v_mul_f32_e32 v46, v238, v46
	v_mul_f32_e32 v47, v238, v47
	v_cvt_pk_bf16_f32 v214, v44, v45
	v_cvt_pk_bf16_f32 v215, v46, v47
	global_store_dwordx2 v231, v[214:215], s[6:7] offset:96
	v_mul_f32_e32 v48, v238, v48
	v_mul_f32_e32 v49, v238, v49
	v_mul_f32_e32 v50, v238, v50
	v_mul_f32_e32 v51, v238, v51
	v_cvt_pk_bf16_f32 v212, v48, v49
	v_cvt_pk_bf16_f32 v213, v50, v51
	global_store_dwordx2 v231, v[212:213], s[6:7] offset:128
	v_mul_f32_e32 v52, v238, v52
	v_mul_f32_e32 v53, v238, v53
	v_mul_f32_e32 v54, v238, v54
	v_mul_f32_e32 v55, v238, v55
	v_cvt_pk_bf16_f32 v214, v52, v53
	v_cvt_pk_bf16_f32 v215, v54, v55
	global_store_dwordx2 v231, v[214:215], s[6:7] offset:160
	v_mul_f32_e32 v56, v238, v56
	v_mul_f32_e32 v57, v238, v57
	v_mul_f32_e32 v58, v238, v58
	v_mul_f32_e32 v59, v238, v59
	v_cvt_pk_bf16_f32 v212, v56, v57
	v_cvt_pk_bf16_f32 v213, v58, v59
	global_store_dwordx2 v231, v[212:213], s[6:7] offset:192
	v_mul_f32_e32 v60, v238, v60
	v_mul_f32_e32 v61, v238, v61
	v_mul_f32_e32 v62, v238, v62
	v_mul_f32_e32 v63, v238, v63
	v_cvt_pk_bf16_f32 v214, v60, v61
	v_cvt_pk_bf16_f32 v215, v62, v63
	global_store_dwordx2 v231, v[214:215], s[6:7] offset:224
	v_mul_f32_e32 v64, v238, v64
	v_mul_f32_e32 v65, v238, v65
	v_mul_f32_e32 v66, v238, v66
	v_mul_f32_e32 v67, v238, v67
	v_cvt_pk_bf16_f32 v212, v64, v65
	v_cvt_pk_bf16_f32 v213, v66, v67
	global_store_dwordx2 v231, v[212:213], s[6:7] offset:256
	v_mul_f32_e32 v68, v238, v68
	v_mul_f32_e32 v69, v238, v69
	v_mul_f32_e32 v70, v238, v70
	v_mul_f32_e32 v71, v238, v71
	v_cvt_pk_bf16_f32 v214, v68, v69
	v_cvt_pk_bf16_f32 v215, v70, v71
	global_store_dwordx2 v231, v[214:215], s[6:7] offset:288
	v_mul_f32_e32 v72, v238, v72
	v_mul_f32_e32 v73, v238, v73
	v_mul_f32_e32 v74, v238, v74
	v_mul_f32_e32 v75, v238, v75
	v_cvt_pk_bf16_f32 v212, v72, v73
	v_cvt_pk_bf16_f32 v213, v74, v75
	global_store_dwordx2 v231, v[212:213], s[6:7] offset:320
	v_mul_f32_e32 v76, v238, v76
	v_mul_f32_e32 v77, v238, v77
	v_mul_f32_e32 v78, v238, v78
	v_mul_f32_e32 v79, v238, v79
	v_cvt_pk_bf16_f32 v214, v76, v77
	v_cvt_pk_bf16_f32 v215, v78, v79
	global_store_dwordx2 v231, v[214:215], s[6:7] offset:352
	v_mul_f32_e32 v80, v238, v80
	v_mul_f32_e32 v81, v238, v81
	v_mul_f32_e32 v82, v238, v82
	v_mul_f32_e32 v83, v238, v83
	v_cvt_pk_bf16_f32 v212, v80, v81
	v_cvt_pk_bf16_f32 v213, v82, v83
	global_store_dwordx2 v231, v[212:213], s[6:7] offset:384
	v_mul_f32_e32 v84, v238, v84
	v_mul_f32_e32 v85, v238, v85
	v_mul_f32_e32 v86, v238, v86
	v_mul_f32_e32 v87, v238, v87
	v_cvt_pk_bf16_f32 v214, v84, v85
	v_cvt_pk_bf16_f32 v215, v86, v87
	global_store_dwordx2 v231, v[214:215], s[6:7] offset:416
	v_mul_f32_e32 v88, v238, v88
	v_mul_f32_e32 v89, v238, v89
	v_mul_f32_e32 v90, v238, v90
	v_mul_f32_e32 v91, v238, v91
	v_cvt_pk_bf16_f32 v212, v88, v89
	v_cvt_pk_bf16_f32 v213, v90, v91
	global_store_dwordx2 v231, v[212:213], s[6:7] offset:448
	v_mul_f32_e32 v92, v238, v92
	v_mul_f32_e32 v93, v238, v93
	v_mul_f32_e32 v94, v238, v94
	v_mul_f32_e32 v95, v238, v95
	v_cvt_pk_bf16_f32 v214, v92, v93
	v_cvt_pk_bf16_f32 v215, v94, v95
	global_store_dwordx2 v231, v[214:215], s[6:7] offset:480
	s_add_u32 s8, s8, s9
	s_cmp_lt_u32 s8, 0x800
	s_cbranch_scc1 .Lp7_tile
.Lp7_done:
.LBB0_1031:
	s_cmp_lt_i32 s89, 8
	s_cbranch_scc1 .LBB0_1085
	s_waitcnt vmcnt(0)
	s_waitcnt lgkmcnt(0)
	s_barrier
	s_mov_b64 s[0:1], exec
	v_readlane_b32 s2, v248, 24
	v_readlane_b32 s3, v248, 25
	s_and_b64 s[2:3], s[0:1], s[2:3]
	s_mov_b64 exec, s[2:3]
	s_cbranch_execz .LBB0_1084
	v_mov_b32_e32 v0, 0x12000
	s_waitcnt vmcnt(0) expcnt(0) lgkmcnt(0)
	ds_read_b32 v2, v0
	v_mov_b32_e32 v0, 0x12004
	ds_read_b32 v0, v0
	s_waitcnt lgkmcnt(1)
	v_cmp_ne_u32_e32 vcc, 0, v2
	s_cbranch_vccnz .LBB0_1048
	s_load_dwordx2 s[6:7], s[68:69], 0x200
	s_load_dword s5, s[68:69], 0x208
	s_add_u32 s2, s64, 0x1000
	s_addc_u32 s3, s65, 0
	s_add_u32 s4, s64, 0x1100
	s_waitcnt lgkmcnt(0)
	s_mul_i32 s16, s7, s6
	s_mul_i32 s16, s16, s5
	s_addc_u32 s5, s65, 0
	s_add_u32 s6, s64, 0x1200
	s_addc_u32 s7, s65, 0
	s_add_u32 s8, s64, 0x1300
	s_addc_u32 s9, s65, 0
	s_mov_b32 s17, 1
	v_mov_b32_e32 v16, 0
	s_branch .LBB0_1036
